# ctx-row GEMM tiles for layer-0 out-proj/FF2 (64x64, K split over waves) so the 256x256 GEMM runs exact rounds; S5 PASS-3 block totals via DPP row broadcast; pipelined P0 transposes and pack copies
# speedup vs baseline: 1.2763x; 1.0503x over previous
_Z3fwd4Args:
	s_load_dwordx8 s[24:31], s[0:1], 0x100
	s_load_dwordx4 s[4:7], s[0:1], 0x120
	s_load_dwordx2 s[78:79], s[0:1], 0x130
	s_load_dword s33, s[0:1], 0x148
	s_load_dwordx2 s[34:35], s[0:1], 0x140
	v_writelane_b32 v243, s0, 0
	v_writelane_b32 v243, s1, 1
	v_and_b32_e32 v186, 0x3ff, v0
	s_mov_b32 s69, s2
	s_waitcnt lgkmcnt(0)
	v_writelane_b32 v247, s4, 0
	s_movk_i32 s2, 0x3ff
	v_readfirstlane_b32 s51, v186
	v_writelane_b32 v247, s5, 1
	v_writelane_b32 v247, s6, 2
	v_writelane_b32 v247, s7, 3
	s_add_u32 s6, s0, 0x140
	s_addc_u32 s7, s1, 0
	s_cmp_gt_i32 s78, -1
	s_cbranch_scc1 .LBB0_12
	v_lshrrev_b32_e32 v1, 20, v0
	v_lshrrev_b32_e32 v0, 10, v0
	v_or_b32_e32 v0, v0, v1
	v_and_or_b32 v0, v0, s2, v186
	v_cmp_eq_u32_e32 vcc, 0, v0
	s_barrier
	s_and_saveexec_b64 s[4:5], vcc
	s_cbranch_execz .LBB0_11
	buffer_wbl2 sc1
	s_load_dwordx2 s[6:7], s[6:7], 0x58
	s_mov_b64 s[8:9], exec
	v_mbcnt_lo_u32_b32 v0, s8, 0
	v_mbcnt_hi_u32_b32 v0, s9, v0
	v_cmp_eq_u32_e32 vcc, 0, v0
	s_waitcnt lgkmcnt(0)
	s_load_dword s2, s[6:7], 0x28
	s_and_saveexec_b64 s[10:11], vcc
	s_cbranch_execz .LBB0_4
	s_bcnt1_i32_b64 s8, s[8:9]
	v_mov_b32_e32 v1, 0
	v_mov_b32_e32 v2, s8
	global_atomic_add v1, v1, v2, s[6:7] offset:32 sc0

.LBB0_24:
	s_cmpk_gt_i32 s2, 0xbf
	s_cbranch_scc0 .LBB0_51
	s_cmpk_lg_i32 s2, 0xc0
	s_cbranch_scc0 .LBB0_52
	s_branch .LBB0_21
	s_add_i32 s61, s2, 0xffffff3f
	s_cmpk_gt_u32 s61, 0xaff
	s_cselect_b64 s[0:1], -1, 0
	s_and_b64 s[56:57], s[0:1], exec
	s_cselect_b32 s60, 0xfffff500, 0
	s_add_i32 s60, s60, s61
	s_and_b64 s[56:57], s[0:1], exec
	s_cselect_b32 s52, 0x1600000, 0
	v_readlane_b32 s56, v247, 26
	s_add_u32 s58, s56, s52
	v_readlane_b32 s52, v247, 28
	s_addc_u32 s59, s52, 0
	s_cmpk_gt_i32 s60, 0x1bf
	s_mov_b64 s[56:57], -1
	s_cbranch_scc0 .LBB0_48
	s_cmpk_gt_u32 s60, 0x1cf
	s_cbranch_scc0 .LBB0_45
	s_cmpk_gt_u32 s60, 0x1df
	s_cbranch_scc0 .LBB0_42
	s_cmpk_gt_u32 s60, 0x1ff
	s_cbranch_scc0 .LBB0_39
	s_cmpk_gt_u32 s60, 0x2ff
	s_cbranch_scc0 .LBB0_36
	s_and_b64 s[56:57], s[0:1], exec
	s_cselect_b32 s52, 0x1000000, 0
	s_cmpk_gt_u32 s60, 0x6ff
	s_mov_b64 s[56:57], -1
	s_cbranch_scc0 .LBB0_33
	s_add_i32 s56, s60, 0xfffff900
	s_add_u32 s64, s26, s52
	s_addc_u32 s65, s27, 0
	s_lshr_b32 s66, s56, 4
	s_lshl_b32 s67, s66, 6
	v_or_b32_e32 v4, s67, v2
	s_lshl_b32 s57, s66, 10
	s_lshl_b32 s56, s56, 6
	v_lshlrev_b64 v[22:23], 12, v[4:5]
	v_or_b32_e32 v4, s67, v1
	s_sub_i32 s56, s56, s57
	v_lshlrev_b64 v[24:25], 12, v[4:5]
	v_or_b32_e32 v4, s67, v3
	s_ashr_i32 s57, s56, 31
	v_lshlrev_b64 v[44:45], 12, v[4:5]
	v_or_b32_e32 v4, s67, v26
	s_lshl_b64 s[62:63], s[56:57], 2
	v_lshlrev_b64 v[46:47], 12, v[4:5]
	v_or_b32_e32 v4, s67, v27
	s_add_u32 s62, s64, s62
	v_lshlrev_b64 v[48:49], 12, v[4:5]
	v_or_b32_e32 v4, s67, v28
	s_addc_u32 s63, s65, s63
	v_mov_b32_e32 v17, v5
	v_lshlrev_b64 v[50:51], 12, v[4:5]
	v_or_b32_e32 v4, s67, v29
	v_lshl_add_u64 v[20:21], s[62:63], 0, v[16:17]
	v_lshlrev_b64 v[52:53], 12, v[4:5]
	v_add_u32_e32 v4, s67, v30
	v_lshl_add_u64 v[22:23], v[20:21], 0, v[22:23]
	v_lshl_add_u64 v[46:47], v[20:21], 0, v[46:47]
	v_lshl_add_u64 v[48:49], v[20:21], 0, v[48:49]
	v_lshl_add_u64 v[50:51], v[20:21], 0, v[50:51]
	v_lshlrev_b64 v[54:55], 12, v[4:5]
	v_lshl_add_u64 v[24:25], v[20:21], 0, v[24:25]
	v_lshl_add_u64 v[44:45], v[20:21], 0, v[44:45]
	v_lshl_add_u64 v[52:53], v[20:21], 0, v[52:53]
	v_lshl_add_u64 v[20:21], v[20:21], 0, v[54:55]
	global_load_dword v4, v[22:23], off
	global_load_dword v17, v[24:25], off
	global_load_dword v54, v[44:45], off
	s_nop 0
	global_load_dword v46, v[46:47], off
	s_nop 0
	global_load_dword v47, v[48:49], off
	s_nop 0
	global_load_dword v48, v[50:51], off
	global_load_dword v49, v[52:53], off
	s_nop 0
	global_load_dword v50, v[20:21], off
	s_lshl_b32 s57, s66, 7
	s_add_u32 s62, s58, s57
	v_mov_b32_e32 v19, v5
	v_or_b32_e32 v20, s56, v31
	s_addc_u32 s63, s59, 0
	v_or_b32_e32 v22, s56, v33
	v_or_b32_e32 v24, s56, v34
	v_ashrrev_i32_e32 v21, 31, v20
	v_lshl_add_u64 v[44:45], s[62:63], 0, v[18:19]
	s_mov_b64 s[62:63], 0xe00000
	v_ashrrev_i32_e32 v23, 31, v22
	v_ashrrev_i32_e32 v25, 31, v24
	v_lshlrev_b64 v[20:21], 13, v[20:21]
	v_lshl_add_u64 v[44:45], v[44:45], 0, s[62:63]
	s_mov_b32 s57, 0xffff0000
	v_lshlrev_b64 v[22:23], 13, v[22:23]
	v_lshlrev_b64 v[24:25], 13, v[24:25]
	v_lshl_add_u64 v[20:21], v[44:45], 0, v[20:21]
	v_lshl_add_u64 v[22:23], v[44:45], 0, v[22:23]
	v_lshl_add_u64 v[24:25], v[44:45], 0, v[24:25]
	v_readlane_b32 s78, v247, 22
	v_readlane_b32 s79, v247, 23
	s_waitcnt vmcnt(7)
	ds_write_b32 v39, v4
	s_waitcnt vmcnt(6)
	ds_write_b32 v39, v17 offset:2080
	s_waitcnt vmcnt(5)
	ds_write_b32 v39, v54 offset:4160
	s_waitcnt vmcnt(4)
	ds_write_b32 v39, v46 offset:6240
	s_waitcnt vmcnt(3)
	ds_write_b32 v39, v47 offset:8320
	s_waitcnt vmcnt(2)
	ds_write_b32 v39, v48 offset:10400
	s_waitcnt vmcnt(1)
	ds_write_b32 v39, v49 offset:12480
	s_waitcnt vmcnt(0)
	ds_write_b32 v39, v50 offset:14560
	s_waitcnt lgkmcnt(0)
	s_barrier
	ds_read2_b32 v[46:47], v32 offset1:16
	ds_read2_b32 v[48:49], v32 offset0:65 offset1:81
	ds_read2_b32 v[50:51], v32 offset0:32 offset1:48
	ds_read2_b32 v[52:53], v32 offset0:97 offset1:113
	s_waitcnt lgkmcnt(3)
	v_bfe_u32 v4, v46, 16, 1
	s_waitcnt lgkmcnt(2)
	v_bfe_u32 v17, v48, 16, 1
	v_bfe_u32 v19, v47, 16, 1
	s_waitcnt lgkmcnt(1)
	v_bfe_u32 v55, v50, 16, 1
	v_add3_u32 v4, v46, v4, s97
	v_bfe_u32 v54, v49, 16, 1
	s_waitcnt lgkmcnt(0)
	v_bfe_u32 v56, v52, 16, 1
	v_add3_u32 v17, v48, v17, s97
	v_add3_u32 v19, v47, v19, s97
	v_add3_u32 v47, v50, v55, s97
	v_lshrrev_b32_e32 v4, 16, v4
	v_add3_u32 v46, v49, v54, s97
	v_add3_u32 v48, v52, v56, s97
	v_lshrrev_b32_e32 v19, 16, v19
	v_lshrrev_b32_e32 v47, 16, v47
	v_and_or_b32 v4, v17, s57, v4
	v_bfe_u32 v57, v51, 16, 1
	v_and_or_b32 v17, v46, s57, v19
	v_and_or_b32 v19, v48, s57, v47
	global_store_dword v[20:21], v4, off
	global_store_dword v[22:23], v17, off
	global_store_dword v[24:25], v19, off
	v_add_u32_e32 v20, s56, v35
	v_bfe_u32 v58, v53, 16, 1
	v_add3_u32 v49, v51, v57, s97
	v_ashrrev_i32_e32 v21, 31, v20
	v_lshrrev_b32_e32 v49, 16, v49
	v_add3_u32 v4, v53, v58, s97
	v_lshlrev_b64 v[20:21], 13, v[20:21]
	v_and_or_b32 v4, v4, s57, v49
	v_lshl_add_u64 v[20:21], v[44:45], 0, v[20:21]
	global_store_dword v[20:21], v4, off
	s_barrier
	s_mov_b64 s[56:57], 0

.LBB0_60:
	s_mov_b32 s0, 0x6000
	s_mov_b32 s1, 0
	v_mov_b64_e32 v[76:77], v[20:21]
	global_load_dword v80, v[76:77], off
	v_lshl_add_u64 v[76:77], v[76:77], 0, s[0:1]
	global_load_dword v81, v[76:77], off
	v_lshl_add_u64 v[76:77], v[76:77], 0, s[0:1]
	global_load_dword v82, v[76:77], off
	v_lshl_add_u64 v[76:77], v[76:77], 0, s[0:1]
	global_load_dword v83, v[76:77], off
	v_lshl_add_u64 v[76:77], v[76:77], 0, s[0:1]
	global_load_dword v84, v[76:77], off
	v_lshl_add_u64 v[76:77], v[76:77], 0, s[0:1]
	global_load_dword v85, v[76:77], off
	v_lshl_add_u64 v[76:77], v[76:77], 0, s[0:1]
	global_load_dword v86, v[76:77], off
	v_lshl_add_u64 v[76:77], v[76:77], 0, s[0:1]
	global_load_dword v87, v[76:77], off
	v_lshl_add_u64 v[76:77], v[76:77], 0, s[0:1]
	global_load_dword v88, v[76:77], off
	v_lshl_add_u64 v[76:77], v[76:77], 0, s[0:1]
	global_load_dword v89, v[76:77], off
	v_lshl_add_u64 v[76:77], v[76:77], 0, s[0:1]
	global_load_dword v90, v[76:77], off
	v_lshl_add_u64 v[76:77], v[76:77], 0, s[0:1]
	global_load_dword v91, v[76:77], off
	v_lshl_add_u64 v[76:77], v[76:77], 0, s[0:1]
	global_load_dword v92, v[76:77], off
	v_lshl_add_u64 v[76:77], v[76:77], 0, s[0:1]
	global_load_dword v93, v[76:77], off
	v_lshl_add_u64 v[76:77], v[76:77], 0, s[0:1]
	global_load_dword v94, v[76:77], off
	v_lshl_add_u64 v[76:77], v[76:77], 0, s[0:1]
	global_load_dword v95, v[76:77], off
	v_lshl_add_u64 v[76:77], v[76:77], 0, s[0:1]
	global_load_dword v96, v[76:77], off
	v_lshl_add_u64 v[76:77], v[76:77], 0, s[0:1]
	global_load_dword v97, v[76:77], off
	v_lshl_add_u64 v[76:77], v[76:77], 0, s[0:1]
	global_load_dword v98, v[76:77], off
	v_lshl_add_u64 v[76:77], v[76:77], 0, s[0:1]
	global_load_dword v99, v[76:77], off
	v_lshl_add_u64 v[76:77], v[76:77], 0, s[0:1]
	global_load_dword v100, v[76:77], off
	v_lshl_add_u64 v[76:77], v[76:77], 0, s[0:1]
	global_load_dword v101, v[76:77], off
	v_lshl_add_u64 v[76:77], v[76:77], 0, s[0:1]
	global_load_dword v102, v[76:77], off
	v_lshl_add_u64 v[76:77], v[76:77], 0, s[0:1]
	global_load_dword v103, v[76:77], off
	v_lshl_add_u64 v[76:77], v[76:77], 0, s[0:1]
	global_load_dword v104, v[76:77], off
	v_lshl_add_u64 v[76:77], v[76:77], 0, s[0:1]
	global_load_dword v105, v[76:77], off
	v_lshl_add_u64 v[76:77], v[76:77], 0, s[0:1]
	global_load_dword v106, v[76:77], off
	v_lshl_add_u64 v[76:77], v[76:77], 0, s[0:1]
	global_load_dword v107, v[76:77], off
	v_lshl_add_u64 v[76:77], v[76:77], 0, s[0:1]
	global_load_dword v108, v[76:77], off
	v_lshl_add_u64 v[76:77], v[76:77], 0, s[0:1]
	global_load_dword v109, v[76:77], off
	v_lshl_add_u64 v[76:77], v[76:77], 0, s[0:1]
	global_load_dword v110, v[76:77], off
	v_lshl_add_u64 v[76:77], v[76:77], 0, s[0:1]
	global_load_dword v111, v[76:77], off
	v_lshl_add_u64 v[76:77], v[76:77], 0, s[0:1]
	ds_read_b128 v[44:47], v17
	ds_read_b128 v[48:51], v17 offset:4096
	ds_read_b128 v[52:55], v17 offset:8192
	ds_read_b128 v[56:59], v17 offset:12288
	ds_read_b128 v[60:63], v17 offset:16384
	v_add_u32_e32 v17, 16, v17
	s_waitcnt vmcnt(31)
	s_waitcnt lgkmcnt(0)
	v_fmac_f32_e32 v22, v80, v44
	v_fmac_f32_e32 v23, v80, v48
	v_fmac_f32_e32 v4, v80, v52
	v_fmac_f32_e32 v25, v80, v56
	v_fmac_f32_e32 v24, v80, v60
	global_load_dword v80, v[76:77], off
	v_lshl_add_u64 v[76:77], v[76:77], 0, s[0:1]
	s_waitcnt vmcnt(31)
	v_fmac_f32_e32 v22, v81, v45
	v_fmac_f32_e32 v23, v81, v49
	v_fmac_f32_e32 v4, v81, v53
	v_fmac_f32_e32 v25, v81, v57
	v_fmac_f32_e32 v24, v81, v61
	global_load_dword v81, v[76:77], off
	v_lshl_add_u64 v[76:77], v[76:77], 0, s[0:1]
	s_waitcnt vmcnt(31)
	v_fmac_f32_e32 v22, v82, v46
	v_fmac_f32_e32 v23, v82, v50
	v_fmac_f32_e32 v4, v82, v54
	v_fmac_f32_e32 v25, v82, v58
	v_fmac_f32_e32 v24, v82, v62
	global_load_dword v82, v[76:77], off
	v_lshl_add_u64 v[76:77], v[76:77], 0, s[0:1]
	s_waitcnt vmcnt(31)
	v_fmac_f32_e32 v22, v83, v47
	v_fmac_f32_e32 v23, v83, v51
	v_fmac_f32_e32 v4, v83, v55
	v_fmac_f32_e32 v25, v83, v59
	v_fmac_f32_e32 v24, v83, v63
	global_load_dword v83, v[76:77], off
	v_lshl_add_u64 v[76:77], v[76:77], 0, s[0:1]
	ds_read_b128 v[44:47], v17
	ds_read_b128 v[48:51], v17 offset:4096
	ds_read_b128 v[52:55], v17 offset:8192
	ds_read_b128 v[56:59], v17 offset:12288
	ds_read_b128 v[60:63], v17 offset:16384
	v_add_u32_e32 v17, 16, v17
	s_waitcnt vmcnt(31)
	s_waitcnt lgkmcnt(0)
	v_fmac_f32_e32 v22, v84, v44
	v_fmac_f32_e32 v23, v84, v48
	v_fmac_f32_e32 v4, v84, v52
	v_fmac_f32_e32 v25, v84, v56
	v_fmac_f32_e32 v24, v84, v60
	global_load_dword v84, v[76:77], off
	v_lshl_add_u64 v[76:77], v[76:77], 0, s[0:1]
	s_waitcnt vmcnt(31)
	v_fmac_f32_e32 v22, v85, v45
	v_fmac_f32_e32 v23, v85, v49
	v_fmac_f32_e32 v4, v85, v53
	v_fmac_f32_e32 v25, v85, v57
	v_fmac_f32_e32 v24, v85, v61
	global_load_dword v85, v[76:77], off
	v_lshl_add_u64 v[76:77], v[76:77], 0, s[0:1]
	s_waitcnt vmcnt(31)
	v_fmac_f32_e32 v22, v86, v46
	v_fmac_f32_e32 v23, v86, v50
	v_fmac_f32_e32 v4, v86, v54
	v_fmac_f32_e32 v25, v86, v58
	v_fmac_f32_e32 v24, v86, v62
	global_load_dword v86, v[76:77], off
	v_lshl_add_u64 v[76:77], v[76:77], 0, s[0:1]
	s_waitcnt vmcnt(31)
	v_fmac_f32_e32 v22, v87, v47
	v_fmac_f32_e32 v23, v87, v51
	v_fmac_f32_e32 v4, v87, v55
	v_fmac_f32_e32 v25, v87, v59
	v_fmac_f32_e32 v24, v87, v63
	global_load_dword v87, v[76:77], off
	v_lshl_add_u64 v[76:77], v[76:77], 0, s[0:1]
	ds_read_b128 v[44:47], v17
	ds_read_b128 v[48:51], v17 offset:4096
	ds_read_b128 v[52:55], v17 offset:8192
	ds_read_b128 v[56:59], v17 offset:12288
	ds_read_b128 v[60:63], v17 offset:16384
	v_add_u32_e32 v17, 16, v17
	s_waitcnt vmcnt(31)
	s_waitcnt lgkmcnt(0)
	v_fmac_f32_e32 v22, v88, v44
	v_fmac_f32_e32 v23, v88, v48
	v_fmac_f32_e32 v4, v88, v52
	v_fmac_f32_e32 v25, v88, v56
	v_fmac_f32_e32 v24, v88, v60
	global_load_dword v88, v[76:77], off
	v_lshl_add_u64 v[76:77], v[76:77], 0, s[0:1]
	s_waitcnt vmcnt(31)
	v_fmac_f32_e32 v22, v89, v45
	v_fmac_f32_e32 v23, v89, v49
	v_fmac_f32_e32 v4, v89, v53
	v_fmac_f32_e32 v25, v89, v57
	v_fmac_f32_e32 v24, v89, v61
	global_load_dword v89, v[76:77], off
	v_lshl_add_u64 v[76:77], v[76:77], 0, s[0:1]
	s_waitcnt vmcnt(31)
	v_fmac_f32_e32 v22, v90, v46
	v_fmac_f32_e32 v23, v90, v50
	v_fmac_f32_e32 v4, v90, v54
	v_fmac_f32_e32 v25, v90, v58
	v_fmac_f32_e32 v24, v90, v62
	global_load_dword v90, v[76:77], off
	v_lshl_add_u64 v[76:77], v[76:77], 0, s[0:1]
	s_waitcnt vmcnt(31)
	v_fmac_f32_e32 v22, v91, v47
	v_fmac_f32_e32 v23, v91, v51
	v_fmac_f32_e32 v4, v91, v55
	v_fmac_f32_e32 v25, v91, v59
	v_fmac_f32_e32 v24, v91, v63
	global_load_dword v91, v[76:77], off
	v_lshl_add_u64 v[76:77], v[76:77], 0, s[0:1]
	ds_read_b128 v[44:47], v17
	ds_read_b128 v[48:51], v17 offset:4096
	ds_read_b128 v[52:55], v17 offset:8192
	ds_read_b128 v[56:59], v17 offset:12288
	ds_read_b128 v[60:63], v17 offset:16384
	v_add_u32_e32 v17, 16, v17
	s_waitcnt vmcnt(31)
	s_waitcnt lgkmcnt(0)
	v_fmac_f32_e32 v22, v92, v44
	v_fmac_f32_e32 v23, v92, v48
	v_fmac_f32_e32 v4, v92, v52
	v_fmac_f32_e32 v25, v92, v56
	v_fmac_f32_e32 v24, v92, v60
	global_load_dword v92, v[76:77], off
	v_lshl_add_u64 v[76:77], v[76:77], 0, s[0:1]
	s_waitcnt vmcnt(31)
	v_fmac_f32_e32 v22, v93, v45
	v_fmac_f32_e32 v23, v93, v49
	v_fmac_f32_e32 v4, v93, v53
	v_fmac_f32_e32 v25, v93, v57
	v_fmac_f32_e32 v24, v93, v61
	global_load_dword v93, v[76:77], off
	v_lshl_add_u64 v[76:77], v[76:77], 0, s[0:1]
	s_waitcnt vmcnt(31)
	v_fmac_f32_e32 v22, v94, v46
	v_fmac_f32_e32 v23, v94, v50
	v_fmac_f32_e32 v4, v94, v54
	v_fmac_f32_e32 v25, v94, v58
	v_fmac_f32_e32 v24, v94, v62
	global_load_dword v94, v[76:77], off
	v_lshl_add_u64 v[76:77], v[76:77], 0, s[0:1]
	s_waitcnt vmcnt(31)
	v_fmac_f32_e32 v22, v95, v47
	v_fmac_f32_e32 v23, v95, v51
	v_fmac_f32_e32 v4, v95, v55
	v_fmac_f32_e32 v25, v95, v59
	v_fmac_f32_e32 v24, v95, v63
	global_load_dword v95, v[76:77], off
	v_lshl_add_u64 v[76:77], v[76:77], 0, s[0:1]
	ds_read_b128 v[44:47], v17
	ds_read_b128 v[48:51], v17 offset:4096
	ds_read_b128 v[52:55], v17 offset:8192
	ds_read_b128 v[56:59], v17 offset:12288
	ds_read_b128 v[60:63], v17 offset:16384
	v_add_u32_e32 v17, 16, v17
	s_waitcnt vmcnt(31)
	s_waitcnt lgkmcnt(0)
	v_fmac_f32_e32 v22, v96, v44
	v_fmac_f32_e32 v23, v96, v48
	v_fmac_f32_e32 v4, v96, v52
	v_fmac_f32_e32 v25, v96, v56
	v_fmac_f32_e32 v24, v96, v60
	global_load_dword v96, v[76:77], off
	v_lshl_add_u64 v[76:77], v[76:77], 0, s[0:1]
	s_waitcnt vmcnt(31)
	v_fmac_f32_e32 v22, v97, v45
	v_fmac_f32_e32 v23, v97, v49
	v_fmac_f32_e32 v4, v97, v53
	v_fmac_f32_e32 v25, v97, v57
	v_fmac_f32_e32 v24, v97, v61
	global_load_dword v97, v[76:77], off
	v_lshl_add_u64 v[76:77], v[76:77], 0, s[0:1]
	s_waitcnt vmcnt(31)
	v_fmac_f32_e32 v22, v98, v46
	v_fmac_f32_e32 v23, v98, v50
	v_fmac_f32_e32 v4, v98, v54
	v_fmac_f32_e32 v25, v98, v58
	v_fmac_f32_e32 v24, v98, v62
	global_load_dword v98, v[76:77], off
	v_lshl_add_u64 v[76:77], v[76:77], 0, s[0:1]
	s_waitcnt vmcnt(31)
	v_fmac_f32_e32 v22, v99, v47
	v_fmac_f32_e32 v23, v99, v51
	v_fmac_f32_e32 v4, v99, v55
	v_fmac_f32_e32 v25, v99, v59
	v_fmac_f32_e32 v24, v99, v63
	global_load_dword v99, v[76:77], off
	v_lshl_add_u64 v[76:77], v[76:77], 0, s[0:1]
	ds_read_b128 v[44:47], v17
	ds_read_b128 v[48:51], v17 offset:4096
	ds_read_b128 v[52:55], v17 offset:8192
	ds_read_b128 v[56:59], v17 offset:12288
	ds_read_b128 v[60:63], v17 offset:16384
	v_add_u32_e32 v17, 16, v17
	s_waitcnt vmcnt(31)
	s_waitcnt lgkmcnt(0)
	v_fmac_f32_e32 v22, v100, v44
	v_fmac_f32_e32 v23, v100, v48
	v_fmac_f32_e32 v4, v100, v52
	v_fmac_f32_e32 v25, v100, v56
	v_fmac_f32_e32 v24, v100, v60
	global_load_dword v100, v[76:77], off
	v_lshl_add_u64 v[76:77], v[76:77], 0, s[0:1]
	s_waitcnt vmcnt(31)
	v_fmac_f32_e32 v22, v101, v45
	v_fmac_f32_e32 v23, v101, v49
	v_fmac_f32_e32 v4, v101, v53
	v_fmac_f32_e32 v25, v101, v57
	v_fmac_f32_e32 v24, v101, v61
	global_load_dword v101, v[76:77], off
	v_lshl_add_u64 v[76:77], v[76:77], 0, s[0:1]
	s_waitcnt vmcnt(31)
	v_fmac_f32_e32 v22, v102, v46
	v_fmac_f32_e32 v23, v102, v50
	v_fmac_f32_e32 v4, v102, v54
	v_fmac_f32_e32 v25, v102, v58
	v_fmac_f32_e32 v24, v102, v62
	global_load_dword v102, v[76:77], off
	v_lshl_add_u64 v[76:77], v[76:77], 0, s[0:1]
	s_waitcnt vmcnt(31)
	v_fmac_f32_e32 v22, v103, v47
	v_fmac_f32_e32 v23, v103, v51
	v_fmac_f32_e32 v4, v103, v55
	v_fmac_f32_e32 v25, v103, v59
	v_fmac_f32_e32 v24, v103, v63
	global_load_dword v103, v[76:77], off
	v_lshl_add_u64 v[76:77], v[76:77], 0, s[0:1]
	ds_read_b128 v[44:47], v17
	ds_read_b128 v[48:51], v17 offset:4096
	ds_read_b128 v[52:55], v17 offset:8192
	ds_read_b128 v[56:59], v17 offset:12288
	ds_read_b128 v[60:63], v17 offset:16384
	v_add_u32_e32 v17, 16, v17
	s_waitcnt vmcnt(31)
	s_waitcnt lgkmcnt(0)
	v_fmac_f32_e32 v22, v104, v44
	v_fmac_f32_e32 v23, v104, v48
	v_fmac_f32_e32 v4, v104, v52
	v_fmac_f32_e32 v25, v104, v56
	v_fmac_f32_e32 v24, v104, v60
	global_load_dword v104, v[76:77], off
	v_lshl_add_u64 v[76:77], v[76:77], 0, s[0:1]
	s_waitcnt vmcnt(31)
	v_fmac_f32_e32 v22, v105, v45
	v_fmac_f32_e32 v23, v105, v49
	v_fmac_f32_e32 v4, v105, v53
	v_fmac_f32_e32 v25, v105, v57
	v_fmac_f32_e32 v24, v105, v61
	global_load_dword v105, v[76:77], off
	v_lshl_add_u64 v[76:77], v[76:77], 0, s[0:1]
	s_waitcnt vmcnt(31)
	v_fmac_f32_e32 v22, v106, v46
	v_fmac_f32_e32 v23, v106, v50
	v_fmac_f32_e32 v4, v106, v54
	v_fmac_f32_e32 v25, v106, v58
	v_fmac_f32_e32 v24, v106, v62
	global_load_dword v106, v[76:77], off
	v_lshl_add_u64 v[76:77], v[76:77], 0, s[0:1]
	s_waitcnt vmcnt(31)
	v_fmac_f32_e32 v22, v107, v47
	v_fmac_f32_e32 v23, v107, v51
	v_fmac_f32_e32 v4, v107, v55
	v_fmac_f32_e32 v25, v107, v59
	v_fmac_f32_e32 v24, v107, v63
	global_load_dword v107, v[76:77], off
	v_lshl_add_u64 v[76:77], v[76:77], 0, s[0:1]
	ds_read_b128 v[44:47], v17
	ds_read_b128 v[48:51], v17 offset:4096
	ds_read_b128 v[52:55], v17 offset:8192
	ds_read_b128 v[56:59], v17 offset:12288
	ds_read_b128 v[60:63], v17 offset:16384
	v_add_u32_e32 v17, 16, v17
	s_waitcnt vmcnt(31)
	s_waitcnt lgkmcnt(0)
	v_fmac_f32_e32 v22, v108, v44
	v_fmac_f32_e32 v23, v108, v48
	v_fmac_f32_e32 v4, v108, v52
	v_fmac_f32_e32 v25, v108, v56
	v_fmac_f32_e32 v24, v108, v60
	global_load_dword v108, v[76:77], off
	v_lshl_add_u64 v[76:77], v[76:77], 0, s[0:1]
	s_waitcnt vmcnt(31)
	v_fmac_f32_e32 v22, v109, v45
	v_fmac_f32_e32 v23, v109, v49
	v_fmac_f32_e32 v4, v109, v53
	v_fmac_f32_e32 v25, v109, v57
	v_fmac_f32_e32 v24, v109, v61
	global_load_dword v109, v[76:77], off
	v_lshl_add_u64 v[76:77], v[76:77], 0, s[0:1]
	s_waitcnt vmcnt(31)
	v_fmac_f32_e32 v22, v110, v46
	v_fmac_f32_e32 v23, v110, v50
	v_fmac_f32_e32 v4, v110, v54
	v_fmac_f32_e32 v25, v110, v58
	v_fmac_f32_e32 v24, v110, v62
	global_load_dword v110, v[76:77], off
	v_lshl_add_u64 v[76:77], v[76:77], 0, s[0:1]
	s_waitcnt vmcnt(31)
	v_fmac_f32_e32 v22, v111, v47
	v_fmac_f32_e32 v23, v111, v51
	v_fmac_f32_e32 v4, v111, v55
	v_fmac_f32_e32 v25, v111, v59
	v_fmac_f32_e32 v24, v111, v63
	global_load_dword v111, v[76:77], off
	v_lshl_add_u64 v[76:77], v[76:77], 0, s[0:1]
	ds_read_b128 v[44:47], v17
	ds_read_b128 v[48:51], v17 offset:4096
	ds_read_b128 v[52:55], v17 offset:8192
	ds_read_b128 v[56:59], v17 offset:12288
	ds_read_b128 v[60:63], v17 offset:16384
	v_add_u32_e32 v17, 16, v17
	s_waitcnt vmcnt(31)
	s_waitcnt lgkmcnt(0)
	v_fmac_f32_e32 v22, v80, v44
	v_fmac_f32_e32 v23, v80, v48
	v_fmac_f32_e32 v4, v80, v52
	v_fmac_f32_e32 v25, v80, v56
	v_fmac_f32_e32 v24, v80, v60
	global_load_dword v80, v[76:77], off
	v_lshl_add_u64 v[76:77], v[76:77], 0, s[0:1]
	s_waitcnt vmcnt(31)
	v_fmac_f32_e32 v22, v81, v45
	v_fmac_f32_e32 v23, v81, v49
	v_fmac_f32_e32 v4, v81, v53
	v_fmac_f32_e32 v25, v81, v57
	v_fmac_f32_e32 v24, v81, v61
	global_load_dword v81, v[76:77], off
	v_lshl_add_u64 v[76:77], v[76:77], 0, s[0:1]
	s_waitcnt vmcnt(31)
	v_fmac_f32_e32 v22, v82, v46
	v_fmac_f32_e32 v23, v82, v50
	v_fmac_f32_e32 v4, v82, v54
	v_fmac_f32_e32 v25, v82, v58
	v_fmac_f32_e32 v24, v82, v62
	global_load_dword v82, v[76:77], off
	v_lshl_add_u64 v[76:77], v[76:77], 0, s[0:1]
	s_waitcnt vmcnt(31)
	v_fmac_f32_e32 v22, v83, v47
	v_fmac_f32_e32 v23, v83, v51
	v_fmac_f32_e32 v4, v83, v55
	v_fmac_f32_e32 v25, v83, v59
	v_fmac_f32_e32 v24, v83, v63
	global_load_dword v83, v[76:77], off
	v_lshl_add_u64 v[76:77], v[76:77], 0, s[0:1]
	ds_read_b128 v[44:47], v17
	ds_read_b128 v[48:51], v17 offset:4096
	ds_read_b128 v[52:55], v17 offset:8192
	ds_read_b128 v[56:59], v17 offset:12288
	ds_read_b128 v[60:63], v17 offset:16384
	v_add_u32_e32 v17, 16, v17
	s_waitcnt vmcnt(31)
	s_waitcnt lgkmcnt(0)
	v_fmac_f32_e32 v22, v84, v44
	v_fmac_f32_e32 v23, v84, v48
	v_fmac_f32_e32 v4, v84, v52
	v_fmac_f32_e32 v25, v84, v56
	v_fmac_f32_e32 v24, v84, v60
	global_load_dword v84, v[76:77], off
	v_lshl_add_u64 v[76:77], v[76:77], 0, s[0:1]
	s_waitcnt vmcnt(31)
	v_fmac_f32_e32 v22, v85, v45
	v_fmac_f32_e32 v23, v85, v49
	v_fmac_f32_e32 v4, v85, v53
	v_fmac_f32_e32 v25, v85, v57
	v_fmac_f32_e32 v24, v85, v61
	global_load_dword v85, v[76:77], off
	v_lshl_add_u64 v[76:77], v[76:77], 0, s[0:1]
	s_waitcnt vmcnt(31)
	v_fmac_f32_e32 v22, v86, v46
	v_fmac_f32_e32 v23, v86, v50
	v_fmac_f32_e32 v4, v86, v54
	v_fmac_f32_e32 v25, v86, v58
	v_fmac_f32_e32 v24, v86, v62
	global_load_dword v86, v[76:77], off
	v_lshl_add_u64 v[76:77], v[76:77], 0, s[0:1]
	s_waitcnt vmcnt(31)
	v_fmac_f32_e32 v22, v87, v47
	v_fmac_f32_e32 v23, v87, v51
	v_fmac_f32_e32 v4, v87, v55
	v_fmac_f32_e32 v25, v87, v59
	v_fmac_f32_e32 v24, v87, v63
	global_load_dword v87, v[76:77], off
	v_lshl_add_u64 v[76:77], v[76:77], 0, s[0:1]
	ds_read_b128 v[44:47], v17
	ds_read_b128 v[48:51], v17 offset:4096
	ds_read_b128 v[52:55], v17 offset:8192
	ds_read_b128 v[56:59], v17 offset:12288
	ds_read_b128 v[60:63], v17 offset:16384
	v_add_u32_e32 v17, 16, v17
	s_waitcnt vmcnt(31)
	s_waitcnt lgkmcnt(0)
	v_fmac_f32_e32 v22, v88, v44
	v_fmac_f32_e32 v23, v88, v48
	v_fmac_f32_e32 v4, v88, v52
	v_fmac_f32_e32 v25, v88, v56
	v_fmac_f32_e32 v24, v88, v60
	global_load_dword v88, v[76:77], off
	v_lshl_add_u64 v[76:77], v[76:77], 0, s[0:1]
	s_waitcnt vmcnt(31)
	v_fmac_f32_e32 v22, v89, v45
	v_fmac_f32_e32 v23, v89, v49
	v_fmac_f32_e32 v4, v89, v53
	v_fmac_f32_e32 v25, v89, v57
	v_fmac_f32_e32 v24, v89, v61
	global_load_dword v89, v[76:77], off
	v_lshl_add_u64 v[76:77], v[76:77], 0, s[0:1]
	s_waitcnt vmcnt(31)
	v_fmac_f32_e32 v22, v90, v46
	v_fmac_f32_e32 v23, v90, v50
	v_fmac_f32_e32 v4, v90, v54
	v_fmac_f32_e32 v25, v90, v58
	v_fmac_f32_e32 v24, v90, v62
	global_load_dword v90, v[76:77], off
	v_lshl_add_u64 v[76:77], v[76:77], 0, s[0:1]
	s_waitcnt vmcnt(31)
	v_fmac_f32_e32 v22, v91, v47
	v_fmac_f32_e32 v23, v91, v51
	v_fmac_f32_e32 v4, v91, v55
	v_fmac_f32_e32 v25, v91, v59
	v_fmac_f32_e32 v24, v91, v63
	global_load_dword v91, v[76:77], off
	v_lshl_add_u64 v[76:77], v[76:77], 0, s[0:1]
	ds_read_b128 v[44:47], v17
	ds_read_b128 v[48:51], v17 offset:4096
	ds_read_b128 v[52:55], v17 offset:8192
	ds_read_b128 v[56:59], v17 offset:12288
	ds_read_b128 v[60:63], v17 offset:16384
	v_add_u32_e32 v17, 16, v17
	s_waitcnt vmcnt(31)
	s_waitcnt lgkmcnt(0)
	v_fmac_f32_e32 v22, v92, v44
	v_fmac_f32_e32 v23, v92, v48
	v_fmac_f32_e32 v4, v92, v52
	v_fmac_f32_e32 v25, v92, v56
	v_fmac_f32_e32 v24, v92, v60
	global_load_dword v92, v[76:77], off
	v_lshl_add_u64 v[76:77], v[76:77], 0, s[0:1]
	s_waitcnt vmcnt(31)
	v_fmac_f32_e32 v22, v93, v45
	v_fmac_f32_e32 v23, v93, v49
	v_fmac_f32_e32 v4, v93, v53
	v_fmac_f32_e32 v25, v93, v57
	v_fmac_f32_e32 v24, v93, v61
	global_load_dword v93, v[76:77], off
	v_lshl_add_u64 v[76:77], v[76:77], 0, s[0:1]
	s_waitcnt vmcnt(31)
	v_fmac_f32_e32 v22, v94, v46
	v_fmac_f32_e32 v23, v94, v50
	v_fmac_f32_e32 v4, v94, v54
	v_fmac_f32_e32 v25, v94, v58
	v_fmac_f32_e32 v24, v94, v62
	global_load_dword v94, v[76:77], off
	v_lshl_add_u64 v[76:77], v[76:77], 0, s[0:1]
	s_waitcnt vmcnt(31)
	v_fmac_f32_e32 v22, v95, v47
	v_fmac_f32_e32 v23, v95, v51
	v_fmac_f32_e32 v4, v95, v55
	v_fmac_f32_e32 v25, v95, v59
	v_fmac_f32_e32 v24, v95, v63
	global_load_dword v95, v[76:77], off
	v_lshl_add_u64 v[76:77], v[76:77], 0, s[0:1]
	ds_read_b128 v[44:47], v17
	ds_read_b128 v[48:51], v17 offset:4096
	ds_read_b128 v[52:55], v17 offset:8192
	ds_read_b128 v[56:59], v17 offset:12288
	ds_read_b128 v[60:63], v17 offset:16384
	v_add_u32_e32 v17, 16, v17
	s_waitcnt vmcnt(31)
	s_waitcnt lgkmcnt(0)
	v_fmac_f32_e32 v22, v96, v44
	v_fmac_f32_e32 v23, v96, v48
	v_fmac_f32_e32 v4, v96, v52
	v_fmac_f32_e32 v25, v96, v56
	v_fmac_f32_e32 v24, v96, v60
	global_load_dword v96, v[76:77], off
	v_lshl_add_u64 v[76:77], v[76:77], 0, s[0:1]
	s_waitcnt vmcnt(31)
	v_fmac_f32_e32 v22, v97, v45
	v_fmac_f32_e32 v23, v97, v49
	v_fmac_f32_e32 v4, v97, v53
	v_fmac_f32_e32 v25, v97, v57
	v_fmac_f32_e32 v24, v97, v61
	global_load_dword v97, v[76:77], off
	v_lshl_add_u64 v[76:77], v[76:77], 0, s[0:1]
	s_waitcnt vmcnt(31)
	v_fmac_f32_e32 v22, v98, v46
	v_fmac_f32_e32 v23, v98, v50
	v_fmac_f32_e32 v4, v98, v54
	v_fmac_f32_e32 v25, v98, v58
	v_fmac_f32_e32 v24, v98, v62
	global_load_dword v98, v[76:77], off
	v_lshl_add_u64 v[76:77], v[76:77], 0, s[0:1]
	s_waitcnt vmcnt(31)
	v_fmac_f32_e32 v22, v99, v47
	v_fmac_f32_e32 v23, v99, v51
	v_fmac_f32_e32 v4, v99, v55
	v_fmac_f32_e32 v25, v99, v59
	v_fmac_f32_e32 v24, v99, v63
	global_load_dword v99, v[76:77], off
	v_lshl_add_u64 v[76:77], v[76:77], 0, s[0:1]
	ds_read_b128 v[44:47], v17
	ds_read_b128 v[48:51], v17 offset:4096
	ds_read_b128 v[52:55], v17 offset:8192
	ds_read_b128 v[56:59], v17 offset:12288
	ds_read_b128 v[60:63], v17 offset:16384
	v_add_u32_e32 v17, 16, v17
	s_waitcnt vmcnt(31)
	s_waitcnt lgkmcnt(0)
	v_fmac_f32_e32 v22, v100, v44
	v_fmac_f32_e32 v23, v100, v48
	v_fmac_f32_e32 v4, v100, v52
	v_fmac_f32_e32 v25, v100, v56
	v_fmac_f32_e32 v24, v100, v60
	global_load_dword v100, v[76:77], off
	v_lshl_add_u64 v[76:77], v[76:77], 0, s[0:1]
	s_waitcnt vmcnt(31)
	v_fmac_f32_e32 v22, v101, v45
	v_fmac_f32_e32 v23, v101, v49
	v_fmac_f32_e32 v4, v101, v53
	v_fmac_f32_e32 v25, v101, v57
	v_fmac_f32_e32 v24, v101, v61
	global_load_dword v101, v[76:77], off
	v_lshl_add_u64 v[76:77], v[76:77], 0, s[0:1]
	s_waitcnt vmcnt(31)
	v_fmac_f32_e32 v22, v102, v46
	v_fmac_f32_e32 v23, v102, v50
	v_fmac_f32_e32 v4, v102, v54
	v_fmac_f32_e32 v25, v102, v58
	v_fmac_f32_e32 v24, v102, v62
	global_load_dword v102, v[76:77], off
	v_lshl_add_u64 v[76:77], v[76:77], 0, s[0:1]
	s_waitcnt vmcnt(31)
	v_fmac_f32_e32 v22, v103, v47
	v_fmac_f32_e32 v23, v103, v51
	v_fmac_f32_e32 v4, v103, v55
	v_fmac_f32_e32 v25, v103, v59
	v_fmac_f32_e32 v24, v103, v63
	global_load_dword v103, v[76:77], off
	v_lshl_add_u64 v[76:77], v[76:77], 0, s[0:1]
	ds_read_b128 v[44:47], v17
	ds_read_b128 v[48:51], v17 offset:4096
	ds_read_b128 v[52:55], v17 offset:8192
	ds_read_b128 v[56:59], v17 offset:12288
	ds_read_b128 v[60:63], v17 offset:16384
	v_add_u32_e32 v17, 16, v17
	s_waitcnt vmcnt(31)
	s_waitcnt lgkmcnt(0)
	v_fmac_f32_e32 v22, v104, v44
	v_fmac_f32_e32 v23, v104, v48
	v_fmac_f32_e32 v4, v104, v52
	v_fmac_f32_e32 v25, v104, v56
	v_fmac_f32_e32 v24, v104, v60
	global_load_dword v104, v[76:77], off
	v_lshl_add_u64 v[76:77], v[76:77], 0, s[0:1]
	s_waitcnt vmcnt(31)
	v_fmac_f32_e32 v22, v105, v45
	v_fmac_f32_e32 v23, v105, v49
	v_fmac_f32_e32 v4, v105, v53
	v_fmac_f32_e32 v25, v105, v57
	v_fmac_f32_e32 v24, v105, v61
	global_load_dword v105, v[76:77], off
	v_lshl_add_u64 v[76:77], v[76:77], 0, s[0:1]
	s_waitcnt vmcnt(31)
	v_fmac_f32_e32 v22, v106, v46
	v_fmac_f32_e32 v23, v106, v50
	v_fmac_f32_e32 v4, v106, v54
	v_fmac_f32_e32 v25, v106, v58
	v_fmac_f32_e32 v24, v106, v62
	global_load_dword v106, v[76:77], off
	v_lshl_add_u64 v[76:77], v[76:77], 0, s[0:1]
	s_waitcnt vmcnt(31)
	v_fmac_f32_e32 v22, v107, v47
	v_fmac_f32_e32 v23, v107, v51
	v_fmac_f32_e32 v4, v107, v55
	v_fmac_f32_e32 v25, v107, v59
	v_fmac_f32_e32 v24, v107, v63
	global_load_dword v107, v[76:77], off
	v_lshl_add_u64 v[76:77], v[76:77], 0, s[0:1]
	ds_read_b128 v[44:47], v17
	ds_read_b128 v[48:51], v17 offset:4096
	ds_read_b128 v[52:55], v17 offset:8192
	ds_read_b128 v[56:59], v17 offset:12288
	ds_read_b128 v[60:63], v17 offset:16384
	v_add_u32_e32 v17, 16, v17
	s_waitcnt vmcnt(31)
	s_waitcnt lgkmcnt(0)
	v_fmac_f32_e32 v22, v108, v44
	v_fmac_f32_e32 v23, v108, v48
	v_fmac_f32_e32 v4, v108, v52
	v_fmac_f32_e32 v25, v108, v56
	v_fmac_f32_e32 v24, v108, v60
	global_load_dword v108, v[76:77], off
	v_lshl_add_u64 v[76:77], v[76:77], 0, s[0:1]
	s_waitcnt vmcnt(31)
	v_fmac_f32_e32 v22, v109, v45
	v_fmac_f32_e32 v23, v109, v49
	v_fmac_f32_e32 v4, v109, v53
	v_fmac_f32_e32 v25, v109, v57
	v_fmac_f32_e32 v24, v109, v61
	global_load_dword v109, v[76:77], off
	v_lshl_add_u64 v[76:77], v[76:77], 0, s[0:1]
	s_waitcnt vmcnt(31)
	v_fmac_f32_e32 v22, v110, v46
	v_fmac_f32_e32 v23, v110, v50
	v_fmac_f32_e32 v4, v110, v54
	v_fmac_f32_e32 v25, v110, v58
	v_fmac_f32_e32 v24, v110, v62
	global_load_dword v110, v[76:77], off
	v_lshl_add_u64 v[76:77], v[76:77], 0, s[0:1]
	s_waitcnt vmcnt(31)
	v_fmac_f32_e32 v22, v111, v47
	v_fmac_f32_e32 v23, v111, v51
	v_fmac_f32_e32 v4, v111, v55
	v_fmac_f32_e32 v25, v111, v59
	v_fmac_f32_e32 v24, v111, v63
	global_load_dword v111, v[76:77], off
	v_lshl_add_u64 v[76:77], v[76:77], 0, s[0:1]
	ds_read_b128 v[44:47], v17
	ds_read_b128 v[48:51], v17 offset:4096
	ds_read_b128 v[52:55], v17 offset:8192
	ds_read_b128 v[56:59], v17 offset:12288
	ds_read_b128 v[60:63], v17 offset:16384
	v_add_u32_e32 v17, 16, v17
	s_waitcnt vmcnt(31)
	s_waitcnt lgkmcnt(0)
	v_fmac_f32_e32 v22, v80, v44
	v_fmac_f32_e32 v23, v80, v48
	v_fmac_f32_e32 v4, v80, v52
	v_fmac_f32_e32 v25, v80, v56
	v_fmac_f32_e32 v24, v80, v60
	global_load_dword v80, v[76:77], off
	v_lshl_add_u64 v[76:77], v[76:77], 0, s[0:1]
	s_waitcnt vmcnt(31)
	v_fmac_f32_e32 v22, v81, v45
	v_fmac_f32_e32 v23, v81, v49
	v_fmac_f32_e32 v4, v81, v53
	v_fmac_f32_e32 v25, v81, v57
	v_fmac_f32_e32 v24, v81, v61
	global_load_dword v81, v[76:77], off
	v_lshl_add_u64 v[76:77], v[76:77], 0, s[0:1]
	s_waitcnt vmcnt(31)
	v_fmac_f32_e32 v22, v82, v46
	v_fmac_f32_e32 v23, v82, v50
	v_fmac_f32_e32 v4, v82, v54
	v_fmac_f32_e32 v25, v82, v58
	v_fmac_f32_e32 v24, v82, v62
	global_load_dword v82, v[76:77], off
	v_lshl_add_u64 v[76:77], v[76:77], 0, s[0:1]
	s_waitcnt vmcnt(31)
	v_fmac_f32_e32 v22, v83, v47
	v_fmac_f32_e32 v23, v83, v51
	v_fmac_f32_e32 v4, v83, v55
	v_fmac_f32_e32 v25, v83, v59
	v_fmac_f32_e32 v24, v83, v63
	global_load_dword v83, v[76:77], off
	v_lshl_add_u64 v[76:77], v[76:77], 0, s[0:1]
	ds_read_b128 v[44:47], v17
	ds_read_b128 v[48:51], v17 offset:4096
	ds_read_b128 v[52:55], v17 offset:8192
	ds_read_b128 v[56:59], v17 offset:12288
	ds_read_b128 v[60:63], v17 offset:16384
	v_add_u32_e32 v17, 16, v17
	s_waitcnt vmcnt(31)
	s_waitcnt lgkmcnt(0)
	v_fmac_f32_e32 v22, v84, v44
	v_fmac_f32_e32 v23, v84, v48
	v_fmac_f32_e32 v4, v84, v52
	v_fmac_f32_e32 v25, v84, v56
	v_fmac_f32_e32 v24, v84, v60
	global_load_dword v84, v[76:77], off
	v_lshl_add_u64 v[76:77], v[76:77], 0, s[0:1]
	s_waitcnt vmcnt(31)
	v_fmac_f32_e32 v22, v85, v45
	v_fmac_f32_e32 v23, v85, v49
	v_fmac_f32_e32 v4, v85, v53
	v_fmac_f32_e32 v25, v85, v57
	v_fmac_f32_e32 v24, v85, v61
	global_load_dword v85, v[76:77], off
	v_lshl_add_u64 v[76:77], v[76:77], 0, s[0:1]
	s_waitcnt vmcnt(31)
	v_fmac_f32_e32 v22, v86, v46
	v_fmac_f32_e32 v23, v86, v50
	v_fmac_f32_e32 v4, v86, v54
	v_fmac_f32_e32 v25, v86, v58
	v_fmac_f32_e32 v24, v86, v62
	global_load_dword v86, v[76:77], off
	v_lshl_add_u64 v[76:77], v[76:77], 0, s[0:1]
	s_waitcnt vmcnt(31)
	v_fmac_f32_e32 v22, v87, v47
	v_fmac_f32_e32 v23, v87, v51
	v_fmac_f32_e32 v4, v87, v55
	v_fmac_f32_e32 v25, v87, v59
	v_fmac_f32_e32 v24, v87, v63
	global_load_dword v87, v[76:77], off
	v_lshl_add_u64 v[76:77], v[76:77], 0, s[0:1]
	ds_read_b128 v[44:47], v17
	ds_read_b128 v[48:51], v17 offset:4096
	ds_read_b128 v[52:55], v17 offset:8192
	ds_read_b128 v[56:59], v17 offset:12288
	ds_read_b128 v[60:63], v17 offset:16384
	v_add_u32_e32 v17, 16, v17
	s_waitcnt vmcnt(31)
	s_waitcnt lgkmcnt(0)
	v_fmac_f32_e32 v22, v88, v44
	v_fmac_f32_e32 v23, v88, v48
	v_fmac_f32_e32 v4, v88, v52
	v_fmac_f32_e32 v25, v88, v56
	v_fmac_f32_e32 v24, v88, v60
	global_load_dword v88, v[76:77], off
	v_lshl_add_u64 v[76:77], v[76:77], 0, s[0:1]
	s_waitcnt vmcnt(31)
	v_fmac_f32_e32 v22, v89, v45
	v_fmac_f32_e32 v23, v89, v49
	v_fmac_f32_e32 v4, v89, v53
	v_fmac_f32_e32 v25, v89, v57
	v_fmac_f32_e32 v24, v89, v61
	global_load_dword v89, v[76:77], off
	v_lshl_add_u64 v[76:77], v[76:77], 0, s[0:1]
	s_waitcnt vmcnt(31)
	v_fmac_f32_e32 v22, v90, v46
	v_fmac_f32_e32 v23, v90, v50
	v_fmac_f32_e32 v4, v90, v54
	v_fmac_f32_e32 v25, v90, v58
	v_fmac_f32_e32 v24, v90, v62
	global_load_dword v90, v[76:77], off
	v_lshl_add_u64 v[76:77], v[76:77], 0, s[0:1]
	s_waitcnt vmcnt(31)
	v_fmac_f32_e32 v22, v91, v47
	v_fmac_f32_e32 v23, v91, v51
	v_fmac_f32_e32 v4, v91, v55
	v_fmac_f32_e32 v25, v91, v59
	v_fmac_f32_e32 v24, v91, v63
	global_load_dword v91, v[76:77], off
	v_lshl_add_u64 v[76:77], v[76:77], 0, s[0:1]
	ds_read_b128 v[44:47], v17
	ds_read_b128 v[48:51], v17 offset:4096
	ds_read_b128 v[52:55], v17 offset:8192
	ds_read_b128 v[56:59], v17 offset:12288
	ds_read_b128 v[60:63], v17 offset:16384
	v_add_u32_e32 v17, 16, v17
	s_waitcnt vmcnt(31)
	s_waitcnt lgkmcnt(0)
	v_fmac_f32_e32 v22, v92, v44
	v_fmac_f32_e32 v23, v92, v48
	v_fmac_f32_e32 v4, v92, v52
	v_fmac_f32_e32 v25, v92, v56
	v_fmac_f32_e32 v24, v92, v60
	global_load_dword v92, v[76:77], off
	v_lshl_add_u64 v[76:77], v[76:77], 0, s[0:1]
	s_waitcnt vmcnt(31)
	v_fmac_f32_e32 v22, v93, v45
	v_fmac_f32_e32 v23, v93, v49
	v_fmac_f32_e32 v4, v93, v53
	v_fmac_f32_e32 v25, v93, v57
	v_fmac_f32_e32 v24, v93, v61
	global_load_dword v93, v[76:77], off
	v_lshl_add_u64 v[76:77], v[76:77], 0, s[0:1]
	s_waitcnt vmcnt(31)
	v_fmac_f32_e32 v22, v94, v46
	v_fmac_f32_e32 v23, v94, v50
	v_fmac_f32_e32 v4, v94, v54
	v_fmac_f32_e32 v25, v94, v58
	v_fmac_f32_e32 v24, v94, v62
	global_load_dword v94, v[76:77], off
	v_lshl_add_u64 v[76:77], v[76:77], 0, s[0:1]
	s_waitcnt vmcnt(31)
	v_fmac_f32_e32 v22, v95, v47
	v_fmac_f32_e32 v23, v95, v51
	v_fmac_f32_e32 v4, v95, v55
	v_fmac_f32_e32 v25, v95, v59
	v_fmac_f32_e32 v24, v95, v63
	global_load_dword v95, v[76:77], off
	v_lshl_add_u64 v[76:77], v[76:77], 0, s[0:1]
	ds_read_b128 v[44:47], v17
	ds_read_b128 v[48:51], v17 offset:4096
	ds_read_b128 v[52:55], v17 offset:8192
	ds_read_b128 v[56:59], v17 offset:12288
	ds_read_b128 v[60:63], v17 offset:16384
	v_add_u32_e32 v17, 16, v17
	s_waitcnt vmcnt(31)
	s_waitcnt lgkmcnt(0)
	v_fmac_f32_e32 v22, v96, v44
	v_fmac_f32_e32 v23, v96, v48
	v_fmac_f32_e32 v4, v96, v52
	v_fmac_f32_e32 v25, v96, v56
	v_fmac_f32_e32 v24, v96, v60
	global_load_dword v96, v[76:77], off
	v_lshl_add_u64 v[76:77], v[76:77], 0, s[0:1]
	s_waitcnt vmcnt(31)
	v_fmac_f32_e32 v22, v97, v45
	v_fmac_f32_e32 v23, v97, v49
	v_fmac_f32_e32 v4, v97, v53
	v_fmac_f32_e32 v25, v97, v57
	v_fmac_f32_e32 v24, v97, v61
	global_load_dword v97, v[76:77], off
	v_lshl_add_u64 v[76:77], v[76:77], 0, s[0:1]
	s_waitcnt vmcnt(31)
	v_fmac_f32_e32 v22, v98, v46
	v_fmac_f32_e32 v23, v98, v50
	v_fmac_f32_e32 v4, v98, v54
	v_fmac_f32_e32 v25, v98, v58
	v_fmac_f32_e32 v24, v98, v62
	global_load_dword v98, v[76:77], off
	v_lshl_add_u64 v[76:77], v[76:77], 0, s[0:1]
	s_waitcnt vmcnt(31)
	v_fmac_f32_e32 v22, v99, v47
	v_fmac_f32_e32 v23, v99, v51
	v_fmac_f32_e32 v4, v99, v55
	v_fmac_f32_e32 v25, v99, v59
	v_fmac_f32_e32 v24, v99, v63
	global_load_dword v99, v[76:77], off
	v_lshl_add_u64 v[76:77], v[76:77], 0, s[0:1]
	ds_read_b128 v[44:47], v17
	ds_read_b128 v[48:51], v17 offset:4096
	ds_read_b128 v[52:55], v17 offset:8192
	ds_read_b128 v[56:59], v17 offset:12288
	ds_read_b128 v[60:63], v17 offset:16384
	v_add_u32_e32 v17, 16, v17
	s_waitcnt vmcnt(31)
	s_waitcnt lgkmcnt(0)
	v_fmac_f32_e32 v22, v100, v44
	v_fmac_f32_e32 v23, v100, v48
	v_fmac_f32_e32 v4, v100, v52
	v_fmac_f32_e32 v25, v100, v56
	v_fmac_f32_e32 v24, v100, v60
	global_load_dword v100, v[76:77], off
	v_lshl_add_u64 v[76:77], v[76:77], 0, s[0:1]
	s_waitcnt vmcnt(31)
	v_fmac_f32_e32 v22, v101, v45
	v_fmac_f32_e32 v23, v101, v49
	v_fmac_f32_e32 v4, v101, v53
	v_fmac_f32_e32 v25, v101, v57
	v_fmac_f32_e32 v24, v101, v61
	global_load_dword v101, v[76:77], off
	v_lshl_add_u64 v[76:77], v[76:77], 0, s[0:1]
	s_waitcnt vmcnt(31)
	v_fmac_f32_e32 v22, v102, v46
	v_fmac_f32_e32 v23, v102, v50
	v_fmac_f32_e32 v4, v102, v54
	v_fmac_f32_e32 v25, v102, v58
	v_fmac_f32_e32 v24, v102, v62
	global_load_dword v102, v[76:77], off
	v_lshl_add_u64 v[76:77], v[76:77], 0, s[0:1]
	s_waitcnt vmcnt(31)
	v_fmac_f32_e32 v22, v103, v47
	v_fmac_f32_e32 v23, v103, v51
	v_fmac_f32_e32 v4, v103, v55
	v_fmac_f32_e32 v25, v103, v59
	v_fmac_f32_e32 v24, v103, v63
	global_load_dword v103, v[76:77], off
	v_lshl_add_u64 v[76:77], v[76:77], 0, s[0:1]
	ds_read_b128 v[44:47], v17
	ds_read_b128 v[48:51], v17 offset:4096
	ds_read_b128 v[52:55], v17 offset:8192
	ds_read_b128 v[56:59], v17 offset:12288
	ds_read_b128 v[60:63], v17 offset:16384
	v_add_u32_e32 v17, 16, v17
	s_waitcnt vmcnt(31)
	s_waitcnt lgkmcnt(0)
	v_fmac_f32_e32 v22, v104, v44
	v_fmac_f32_e32 v23, v104, v48
	v_fmac_f32_e32 v4, v104, v52
	v_fmac_f32_e32 v25, v104, v56
	v_fmac_f32_e32 v24, v104, v60
	global_load_dword v104, v[76:77], off
	v_lshl_add_u64 v[76:77], v[76:77], 0, s[0:1]
	s_waitcnt vmcnt(31)
	v_fmac_f32_e32 v22, v105, v45
	v_fmac_f32_e32 v23, v105, v49
	v_fmac_f32_e32 v4, v105, v53
	v_fmac_f32_e32 v25, v105, v57
	v_fmac_f32_e32 v24, v105, v61
	global_load_dword v105, v[76:77], off
	v_lshl_add_u64 v[76:77], v[76:77], 0, s[0:1]
	s_waitcnt vmcnt(31)
	v_fmac_f32_e32 v22, v106, v46
	v_fmac_f32_e32 v23, v106, v50
	v_fmac_f32_e32 v4, v106, v54
	v_fmac_f32_e32 v25, v106, v58
	v_fmac_f32_e32 v24, v106, v62
	global_load_dword v106, v[76:77], off
	v_lshl_add_u64 v[76:77], v[76:77], 0, s[0:1]
	s_waitcnt vmcnt(31)
	v_fmac_f32_e32 v22, v107, v47
	v_fmac_f32_e32 v23, v107, v51
	v_fmac_f32_e32 v4, v107, v55
	v_fmac_f32_e32 v25, v107, v59
	v_fmac_f32_e32 v24, v107, v63
	global_load_dword v107, v[76:77], off
	v_lshl_add_u64 v[76:77], v[76:77], 0, s[0:1]
	ds_read_b128 v[44:47], v17
	ds_read_b128 v[48:51], v17 offset:4096
	ds_read_b128 v[52:55], v17 offset:8192
	ds_read_b128 v[56:59], v17 offset:12288
	ds_read_b128 v[60:63], v17 offset:16384
	v_add_u32_e32 v17, 16, v17
	s_waitcnt vmcnt(31)
	s_waitcnt lgkmcnt(0)
	v_fmac_f32_e32 v22, v108, v44
	v_fmac_f32_e32 v23, v108, v48
	v_fmac_f32_e32 v4, v108, v52
	v_fmac_f32_e32 v25, v108, v56
	v_fmac_f32_e32 v24, v108, v60
	global_load_dword v108, v[76:77], off
	v_lshl_add_u64 v[76:77], v[76:77], 0, s[0:1]
	s_waitcnt vmcnt(31)
	v_fmac_f32_e32 v22, v109, v45
	v_fmac_f32_e32 v23, v109, v49
	v_fmac_f32_e32 v4, v109, v53
	v_fmac_f32_e32 v25, v109, v57
	v_fmac_f32_e32 v24, v109, v61
	global_load_dword v109, v[76:77], off
	v_lshl_add_u64 v[76:77], v[76:77], 0, s[0:1]
	s_waitcnt vmcnt(31)
	v_fmac_f32_e32 v22, v110, v46
	v_fmac_f32_e32 v23, v110, v50
	v_fmac_f32_e32 v4, v110, v54
	v_fmac_f32_e32 v25, v110, v58
	v_fmac_f32_e32 v24, v110, v62
	global_load_dword v110, v[76:77], off
	v_lshl_add_u64 v[76:77], v[76:77], 0, s[0:1]
	s_waitcnt vmcnt(31)
	v_fmac_f32_e32 v22, v111, v47
	v_fmac_f32_e32 v23, v111, v51
	v_fmac_f32_e32 v4, v111, v55
	v_fmac_f32_e32 v25, v111, v59
	v_fmac_f32_e32 v24, v111, v63
	global_load_dword v111, v[76:77], off
	v_lshl_add_u64 v[76:77], v[76:77], 0, s[0:1]
	ds_read_b128 v[44:47], v17
	ds_read_b128 v[48:51], v17 offset:4096
	ds_read_b128 v[52:55], v17 offset:8192
	ds_read_b128 v[56:59], v17 offset:12288
	ds_read_b128 v[60:63], v17 offset:16384
	v_add_u32_e32 v17, 16, v17
	s_waitcnt vmcnt(31)
	s_waitcnt lgkmcnt(0)
	v_fmac_f32_e32 v22, v80, v44
	v_fmac_f32_e32 v23, v80, v48
	v_fmac_f32_e32 v4, v80, v52
	v_fmac_f32_e32 v25, v80, v56
	v_fmac_f32_e32 v24, v80, v60
	s_waitcnt vmcnt(30)
	v_fmac_f32_e32 v22, v81, v45
	v_fmac_f32_e32 v23, v81, v49
	v_fmac_f32_e32 v4, v81, v53
	v_fmac_f32_e32 v25, v81, v57
	v_fmac_f32_e32 v24, v81, v61
	s_waitcnt vmcnt(29)
	v_fmac_f32_e32 v22, v82, v46
	v_fmac_f32_e32 v23, v82, v50
	v_fmac_f32_e32 v4, v82, v54
	v_fmac_f32_e32 v25, v82, v58
	v_fmac_f32_e32 v24, v82, v62
	s_waitcnt vmcnt(28)
	v_fmac_f32_e32 v22, v83, v47
	v_fmac_f32_e32 v23, v83, v51
	v_fmac_f32_e32 v4, v83, v55
	v_fmac_f32_e32 v25, v83, v59
	v_fmac_f32_e32 v24, v83, v63
	ds_read_b128 v[44:47], v17
	ds_read_b128 v[48:51], v17 offset:4096
	ds_read_b128 v[52:55], v17 offset:8192
	ds_read_b128 v[56:59], v17 offset:12288
	ds_read_b128 v[60:63], v17 offset:16384
	v_add_u32_e32 v17, 16, v17
	s_waitcnt vmcnt(27)
	s_waitcnt lgkmcnt(0)
	v_fmac_f32_e32 v22, v84, v44
	v_fmac_f32_e32 v23, v84, v48
	v_fmac_f32_e32 v4, v84, v52
	v_fmac_f32_e32 v25, v84, v56
	v_fmac_f32_e32 v24, v84, v60
	s_waitcnt vmcnt(26)
	v_fmac_f32_e32 v22, v85, v45
	v_fmac_f32_e32 v23, v85, v49
	v_fmac_f32_e32 v4, v85, v53
	v_fmac_f32_e32 v25, v85, v57
	v_fmac_f32_e32 v24, v85, v61
	s_waitcnt vmcnt(25)
	v_fmac_f32_e32 v22, v86, v46
	v_fmac_f32_e32 v23, v86, v50
	v_fmac_f32_e32 v4, v86, v54
	v_fmac_f32_e32 v25, v86, v58
	v_fmac_f32_e32 v24, v86, v62
	s_waitcnt vmcnt(24)
	v_fmac_f32_e32 v22, v87, v47
	v_fmac_f32_e32 v23, v87, v51
	v_fmac_f32_e32 v4, v87, v55
	v_fmac_f32_e32 v25, v87, v59
	v_fmac_f32_e32 v24, v87, v63
	ds_read_b128 v[44:47], v17
	ds_read_b128 v[48:51], v17 offset:4096
	ds_read_b128 v[52:55], v17 offset:8192
	ds_read_b128 v[56:59], v17 offset:12288
	ds_read_b128 v[60:63], v17 offset:16384
	v_add_u32_e32 v17, 16, v17
	s_waitcnt vmcnt(23)
	s_waitcnt lgkmcnt(0)
	v_fmac_f32_e32 v22, v88, v44
	v_fmac_f32_e32 v23, v88, v48
	v_fmac_f32_e32 v4, v88, v52
	v_fmac_f32_e32 v25, v88, v56
	v_fmac_f32_e32 v24, v88, v60
	s_waitcnt vmcnt(22)
	v_fmac_f32_e32 v22, v89, v45
	v_fmac_f32_e32 v23, v89, v49
	v_fmac_f32_e32 v4, v89, v53
	v_fmac_f32_e32 v25, v89, v57
	v_fmac_f32_e32 v24, v89, v61
	s_waitcnt vmcnt(21)
	v_fmac_f32_e32 v22, v90, v46
	v_fmac_f32_e32 v23, v90, v50
	v_fmac_f32_e32 v4, v90, v54
	v_fmac_f32_e32 v25, v90, v58
	v_fmac_f32_e32 v24, v90, v62
	s_waitcnt vmcnt(20)
	v_fmac_f32_e32 v22, v91, v47
	v_fmac_f32_e32 v23, v91, v51
	v_fmac_f32_e32 v4, v91, v55
	v_fmac_f32_e32 v25, v91, v59
	v_fmac_f32_e32 v24, v91, v63
	ds_read_b128 v[44:47], v17
	ds_read_b128 v[48:51], v17 offset:4096
	ds_read_b128 v[52:55], v17 offset:8192
	ds_read_b128 v[56:59], v17 offset:12288
	ds_read_b128 v[60:63], v17 offset:16384
	v_add_u32_e32 v17, 16, v17
	s_waitcnt vmcnt(19)
	s_waitcnt lgkmcnt(0)
	v_fmac_f32_e32 v22, v92, v44
	v_fmac_f32_e32 v23, v92, v48
	v_fmac_f32_e32 v4, v92, v52
	v_fmac_f32_e32 v25, v92, v56
	v_fmac_f32_e32 v24, v92, v60
	s_waitcnt vmcnt(18)
	v_fmac_f32_e32 v22, v93, v45
	v_fmac_f32_e32 v23, v93, v49
	v_fmac_f32_e32 v4, v93, v53
	v_fmac_f32_e32 v25, v93, v57
	v_fmac_f32_e32 v24, v93, v61
	s_waitcnt vmcnt(17)
	v_fmac_f32_e32 v22, v94, v46
	v_fmac_f32_e32 v23, v94, v50
	v_fmac_f32_e32 v4, v94, v54
	v_fmac_f32_e32 v25, v94, v58
	v_fmac_f32_e32 v24, v94, v62
	s_waitcnt vmcnt(16)
	v_fmac_f32_e32 v22, v95, v47
	v_fmac_f32_e32 v23, v95, v51
	v_fmac_f32_e32 v4, v95, v55
	v_fmac_f32_e32 v25, v95, v59
	v_fmac_f32_e32 v24, v95, v63
	ds_read_b128 v[44:47], v17
	ds_read_b128 v[48:51], v17 offset:4096
	ds_read_b128 v[52:55], v17 offset:8192
	ds_read_b128 v[56:59], v17 offset:12288
	ds_read_b128 v[60:63], v17 offset:16384
	v_add_u32_e32 v17, 16, v17
	s_waitcnt vmcnt(15)
	s_waitcnt lgkmcnt(0)
	v_fmac_f32_e32 v22, v96, v44
	v_fmac_f32_e32 v23, v96, v48
	v_fmac_f32_e32 v4, v96, v52
	v_fmac_f32_e32 v25, v96, v56
	v_fmac_f32_e32 v24, v96, v60
	s_waitcnt vmcnt(14)
	v_fmac_f32_e32 v22, v97, v45
	v_fmac_f32_e32 v23, v97, v49
	v_fmac_f32_e32 v4, v97, v53
	v_fmac_f32_e32 v25, v97, v57
	v_fmac_f32_e32 v24, v97, v61
	s_waitcnt vmcnt(13)
	v_fmac_f32_e32 v22, v98, v46
	v_fmac_f32_e32 v23, v98, v50
	v_fmac_f32_e32 v4, v98, v54
	v_fmac_f32_e32 v25, v98, v58
	v_fmac_f32_e32 v24, v98, v62
	s_waitcnt vmcnt(12)
	v_fmac_f32_e32 v22, v99, v47
	v_fmac_f32_e32 v23, v99, v51
	v_fmac_f32_e32 v4, v99, v55
	v_fmac_f32_e32 v25, v99, v59
	v_fmac_f32_e32 v24, v99, v63
	ds_read_b128 v[44:47], v17
	ds_read_b128 v[48:51], v17 offset:4096
	ds_read_b128 v[52:55], v17 offset:8192
	ds_read_b128 v[56:59], v17 offset:12288
	ds_read_b128 v[60:63], v17 offset:16384
	v_add_u32_e32 v17, 16, v17
	s_waitcnt vmcnt(11)
	s_waitcnt lgkmcnt(0)
	v_fmac_f32_e32 v22, v100, v44
	v_fmac_f32_e32 v23, v100, v48
	v_fmac_f32_e32 v4, v100, v52
	v_fmac_f32_e32 v25, v100, v56
	v_fmac_f32_e32 v24, v100, v60
	s_waitcnt vmcnt(10)
	v_fmac_f32_e32 v22, v101, v45
	v_fmac_f32_e32 v23, v101, v49
	v_fmac_f32_e32 v4, v101, v53
	v_fmac_f32_e32 v25, v101, v57
	v_fmac_f32_e32 v24, v101, v61
	s_waitcnt vmcnt(9)
	v_fmac_f32_e32 v22, v102, v46
	v_fmac_f32_e32 v23, v102, v50
	v_fmac_f32_e32 v4, v102, v54
	v_fmac_f32_e32 v25, v102, v58
	v_fmac_f32_e32 v24, v102, v62
	s_waitcnt vmcnt(8)
	v_fmac_f32_e32 v22, v103, v47
	v_fmac_f32_e32 v23, v103, v51
	v_fmac_f32_e32 v4, v103, v55
	v_fmac_f32_e32 v25, v103, v59
	v_fmac_f32_e32 v24, v103, v63
	ds_read_b128 v[44:47], v17
	ds_read_b128 v[48:51], v17 offset:4096
	ds_read_b128 v[52:55], v17 offset:8192
	ds_read_b128 v[56:59], v17 offset:12288
	ds_read_b128 v[60:63], v17 offset:16384
	v_add_u32_e32 v17, 16, v17
	s_waitcnt vmcnt(7)
	s_waitcnt lgkmcnt(0)
	v_fmac_f32_e32 v22, v104, v44
	v_fmac_f32_e32 v23, v104, v48
	v_fmac_f32_e32 v4, v104, v52
	v_fmac_f32_e32 v25, v104, v56
	v_fmac_f32_e32 v24, v104, v60
	s_waitcnt vmcnt(6)
	v_fmac_f32_e32 v22, v105, v45
	v_fmac_f32_e32 v23, v105, v49
	v_fmac_f32_e32 v4, v105, v53
	v_fmac_f32_e32 v25, v105, v57
	v_fmac_f32_e32 v24, v105, v61
	s_waitcnt vmcnt(5)
	v_fmac_f32_e32 v22, v106, v46
	v_fmac_f32_e32 v23, v106, v50
	v_fmac_f32_e32 v4, v106, v54
	v_fmac_f32_e32 v25, v106, v58
	v_fmac_f32_e32 v24, v106, v62
	s_waitcnt vmcnt(4)
	v_fmac_f32_e32 v22, v107, v47
	v_fmac_f32_e32 v23, v107, v51
	v_fmac_f32_e32 v4, v107, v55
	v_fmac_f32_e32 v25, v107, v59
	v_fmac_f32_e32 v24, v107, v63
	ds_read_b128 v[44:47], v17
	ds_read_b128 v[48:51], v17 offset:4096
	ds_read_b128 v[52:55], v17 offset:8192
	ds_read_b128 v[56:59], v17 offset:12288
	ds_read_b128 v[60:63], v17 offset:16384
	v_add_u32_e32 v17, 16, v17
	s_waitcnt vmcnt(3)
	s_waitcnt lgkmcnt(0)
	v_fmac_f32_e32 v22, v108, v44
	v_fmac_f32_e32 v23, v108, v48
	v_fmac_f32_e32 v4, v108, v52
	v_fmac_f32_e32 v25, v108, v56
	v_fmac_f32_e32 v24, v108, v60
	s_waitcnt vmcnt(2)
	v_fmac_f32_e32 v22, v109, v45
	v_fmac_f32_e32 v23, v109, v49
	v_fmac_f32_e32 v4, v109, v53
	v_fmac_f32_e32 v25, v109, v57
	v_fmac_f32_e32 v24, v109, v61
	s_waitcnt vmcnt(1)
	v_fmac_f32_e32 v22, v110, v46
	v_fmac_f32_e32 v23, v110, v50
	v_fmac_f32_e32 v4, v110, v54
	v_fmac_f32_e32 v25, v110, v58
	v_fmac_f32_e32 v24, v110, v62
	s_waitcnt vmcnt(0)
	v_fmac_f32_e32 v22, v111, v47
	v_fmac_f32_e32 v23, v111, v51
	v_fmac_f32_e32 v4, v111, v55
	v_fmac_f32_e32 v25, v111, v59
	v_fmac_f32_e32 v24, v111, v63
	ds_write2st64_b32 v36, v22, v23 offset0:80 offset1:81
	ds_write2st64_b32 v36, v4, v25 offset0:82 offset1:83
	ds_write_b32 v36, v24 offset:21504
	s_waitcnt lgkmcnt(0)
	s_barrier
	s_and_saveexec_b64 s[0:1], s[4:5]
	s_cbranch_execz .LBB0_63
	s_mul_i32 s57, s52, 0xffffffa0
	s_add_i32 s57, s57, s2
	s_lshl_b32 s58, s57, 6
	s_add_i32 s56, s58, s56
	v_or_b32_e32 v20, s56, v0
	v_readlane_b32 s60, v247, 6
	v_ashrrev_i32_e32 v21, 31, v20
	v_readlane_b32 s70, v247, 16
	v_readlane_b32 s71, v247, 17
	v_mad_u64_u32 v[46:47], s[56:57], s52, 5, v[2:3]
	s_nop 0
	v_lshl_add_u64 v[20:21], v[20:21], 2, s[70:71]
	global_load_dword v4, v[20:21], off
	s_movk_i32 s52, 0x1800
	ds_read2st64_b32 v[20:21], v42 offset0:80 offset1:85
	ds_read2st64_b32 v[22:23], v42 offset0:90 offset1:95
	ds_read2st64_b32 v[24:25], v42 offset0:100 offset1:105
	ds_read2st64_b32 v[44:45], v42 offset0:110 offset1:115
	v_mul_lo_u32 v17, v46, s52
	v_add_u32_e32 v17, s58, v17
	v_or_b32_e32 v46, v17, v0
	s_waitcnt lgkmcnt(3)
	v_add_f32_e32 v17, 0, v20
	v_add_f32_e32 v17, v17, v21
	s_waitcnt lgkmcnt(2)
	v_add_f32_e32 v17, v17, v22
	v_add_f32_e32 v17, v17, v23
	s_waitcnt lgkmcnt(1)
	v_add_f32_e32 v17, v17, v24
	v_add_f32_e32 v17, v17, v25
	s_waitcnt lgkmcnt(0)
	v_add_f32_e32 v17, v17, v44
	v_readlane_b32 s56, v247, 0
	v_ashrrev_i32_e32 v47, 31, v46
	v_add_f32_e32 v17, v17, v45
	v_readlane_b32 s58, v247, 2
	v_readlane_b32 s59, v247, 3
	v_readlane_b32 s61, v247, 7
	v_readlane_b32 s62, v247, 8
	v_lshl_add_u64 v[20:21], v[46:47], 2, s[58:59]
	v_readlane_b32 s63, v247, 9
	v_readlane_b32 s64, v247, 10
	v_readlane_b32 s65, v247, 11
	v_readlane_b32 s66, v247, 12
	v_readlane_b32 s67, v247, 13
	v_readlane_b32 s68, v247, 14
	v_readlane_b32 s69, v247, 15
	v_readlane_b32 s72, v247, 18
	v_readlane_b32 s73, v247, 19
	v_readlane_b32 s74, v247, 20
	v_readlane_b32 s75, v247, 21
	v_readlane_b32 s57, v247, 1
	s_waitcnt vmcnt(0)
	v_add_f32_e32 v4, v17, v4
	global_store_dword v[20:21], v4, off

.LBB0_69:
	s_lshr_b32 s56, s78, 2
	v_lshlrev_b32_e32 v86, 2, v186
	v_mul_u32_u24_e32 v84, 60, v186
	v_mov_b32_e32 v85, 0
	v_lshl_add_u64 v[80:81], v[84:85], 0, v[20:21]
	v_lshl_add_u64 v[82:83], v[84:85], 0, v[22:23]
	s_mov_b64 s[60:61], exec
	s_mov_b64 s[62:63], 0x8000
.Lpk_loop:
	v_cmp_gt_u32_e32 vcc, s56, v86
	s_and_b64 exec, exec, vcc
	s_cbranch_execz .Lpk_done
	v_add_u32_e32 v87, 0, v86
	v_cmp_gt_u32_e32 vcc, s56, v87
	s_and_saveexec_b64 s[58:59], vcc
	global_load_dwordx4 v[88:91], v[80:81], off offset:0
	s_mov_b64 exec, s[58:59]
	v_add_u32_e32 v87, 1, v86
	v_cmp_gt_u32_e32 vcc, s56, v87
	s_and_saveexec_b64 s[58:59], vcc
	global_load_dwordx4 v[92:95], v[80:81], off offset:16
	s_mov_b64 exec, s[58:59]
	v_add_u32_e32 v87, 2, v86
	v_cmp_gt_u32_e32 vcc, s56, v87
	s_and_saveexec_b64 s[58:59], vcc
	global_load_dwordx4 v[96:99], v[80:81], off offset:32
	s_mov_b64 exec, s[58:59]
	v_add_u32_e32 v87, 3, v86
	v_cmp_gt_u32_e32 vcc, s56, v87
	s_and_saveexec_b64 s[58:59], vcc
	global_load_dwordx4 v[100:103], v[80:81], off offset:48
	s_mov_b64 exec, s[58:59]
	s_waitcnt vmcnt(0)
	v_add_u32_e32 v87, 0, v86
	v_cmp_gt_u32_e32 vcc, s56, v87
	s_and_saveexec_b64 s[58:59], vcc
	global_store_dwordx4 v[82:83], v[88:91], off offset:0
	s_mov_b64 exec, s[58:59]
	v_add_u32_e32 v87, 1, v86
	v_cmp_gt_u32_e32 vcc, s56, v87
	s_and_saveexec_b64 s[58:59], vcc
	global_store_dwordx4 v[82:83], v[92:95], off offset:16
	s_mov_b64 exec, s[58:59]
	v_add_u32_e32 v87, 2, v86
	v_cmp_gt_u32_e32 vcc, s56, v87
	s_and_saveexec_b64 s[58:59], vcc
	global_store_dwordx4 v[82:83], v[96:99], off offset:32
	s_mov_b64 exec, s[58:59]
	v_add_u32_e32 v87, 3, v86
	v_cmp_gt_u32_e32 vcc, s56, v87
	s_and_saveexec_b64 s[58:59], vcc
	global_store_dwordx4 v[82:83], v[100:103], off offset:48
	s_mov_b64 exec, s[58:59]
	v_add_u32_e32 v86, 0x800, v86
	v_lshl_add_u64 v[80:81], v[80:81], 0, s[62:63]
	v_lshl_add_u64 v[82:83], v[82:83], 0, s[62:63]
	s_branch .Lpk_loop
.Lpk_done:
	s_mov_b64 exec, s[60:61]
	s_branch .LBB0_20
.LBB0_70:
	v_readlane_b32 s8, v243, 0
	v_readlane_b32 s9, v243, 1
	v_readlane_b32 s24, v247, 2
	v_readlane_b32 s25, v247, 3
	s_nop 3
	s_load_dwordx2 s[10:11], s[8:9], 0x38
	s_load_dwordx2 s[12:13], s[8:9], 0x60
	s_load_dwordx2 s[14:15], s[8:9], 0x70
	s_load_dwordx2 s[16:17], s[8:9], 0xc8
	s_load_dwordx2 s[18:19], s[8:9], 0xe0
	s_load_dwordx2 s[20:21], s[8:9], 0xf8
	s_load_dwordx2 s[22:23], s[8:9], 0x108
	v_lshrrev_b32_e32 v0, 4, v186
	v_and_b32_e32 v1, 15, v186
	v_lshlrev_b32_e32 v1, 4, v1
	v_mul_u32_u24_e32 v2, 0x104, v0
	v_add_u32_e32 v2, v2, v1
	v_and_b32_e32 v3, 7, v186
	v_lshrrev_b32_e32 v4, 3, v186
	v_mul_u32_u24_e32 v5, 0x820, v3
	v_lshl_add_u32 v5, v4, 2, v5
	v_lshlrev_b32_e32 v3, 4, v3
	s_mov_b32 s26, s69
	s_waitcnt lgkmcnt(0)
	s_barrier
	s_cmp_ge_u32 s26, 0xb00
	s_cselect_b32 s28, 1, 0
	s_mul_i32 s29, s28, 0xb00
	s_sub_i32 s29, s26, s29
	s_cmp_ge_u32 s29, 0x700
	s_cbranch_scc1 .Lp0t_r0_6
	s_cmp_ge_u32 s29, 0x300
	s_cbranch_scc1 .Lp0t_r0_5
	s_cmp_ge_u32 s29, 0x200
	s_cbranch_scc1 .Lp0t_r0_4
	s_cmp_ge_u32 s29, 0x1e0
	s_cbranch_scc1 .Lp0t_r0_3
	s_cmp_ge_u32 s29, 0x1d0
	s_cbranch_scc1 .Lp0t_r0_2
	s_cmp_ge_u32 s29, 0x1c0
	s_cbranch_scc1 .Lp0t_r0_1
.Lp0t_r0_0:
	s_mov_b64 s[54:55], s[10:11]
	s_mov_b32 s56, 0x700000
	s_mov_b32 s57, 0x700
	s_mov_b32 s58, 0x400
	s_mov_b32 s59, 0x0
	s_sub_i32 s60, s29, 0x0
	s_mul_i32 s30, s60, 0x925
	s_lshr_b32 s30, s30, 16
	s_mul_i32 s31, s30, 28
	s_sub_i32 s31, s60, s31
	s_branch .Lp0t_rd0
.Lp0t_r0_1:
	s_mov_b64 s[54:55], s[12:13]
	s_mov_b32 s56, 0x40000
	s_mov_b32 s57, 0x100
	s_mov_b32 s58, 0x100
	s_mov_b32 s59, 0x380000
	s_sub_i32 s60, s29, 0x1c0
	s_lshr_b32 s30, s60, 2
	s_and_b32 s31, s60, 3
	s_branch .Lp0t_rd0
.Lp0t_r0_2:
	s_mov_b64 s[54:55], s[14:15]
	s_mov_b32 s56, 0x40000
	s_mov_b32 s57, 0x100
	s_mov_b32 s58, 0x100
	s_mov_b32 s59, 0x3a0000
	s_sub_i32 s60, s29, 0x1d0
	s_lshr_b32 s30, s60, 2
	s_and_b32 s31, s60, 3
	s_branch .Lp0t_rd0
.Lp0t_r0_3:
	s_mov_b64 s[54:55], s[16:17]
	s_mov_b32 s56, 0x80000
	s_mov_b32 s57, 0x200
	s_mov_b32 s58, 0x100
	s_mov_b32 s59, 0x3c0000
	s_sub_i32 s60, s29, 0x1e0
	s_lshr_b32 s30, s60, 3
	s_and_b32 s31, s60, 7
	s_branch .Lp0t_rd0
.Lp0t_r0_4:
	s_mov_b64 s[54:55], s[18:19]
	s_mov_b32 s56, 0x400000
	s_mov_b32 s57, 0x400
	s_mov_b32 s58, 0x400
	s_mov_b32 s59, 0x400000
	s_sub_i32 s60, s29, 0x200
	s_lshr_b32 s30, s60, 4
	s_and_b32 s31, s60, 15
	s_branch .Lp0t_rd0
.Lp0t_r0_5:
	s_mov_b64 s[54:55], s[20:21]
	s_mov_b32 s56, 0x1000000
	s_mov_b32 s57, 0x1000
	s_mov_b32 s58, 0x400
	s_mov_b32 s59, 0x600000
	s_sub_i32 s60, s29, 0x300
	s_lshr_b32 s30, s60, 6
	s_and_b32 s31, s60, 63
	s_branch .Lp0t_rd0
.Lp0t_r0_6:
	s_mov_b64 s[54:55], s[22:23]
	s_mov_b32 s56, 0x1000000
	s_mov_b32 s57, 0x400
	s_mov_b32 s58, 0x1000
	s_mov_b32 s59, 0xe00000
	s_sub_i32 s60, s29, 0x700
	s_lshr_b32 s30, s60, 4
	s_and_b32 s31, s60, 15
.Lp0t_rd0:
	s_mul_i32 s56, s56, s28
	s_lshl_b32 s42, s30, 6
	s_lshl_b32 s43, s31, 6
	s_mul_i32 s44, s42, s57
	s_add_i32 s44, s44, s43
	s_lshl_b32 s44, s44, 2
	s_add_u32 s44, s44, s56
	s_add_u32 s36, s54, s44
	s_addc_u32 s37, s55, 0
	s_lshl_b32 s40, s57, 2
	s_mul_i32 s44, s43, s58
	s_add_i32 s44, s44, s42
	s_lshl_b32 s44, s44, 1
	s_mul_i32 s45, s28, 0x1600000
	s_add_u32 s44, s44, s45
	s_add_u32 s44, s44, s59
	s_add_u32 s44, s44, 0xc00000
	s_add_u32 s38, s24, s44
	s_addc_u32 s39, s25, 0
	s_lshl_b32 s41, s58, 1
	v_mad_u32_u24 v6, v0, s40, v1
	global_load_dwordx4 v[8:11], v6, s[36:37]
	s_lshl_b32 s42, s40, 5
	s_add_u32 s36, s36, s42
	s_addc_u32 s37, s37, 0
	global_load_dwordx4 v[12:15], v6, s[36:37]
	s_mov_b32 s27, 0
.Lp0t_loop:
	s_add_i32 s26, s26, 0x100
	s_cmp_ge_u32 s26, 0xb00
	s_cselect_b32 s28, 1, 0
	s_mul_i32 s29, s28, 0xb00
	s_sub_i32 s29, s26, s29
	s_cmp_ge_u32 s29, 0x700
	s_cbranch_scc1 .Lp0t_r1_6
	s_cmp_ge_u32 s29, 0x300
	s_cbranch_scc1 .Lp0t_r1_5
	s_cmp_ge_u32 s29, 0x200
	s_cbranch_scc1 .Lp0t_r1_4
	s_cmp_ge_u32 s29, 0x1e0
	s_cbranch_scc1 .Lp0t_r1_3
	s_cmp_ge_u32 s29, 0x1d0
	s_cbranch_scc1 .Lp0t_r1_2
	s_cmp_ge_u32 s29, 0x1c0
	s_cbranch_scc1 .Lp0t_r1_1

.Lp0t_rd1:
	s_mul_i32 s56, s56, s28
	s_lshl_b32 s42, s30, 6
	s_lshl_b32 s43, s31, 6
	s_mul_i32 s44, s42, s57
	s_add_i32 s44, s44, s43
	s_lshl_b32 s44, s44, 2
	s_add_u32 s44, s44, s56
	s_add_u32 s48, s54, s44
	s_addc_u32 s49, s55, 0
	s_lshl_b32 s52, s57, 2
	s_mul_i32 s44, s43, s58
	s_add_i32 s44, s44, s42
	s_lshl_b32 s44, s44, 1
	s_mul_i32 s45, s28, 0x1600000
	s_add_u32 s44, s44, s45
	s_add_u32 s44, s44, s59
	s_add_u32 s44, s44, 0xc00000
	s_add_u32 s50, s24, s44
	s_addc_u32 s51, s25, 0
	s_lshl_b32 s53, s58, 1
	v_mad_u32_u24 v6, v0, s52, v1
	global_load_dwordx4 v[16:19], v6, s[48:49]
	s_lshl_b32 s42, s52, 5
	s_add_u32 s48, s48, s42
	s_addc_u32 s49, s49, 0
	global_load_dwordx4 v[20:23], v6, s[48:49]
	s_waitcnt vmcnt(2)
	ds_write_b32 v2, v8 offset:0
	ds_write_b32 v2, v9 offset:4
	ds_write_b32 v2, v10 offset:8
	ds_write_b32 v2, v11 offset:12
	ds_write_b32 v2, v12 offset:8320
	ds_write_b32 v2, v13 offset:8324
	ds_write_b32 v2, v14 offset:8328
	ds_write_b32 v2, v15 offset:8332
	s_waitcnt lgkmcnt(0)
	s_barrier
	ds_read_b32 v24, v5 offset:0
	ds_read_b32 v25, v5 offset:260
	ds_read_b32 v26, v5 offset:520
	ds_read_b32 v27, v5 offset:780
	ds_read_b32 v28, v5 offset:1040
	ds_read_b32 v29, v5 offset:1300
	ds_read_b32 v30, v5 offset:1560
	ds_read_b32 v31, v5 offset:1820
	v_mad_u32_u24 v7, v4, s41, v3
	s_waitcnt lgkmcnt(0)
	v_cvt_pk_bf16_f32 v32, v24, v25
	v_cvt_pk_bf16_f32 v33, v26, v27
	v_cvt_pk_bf16_f32 v34, v28, v29
	v_cvt_pk_bf16_f32 v35, v30, v31
	global_store_dwordx4 v7, v[32:35], s[38:39]
	s_add_i32 s26, s26, 0x100
	s_add_i32 s27, s27, 1
	s_cmp_eq_u32 s27, 11
	s_cbranch_scc1 .Lp0t_last
	s_cmp_ge_u32 s26, 0xb00
	s_cselect_b32 s28, 1, 0
	s_mul_i32 s29, s28, 0xb00
	s_sub_i32 s29, s26, s29
	s_cmp_ge_u32 s29, 0x700
	s_cbranch_scc1 .Lp0t_r2_6
	s_cmp_ge_u32 s29, 0x300
	s_cbranch_scc1 .Lp0t_r2_5
	s_cmp_ge_u32 s29, 0x200
	s_cbranch_scc1 .Lp0t_r2_4
	s_cmp_ge_u32 s29, 0x1e0
	s_cbranch_scc1 .Lp0t_r2_3
	s_cmp_ge_u32 s29, 0x1d0
	s_cbranch_scc1 .Lp0t_r2_2
	s_cmp_ge_u32 s29, 0x1c0
	s_cbranch_scc1 .Lp0t_r2_1

.Lp0t_rd2:
	s_mul_i32 s56, s56, s28
	s_lshl_b32 s42, s30, 6
	s_lshl_b32 s43, s31, 6
	s_mul_i32 s44, s42, s57
	s_add_i32 s44, s44, s43
	s_lshl_b32 s44, s44, 2
	s_add_u32 s44, s44, s56
	s_add_u32 s36, s54, s44
	s_addc_u32 s37, s55, 0
	s_lshl_b32 s40, s57, 2
	s_mul_i32 s44, s43, s58
	s_add_i32 s44, s44, s42
	s_lshl_b32 s44, s44, 1
	s_mul_i32 s45, s28, 0x1600000
	s_add_u32 s44, s44, s45
	s_add_u32 s44, s44, s59
	s_add_u32 s44, s44, 0xc00000
	s_add_u32 s38, s24, s44
	s_addc_u32 s39, s25, 0
	s_lshl_b32 s41, s58, 1
	v_mad_u32_u24 v6, v0, s40, v1
	global_load_dwordx4 v[8:11], v6, s[36:37]
	s_lshl_b32 s42, s40, 5
	s_add_u32 s36, s36, s42
	s_addc_u32 s37, s37, 0
	global_load_dwordx4 v[12:15], v6, s[36:37]
	s_waitcnt vmcnt(3)
	ds_write_b32 v2, v16 offset:16640
	ds_write_b32 v2, v17 offset:16644
	ds_write_b32 v2, v18 offset:16648
	ds_write_b32 v2, v19 offset:16652
	ds_write_b32 v2, v20 offset:24960
	ds_write_b32 v2, v21 offset:24964
	ds_write_b32 v2, v22 offset:24968
	ds_write_b32 v2, v23 offset:24972
	s_waitcnt lgkmcnt(0)
	s_barrier
	ds_read_b32 v24, v5 offset:16640
	ds_read_b32 v25, v5 offset:16900
	ds_read_b32 v26, v5 offset:17160
	ds_read_b32 v27, v5 offset:17420
	ds_read_b32 v28, v5 offset:17680
	ds_read_b32 v29, v5 offset:17940
	ds_read_b32 v30, v5 offset:18200
	ds_read_b32 v31, v5 offset:18460
	v_mad_u32_u24 v7, v4, s53, v3
	s_waitcnt lgkmcnt(0)
	v_cvt_pk_bf16_f32 v32, v24, v25
	v_cvt_pk_bf16_f32 v33, v26, v27
	v_cvt_pk_bf16_f32 v34, v28, v29
	v_cvt_pk_bf16_f32 v35, v30, v31
	global_store_dwordx4 v7, v[32:35], s[50:51]
	s_branch .Lp0t_loop
.Lp0t_last:
	s_waitcnt vmcnt(1)
	ds_write_b32 v2, v16 offset:16640
	ds_write_b32 v2, v17 offset:16644
	ds_write_b32 v2, v18 offset:16648
	ds_write_b32 v2, v19 offset:16652
	ds_write_b32 v2, v20 offset:24960
	ds_write_b32 v2, v21 offset:24964
	ds_write_b32 v2, v22 offset:24968
	ds_write_b32 v2, v23 offset:24972
	s_waitcnt lgkmcnt(0)
	s_barrier
	ds_read_b32 v24, v5 offset:16640
	ds_read_b32 v25, v5 offset:16900
	ds_read_b32 v26, v5 offset:17160
	ds_read_b32 v27, v5 offset:17420
	ds_read_b32 v28, v5 offset:17680
	ds_read_b32 v29, v5 offset:17940
	ds_read_b32 v30, v5 offset:18200
	ds_read_b32 v31, v5 offset:18460
	v_mad_u32_u24 v7, v4, s53, v3
	s_waitcnt lgkmcnt(0)
	v_cvt_pk_bf16_f32 v32, v24, v25
	v_cvt_pk_bf16_f32 v33, v26, v27
	v_cvt_pk_bf16_f32 v34, v28, v29
	v_cvt_pk_bf16_f32 v35, v30, v31
	global_store_dwordx4 v7, v[32:35], s[50:51]
	s_cmp_lt_i32 s79, 2
	v_readlane_b32 s51, v247, 25
	s_cbranch_scc1 .LBB0_124
	s_waitcnt vmcnt(0)
	s_barrier
	s_mov_b64 s[0:1], exec
	v_readlane_b32 s4, v247, 4
	v_readlane_b32 s5, v247, 5
	s_and_b64 s[4:5], s[0:1], s[4:5]
	s_mov_b64 exec, s[4:5]
	s_cbranch_execz .LBB0_123
	s_add_i32 s2, 0, 0x23fc0
	v_mov_b32_e32 v0, s2
	s_waitcnt vmcnt(0) expcnt(0) lgkmcnt(0)
	ds_read_b32 v2, v0
	s_add_i32 s2, 0, 0x23fc4
	v_mov_b32_e32 v0, s2
	ds_read_b32 v0, v0
	s_waitcnt lgkmcnt(1)
	v_cmp_ne_u32_e32 vcc, 0, v2
	s_cbranch_vccnz .LBB0_87
	v_readlane_b32 s40, v247, 0
	v_readlane_b32 s42, v247, 2
	v_readlane_b32 s43, v247, 3
	s_add_u32 s4, s42, 0x80200
	s_addc_u32 s5, s43, 0
	s_add_u32 s8, s42, 0x80400
	s_addc_u32 s9, s43, 0
	s_add_u32 s10, s42, 0x80500
	s_addc_u32 s11, s43, 0
	s_add_u32 s12, s42, 0x80600
	s_addc_u32 s13, s43, 0
	s_add_u32 s14, s42, 0x80700
	s_addc_u32 s15, s43, 0
	s_add_u32 s16, s42, 0x80800
	s_addc_u32 s17, s43, 0
	s_add_u32 s18, s42, 0x80900
	s_addc_u32 s19, s43, 0
	s_add_u32 s20, s42, 0x80a00
	s_addc_u32 s21, s43, 0
	s_add_u32 s22, s42, 0x80b00
	s_addc_u32 s23, s43, 0
	s_add_u32 s24, s42, 0x80c00
	s_addc_u32 s25, s43, 0
	s_add_u32 s26, s42, 0x80d00
	s_addc_u32 s27, s43, 0
	s_add_u32 s28, s42, 0x80e00
	s_addc_u32 s29, s43, 0
	s_add_u32 s30, s42, 0x80f00
	s_addc_u32 s31, s43, 0
	s_add_u32 s36, s42, 0x81000
	s_addc_u32 s37, s43, 0
	s_add_u32 s38, s42, 0x81100
	s_addc_u32 s39, s43, 0
	v_readlane_b32 s41, v247, 1
	s_add_u32 s40, s42, 0x81200
	s_addc_u32 s41, s43, 0
	s_mul_i32 s2, s35, s33
	s_add_u32 s42, s42, 0x81300
	s_mul_i32 s2, s2, s34
	s_addc_u32 s43, s43, 0
	s_mov_b32 s50, 1
	v_mov_b32_e32 v16, 0
	s_branch .LBB0_75

.LBB0_165:
	s_add_i32 s0, s36, 9
	s_add_u32 s71, s4, 0x3800000
	s_addc_u32 s72, s5, 0
	s_cmp_lt_u32 s0, 21
	v_writelane_b32 v245, s36, 37
	s_cselect_b64 s[0:1], -1, 0
	v_writelane_b32 v245, s0, 38
	s_mov_b32 s24, 0
	s_nop 0
	v_writelane_b32 v245, s1, 39
	s_and_b64 s[0:1], s[0:1], exec
	s_cselect_b32 s7, 0, 0x400
	s_cselect_b32 s100, 1, 0
	s_mov_b32 s101, 0x900
	s_bitcmp1_b32 s101, s36
	s_cselect_b32 s7, 0x400, s7
	s_cmp_eq_u32 s100, 1
	v_writelane_b32 v245, s7, 40
	s_cselect_b32 s0, s16, s71
	v_writelane_b32 v245, s0, 41
	s_cselect_b32 s0, s17, s72
	s_xor_b32 s46, s7, 0x4400
	s_mul_i32 s1, s70, 0x1600000
	v_writelane_b32 v245, s0, 42
	s_mul_hi_i32 s0, s70, 0x1600000
	s_add_u32 s1, s4, s1
	s_addc_u32 s0, s5, s0
	s_add_u32 s8, s1, 0xc00000
	s_addc_u32 s9, s0, 0
	v_writelane_b32 v245, s8, 43
	s_nop 1
	v_writelane_b32 v245, s9, 44
	s_add_u32 s8, s4, 0x3c00000
	s_addc_u32 s9, s5, 0
	s_lshl_b32 s6, s7, 11
	s_add_u32 s10, s8, s6
	v_writelane_b32 v245, s8, 45
	s_addc_u32 s11, s9, 0
	s_nop 0
	v_writelane_b32 v245, s9, 46
	v_writelane_b32 v245, s10, 47
	s_add_u32 s8, s1, 0x1000000
	s_addc_u32 s9, s0, 0
	v_writelane_b32 v245, s11, 48
	v_writelane_b32 v245, s8, 49
	s_nop 1
	v_writelane_b32 v245, s9, 50
	s_add_u32 s8, s1, 0x1200000
	s_addc_u32 s9, s0, 0
	v_writelane_b32 v245, s8, 51
	s_nop 1
	v_writelane_b32 v245, s9, 52
	s_add_u32 s8, s4, 0xc500000
	s_addc_u32 s9, s5, 0
	s_lshl_b32 s6, s7, 9
	s_add_u32 s10, s8, s6
	v_writelane_b32 v245, s8, 53
	s_addc_u32 s11, s9, 0
	s_nop 0
	v_writelane_b32 v245, s9, 54
	v_writelane_b32 v245, s10, 55
	s_add_u32 s8, s1, 0xfc0000
	s_addc_u32 s9, s0, 0
	v_writelane_b32 v245, s11, 56
	v_writelane_b32 v245, s8, 57
	s_nop 1
	v_writelane_b32 v245, s9, 58
	s_add_u32 s8, s4, 0xbc00000
	s_addc_u32 s9, s5, 0
	v_writelane_b32 v245, s8, 59
	s_add_u32 s8, s8, s6
	v_writelane_b32 v245, s9, 60
	s_addc_u32 s9, s9, 0
	v_writelane_b32 v245, s8, 61
	s_nop 1
	v_writelane_b32 v245, s9, 62
	s_add_u32 s8, s1, 0xfa0000
	s_addc_u32 s9, s0, 0
	v_writelane_b32 v245, s8, 63
	s_nop 1
	v_writelane_b32 v244, s9, 0
	s_add_u32 s8, s4, 0xa300000
	s_addc_u32 s9, s5, 0
	s_add_u32 s10, s8, s6
	v_writelane_b32 v244, s8, 1
	s_addc_u32 s11, s9, 0
	s_nop 0
	v_writelane_b32 v244, s9, 2
	v_writelane_b32 v244, s10, 3
	s_add_u32 s8, s1, 0xf80000
	s_addc_u32 s9, s0, 0
	v_writelane_b32 v244, s11, 4
	v_writelane_b32 v244, s8, 5
	s_nop 1
	v_writelane_b32 v244, s9, 6
	s_add_u32 s8, s1, 0xe80000
	s_addc_u32 s9, s0, 0
	v_writelane_b32 v244, s8, 7
	s_nop 1
	v_writelane_b32 v244, s9, 8
	s_add_u32 s8, s4, 0x5e00000
	s_addc_u32 s9, s5, 0
	s_lshl_b32 s6, s7, 13
	s_add_u32 s10, s8, s6
	v_writelane_b32 v247, s8, 26
	s_addc_u32 s11, s9, 0
	v_writelane_b32 v244, s10, 9
	v_writelane_b32 v247, s9, 27
	s_add_u32 s8, s1, 0x1a00000
	s_addc_u32 s9, s0, 0
	s_lshl_b32 s0, s70, 10
	v_writelane_b32 v244, s11, 10
	s_ashr_i32 s1, s0, 31
	v_writelane_b32 v244, s8, 11
	s_lshr_b32 s47, s7, 8
	s_lshl_b64 s[0:1], s[0:1], 2
	v_writelane_b32 v244, s9, 12
	s_add_u32 s6, s4, s0
	v_writelane_b32 v244, s6, 13
	v_writelane_b32 v244, s0, 14
	s_nop 1
	v_writelane_b32 v244, s1, 15
	s_addc_u32 s0, s5, s1
	v_writelane_b32 v244, s0, 16
	s_add_u32 s0, s4, 0xce00000
	s_addc_u32 s1, s5, 0
	v_writelane_b32 v244, s0, 17
	s_nop 1
	v_writelane_b32 v244, s1, 18
	s_lshl_b32 s0, s70, 9
	s_ashr_i32 s1, s0, 31
	s_lshl_b64 s[0:1], s[0:1], 2
	s_add_u32 s0, s4, s0
	s_addc_u32 s1, s5, s1
	s_add_u32 s0, s0, 0x220320
	s_addc_u32 s1, s1, 0
	v_writelane_b32 v244, s0, 19
	s_lshl_b32 s6, s70, 8
	s_ashr_i32 s7, s6, 31
	v_writelane_b32 v244, s1, 20
	s_mov_b32 s0, s6
	v_writelane_b32 v244, s0, 21
	s_lshl_b64 s[6:7], s[6:7], 2
	s_nop 0
	v_writelane_b32 v244, s1, 22
	s_add_u32 s0, s4, s6
	v_writelane_b32 v244, s6, 23
	s_addc_u32 s1, s5, s7
	s_add_u32 s8, s0, 0x113800
	s_addc_u32 s9, s1, 0
	s_add_u32 s28, s4, 0xdf00000
	s_addc_u32 s29, s5, 0
	s_add_u32 s84, s0, 0x113000
	s_addc_u32 s85, s1, 0
	v_writelane_b32 v244, s7, 24
	s_add_u32 s0, s4, 0x9a00000
	v_writelane_b32 v244, s0, 25
	s_addc_u32 s0, s5, 0
	v_writelane_b32 v244, s0, 26
	s_add_u32 s0, s4, 0xa200000
	v_writelane_b32 v247, s0, 25
	s_addc_u32 s0, s5, 0
	v_writelane_b32 v244, s0, 27
	s_lshl_b32 s0, s70, 12
	s_ashr_i32 s1, s0, 31
	s_lshl_b64 s[0:1], s[0:1], 2
	s_add_u32 s0, s4, s0
	s_addc_u32 s1, s5, s1
	s_add_u32 s0, s0, 0x227320
	s_addc_u32 s1, s1, 0
	v_writelane_b32 v244, s0, 28
	v_writelane_b32 v247, s70, 28
	s_nop 0
	v_writelane_b32 v244, s1, 29
	v_writelane_b32 v244, s71, 30
	v_writelane_b32 v244, s72, 31
	s_branch .LBB0_168

.LBB0_342:
	v_readlane_b32 s100, v245, 37
	s_mov_b32 s101, 0x900
	s_nop 0
	s_bitcmp1_b32 s101, s100
	s_cbranch_scc0 .Lcg_skip
	v_writelane_b32 v243, s8, 8
	v_writelane_b32 v243, s9, 9
	v_writelane_b32 v243, s10, 10
	v_writelane_b32 v243, s11, 11
	v_writelane_b32 v243, s12, 12
	v_writelane_b32 v243, s13, 13
	v_writelane_b32 v243, s14, 14
	v_writelane_b32 v243, s15, 15
	v_writelane_b32 v243, s16, 16
	v_writelane_b32 v243, s17, 17
	v_writelane_b32 v243, s18, 18
	v_writelane_b32 v243, s19, 19
	v_writelane_b32 v243, s20, 20
	v_writelane_b32 v243, s21, 21
	v_writelane_b32 v243, s22, 22
	v_writelane_b32 v243, s23, 23
	v_writelane_b32 v243, s24, 24
	v_writelane_b32 v243, s25, 25
	v_writelane_b32 v243, s26, 26
	v_writelane_b32 v243, s27, 27
	v_writelane_b32 v243, s28, 28
	v_writelane_b32 v243, s29, 29
	v_writelane_b32 v243, s30, 30
	v_writelane_b32 v243, s31, 31
	v_lshrrev_b32_e32 v132, 6, v186
	v_and_b32_e32 v133, 63, v186
	v_and_b32_e32 v134, 15, v133
	v_lshrrev_b32_e32 v135, 4, v133
	s_nop 0
	v_readfirstlane_b32 s24, v132
	s_cmp_eq_u32 s100, 10
	s_cbranch_scc1 .Lcg_k5
	s_cmp_eq_u32 s100, 11
	s_cbranch_scc1 .Lcg_k7
.Lcg_k6:
	v_mul_u32_u24_e32 v128, 0x800, v134
	v_lshl_add_u32 v128, v135, 4, v128
	v_add_u32_e32 v129, 0x8000, v128
	v_add_u32_e32 v130, 0x8000, v129
	v_add_u32_e32 v131, 0x8000, v130
	s_mov_b32 s14, 0
.Lcg_tile_k6:
	s_lshr_b32 s16, s69, 4
	s_and_b32 s17, s69, 15
	s_mul_i32 s25, s24, 0x100
	s_mul_i32 s26, s16, 0x20000
	s_add_u32 s26, s26, s25
	s_add_u32 s26, s26, 0x3c00000
	s_add_u32 s10, s4, s26
	s_addc_u32 s11, s5, 0
	s_mul_i32 s26, s17, 0x20000
	s_add_u32 s26, s26, s25
	s_add_u32 s26, s26, 0x1000000
	s_add_u32 s12, s4, s26
	s_addc_u32 s13, s5, 0
	global_load_dwordx4 v[64:67], v128, s[10:11] offset:0
	global_load_dwordx4 v[68:71], v129, s[10:11] offset:0
	global_load_dwordx4 v[72:75], v130, s[10:11] offset:0
	global_load_dwordx4 v[76:79], v131, s[10:11] offset:0
	global_load_dwordx4 v[80:83], v128, s[12:13] offset:0
	global_load_dwordx4 v[84:87], v129, s[12:13] offset:0
	global_load_dwordx4 v[88:91], v130, s[12:13] offset:0
	global_load_dwordx4 v[92:95], v131, s[12:13] offset:0
	global_load_dwordx4 v[96:99], v128, s[10:11] offset:64
	global_load_dwordx4 v[100:103], v129, s[10:11] offset:64
	global_load_dwordx4 v[104:107], v130, s[10:11] offset:64
	global_load_dwordx4 v[108:111], v131, s[10:11] offset:64
	global_load_dwordx4 v[112:115], v128, s[12:13] offset:64
	global_load_dwordx4 v[116:119], v129, s[12:13] offset:64
	global_load_dwordx4 v[120:123], v130, s[12:13] offset:64
	global_load_dwordx4 v[124:127], v131, s[12:13] offset:64
	global_load_dwordx4 v[138:141], v128, s[10:11] offset:128
	global_load_dwordx4 v[142:145], v129, s[10:11] offset:128
	global_load_dwordx4 v[146:149], v130, s[10:11] offset:128
	global_load_dwordx4 v[150:153], v131, s[10:11] offset:128
	global_load_dwordx4 v[154:157], v128, s[12:13] offset:128
	global_load_dwordx4 v[158:161], v129, s[12:13] offset:128
	global_load_dwordx4 v[162:165], v130, s[12:13] offset:128
	global_load_dwordx4 v[166:169], v131, s[12:13] offset:128
	s_waitcnt vmcnt(16)
	v_mfma_f32_16x16x32_bf16 v[0:3], v[80:83], v[64:67], 0
	v_mfma_f32_16x16x32_bf16 v[4:7], v[84:87], v[64:67], 0
	v_mfma_f32_16x16x32_bf16 v[8:11], v[88:91], v[64:67], 0
	v_mfma_f32_16x16x32_bf16 v[12:15], v[92:95], v[64:67], 0
	v_mfma_f32_16x16x32_bf16 v[16:19], v[80:83], v[68:71], 0
	v_mfma_f32_16x16x32_bf16 v[20:23], v[84:87], v[68:71], 0
	v_mfma_f32_16x16x32_bf16 v[24:27], v[88:91], v[68:71], 0
	v_mfma_f32_16x16x32_bf16 v[28:31], v[92:95], v[68:71], 0
	v_mfma_f32_16x16x32_bf16 v[32:35], v[80:83], v[72:75], 0
	v_mfma_f32_16x16x32_bf16 v[36:39], v[84:87], v[72:75], 0
	v_mfma_f32_16x16x32_bf16 v[40:43], v[88:91], v[72:75], 0
	v_mfma_f32_16x16x32_bf16 v[44:47], v[92:95], v[72:75], 0
	v_mfma_f32_16x16x32_bf16 v[48:51], v[80:83], v[76:79], 0
	v_mfma_f32_16x16x32_bf16 v[52:55], v[84:87], v[76:79], 0
	v_mfma_f32_16x16x32_bf16 v[56:59], v[88:91], v[76:79], 0
	v_mfma_f32_16x16x32_bf16 v[60:63], v[92:95], v[76:79], 0
	global_load_dwordx4 v[64:67], v128, s[10:11] offset:192
	global_load_dwordx4 v[68:71], v129, s[10:11] offset:192
	global_load_dwordx4 v[72:75], v130, s[10:11] offset:192
	global_load_dwordx4 v[76:79], v131, s[10:11] offset:192
	global_load_dwordx4 v[80:83], v128, s[12:13] offset:192
	global_load_dwordx4 v[84:87], v129, s[12:13] offset:192
	global_load_dwordx4 v[88:91], v130, s[12:13] offset:192
	global_load_dwordx4 v[92:95], v131, s[12:13] offset:192
	s_waitcnt vmcnt(16)
	v_mfma_f32_16x16x32_bf16 v[0:3], v[112:115], v[96:99], v[0:3]
	v_mfma_f32_16x16x32_bf16 v[4:7], v[116:119], v[96:99], v[4:7]
	v_mfma_f32_16x16x32_bf16 v[8:11], v[120:123], v[96:99], v[8:11]
	v_mfma_f32_16x16x32_bf16 v[12:15], v[124:127], v[96:99], v[12:15]
	v_mfma_f32_16x16x32_bf16 v[16:19], v[112:115], v[100:103], v[16:19]
	v_mfma_f32_16x16x32_bf16 v[20:23], v[116:119], v[100:103], v[20:23]
	v_mfma_f32_16x16x32_bf16 v[24:27], v[120:123], v[100:103], v[24:27]
	v_mfma_f32_16x16x32_bf16 v[28:31], v[124:127], v[100:103], v[28:31]
	v_mfma_f32_16x16x32_bf16 v[32:35], v[112:115], v[104:107], v[32:35]
	v_mfma_f32_16x16x32_bf16 v[36:39], v[116:119], v[104:107], v[36:39]
	v_mfma_f32_16x16x32_bf16 v[40:43], v[120:123], v[104:107], v[40:43]
	v_mfma_f32_16x16x32_bf16 v[44:47], v[124:127], v[104:107], v[44:47]
	v_mfma_f32_16x16x32_bf16 v[48:51], v[112:115], v[108:111], v[48:51]
	v_mfma_f32_16x16x32_bf16 v[52:55], v[116:119], v[108:111], v[52:55]
	v_mfma_f32_16x16x32_bf16 v[56:59], v[120:123], v[108:111], v[56:59]
	v_mfma_f32_16x16x32_bf16 v[60:63], v[124:127], v[108:111], v[60:63]
	s_waitcnt vmcnt(8)
	v_mfma_f32_16x16x32_bf16 v[0:3], v[154:157], v[138:141], v[0:3]
	v_mfma_f32_16x16x32_bf16 v[4:7], v[158:161], v[138:141], v[4:7]
	v_mfma_f32_16x16x32_bf16 v[8:11], v[162:165], v[138:141], v[8:11]
	v_mfma_f32_16x16x32_bf16 v[12:15], v[166:169], v[138:141], v[12:15]
	v_mfma_f32_16x16x32_bf16 v[16:19], v[154:157], v[142:145], v[16:19]
	v_mfma_f32_16x16x32_bf16 v[20:23], v[158:161], v[142:145], v[20:23]
	v_mfma_f32_16x16x32_bf16 v[24:27], v[162:165], v[142:145], v[24:27]
	v_mfma_f32_16x16x32_bf16 v[28:31], v[166:169], v[142:145], v[28:31]
	v_mfma_f32_16x16x32_bf16 v[32:35], v[154:157], v[146:149], v[32:35]
	v_mfma_f32_16x16x32_bf16 v[36:39], v[158:161], v[146:149], v[36:39]
	v_mfma_f32_16x16x32_bf16 v[40:43], v[162:165], v[146:149], v[40:43]
	v_mfma_f32_16x16x32_bf16 v[44:47], v[166:169], v[146:149], v[44:47]
	v_mfma_f32_16x16x32_bf16 v[48:51], v[154:157], v[150:153], v[48:51]
	v_mfma_f32_16x16x32_bf16 v[52:55], v[158:161], v[150:153], v[52:55]
	v_mfma_f32_16x16x32_bf16 v[56:59], v[162:165], v[150:153], v[56:59]
	v_mfma_f32_16x16x32_bf16 v[60:63], v[166:169], v[150:153], v[60:63]
	s_waitcnt vmcnt(0)
	v_mfma_f32_16x16x32_bf16 v[0:3], v[80:83], v[64:67], v[0:3]
	v_mfma_f32_16x16x32_bf16 v[4:7], v[84:87], v[64:67], v[4:7]
	v_mfma_f32_16x16x32_bf16 v[8:11], v[88:91], v[64:67], v[8:11]
	v_mfma_f32_16x16x32_bf16 v[12:15], v[92:95], v[64:67], v[12:15]
	v_mfma_f32_16x16x32_bf16 v[16:19], v[80:83], v[68:71], v[16:19]
	v_mfma_f32_16x16x32_bf16 v[20:23], v[84:87], v[68:71], v[20:23]
	v_mfma_f32_16x16x32_bf16 v[24:27], v[88:91], v[68:71], v[24:27]
	v_mfma_f32_16x16x32_bf16 v[28:31], v[92:95], v[68:71], v[28:31]
	v_mfma_f32_16x16x32_bf16 v[32:35], v[80:83], v[72:75], v[32:35]
	v_mfma_f32_16x16x32_bf16 v[36:39], v[84:87], v[72:75], v[36:39]
	v_mfma_f32_16x16x32_bf16 v[40:43], v[88:91], v[72:75], v[40:43]
	v_mfma_f32_16x16x32_bf16 v[44:47], v[92:95], v[72:75], v[44:47]
	v_mfma_f32_16x16x32_bf16 v[48:51], v[80:83], v[76:79], v[48:51]
	v_mfma_f32_16x16x32_bf16 v[52:55], v[84:87], v[76:79], v[52:55]
	v_mfma_f32_16x16x32_bf16 v[56:59], v[88:91], v[76:79], v[56:59]
	v_mfma_f32_16x16x32_bf16 v[60:63], v[92:95], v[76:79], v[60:63]
	v_lshlrev_b32_e32 v170, 14, v132
	v_lshl_add_u32 v170, v133, 4, v170
	s_nop 7
	ds_write_b128 v170, v[0:3] offset:0
	ds_write_b128 v170, v[4:7] offset:1024
	ds_write_b128 v170, v[8:11] offset:2048
	ds_write_b128 v170, v[12:15] offset:3072
	ds_write_b128 v170, v[16:19] offset:4096
	ds_write_b128 v170, v[20:23] offset:5120
	ds_write_b128 v170, v[24:27] offset:6144
	ds_write_b128 v170, v[28:31] offset:7168
	ds_write_b128 v170, v[32:35] offset:8192
	ds_write_b128 v170, v[36:39] offset:9216
	ds_write_b128 v170, v[40:43] offset:10240
	ds_write_b128 v170, v[44:47] offset:11264
	ds_write_b128 v170, v[48:51] offset:12288
	ds_write_b128 v170, v[52:55] offset:13312
	ds_write_b128 v170, v[56:59] offset:14336
	ds_write_b128 v170, v[60:63] offset:15360
	s_lshr_b32 s25, s24, 1
	s_lshl_b32 s25, s25, 4
	s_lshl_b32 s26, s16, 6
	s_add_i32 s25, s25, s26
	s_and_b32 s26, s24, 1
	s_lshl_b32 s26, s26, 5
	s_lshl_b32 s27, s17, 6
	s_add_i32 s26, s26, s27
	v_add_u32_e32 v171, s25, v134
	v_lshl_add_u32 v172, v135, 2, s26
	v_lshlrev_b32_e32 v173, 10, v171
	v_add_lshl_u32 v173, v173, v172, 2
	v_readlane_b32 s18, v247, 10
	v_readlane_b32 s19, v247, 11
	s_add_u32 s20, s4, 0x3800000
	s_addc_u32 s21, s5, 0
	v_lshlrev_b32_e32 v174, 2, v172
	s_add_u32 s22, s4, 0x223320
	s_addc_u32 s23, s5, 0
	s_add_u32 s28, s4, 0x1a000
	s_addc_u32 s29, s5, 0
	s_nop 2
	global_load_dwordx4 v[176:179], v173, s[18:19] offset:0
	global_load_dwordx4 v[64:67], v174, s[22:23] offset:0
	global_load_dwordx4 v[72:75], v174, s[28:29] offset:0
	global_load_dwordx4 v[180:183], v173, s[18:19] offset:64
	global_load_dwordx4 v[68:71], v174, s[22:23] offset:64
	global_load_dwordx4 v[76:79], v174, s[28:29] offset:64
	s_waitcnt lgkmcnt(0)
	s_barrier
	v_lshlrev_b32_e32 v175, 11, v132
	v_lshl_add_u32 v175, v133, 4, v175
	v_add_u32_e32 v100, 0x4000, v175
	v_add_u32_e32 v101, 0x8000, v175
	v_add_u32_e32 v102, 0xc000, v175
	v_add_u32_e32 v103, 0x10000, v175
	v_add_u32_e32 v166, 0x14000, v175
	v_add_u32_e32 v167, 0x18000, v175
	v_add_u32_e32 v168, 0x1c000, v175
	ds_read_b128 v[80:83], v175 offset:0
	ds_read_b128 v[0:3], v100 offset:0
	ds_read_b128 v[4:7], v101 offset:0
	ds_read_b128 v[8:11], v102 offset:0
	ds_read_b128 v[12:15], v103 offset:0
	ds_read_b128 v[16:19], v166 offset:0
	ds_read_b128 v[20:23], v167 offset:0
	ds_read_b128 v[24:27], v168 offset:0
	s_waitcnt lgkmcnt(0)
	ds_read_b128 v[96:99], v175 offset:1024
	ds_read_b128 v[138:141], v100 offset:1024
	ds_read_b128 v[142:145], v101 offset:1024
	ds_read_b128 v[146:149], v102 offset:1024
	ds_read_b128 v[150:153], v103 offset:1024
	ds_read_b128 v[154:157], v166 offset:1024
	ds_read_b128 v[158:161], v167 offset:1024
	ds_read_b128 v[162:165], v168 offset:1024
	s_waitcnt lgkmcnt(0)
	v_add_f32_e32 v80, v80, v0
	v_add_f32_e32 v81, v81, v1
	v_add_f32_e32 v82, v82, v2
	v_add_f32_e32 v83, v83, v3
	v_add_f32_e32 v80, v80, v4
	v_add_f32_e32 v81, v81, v5
	v_add_f32_e32 v82, v82, v6
	v_add_f32_e32 v83, v83, v7
	v_add_f32_e32 v80, v80, v8
	v_add_f32_e32 v81, v81, v9
	v_add_f32_e32 v82, v82, v10
	v_add_f32_e32 v83, v83, v11
	v_add_f32_e32 v80, v80, v12
	v_add_f32_e32 v81, v81, v13
	v_add_f32_e32 v82, v82, v14
	v_add_f32_e32 v83, v83, v15
	v_add_f32_e32 v80, v80, v16
	v_add_f32_e32 v81, v81, v17
	v_add_f32_e32 v82, v82, v18
	v_add_f32_e32 v83, v83, v19
	v_add_f32_e32 v80, v80, v20
	v_add_f32_e32 v81, v81, v21
	v_add_f32_e32 v82, v82, v22
	v_add_f32_e32 v83, v83, v23
	v_add_f32_e32 v80, v80, v24
	v_add_f32_e32 v81, v81, v25
	v_add_f32_e32 v82, v82, v26
	v_add_f32_e32 v83, v83, v27
	v_add_f32_e32 v96, v96, v138
	v_add_f32_e32 v97, v97, v139
	v_add_f32_e32 v98, v98, v140
	v_add_f32_e32 v99, v99, v141
	v_add_f32_e32 v96, v96, v142
	v_add_f32_e32 v97, v97, v143
	v_add_f32_e32 v98, v98, v144
	v_add_f32_e32 v99, v99, v145
	v_add_f32_e32 v96, v96, v146
	v_add_f32_e32 v97, v97, v147
	v_add_f32_e32 v98, v98, v148
	v_add_f32_e32 v99, v99, v149
	v_add_f32_e32 v96, v96, v150
	v_add_f32_e32 v97, v97, v151
	v_add_f32_e32 v98, v98, v152
	v_add_f32_e32 v99, v99, v153
	v_add_f32_e32 v96, v96, v154
	v_add_f32_e32 v97, v97, v155
	v_add_f32_e32 v98, v98, v156
	v_add_f32_e32 v99, v99, v157
	v_add_f32_e32 v96, v96, v158
	v_add_f32_e32 v97, v97, v159
	v_add_f32_e32 v98, v98, v160
	v_add_f32_e32 v99, v99, v161
	v_add_f32_e32 v96, v96, v162
	v_add_f32_e32 v97, v97, v163
	v_add_f32_e32 v98, v98, v164
	v_add_f32_e32 v99, v99, v165
	s_waitcnt vmcnt(0)
	v_add_f32_e32 v80, v80, v64
	v_add_f32_e32 v81, v81, v65
	v_add_f32_e32 v82, v82, v66
	v_add_f32_e32 v83, v83, v67
	v_fma_f32 v80, v72, v80, v176
	v_fma_f32 v81, v73, v81, v177
	v_fma_f32 v82, v74, v82, v178
	v_fma_f32 v83, v75, v83, v179
	global_store_dwordx4 v173, v[80:83], s[20:21] offset:0
	v_add_f32_e32 v96, v96, v68
	v_add_f32_e32 v97, v97, v69
	v_add_f32_e32 v98, v98, v70
	v_add_f32_e32 v99, v99, v71
	v_fma_f32 v96, v76, v96, v180
	v_fma_f32 v97, v77, v97, v181
	v_fma_f32 v98, v78, v98, v182
	v_fma_f32 v99, v79, v99, v183
	global_store_dwordx4 v173, v[96:99], s[20:21] offset:64
	s_barrier
	s_branch .Lcg_done

.Lcg_tile_k5:
	s_lshl_b32 s15, s69, 2
	s_add_i32 s15, s15, s14
	s_lshr_b32 s16, s15, 6
	s_and_b32 s17, s15, 63
	s_mul_i32 s25, s24, 0x100
	s_mul_i32 s26, s16, 0x20000
	s_add_u32 s26, s26, s25
	s_add_u32 s26, s26, 0x3c00000
	s_add_u32 s10, s4, s26
	s_addc_u32 s11, s5, 0
	s_mul_i32 s26, s17, 0x20000
	s_add_u32 s26, s26, s25
	s_add_u32 s26, s26, 0x1200000
	s_add_u32 s12, s4, s26
	s_addc_u32 s13, s5, 0
	global_load_dwordx4 v[64:67], v128, s[10:11] offset:0
	global_load_dwordx4 v[68:71], v129, s[10:11] offset:0
	global_load_dwordx4 v[72:75], v130, s[10:11] offset:0
	global_load_dwordx4 v[76:79], v131, s[10:11] offset:0
	global_load_dwordx4 v[80:83], v128, s[12:13] offset:0
	global_load_dwordx4 v[84:87], v129, s[12:13] offset:0
	global_load_dwordx4 v[88:91], v130, s[12:13] offset:0
	global_load_dwordx4 v[92:95], v131, s[12:13] offset:0
	global_load_dwordx4 v[96:99], v128, s[10:11] offset:64
	global_load_dwordx4 v[100:103], v129, s[10:11] offset:64
	global_load_dwordx4 v[104:107], v130, s[10:11] offset:64
	global_load_dwordx4 v[108:111], v131, s[10:11] offset:64
	global_load_dwordx4 v[112:115], v128, s[12:13] offset:64
	global_load_dwordx4 v[116:119], v129, s[12:13] offset:64
	global_load_dwordx4 v[120:123], v130, s[12:13] offset:64
	global_load_dwordx4 v[124:127], v131, s[12:13] offset:64
	global_load_dwordx4 v[138:141], v128, s[10:11] offset:128
	global_load_dwordx4 v[142:145], v129, s[10:11] offset:128
	global_load_dwordx4 v[146:149], v130, s[10:11] offset:128
	global_load_dwordx4 v[150:153], v131, s[10:11] offset:128
	global_load_dwordx4 v[154:157], v128, s[12:13] offset:128
	global_load_dwordx4 v[158:161], v129, s[12:13] offset:128
	global_load_dwordx4 v[162:165], v130, s[12:13] offset:128
	global_load_dwordx4 v[166:169], v131, s[12:13] offset:128
	s_waitcnt vmcnt(16)
	v_mfma_f32_16x16x32_bf16 v[0:3], v[80:83], v[64:67], 0
	v_mfma_f32_16x16x32_bf16 v[4:7], v[84:87], v[64:67], 0
	v_mfma_f32_16x16x32_bf16 v[8:11], v[88:91], v[64:67], 0
	v_mfma_f32_16x16x32_bf16 v[12:15], v[92:95], v[64:67], 0
	v_mfma_f32_16x16x32_bf16 v[16:19], v[80:83], v[68:71], 0
	v_mfma_f32_16x16x32_bf16 v[20:23], v[84:87], v[68:71], 0
	v_mfma_f32_16x16x32_bf16 v[24:27], v[88:91], v[68:71], 0
	v_mfma_f32_16x16x32_bf16 v[28:31], v[92:95], v[68:71], 0
	v_mfma_f32_16x16x32_bf16 v[32:35], v[80:83], v[72:75], 0
	v_mfma_f32_16x16x32_bf16 v[36:39], v[84:87], v[72:75], 0
	v_mfma_f32_16x16x32_bf16 v[40:43], v[88:91], v[72:75], 0
	v_mfma_f32_16x16x32_bf16 v[44:47], v[92:95], v[72:75], 0
	v_mfma_f32_16x16x32_bf16 v[48:51], v[80:83], v[76:79], 0
	v_mfma_f32_16x16x32_bf16 v[52:55], v[84:87], v[76:79], 0
	v_mfma_f32_16x16x32_bf16 v[56:59], v[88:91], v[76:79], 0
	v_mfma_f32_16x16x32_bf16 v[60:63], v[92:95], v[76:79], 0
	global_load_dwordx4 v[64:67], v128, s[10:11] offset:192
	global_load_dwordx4 v[68:71], v129, s[10:11] offset:192
	global_load_dwordx4 v[72:75], v130, s[10:11] offset:192
	global_load_dwordx4 v[76:79], v131, s[10:11] offset:192
	global_load_dwordx4 v[80:83], v128, s[12:13] offset:192
	global_load_dwordx4 v[84:87], v129, s[12:13] offset:192
	global_load_dwordx4 v[88:91], v130, s[12:13] offset:192
	global_load_dwordx4 v[92:95], v131, s[12:13] offset:192
	s_waitcnt vmcnt(16)
	v_mfma_f32_16x16x32_bf16 v[0:3], v[112:115], v[96:99], v[0:3]
	v_mfma_f32_16x16x32_bf16 v[4:7], v[116:119], v[96:99], v[4:7]
	v_mfma_f32_16x16x32_bf16 v[8:11], v[120:123], v[96:99], v[8:11]
	v_mfma_f32_16x16x32_bf16 v[12:15], v[124:127], v[96:99], v[12:15]
	v_mfma_f32_16x16x32_bf16 v[16:19], v[112:115], v[100:103], v[16:19]
	v_mfma_f32_16x16x32_bf16 v[20:23], v[116:119], v[100:103], v[20:23]
	v_mfma_f32_16x16x32_bf16 v[24:27], v[120:123], v[100:103], v[24:27]
	v_mfma_f32_16x16x32_bf16 v[28:31], v[124:127], v[100:103], v[28:31]
	v_mfma_f32_16x16x32_bf16 v[32:35], v[112:115], v[104:107], v[32:35]
	v_mfma_f32_16x16x32_bf16 v[36:39], v[116:119], v[104:107], v[36:39]
	v_mfma_f32_16x16x32_bf16 v[40:43], v[120:123], v[104:107], v[40:43]
	v_mfma_f32_16x16x32_bf16 v[44:47], v[124:127], v[104:107], v[44:47]
	v_mfma_f32_16x16x32_bf16 v[48:51], v[112:115], v[108:111], v[48:51]
	v_mfma_f32_16x16x32_bf16 v[52:55], v[116:119], v[108:111], v[52:55]
	v_mfma_f32_16x16x32_bf16 v[56:59], v[120:123], v[108:111], v[56:59]
	v_mfma_f32_16x16x32_bf16 v[60:63], v[124:127], v[108:111], v[60:63]
	s_waitcnt vmcnt(8)
	v_mfma_f32_16x16x32_bf16 v[0:3], v[154:157], v[138:141], v[0:3]
	v_mfma_f32_16x16x32_bf16 v[4:7], v[158:161], v[138:141], v[4:7]
	v_mfma_f32_16x16x32_bf16 v[8:11], v[162:165], v[138:141], v[8:11]
	v_mfma_f32_16x16x32_bf16 v[12:15], v[166:169], v[138:141], v[12:15]
	v_mfma_f32_16x16x32_bf16 v[16:19], v[154:157], v[142:145], v[16:19]
	v_mfma_f32_16x16x32_bf16 v[20:23], v[158:161], v[142:145], v[20:23]
	v_mfma_f32_16x16x32_bf16 v[24:27], v[162:165], v[142:145], v[24:27]
	v_mfma_f32_16x16x32_bf16 v[28:31], v[166:169], v[142:145], v[28:31]
	v_mfma_f32_16x16x32_bf16 v[32:35], v[154:157], v[146:149], v[32:35]
	v_mfma_f32_16x16x32_bf16 v[36:39], v[158:161], v[146:149], v[36:39]
	v_mfma_f32_16x16x32_bf16 v[40:43], v[162:165], v[146:149], v[40:43]
	v_mfma_f32_16x16x32_bf16 v[44:47], v[166:169], v[146:149], v[44:47]
	v_mfma_f32_16x16x32_bf16 v[48:51], v[154:157], v[150:153], v[48:51]
	v_mfma_f32_16x16x32_bf16 v[52:55], v[158:161], v[150:153], v[52:55]
	v_mfma_f32_16x16x32_bf16 v[56:59], v[162:165], v[150:153], v[56:59]
	v_mfma_f32_16x16x32_bf16 v[60:63], v[166:169], v[150:153], v[60:63]
	s_waitcnt vmcnt(0)
	v_mfma_f32_16x16x32_bf16 v[0:3], v[80:83], v[64:67], v[0:3]
	v_mfma_f32_16x16x32_bf16 v[4:7], v[84:87], v[64:67], v[4:7]
	v_mfma_f32_16x16x32_bf16 v[8:11], v[88:91], v[64:67], v[8:11]
	v_mfma_f32_16x16x32_bf16 v[12:15], v[92:95], v[64:67], v[12:15]
	v_mfma_f32_16x16x32_bf16 v[16:19], v[80:83], v[68:71], v[16:19]
	v_mfma_f32_16x16x32_bf16 v[20:23], v[84:87], v[68:71], v[20:23]
	v_mfma_f32_16x16x32_bf16 v[24:27], v[88:91], v[68:71], v[24:27]
	v_mfma_f32_16x16x32_bf16 v[28:31], v[92:95], v[68:71], v[28:31]
	v_mfma_f32_16x16x32_bf16 v[32:35], v[80:83], v[72:75], v[32:35]
	v_mfma_f32_16x16x32_bf16 v[36:39], v[84:87], v[72:75], v[36:39]
	v_mfma_f32_16x16x32_bf16 v[40:43], v[88:91], v[72:75], v[40:43]
	v_mfma_f32_16x16x32_bf16 v[44:47], v[92:95], v[72:75], v[44:47]
	v_mfma_f32_16x16x32_bf16 v[48:51], v[80:83], v[76:79], v[48:51]
	v_mfma_f32_16x16x32_bf16 v[52:55], v[84:87], v[76:79], v[52:55]
	v_mfma_f32_16x16x32_bf16 v[56:59], v[88:91], v[76:79], v[56:59]
	v_mfma_f32_16x16x32_bf16 v[60:63], v[92:95], v[76:79], v[60:63]
	v_lshlrev_b32_e32 v170, 14, v132
	v_lshl_add_u32 v170, v133, 4, v170
	s_nop 7
	ds_write_b128 v170, v[0:3] offset:0
	ds_write_b128 v170, v[4:7] offset:1024
	ds_write_b128 v170, v[8:11] offset:2048
	ds_write_b128 v170, v[12:15] offset:3072
	ds_write_b128 v170, v[16:19] offset:4096
	ds_write_b128 v170, v[20:23] offset:5120
	ds_write_b128 v170, v[24:27] offset:6144
	ds_write_b128 v170, v[28:31] offset:7168
	ds_write_b128 v170, v[32:35] offset:8192
	ds_write_b128 v170, v[36:39] offset:9216
	ds_write_b128 v170, v[40:43] offset:10240
	ds_write_b128 v170, v[44:47] offset:11264
	ds_write_b128 v170, v[48:51] offset:12288
	ds_write_b128 v170, v[52:55] offset:13312
	ds_write_b128 v170, v[56:59] offset:14336
	ds_write_b128 v170, v[60:63] offset:15360
	s_lshr_b32 s25, s24, 1
	s_lshl_b32 s25, s25, 4
	s_lshl_b32 s26, s16, 6
	s_add_i32 s25, s25, s26
	s_and_b32 s26, s24, 1
	s_lshl_b32 s26, s26, 5
	s_lshl_b32 s27, s17, 6
	s_add_i32 s26, s26, s27
	v_add_u32_e32 v171, s25, v134
	v_lshl_add_u32 v172, v135, 2, s26
	v_lshlrev_b32_e32 v174, 2, v172
	s_add_u32 s22, s4, 0x227320
	s_addc_u32 s23, s5, 0
	global_load_dwordx4 v[64:67], v174, s[22:23] offset:0
	global_load_dwordx4 v[68:71], v174, s[22:23] offset:64
	v_lshlrev_b32_e32 v173, 12, v171
	v_add_lshl_u32 v173, v173, v172, 1
	s_add_u32 s20, s4, 0x5e00000
	s_addc_u32 s21, s5, 0
	s_waitcnt lgkmcnt(0)
	s_barrier
	v_lshlrev_b32_e32 v175, 11, v132
	v_lshl_add_u32 v175, v133, 4, v175
	v_add_u32_e32 v100, 0x4000, v175
	v_add_u32_e32 v101, 0x8000, v175
	v_add_u32_e32 v102, 0xc000, v175
	v_add_u32_e32 v103, 0x10000, v175
	v_add_u32_e32 v166, 0x14000, v175
	v_add_u32_e32 v167, 0x18000, v175
	v_add_u32_e32 v168, 0x1c000, v175
	ds_read_b128 v[80:83], v175 offset:0
	ds_read_b128 v[0:3], v100 offset:0
	ds_read_b128 v[4:7], v101 offset:0
	ds_read_b128 v[8:11], v102 offset:0
	ds_read_b128 v[12:15], v103 offset:0
	ds_read_b128 v[16:19], v166 offset:0
	ds_read_b128 v[20:23], v167 offset:0
	ds_read_b128 v[24:27], v168 offset:0
	s_waitcnt lgkmcnt(0)
	ds_read_b128 v[96:99], v175 offset:1024
	ds_read_b128 v[138:141], v100 offset:1024
	ds_read_b128 v[142:145], v101 offset:1024
	ds_read_b128 v[146:149], v102 offset:1024
	ds_read_b128 v[150:153], v103 offset:1024
	ds_read_b128 v[154:157], v166 offset:1024
	ds_read_b128 v[158:161], v167 offset:1024
	ds_read_b128 v[162:165], v168 offset:1024
	s_waitcnt lgkmcnt(0)
	v_add_f32_e32 v80, v80, v0
	v_add_f32_e32 v81, v81, v1
	v_add_f32_e32 v82, v82, v2
	v_add_f32_e32 v83, v83, v3
	v_add_f32_e32 v80, v80, v4
	v_add_f32_e32 v81, v81, v5
	v_add_f32_e32 v82, v82, v6
	v_add_f32_e32 v83, v83, v7
	v_add_f32_e32 v80, v80, v8
	v_add_f32_e32 v81, v81, v9
	v_add_f32_e32 v82, v82, v10
	v_add_f32_e32 v83, v83, v11
	v_add_f32_e32 v80, v80, v12
	v_add_f32_e32 v81, v81, v13
	v_add_f32_e32 v82, v82, v14
	v_add_f32_e32 v83, v83, v15
	v_add_f32_e32 v80, v80, v16
	v_add_f32_e32 v81, v81, v17
	v_add_f32_e32 v82, v82, v18
	v_add_f32_e32 v83, v83, v19
	v_add_f32_e32 v80, v80, v20
	v_add_f32_e32 v81, v81, v21
	v_add_f32_e32 v82, v82, v22
	v_add_f32_e32 v83, v83, v23
	v_add_f32_e32 v80, v80, v24
	v_add_f32_e32 v81, v81, v25
	v_add_f32_e32 v82, v82, v26
	v_add_f32_e32 v83, v83, v27
	v_add_f32_e32 v96, v96, v138
	v_add_f32_e32 v97, v97, v139
	v_add_f32_e32 v98, v98, v140
	v_add_f32_e32 v99, v99, v141
	v_add_f32_e32 v96, v96, v142
	v_add_f32_e32 v97, v97, v143
	v_add_f32_e32 v98, v98, v144
	v_add_f32_e32 v99, v99, v145
	v_add_f32_e32 v96, v96, v146
	v_add_f32_e32 v97, v97, v147
	v_add_f32_e32 v98, v98, v148
	v_add_f32_e32 v99, v99, v149
	v_add_f32_e32 v96, v96, v150
	v_add_f32_e32 v97, v97, v151
	v_add_f32_e32 v98, v98, v152
	v_add_f32_e32 v99, v99, v153
	v_add_f32_e32 v96, v96, v154
	v_add_f32_e32 v97, v97, v155
	v_add_f32_e32 v98, v98, v156
	v_add_f32_e32 v99, v99, v157
	v_add_f32_e32 v96, v96, v158
	v_add_f32_e32 v97, v97, v159
	v_add_f32_e32 v98, v98, v160
	v_add_f32_e32 v99, v99, v161
	v_add_f32_e32 v96, v96, v162
	v_add_f32_e32 v97, v97, v163
	v_add_f32_e32 v98, v98, v164
	v_add_f32_e32 v99, v99, v165
	s_waitcnt vmcnt(0)
	v_add_f32_e32 v80, v80, v64
	v_max_f32_e32 v80, 0, v80
	v_mul_f32_e32 v80, v80, v80
	v_add_f32_e32 v81, v81, v65
	v_max_f32_e32 v81, 0, v81
	v_mul_f32_e32 v81, v81, v81
	v_add_f32_e32 v82, v82, v66
	v_max_f32_e32 v82, 0, v82
	v_mul_f32_e32 v82, v82, v82
	v_add_f32_e32 v83, v83, v67
	v_max_f32_e32 v83, 0, v83
	v_mul_f32_e32 v83, v83, v83
	v_cvt_pk_bf16_f32 v112, v80, v81
	v_cvt_pk_bf16_f32 v113, v82, v83
	global_store_dwordx2 v173, v[112:113], s[20:21] offset:0
	v_add_f32_e32 v96, v96, v68
	v_max_f32_e32 v96, 0, v96
	v_mul_f32_e32 v96, v96, v96
	v_add_f32_e32 v97, v97, v69
	v_max_f32_e32 v97, 0, v97
	v_mul_f32_e32 v97, v97, v97
	v_add_f32_e32 v98, v98, v70
	v_max_f32_e32 v98, 0, v98
	v_mul_f32_e32 v98, v98, v98
	v_add_f32_e32 v99, v99, v71
	v_max_f32_e32 v99, 0, v99
	v_mul_f32_e32 v99, v99, v99
	v_cvt_pk_bf16_f32 v114, v96, v97
	v_cvt_pk_bf16_f32 v115, v98, v99
	global_store_dwordx2 v173, v[114:115], s[20:21] offset:32
	s_barrier
	s_add_i32 s14, s14, 1
	s_cmp_lt_u32 s14, 4
	s_cbranch_scc1 .Lcg_tile_k5
	s_branch .Lcg_done
.Lcg_k7:
	v_mul_u32_u24_e32 v128, 0x2000, v134
	v_lshl_add_u32 v128, v135, 4, v128
	v_add_u32_e32 v129, 0x20000, v128
	v_add_u32_e32 v130, 0x20000, v129
	v_add_u32_e32 v131, 0x20000, v130
	s_mov_b32 s14, 0
.Lcg_tile_k7:
	s_lshr_b32 s16, s69, 4
	s_and_b32 s17, s69, 15
	s_mul_i32 s25, s24, 0x400
	s_mul_i32 s26, s16, 0x80000
	s_add_u32 s26, s26, s25
	s_add_u32 s26, s26, 0x5e00000
	s_add_u32 s10, s4, s26
	s_addc_u32 s11, s5, 0
	s_mul_i32 s26, s17, 0x80000
	s_add_u32 s26, s26, s25
	s_add_u32 s26, s26, 0x1a00000
	s_add_u32 s12, s4, s26
	s_addc_u32 s13, s5, 0
	global_load_dwordx4 v[64:67], v128, s[10:11] offset:0
	global_load_dwordx4 v[68:71], v129, s[10:11] offset:0
	global_load_dwordx4 v[72:75], v130, s[10:11] offset:0
	global_load_dwordx4 v[76:79], v131, s[10:11] offset:0
	global_load_dwordx4 v[80:83], v128, s[12:13] offset:0
	global_load_dwordx4 v[84:87], v129, s[12:13] offset:0
	global_load_dwordx4 v[88:91], v130, s[12:13] offset:0
	global_load_dwordx4 v[92:95], v131, s[12:13] offset:0
	global_load_dwordx4 v[96:99], v128, s[10:11] offset:64
	global_load_dwordx4 v[100:103], v129, s[10:11] offset:64
	global_load_dwordx4 v[104:107], v130, s[10:11] offset:64
	global_load_dwordx4 v[108:111], v131, s[10:11] offset:64
	global_load_dwordx4 v[112:115], v128, s[12:13] offset:64
	global_load_dwordx4 v[116:119], v129, s[12:13] offset:64
	global_load_dwordx4 v[120:123], v130, s[12:13] offset:64
	global_load_dwordx4 v[124:127], v131, s[12:13] offset:64
	global_load_dwordx4 v[138:141], v128, s[10:11] offset:128
	global_load_dwordx4 v[142:145], v129, s[10:11] offset:128
	global_load_dwordx4 v[146:149], v130, s[10:11] offset:128
	global_load_dwordx4 v[150:153], v131, s[10:11] offset:128
	global_load_dwordx4 v[154:157], v128, s[12:13] offset:128
	global_load_dwordx4 v[158:161], v129, s[12:13] offset:128
	global_load_dwordx4 v[162:165], v130, s[12:13] offset:128
	global_load_dwordx4 v[166:169], v131, s[12:13] offset:128
	s_waitcnt vmcnt(16)
	v_mfma_f32_16x16x32_bf16 v[0:3], v[80:83], v[64:67], 0
	v_mfma_f32_16x16x32_bf16 v[4:7], v[84:87], v[64:67], 0
	v_mfma_f32_16x16x32_bf16 v[8:11], v[88:91], v[64:67], 0
	v_mfma_f32_16x16x32_bf16 v[12:15], v[92:95], v[64:67], 0
	v_mfma_f32_16x16x32_bf16 v[16:19], v[80:83], v[68:71], 0
	v_mfma_f32_16x16x32_bf16 v[20:23], v[84:87], v[68:71], 0
	v_mfma_f32_16x16x32_bf16 v[24:27], v[88:91], v[68:71], 0
	v_mfma_f32_16x16x32_bf16 v[28:31], v[92:95], v[68:71], 0
	v_mfma_f32_16x16x32_bf16 v[32:35], v[80:83], v[72:75], 0
	v_mfma_f32_16x16x32_bf16 v[36:39], v[84:87], v[72:75], 0
	v_mfma_f32_16x16x32_bf16 v[40:43], v[88:91], v[72:75], 0
	v_mfma_f32_16x16x32_bf16 v[44:47], v[92:95], v[72:75], 0
	v_mfma_f32_16x16x32_bf16 v[48:51], v[80:83], v[76:79], 0
	v_mfma_f32_16x16x32_bf16 v[52:55], v[84:87], v[76:79], 0
	v_mfma_f32_16x16x32_bf16 v[56:59], v[88:91], v[76:79], 0
	v_mfma_f32_16x16x32_bf16 v[60:63], v[92:95], v[76:79], 0
	global_load_dwordx4 v[64:67], v128, s[10:11] offset:192
	global_load_dwordx4 v[68:71], v129, s[10:11] offset:192
	global_load_dwordx4 v[72:75], v130, s[10:11] offset:192
	global_load_dwordx4 v[76:79], v131, s[10:11] offset:192
	global_load_dwordx4 v[80:83], v128, s[12:13] offset:192
	global_load_dwordx4 v[84:87], v129, s[12:13] offset:192
	global_load_dwordx4 v[88:91], v130, s[12:13] offset:192
	global_load_dwordx4 v[92:95], v131, s[12:13] offset:192
	s_waitcnt vmcnt(16)
	v_mfma_f32_16x16x32_bf16 v[0:3], v[112:115], v[96:99], v[0:3]
	v_mfma_f32_16x16x32_bf16 v[4:7], v[116:119], v[96:99], v[4:7]
	v_mfma_f32_16x16x32_bf16 v[8:11], v[120:123], v[96:99], v[8:11]
	v_mfma_f32_16x16x32_bf16 v[12:15], v[124:127], v[96:99], v[12:15]
	v_mfma_f32_16x16x32_bf16 v[16:19], v[112:115], v[100:103], v[16:19]
	v_mfma_f32_16x16x32_bf16 v[20:23], v[116:119], v[100:103], v[20:23]
	v_mfma_f32_16x16x32_bf16 v[24:27], v[120:123], v[100:103], v[24:27]
	v_mfma_f32_16x16x32_bf16 v[28:31], v[124:127], v[100:103], v[28:31]
	v_mfma_f32_16x16x32_bf16 v[32:35], v[112:115], v[104:107], v[32:35]
	v_mfma_f32_16x16x32_bf16 v[36:39], v[116:119], v[104:107], v[36:39]
	v_mfma_f32_16x16x32_bf16 v[40:43], v[120:123], v[104:107], v[40:43]
	v_mfma_f32_16x16x32_bf16 v[44:47], v[124:127], v[104:107], v[44:47]
	v_mfma_f32_16x16x32_bf16 v[48:51], v[112:115], v[108:111], v[48:51]
	v_mfma_f32_16x16x32_bf16 v[52:55], v[116:119], v[108:111], v[52:55]
	v_mfma_f32_16x16x32_bf16 v[56:59], v[120:123], v[108:111], v[56:59]
	v_mfma_f32_16x16x32_bf16 v[60:63], v[124:127], v[108:111], v[60:63]
	global_load_dwordx4 v[96:99], v128, s[10:11] offset:256
	global_load_dwordx4 v[100:103], v129, s[10:11] offset:256
	global_load_dwordx4 v[104:107], v130, s[10:11] offset:256
	global_load_dwordx4 v[108:111], v131, s[10:11] offset:256
	global_load_dwordx4 v[112:115], v128, s[12:13] offset:256
	global_load_dwordx4 v[116:119], v129, s[12:13] offset:256
	global_load_dwordx4 v[120:123], v130, s[12:13] offset:256
	global_load_dwordx4 v[124:127], v131, s[12:13] offset:256
	s_waitcnt vmcnt(16)
	v_mfma_f32_16x16x32_bf16 v[0:3], v[154:157], v[138:141], v[0:3]
	v_mfma_f32_16x16x32_bf16 v[4:7], v[158:161], v[138:141], v[4:7]
	v_mfma_f32_16x16x32_bf16 v[8:11], v[162:165], v[138:141], v[8:11]
	v_mfma_f32_16x16x32_bf16 v[12:15], v[166:169], v[138:141], v[12:15]
	v_mfma_f32_16x16x32_bf16 v[16:19], v[154:157], v[142:145], v[16:19]
	v_mfma_f32_16x16x32_bf16 v[20:23], v[158:161], v[142:145], v[20:23]
	v_mfma_f32_16x16x32_bf16 v[24:27], v[162:165], v[142:145], v[24:27]
	v_mfma_f32_16x16x32_bf16 v[28:31], v[166:169], v[142:145], v[28:31]
	v_mfma_f32_16x16x32_bf16 v[32:35], v[154:157], v[146:149], v[32:35]
	v_mfma_f32_16x16x32_bf16 v[36:39], v[158:161], v[146:149], v[36:39]
	v_mfma_f32_16x16x32_bf16 v[40:43], v[162:165], v[146:149], v[40:43]
	v_mfma_f32_16x16x32_bf16 v[44:47], v[166:169], v[146:149], v[44:47]
	v_mfma_f32_16x16x32_bf16 v[48:51], v[154:157], v[150:153], v[48:51]
	v_mfma_f32_16x16x32_bf16 v[52:55], v[158:161], v[150:153], v[52:55]
	v_mfma_f32_16x16x32_bf16 v[56:59], v[162:165], v[150:153], v[56:59]
	v_mfma_f32_16x16x32_bf16 v[60:63], v[166:169], v[150:153], v[60:63]
	global_load_dwordx4 v[138:141], v128, s[10:11] offset:320
	global_load_dwordx4 v[142:145], v129, s[10:11] offset:320
	global_load_dwordx4 v[146:149], v130, s[10:11] offset:320
	global_load_dwordx4 v[150:153], v131, s[10:11] offset:320
	global_load_dwordx4 v[154:157], v128, s[12:13] offset:320
	global_load_dwordx4 v[158:161], v129, s[12:13] offset:320
	global_load_dwordx4 v[162:165], v130, s[12:13] offset:320
	global_load_dwordx4 v[166:169], v131, s[12:13] offset:320
	s_waitcnt vmcnt(16)
	v_mfma_f32_16x16x32_bf16 v[0:3], v[80:83], v[64:67], v[0:3]
	v_mfma_f32_16x16x32_bf16 v[4:7], v[84:87], v[64:67], v[4:7]
	v_mfma_f32_16x16x32_bf16 v[8:11], v[88:91], v[64:67], v[8:11]
	v_mfma_f32_16x16x32_bf16 v[12:15], v[92:95], v[64:67], v[12:15]
	v_mfma_f32_16x16x32_bf16 v[16:19], v[80:83], v[68:71], v[16:19]
	v_mfma_f32_16x16x32_bf16 v[20:23], v[84:87], v[68:71], v[20:23]
	v_mfma_f32_16x16x32_bf16 v[24:27], v[88:91], v[68:71], v[24:27]
	v_mfma_f32_16x16x32_bf16 v[28:31], v[92:95], v[68:71], v[28:31]
	v_mfma_f32_16x16x32_bf16 v[32:35], v[80:83], v[72:75], v[32:35]
	v_mfma_f32_16x16x32_bf16 v[36:39], v[84:87], v[72:75], v[36:39]
	v_mfma_f32_16x16x32_bf16 v[40:43], v[88:91], v[72:75], v[40:43]
	v_mfma_f32_16x16x32_bf16 v[44:47], v[92:95], v[72:75], v[44:47]
	v_mfma_f32_16x16x32_bf16 v[48:51], v[80:83], v[76:79], v[48:51]
	v_mfma_f32_16x16x32_bf16 v[52:55], v[84:87], v[76:79], v[52:55]
	v_mfma_f32_16x16x32_bf16 v[56:59], v[88:91], v[76:79], v[56:59]
	v_mfma_f32_16x16x32_bf16 v[60:63], v[92:95], v[76:79], v[60:63]
	global_load_dwordx4 v[64:67], v128, s[10:11] offset:384
	global_load_dwordx4 v[68:71], v129, s[10:11] offset:384
	global_load_dwordx4 v[72:75], v130, s[10:11] offset:384
	global_load_dwordx4 v[76:79], v131, s[10:11] offset:384
	global_load_dwordx4 v[80:83], v128, s[12:13] offset:384
	global_load_dwordx4 v[84:87], v129, s[12:13] offset:384
	global_load_dwordx4 v[88:91], v130, s[12:13] offset:384
	global_load_dwordx4 v[92:95], v131, s[12:13] offset:384
	s_waitcnt vmcnt(16)
	v_mfma_f32_16x16x32_bf16 v[0:3], v[112:115], v[96:99], v[0:3]
	v_mfma_f32_16x16x32_bf16 v[4:7], v[116:119], v[96:99], v[4:7]
	v_mfma_f32_16x16x32_bf16 v[8:11], v[120:123], v[96:99], v[8:11]
	v_mfma_f32_16x16x32_bf16 v[12:15], v[124:127], v[96:99], v[12:15]
	v_mfma_f32_16x16x32_bf16 v[16:19], v[112:115], v[100:103], v[16:19]
	v_mfma_f32_16x16x32_bf16 v[20:23], v[116:119], v[100:103], v[20:23]
	v_mfma_f32_16x16x32_bf16 v[24:27], v[120:123], v[100:103], v[24:27]
	v_mfma_f32_16x16x32_bf16 v[28:31], v[124:127], v[100:103], v[28:31]
	v_mfma_f32_16x16x32_bf16 v[32:35], v[112:115], v[104:107], v[32:35]
	v_mfma_f32_16x16x32_bf16 v[36:39], v[116:119], v[104:107], v[36:39]
	v_mfma_f32_16x16x32_bf16 v[40:43], v[120:123], v[104:107], v[40:43]
	v_mfma_f32_16x16x32_bf16 v[44:47], v[124:127], v[104:107], v[44:47]
	v_mfma_f32_16x16x32_bf16 v[48:51], v[112:115], v[108:111], v[48:51]
	v_mfma_f32_16x16x32_bf16 v[52:55], v[116:119], v[108:111], v[52:55]
	v_mfma_f32_16x16x32_bf16 v[56:59], v[120:123], v[108:111], v[56:59]
	v_mfma_f32_16x16x32_bf16 v[60:63], v[124:127], v[108:111], v[60:63]
	global_load_dwordx4 v[96:99], v128, s[10:11] offset:448
	global_load_dwordx4 v[100:103], v129, s[10:11] offset:448
	global_load_dwordx4 v[104:107], v130, s[10:11] offset:448
	global_load_dwordx4 v[108:111], v131, s[10:11] offset:448
	global_load_dwordx4 v[112:115], v128, s[12:13] offset:448
	global_load_dwordx4 v[116:119], v129, s[12:13] offset:448
	global_load_dwordx4 v[120:123], v130, s[12:13] offset:448
	global_load_dwordx4 v[124:127], v131, s[12:13] offset:448
	s_waitcnt vmcnt(16)
	v_mfma_f32_16x16x32_bf16 v[0:3], v[154:157], v[138:141], v[0:3]
	v_mfma_f32_16x16x32_bf16 v[4:7], v[158:161], v[138:141], v[4:7]
	v_mfma_f32_16x16x32_bf16 v[8:11], v[162:165], v[138:141], v[8:11]
	v_mfma_f32_16x16x32_bf16 v[12:15], v[166:169], v[138:141], v[12:15]
	v_mfma_f32_16x16x32_bf16 v[16:19], v[154:157], v[142:145], v[16:19]
	v_mfma_f32_16x16x32_bf16 v[20:23], v[158:161], v[142:145], v[20:23]
	v_mfma_f32_16x16x32_bf16 v[24:27], v[162:165], v[142:145], v[24:27]
	v_mfma_f32_16x16x32_bf16 v[28:31], v[166:169], v[142:145], v[28:31]
	v_mfma_f32_16x16x32_bf16 v[32:35], v[154:157], v[146:149], v[32:35]
	v_mfma_f32_16x16x32_bf16 v[36:39], v[158:161], v[146:149], v[36:39]
	v_mfma_f32_16x16x32_bf16 v[40:43], v[162:165], v[146:149], v[40:43]
	v_mfma_f32_16x16x32_bf16 v[44:47], v[166:169], v[146:149], v[44:47]
	v_mfma_f32_16x16x32_bf16 v[48:51], v[154:157], v[150:153], v[48:51]
	v_mfma_f32_16x16x32_bf16 v[52:55], v[158:161], v[150:153], v[52:55]
	v_mfma_f32_16x16x32_bf16 v[56:59], v[162:165], v[150:153], v[56:59]
	v_mfma_f32_16x16x32_bf16 v[60:63], v[166:169], v[150:153], v[60:63]
	global_load_dwordx4 v[138:141], v128, s[10:11] offset:512
	global_load_dwordx4 v[142:145], v129, s[10:11] offset:512
	global_load_dwordx4 v[146:149], v130, s[10:11] offset:512
	global_load_dwordx4 v[150:153], v131, s[10:11] offset:512
	global_load_dwordx4 v[154:157], v128, s[12:13] offset:512
	global_load_dwordx4 v[158:161], v129, s[12:13] offset:512
	global_load_dwordx4 v[162:165], v130, s[12:13] offset:512
	global_load_dwordx4 v[166:169], v131, s[12:13] offset:512
	s_waitcnt vmcnt(16)
	v_mfma_f32_16x16x32_bf16 v[0:3], v[80:83], v[64:67], v[0:3]
	v_mfma_f32_16x16x32_bf16 v[4:7], v[84:87], v[64:67], v[4:7]
	v_mfma_f32_16x16x32_bf16 v[8:11], v[88:91], v[64:67], v[8:11]
	v_mfma_f32_16x16x32_bf16 v[12:15], v[92:95], v[64:67], v[12:15]
	v_mfma_f32_16x16x32_bf16 v[16:19], v[80:83], v[68:71], v[16:19]
	v_mfma_f32_16x16x32_bf16 v[20:23], v[84:87], v[68:71], v[20:23]
	v_mfma_f32_16x16x32_bf16 v[24:27], v[88:91], v[68:71], v[24:27]
	v_mfma_f32_16x16x32_bf16 v[28:31], v[92:95], v[68:71], v[28:31]
	v_mfma_f32_16x16x32_bf16 v[32:35], v[80:83], v[72:75], v[32:35]
	v_mfma_f32_16x16x32_bf16 v[36:39], v[84:87], v[72:75], v[36:39]
	v_mfma_f32_16x16x32_bf16 v[40:43], v[88:91], v[72:75], v[40:43]
	v_mfma_f32_16x16x32_bf16 v[44:47], v[92:95], v[72:75], v[44:47]
	v_mfma_f32_16x16x32_bf16 v[48:51], v[80:83], v[76:79], v[48:51]
	v_mfma_f32_16x16x32_bf16 v[52:55], v[84:87], v[76:79], v[52:55]
	v_mfma_f32_16x16x32_bf16 v[56:59], v[88:91], v[76:79], v[56:59]
	v_mfma_f32_16x16x32_bf16 v[60:63], v[92:95], v[76:79], v[60:63]
	global_load_dwordx4 v[64:67], v128, s[10:11] offset:576
	global_load_dwordx4 v[68:71], v129, s[10:11] offset:576
	global_load_dwordx4 v[72:75], v130, s[10:11] offset:576
	global_load_dwordx4 v[76:79], v131, s[10:11] offset:576
	global_load_dwordx4 v[80:83], v128, s[12:13] offset:576
	global_load_dwordx4 v[84:87], v129, s[12:13] offset:576
	global_load_dwordx4 v[88:91], v130, s[12:13] offset:576
	global_load_dwordx4 v[92:95], v131, s[12:13] offset:576
	s_waitcnt vmcnt(16)
	v_mfma_f32_16x16x32_bf16 v[0:3], v[112:115], v[96:99], v[0:3]
	v_mfma_f32_16x16x32_bf16 v[4:7], v[116:119], v[96:99], v[4:7]
	v_mfma_f32_16x16x32_bf16 v[8:11], v[120:123], v[96:99], v[8:11]
	v_mfma_f32_16x16x32_bf16 v[12:15], v[124:127], v[96:99], v[12:15]
	v_mfma_f32_16x16x32_bf16 v[16:19], v[112:115], v[100:103], v[16:19]
	v_mfma_f32_16x16x32_bf16 v[20:23], v[116:119], v[100:103], v[20:23]
	v_mfma_f32_16x16x32_bf16 v[24:27], v[120:123], v[100:103], v[24:27]
	v_mfma_f32_16x16x32_bf16 v[28:31], v[124:127], v[100:103], v[28:31]
	v_mfma_f32_16x16x32_bf16 v[32:35], v[112:115], v[104:107], v[32:35]
	v_mfma_f32_16x16x32_bf16 v[36:39], v[116:119], v[104:107], v[36:39]
	v_mfma_f32_16x16x32_bf16 v[40:43], v[120:123], v[104:107], v[40:43]
	v_mfma_f32_16x16x32_bf16 v[44:47], v[124:127], v[104:107], v[44:47]
	v_mfma_f32_16x16x32_bf16 v[48:51], v[112:115], v[108:111], v[48:51]
	v_mfma_f32_16x16x32_bf16 v[52:55], v[116:119], v[108:111], v[52:55]
	v_mfma_f32_16x16x32_bf16 v[56:59], v[120:123], v[108:111], v[56:59]
	v_mfma_f32_16x16x32_bf16 v[60:63], v[124:127], v[108:111], v[60:63]
	global_load_dwordx4 v[96:99], v128, s[10:11] offset:640
	global_load_dwordx4 v[100:103], v129, s[10:11] offset:640
	global_load_dwordx4 v[104:107], v130, s[10:11] offset:640
	global_load_dwordx4 v[108:111], v131, s[10:11] offset:640
	global_load_dwordx4 v[112:115], v128, s[12:13] offset:640
	global_load_dwordx4 v[116:119], v129, s[12:13] offset:640
	global_load_dwordx4 v[120:123], v130, s[12:13] offset:640
	global_load_dwordx4 v[124:127], v131, s[12:13] offset:640
	s_waitcnt vmcnt(16)
	v_mfma_f32_16x16x32_bf16 v[0:3], v[154:157], v[138:141], v[0:3]
	v_mfma_f32_16x16x32_bf16 v[4:7], v[158:161], v[138:141], v[4:7]
	v_mfma_f32_16x16x32_bf16 v[8:11], v[162:165], v[138:141], v[8:11]
	v_mfma_f32_16x16x32_bf16 v[12:15], v[166:169], v[138:141], v[12:15]
	v_mfma_f32_16x16x32_bf16 v[16:19], v[154:157], v[142:145], v[16:19]
	v_mfma_f32_16x16x32_bf16 v[20:23], v[158:161], v[142:145], v[20:23]
	v_mfma_f32_16x16x32_bf16 v[24:27], v[162:165], v[142:145], v[24:27]
	v_mfma_f32_16x16x32_bf16 v[28:31], v[166:169], v[142:145], v[28:31]
	v_mfma_f32_16x16x32_bf16 v[32:35], v[154:157], v[146:149], v[32:35]
	v_mfma_f32_16x16x32_bf16 v[36:39], v[158:161], v[146:149], v[36:39]
	v_mfma_f32_16x16x32_bf16 v[40:43], v[162:165], v[146:149], v[40:43]
	v_mfma_f32_16x16x32_bf16 v[44:47], v[166:169], v[146:149], v[44:47]
	v_mfma_f32_16x16x32_bf16 v[48:51], v[154:157], v[150:153], v[48:51]
	v_mfma_f32_16x16x32_bf16 v[52:55], v[158:161], v[150:153], v[52:55]
	v_mfma_f32_16x16x32_bf16 v[56:59], v[162:165], v[150:153], v[56:59]
	v_mfma_f32_16x16x32_bf16 v[60:63], v[166:169], v[150:153], v[60:63]
	global_load_dwordx4 v[138:141], v128, s[10:11] offset:704
	global_load_dwordx4 v[142:145], v129, s[10:11] offset:704
	global_load_dwordx4 v[146:149], v130, s[10:11] offset:704
	global_load_dwordx4 v[150:153], v131, s[10:11] offset:704
	global_load_dwordx4 v[154:157], v128, s[12:13] offset:704
	global_load_dwordx4 v[158:161], v129, s[12:13] offset:704
	global_load_dwordx4 v[162:165], v130, s[12:13] offset:704
	global_load_dwordx4 v[166:169], v131, s[12:13] offset:704
	s_waitcnt vmcnt(16)
	v_mfma_f32_16x16x32_bf16 v[0:3], v[80:83], v[64:67], v[0:3]
	v_mfma_f32_16x16x32_bf16 v[4:7], v[84:87], v[64:67], v[4:7]
	v_mfma_f32_16x16x32_bf16 v[8:11], v[88:91], v[64:67], v[8:11]
	v_mfma_f32_16x16x32_bf16 v[12:15], v[92:95], v[64:67], v[12:15]
	v_mfma_f32_16x16x32_bf16 v[16:19], v[80:83], v[68:71], v[16:19]
	v_mfma_f32_16x16x32_bf16 v[20:23], v[84:87], v[68:71], v[20:23]
	v_mfma_f32_16x16x32_bf16 v[24:27], v[88:91], v[68:71], v[24:27]
	v_mfma_f32_16x16x32_bf16 v[28:31], v[92:95], v[68:71], v[28:31]
	v_mfma_f32_16x16x32_bf16 v[32:35], v[80:83], v[72:75], v[32:35]
	v_mfma_f32_16x16x32_bf16 v[36:39], v[84:87], v[72:75], v[36:39]
	v_mfma_f32_16x16x32_bf16 v[40:43], v[88:91], v[72:75], v[40:43]
	v_mfma_f32_16x16x32_bf16 v[44:47], v[92:95], v[72:75], v[44:47]
	v_mfma_f32_16x16x32_bf16 v[48:51], v[80:83], v[76:79], v[48:51]
	v_mfma_f32_16x16x32_bf16 v[52:55], v[84:87], v[76:79], v[52:55]
	v_mfma_f32_16x16x32_bf16 v[56:59], v[88:91], v[76:79], v[56:59]
	v_mfma_f32_16x16x32_bf16 v[60:63], v[92:95], v[76:79], v[60:63]
	global_load_dwordx4 v[64:67], v128, s[10:11] offset:768
	global_load_dwordx4 v[68:71], v129, s[10:11] offset:768
	global_load_dwordx4 v[72:75], v130, s[10:11] offset:768
	global_load_dwordx4 v[76:79], v131, s[10:11] offset:768
	global_load_dwordx4 v[80:83], v128, s[12:13] offset:768
	global_load_dwordx4 v[84:87], v129, s[12:13] offset:768
	global_load_dwordx4 v[88:91], v130, s[12:13] offset:768
	global_load_dwordx4 v[92:95], v131, s[12:13] offset:768
	s_waitcnt vmcnt(16)
	v_mfma_f32_16x16x32_bf16 v[0:3], v[112:115], v[96:99], v[0:3]
	v_mfma_f32_16x16x32_bf16 v[4:7], v[116:119], v[96:99], v[4:7]
	v_mfma_f32_16x16x32_bf16 v[8:11], v[120:123], v[96:99], v[8:11]
	v_mfma_f32_16x16x32_bf16 v[12:15], v[124:127], v[96:99], v[12:15]
	v_mfma_f32_16x16x32_bf16 v[16:19], v[112:115], v[100:103], v[16:19]
	v_mfma_f32_16x16x32_bf16 v[20:23], v[116:119], v[100:103], v[20:23]
	v_mfma_f32_16x16x32_bf16 v[24:27], v[120:123], v[100:103], v[24:27]
	v_mfma_f32_16x16x32_bf16 v[28:31], v[124:127], v[100:103], v[28:31]
	v_mfma_f32_16x16x32_bf16 v[32:35], v[112:115], v[104:107], v[32:35]
	v_mfma_f32_16x16x32_bf16 v[36:39], v[116:119], v[104:107], v[36:39]
	v_mfma_f32_16x16x32_bf16 v[40:43], v[120:123], v[104:107], v[40:43]
	v_mfma_f32_16x16x32_bf16 v[44:47], v[124:127], v[104:107], v[44:47]
	v_mfma_f32_16x16x32_bf16 v[48:51], v[112:115], v[108:111], v[48:51]
	v_mfma_f32_16x16x32_bf16 v[52:55], v[116:119], v[108:111], v[52:55]
	v_mfma_f32_16x16x32_bf16 v[56:59], v[120:123], v[108:111], v[56:59]
	v_mfma_f32_16x16x32_bf16 v[60:63], v[124:127], v[108:111], v[60:63]
	global_load_dwordx4 v[96:99], v128, s[10:11] offset:832
	global_load_dwordx4 v[100:103], v129, s[10:11] offset:832
	global_load_dwordx4 v[104:107], v130, s[10:11] offset:832
	global_load_dwordx4 v[108:111], v131, s[10:11] offset:832
	global_load_dwordx4 v[112:115], v128, s[12:13] offset:832
	global_load_dwordx4 v[116:119], v129, s[12:13] offset:832
	global_load_dwordx4 v[120:123], v130, s[12:13] offset:832
	global_load_dwordx4 v[124:127], v131, s[12:13] offset:832
	s_waitcnt vmcnt(16)
	v_mfma_f32_16x16x32_bf16 v[0:3], v[154:157], v[138:141], v[0:3]
	v_mfma_f32_16x16x32_bf16 v[4:7], v[158:161], v[138:141], v[4:7]
	v_mfma_f32_16x16x32_bf16 v[8:11], v[162:165], v[138:141], v[8:11]
	v_mfma_f32_16x16x32_bf16 v[12:15], v[166:169], v[138:141], v[12:15]
	v_mfma_f32_16x16x32_bf16 v[16:19], v[154:157], v[142:145], v[16:19]
	v_mfma_f32_16x16x32_bf16 v[20:23], v[158:161], v[142:145], v[20:23]
	v_mfma_f32_16x16x32_bf16 v[24:27], v[162:165], v[142:145], v[24:27]
	v_mfma_f32_16x16x32_bf16 v[28:31], v[166:169], v[142:145], v[28:31]
	v_mfma_f32_16x16x32_bf16 v[32:35], v[154:157], v[146:149], v[32:35]
	v_mfma_f32_16x16x32_bf16 v[36:39], v[158:161], v[146:149], v[36:39]
	v_mfma_f32_16x16x32_bf16 v[40:43], v[162:165], v[146:149], v[40:43]
	v_mfma_f32_16x16x32_bf16 v[44:47], v[166:169], v[146:149], v[44:47]
	v_mfma_f32_16x16x32_bf16 v[48:51], v[154:157], v[150:153], v[48:51]
	v_mfma_f32_16x16x32_bf16 v[52:55], v[158:161], v[150:153], v[52:55]
	v_mfma_f32_16x16x32_bf16 v[56:59], v[162:165], v[150:153], v[56:59]
	v_mfma_f32_16x16x32_bf16 v[60:63], v[166:169], v[150:153], v[60:63]
	global_load_dwordx4 v[138:141], v128, s[10:11] offset:896
	global_load_dwordx4 v[142:145], v129, s[10:11] offset:896
	global_load_dwordx4 v[146:149], v130, s[10:11] offset:896
	global_load_dwordx4 v[150:153], v131, s[10:11] offset:896
	global_load_dwordx4 v[154:157], v128, s[12:13] offset:896
	global_load_dwordx4 v[158:161], v129, s[12:13] offset:896
	global_load_dwordx4 v[162:165], v130, s[12:13] offset:896
	global_load_dwordx4 v[166:169], v131, s[12:13] offset:896
	s_waitcnt vmcnt(16)
	v_mfma_f32_16x16x32_bf16 v[0:3], v[80:83], v[64:67], v[0:3]
	v_mfma_f32_16x16x32_bf16 v[4:7], v[84:87], v[64:67], v[4:7]
	v_mfma_f32_16x16x32_bf16 v[8:11], v[88:91], v[64:67], v[8:11]
	v_mfma_f32_16x16x32_bf16 v[12:15], v[92:95], v[64:67], v[12:15]
	v_mfma_f32_16x16x32_bf16 v[16:19], v[80:83], v[68:71], v[16:19]
	v_mfma_f32_16x16x32_bf16 v[20:23], v[84:87], v[68:71], v[20:23]
	v_mfma_f32_16x16x32_bf16 v[24:27], v[88:91], v[68:71], v[24:27]
	v_mfma_f32_16x16x32_bf16 v[28:31], v[92:95], v[68:71], v[28:31]
	v_mfma_f32_16x16x32_bf16 v[32:35], v[80:83], v[72:75], v[32:35]
	v_mfma_f32_16x16x32_bf16 v[36:39], v[84:87], v[72:75], v[36:39]
	v_mfma_f32_16x16x32_bf16 v[40:43], v[88:91], v[72:75], v[40:43]
	v_mfma_f32_16x16x32_bf16 v[44:47], v[92:95], v[72:75], v[44:47]
	v_mfma_f32_16x16x32_bf16 v[48:51], v[80:83], v[76:79], v[48:51]
	v_mfma_f32_16x16x32_bf16 v[52:55], v[84:87], v[76:79], v[52:55]
	v_mfma_f32_16x16x32_bf16 v[56:59], v[88:91], v[76:79], v[56:59]
	v_mfma_f32_16x16x32_bf16 v[60:63], v[92:95], v[76:79], v[60:63]
	global_load_dwordx4 v[64:67], v128, s[10:11] offset:960
	global_load_dwordx4 v[68:71], v129, s[10:11] offset:960
	global_load_dwordx4 v[72:75], v130, s[10:11] offset:960
	global_load_dwordx4 v[76:79], v131, s[10:11] offset:960
	global_load_dwordx4 v[80:83], v128, s[12:13] offset:960
	global_load_dwordx4 v[84:87], v129, s[12:13] offset:960
	global_load_dwordx4 v[88:91], v130, s[12:13] offset:960
	global_load_dwordx4 v[92:95], v131, s[12:13] offset:960
	s_waitcnt vmcnt(16)
	v_mfma_f32_16x16x32_bf16 v[0:3], v[112:115], v[96:99], v[0:3]
	v_mfma_f32_16x16x32_bf16 v[4:7], v[116:119], v[96:99], v[4:7]
	v_mfma_f32_16x16x32_bf16 v[8:11], v[120:123], v[96:99], v[8:11]
	v_mfma_f32_16x16x32_bf16 v[12:15], v[124:127], v[96:99], v[12:15]
	v_mfma_f32_16x16x32_bf16 v[16:19], v[112:115], v[100:103], v[16:19]
	v_mfma_f32_16x16x32_bf16 v[20:23], v[116:119], v[100:103], v[20:23]
	v_mfma_f32_16x16x32_bf16 v[24:27], v[120:123], v[100:103], v[24:27]
	v_mfma_f32_16x16x32_bf16 v[28:31], v[124:127], v[100:103], v[28:31]
	v_mfma_f32_16x16x32_bf16 v[32:35], v[112:115], v[104:107], v[32:35]
	v_mfma_f32_16x16x32_bf16 v[36:39], v[116:119], v[104:107], v[36:39]
	v_mfma_f32_16x16x32_bf16 v[40:43], v[120:123], v[104:107], v[40:43]
	v_mfma_f32_16x16x32_bf16 v[44:47], v[124:127], v[104:107], v[44:47]
	v_mfma_f32_16x16x32_bf16 v[48:51], v[112:115], v[108:111], v[48:51]
	v_mfma_f32_16x16x32_bf16 v[52:55], v[116:119], v[108:111], v[52:55]
	v_mfma_f32_16x16x32_bf16 v[56:59], v[120:123], v[108:111], v[56:59]
	v_mfma_f32_16x16x32_bf16 v[60:63], v[124:127], v[108:111], v[60:63]
	s_waitcnt vmcnt(8)
	v_mfma_f32_16x16x32_bf16 v[0:3], v[154:157], v[138:141], v[0:3]
	v_mfma_f32_16x16x32_bf16 v[4:7], v[158:161], v[138:141], v[4:7]
	v_mfma_f32_16x16x32_bf16 v[8:11], v[162:165], v[138:141], v[8:11]
	v_mfma_f32_16x16x32_bf16 v[12:15], v[166:169], v[138:141], v[12:15]
	v_mfma_f32_16x16x32_bf16 v[16:19], v[154:157], v[142:145], v[16:19]
	v_mfma_f32_16x16x32_bf16 v[20:23], v[158:161], v[142:145], v[20:23]
	v_mfma_f32_16x16x32_bf16 v[24:27], v[162:165], v[142:145], v[24:27]
	v_mfma_f32_16x16x32_bf16 v[28:31], v[166:169], v[142:145], v[28:31]
	v_mfma_f32_16x16x32_bf16 v[32:35], v[154:157], v[146:149], v[32:35]
	v_mfma_f32_16x16x32_bf16 v[36:39], v[158:161], v[146:149], v[36:39]
	v_mfma_f32_16x16x32_bf16 v[40:43], v[162:165], v[146:149], v[40:43]
	v_mfma_f32_16x16x32_bf16 v[44:47], v[166:169], v[146:149], v[44:47]
	v_mfma_f32_16x16x32_bf16 v[48:51], v[154:157], v[150:153], v[48:51]
	v_mfma_f32_16x16x32_bf16 v[52:55], v[158:161], v[150:153], v[52:55]
	v_mfma_f32_16x16x32_bf16 v[56:59], v[162:165], v[150:153], v[56:59]
	v_mfma_f32_16x16x32_bf16 v[60:63], v[166:169], v[150:153], v[60:63]
	s_waitcnt vmcnt(0)
	v_mfma_f32_16x16x32_bf16 v[0:3], v[80:83], v[64:67], v[0:3]
	v_mfma_f32_16x16x32_bf16 v[4:7], v[84:87], v[64:67], v[4:7]
	v_mfma_f32_16x16x32_bf16 v[8:11], v[88:91], v[64:67], v[8:11]
	v_mfma_f32_16x16x32_bf16 v[12:15], v[92:95], v[64:67], v[12:15]
	v_mfma_f32_16x16x32_bf16 v[16:19], v[80:83], v[68:71], v[16:19]
	v_mfma_f32_16x16x32_bf16 v[20:23], v[84:87], v[68:71], v[20:23]
	v_mfma_f32_16x16x32_bf16 v[24:27], v[88:91], v[68:71], v[24:27]
	v_mfma_f32_16x16x32_bf16 v[28:31], v[92:95], v[68:71], v[28:31]
	v_mfma_f32_16x16x32_bf16 v[32:35], v[80:83], v[72:75], v[32:35]
	v_mfma_f32_16x16x32_bf16 v[36:39], v[84:87], v[72:75], v[36:39]
	v_mfma_f32_16x16x32_bf16 v[40:43], v[88:91], v[72:75], v[40:43]
	v_mfma_f32_16x16x32_bf16 v[44:47], v[92:95], v[72:75], v[44:47]
	v_mfma_f32_16x16x32_bf16 v[48:51], v[80:83], v[76:79], v[48:51]
	v_mfma_f32_16x16x32_bf16 v[52:55], v[84:87], v[76:79], v[52:55]
	v_mfma_f32_16x16x32_bf16 v[56:59], v[88:91], v[76:79], v[56:59]
	v_mfma_f32_16x16x32_bf16 v[60:63], v[92:95], v[76:79], v[60:63]
	v_lshlrev_b32_e32 v170, 14, v132
	v_lshl_add_u32 v170, v133, 4, v170
	s_nop 7
	ds_write_b128 v170, v[0:3] offset:0
	ds_write_b128 v170, v[4:7] offset:1024
	ds_write_b128 v170, v[8:11] offset:2048
	ds_write_b128 v170, v[12:15] offset:3072
	ds_write_b128 v170, v[16:19] offset:4096
	ds_write_b128 v170, v[20:23] offset:5120
	ds_write_b128 v170, v[24:27] offset:6144
	ds_write_b128 v170, v[28:31] offset:7168
	ds_write_b128 v170, v[32:35] offset:8192
	ds_write_b128 v170, v[36:39] offset:9216
	ds_write_b128 v170, v[40:43] offset:10240
	ds_write_b128 v170, v[44:47] offset:11264
	ds_write_b128 v170, v[48:51] offset:12288
	ds_write_b128 v170, v[52:55] offset:13312
	ds_write_b128 v170, v[56:59] offset:14336
	ds_write_b128 v170, v[60:63] offset:15360
	s_lshr_b32 s25, s24, 1
	s_lshl_b32 s25, s25, 4
	s_lshl_b32 s26, s16, 6
	s_add_i32 s25, s25, s26
	s_and_b32 s26, s24, 1
	s_lshl_b32 s26, s26, 5
	s_lshl_b32 s27, s17, 6
	s_add_i32 s26, s26, s27
	v_add_u32_e32 v171, s25, v134
	v_lshl_add_u32 v172, v135, 2, s26
	v_lshlrev_b32_e32 v173, 10, v171
	v_add_lshl_u32 v173, v173, v172, 2
	s_add_u32 s18, s4, 0x3800000
	s_addc_u32 s19, s5, 0
	s_add_u32 s20, s4, 0x3800000
	s_addc_u32 s21, s5, 0
	v_lshlrev_b32_e32 v174, 2, v172
	s_add_u32 s22, s4, 0x22f320
	s_addc_u32 s23, s5, 0
	s_add_u32 s28, s4, 0x1d000
	s_addc_u32 s29, s5, 0
	s_nop 2
	global_load_dwordx4 v[176:179], v173, s[18:19] offset:0
	global_load_dwordx4 v[64:67], v174, s[22:23] offset:0
	global_load_dwordx4 v[72:75], v174, s[28:29] offset:0
	global_load_dwordx4 v[180:183], v173, s[18:19] offset:64
	global_load_dwordx4 v[68:71], v174, s[22:23] offset:64
	global_load_dwordx4 v[76:79], v174, s[28:29] offset:64
	s_waitcnt lgkmcnt(0)
	s_barrier
	v_lshlrev_b32_e32 v175, 11, v132
	v_lshl_add_u32 v175, v133, 4, v175
	v_add_u32_e32 v100, 0x4000, v175
	v_add_u32_e32 v101, 0x8000, v175
	v_add_u32_e32 v102, 0xc000, v175
	v_add_u32_e32 v103, 0x10000, v175
	v_add_u32_e32 v166, 0x14000, v175
	v_add_u32_e32 v167, 0x18000, v175
	v_add_u32_e32 v168, 0x1c000, v175
	ds_read_b128 v[80:83], v175 offset:0
	ds_read_b128 v[0:3], v100 offset:0
	ds_read_b128 v[4:7], v101 offset:0
	ds_read_b128 v[8:11], v102 offset:0
	ds_read_b128 v[12:15], v103 offset:0
	ds_read_b128 v[16:19], v166 offset:0
	ds_read_b128 v[20:23], v167 offset:0
	ds_read_b128 v[24:27], v168 offset:0
	s_waitcnt lgkmcnt(0)
	ds_read_b128 v[96:99], v175 offset:1024
	ds_read_b128 v[138:141], v100 offset:1024
	ds_read_b128 v[142:145], v101 offset:1024
	ds_read_b128 v[146:149], v102 offset:1024
	ds_read_b128 v[150:153], v103 offset:1024
	ds_read_b128 v[154:157], v166 offset:1024
	ds_read_b128 v[158:161], v167 offset:1024
	ds_read_b128 v[162:165], v168 offset:1024
	s_waitcnt lgkmcnt(0)
	v_add_f32_e32 v80, v80, v0
	v_add_f32_e32 v81, v81, v1
	v_add_f32_e32 v82, v82, v2
	v_add_f32_e32 v83, v83, v3
	v_add_f32_e32 v80, v80, v4
	v_add_f32_e32 v81, v81, v5
	v_add_f32_e32 v82, v82, v6
	v_add_f32_e32 v83, v83, v7
	v_add_f32_e32 v80, v80, v8
	v_add_f32_e32 v81, v81, v9
	v_add_f32_e32 v82, v82, v10
	v_add_f32_e32 v83, v83, v11
	v_add_f32_e32 v80, v80, v12
	v_add_f32_e32 v81, v81, v13
	v_add_f32_e32 v82, v82, v14
	v_add_f32_e32 v83, v83, v15
	v_add_f32_e32 v80, v80, v16
	v_add_f32_e32 v81, v81, v17
	v_add_f32_e32 v82, v82, v18
	v_add_f32_e32 v83, v83, v19
	v_add_f32_e32 v80, v80, v20
	v_add_f32_e32 v81, v81, v21
	v_add_f32_e32 v82, v82, v22
	v_add_f32_e32 v83, v83, v23
	v_add_f32_e32 v80, v80, v24
	v_add_f32_e32 v81, v81, v25
	v_add_f32_e32 v82, v82, v26
	v_add_f32_e32 v83, v83, v27
	v_add_f32_e32 v96, v96, v138
	v_add_f32_e32 v97, v97, v139
	v_add_f32_e32 v98, v98, v140
	v_add_f32_e32 v99, v99, v141
	v_add_f32_e32 v96, v96, v142
	v_add_f32_e32 v97, v97, v143
	v_add_f32_e32 v98, v98, v144
	v_add_f32_e32 v99, v99, v145
	v_add_f32_e32 v96, v96, v146
	v_add_f32_e32 v97, v97, v147
	v_add_f32_e32 v98, v98, v148
	v_add_f32_e32 v99, v99, v149
	v_add_f32_e32 v96, v96, v150
	v_add_f32_e32 v97, v97, v151
	v_add_f32_e32 v98, v98, v152
	v_add_f32_e32 v99, v99, v153
	v_add_f32_e32 v96, v96, v154
	v_add_f32_e32 v97, v97, v155
	v_add_f32_e32 v98, v98, v156
	v_add_f32_e32 v99, v99, v157
	v_add_f32_e32 v96, v96, v158
	v_add_f32_e32 v97, v97, v159
	v_add_f32_e32 v98, v98, v160
	v_add_f32_e32 v99, v99, v161
	v_add_f32_e32 v96, v96, v162
	v_add_f32_e32 v97, v97, v163
	v_add_f32_e32 v98, v98, v164
	v_add_f32_e32 v99, v99, v165
	s_waitcnt vmcnt(0)
	v_add_f32_e32 v80, v80, v64
	v_add_f32_e32 v81, v81, v65
	v_add_f32_e32 v82, v82, v66
	v_add_f32_e32 v83, v83, v67
	v_fma_f32 v80, v72, v80, v176
	v_fma_f32 v81, v73, v81, v177
	v_fma_f32 v82, v74, v82, v178
	v_fma_f32 v83, v75, v83, v179
	global_store_dwordx4 v173, v[80:83], s[20:21] offset:0
	v_add_f32_e32 v96, v96, v68
	v_add_f32_e32 v97, v97, v69
	v_add_f32_e32 v98, v98, v70
	v_add_f32_e32 v99, v99, v71
	v_fma_f32 v96, v76, v96, v180
	v_fma_f32 v97, v77, v97, v181
	v_fma_f32 v98, v78, v98, v182
	v_fma_f32 v99, v79, v99, v183
	global_store_dwordx4 v173, v[96:99], s[20:21] offset:64
	s_barrier
	s_branch .Lcg_done
.Lcg_done:
	v_readlane_b32 s8, v243, 8
	v_readlane_b32 s9, v243, 9
	v_readlane_b32 s10, v243, 10
	v_readlane_b32 s11, v243, 11
	v_readlane_b32 s12, v243, 12
	v_readlane_b32 s13, v243, 13
	v_readlane_b32 s14, v243, 14
	v_readlane_b32 s15, v243, 15
	v_readlane_b32 s16, v243, 16
	v_readlane_b32 s17, v243, 17
	v_readlane_b32 s18, v243, 18
	v_readlane_b32 s19, v243, 19
	v_readlane_b32 s20, v243, 20
	v_readlane_b32 s21, v243, 21
	v_readlane_b32 s22, v243, 22
	v_readlane_b32 s23, v243, 23
	v_readlane_b32 s24, v243, 24
	v_readlane_b32 s25, v243, 25
	v_readlane_b32 s26, v243, 26
	v_readlane_b32 s27, v243, 27
	v_readlane_b32 s28, v243, 28
	v_readlane_b32 s29, v243, 29
	v_readlane_b32 s30, v243, 30
	v_readlane_b32 s31, v243, 31

.Lss3_body:
	s_mul_i32 s10, s36, 0xf0f1
	s_lshr_b32 s10, s10, 22
	s_mul_i32 s11, s10, 68
	s_sub_i32 s8, s36, s11
	s_and_b32 s7, s10, 15
	s_lshr_b32 s6, s10, 4
	s_lshl_b32 s10, s8, 6
	s_lshl_b32 s11, s6, 8
	s_add_i32 s9, s10, s11
	s_lshl_b32 s11, s6, 12
	s_add_i32 s11, s11, s10
	s_add_i32 s11, s11, 0x300
	s_cmp_lt_u32 s8, 4
	s_cselect_b32 s9, s9, s11
	v_mov_b32_e32 v0, 0
	v_mov_b32_e32 v1, 0
	v_mov_b32_e32 v2, 0
	v_mov_b32_e32 v3, 0
	v_mov_b32_e32 v4, 0
	v_mov_b32_e32 v5, 0
	v_mov_b32_e32 v6, 0
	v_mov_b32_e32 v7, 0
	v_mov_b32_e32 v8, 0
	v_mov_b32_e32 v9, 0
	v_mov_b32_e32 v10, 0
	v_mov_b32_e32 v11, 0
	v_mov_b32_e32 v12, 0
	v_mov_b32_e32 v13, 0
	v_mov_b32_e32 v14, 0
	v_mov_b32_e32 v15, 0
	v_and_b32_e32 v207, 15, v205
	v_mul_u32_u24_e32 v207, 0xe00, v207
	v_and_b32_e32 v208, 16, v205
	v_add_u32_e32 v207, v207, v208
	s_mul_i32 s18, s9, 0xe00
	s_lshl_b32 s19, s7, 5
	s_add_i32 s18, s18, s19
	s_add_u32 s18, s18, 0x5e00c00
	s_add_u32 s18, s4, s18
	s_addc_u32 s19, s5, 0
	s_mov_b32 exec_hi, 0
	global_load_dwordx4 v[0:3], v207, s[18:19]
	s_add_u32 s18, s18, 0xe000
	s_addc_u32 s19, s19, 0
	global_load_dwordx4 v[4:7], v207, s[18:19]
	s_add_u32 s18, s18, 0xe000
	s_addc_u32 s19, s19, 0
	global_load_dwordx4 v[8:11], v207, s[18:19]
	s_add_u32 s18, s18, 0xe000
	s_addc_u32 s19, s19, 0
	global_load_dwordx4 v[12:15], v207, s[18:19]
	s_mov_b64 exec, -1
	v_mov_b32_e32 v64, 0
	v_mov_b32_e32 v65, 0
	v_mov_b32_e32 v66, 0
	v_mov_b32_e32 v67, 0
	v_mov_b32_e32 v68, 0
	v_mov_b32_e32 v69, 0
	v_mov_b32_e32 v70, 0
	v_mov_b32_e32 v71, 0
	v_mov_b32_e32 v72, 0
	v_mov_b32_e32 v73, 0
	v_mov_b32_e32 v74, 0
	v_mov_b32_e32 v75, 0
	v_mov_b32_e32 v76, 0
	v_mov_b32_e32 v77, 0
	v_mov_b32_e32 v78, 0
	v_mov_b32_e32 v79, 0
	v_lshlrev_b32_e32 v134, 7, v205
	v_and_b32_e32 v135, 15, v205
	v_lshlrev_b32_e32 v136, 8, v135
	v_lshlrev_b32_e32 v135, 6, v135
	v_and_b32_e32 v207, 16, v205
	v_lshl_add_u32 v135, v207, 1, v135
	v_lshrrev_b32_e32 v207, 4, v205
	v_lshl_add_u32 v136, v207, 4, v136
	v_lshlrev_b32_e32 v206, 5, v207
	v_readlane_b32 s10, v247, 28
	s_mov_b32 s11, s8
	s_lshl_b32 s16, s10, 1
	s_add_i32 s16, s16, 0
	s_lshl_b32 s16, s16, 4
	s_add_i32 s16, s16, s7
	s_lshl_b32 s17, s6, 1
	s_add_i32 s17, s17, 0
	s_lshl_b32 s17, s17, 4
	s_add_i32 s17, s17, s7
	s_mul_i32 s17, s17, 68
	s_add_i32 s17, s17, s11
	s_lshl_b32 s17, s17, 6
	s_lshl_b32 s20, s16, 12
	s_add_u32 s20, s20, 0x11fb20
	s_add_u32 s20, s4, s20
	s_addc_u32 s21, s5, 0
	s_add_u32 s22, s20, 0x40000
	s_addc_u32 s23, s21, 0
	s_lshl_b32 s38, s16, 12
	s_add_u32 s38, s38, 0x19fb20
	s_add_u32 s38, s4, s38
	s_addc_u32 s39, s5, 0
	s_add_u32 s40, s38, 0x40000
	s_addc_u32 s41, s39, 0
	s_lshl_b32 s42, s16, 15
	s_add_u32 s42, s42, 0xf900000
	s_add_u32 s42, s4, s42
	s_addc_u32 s43, s5, 0
	s_lshl_b32 s44, s17, 3
	s_add_u32 s44, s44, 0x740000
	s_add_u32 s44, s4, s44
	s_addc_u32 s45, s5, 0
	s_mov_b32 exec_hi, 0
	global_load_dwordx4 v[64:67], v135, s[20:21]
	global_load_dwordx4 v[68:71], v135, s[20:21] offset:16
	global_load_dwordx4 v[72:75], v135, s[22:23]
	global_load_dwordx4 v[76:79], v135, s[22:23] offset:16
	s_mov_b64 exec, -1
	s_add_u32 s20, s20, 0x400
	s_addc_u32 s21, s21, 0
	s_add_u32 s22, s22, 0x400
	s_addc_u32 s23, s23, 0
	global_load_dwordx4 v[138:141], v134, s[42:43] offset:0
	global_load_dwordx4 v[142:145], v134, s[42:43] offset:16
	global_load_dwordx4 v[146:149], v134, s[42:43] offset:32
	global_load_dwordx4 v[150:153], v134, s[42:43] offset:48
	global_load_dwordx4 v[154:157], v134, s[42:43] offset:64
	global_load_dwordx4 v[158:161], v134, s[42:43] offset:80
	global_load_dwordx4 v[162:165], v134, s[42:43] offset:96
	global_load_dwordx4 v[166:169], v134, s[42:43] offset:112
	global_load_dwordx4 v[170:173], v206, s[44:45]
	global_load_dwordx4 v[174:177], v206, s[44:45] offset:16
	s_add_u32 s42, s42, 0x2000
	s_addc_u32 s43, s43, 0
	s_add_u32 s44, s44, 0x80
	s_addc_u32 s45, s45, 0
	s_waitcnt vmcnt(14)
	s_waitcnt vmcnt(10)
	v_cvt_pk_bf16_f32 v64, v64, v65
	v_cvt_pk_bf16_f32 v65, v66, v67
	v_cvt_pk_bf16_f32 v66, v68, v69
	v_cvt_pk_bf16_f32 v67, v70, v71
	v_cvt_pk_bf16_f32 v72, v72, v73
	v_cvt_pk_bf16_f32 v73, v74, v75
	v_cvt_pk_bf16_f32 v74, v76, v77
	v_cvt_pk_bf16_f32 v75, v78, v79
	global_load_dwordx4 v[80:83], v136, s[38:39]
	global_load_dwordx4 v[84:87], v136, s[40:41]
	s_add_u32 s38, s38, 0x40
	s_addc_u32 s39, s39, 0
	s_add_u32 s40, s40, 0x40
	s_addc_u32 s41, s41, 0
	s_nop 0
	v_mfma_f32_16x16x32_bf16 v[32:35], v[64:67], v[0:3], 0
	v_mfma_f32_16x16x32_bf16 v[36:39], v[72:75], v[0:3], 0
	v_mfma_f32_16x16x32_bf16 v[40:43], v[64:67], v[4:7], 0
	v_mfma_f32_16x16x32_bf16 v[44:47], v[72:75], v[4:7], 0
	v_mfma_f32_16x16x32_bf16 v[48:51], v[64:67], v[8:11], 0
	v_mfma_f32_16x16x32_bf16 v[52:55], v[72:75], v[8:11], 0
	v_mfma_f32_16x16x32_bf16 v[56:59], v[64:67], v[12:15], 0
	v_mfma_f32_16x16x32_bf16 v[60:63], v[72:75], v[12:15], 0
	s_mov_b32 exec_hi, 0
	global_load_dwordx4 v[64:67], v135, s[20:21]
	global_load_dwordx4 v[68:71], v135, s[20:21] offset:16
	global_load_dwordx4 v[72:75], v135, s[22:23]
	global_load_dwordx4 v[76:79], v135, s[22:23] offset:16
	s_mov_b64 exec, -1
	s_add_u32 s20, s20, 0x400
	s_addc_u32 s21, s21, 0
	s_add_u32 s22, s22, 0x400
	s_addc_u32 s23, s23, 0
	global_load_dwordx4 v[100:103], v134, s[42:43] offset:0
	global_load_dwordx4 v[104:107], v134, s[42:43] offset:16
	global_load_dwordx4 v[108:111], v134, s[42:43] offset:32
	global_load_dwordx4 v[112:115], v134, s[42:43] offset:48
	global_load_dwordx4 v[116:119], v134, s[42:43] offset:64
	global_load_dwordx4 v[120:123], v134, s[42:43] offset:80
	global_load_dwordx4 v[124:127], v134, s[42:43] offset:96
	global_load_dwordx4 v[128:131], v134, s[42:43] offset:112
	global_load_dwordx4 v[178:181], v206, s[44:45]
	global_load_dwordx4 v[182:185], v206, s[44:45] offset:16
	s_add_u32 s42, s42, 0x2000
	s_addc_u32 s43, s43, 0
	s_add_u32 s44, s44, 0x80
	s_addc_u32 s45, s45, 0
	s_waitcnt vmcnt(16)
	v_mul_f32_e32 v132, v171, v157
	v_mul_f32_e32 v133, v170, v157
	v_fma_f32 v170, v170, v156, -v132
	v_fma_f32 v171, v171, v156, v133
	v_mul_f32_e32 v132, v173, v161
	v_mul_f32_e32 v133, v172, v161
	v_fma_f32 v172, v172, v160, -v132
	v_fma_f32 v173, v173, v160, v133
	v_mul_f32_e32 v132, v175, v165
	v_mul_f32_e32 v133, v174, v165
	v_fma_f32 v174, v174, v164, -v132
	v_fma_f32 v175, v175, v164, v133
	v_mul_f32_e32 v132, v177, v169
	v_mul_f32_e32 v133, v176, v169
	v_fma_f32 v176, v176, v168, -v132
	v_fma_f32 v177, v177, v168, v133
	v_mul_f32_e32 v132, v32, v139
	v_mul_f32_e32 v32, v32, v138
	v_fma_f32 v32, -v36, v139, v32
	v_fma_f32 v36, v36, v138, v132
	v_mul_f32_e32 v133, v33, v143
	v_mul_f32_e32 v33, v33, v142
	v_fma_f32 v33, -v37, v143, v33
	v_fma_f32 v37, v37, v142, v133
	v_mul_f32_e32 v132, v34, v147
	v_mul_f32_e32 v34, v34, v146
	v_fma_f32 v34, -v38, v147, v34
	v_fma_f32 v38, v38, v146, v132
	v_mul_f32_e32 v133, v35, v151
	v_mul_f32_e32 v35, v35, v150
	v_fma_f32 v35, -v39, v151, v35
	v_fma_f32 v39, v39, v150, v133
	v_add_f32_dpp v32, v32, v32 row_shr:1 row_mask:0xf bank_mask:0xf bound_ctrl:1
	v_add_f32_dpp v33, v33, v33 row_shr:1 row_mask:0xf bank_mask:0xf bound_ctrl:1
	v_add_f32_dpp v34, v34, v34 row_shr:1 row_mask:0xf bank_mask:0xf bound_ctrl:1
	v_add_f32_dpp v35, v35, v35 row_shr:1 row_mask:0xf bank_mask:0xf bound_ctrl:1
	v_add_f32_dpp v36, v36, v36 row_shr:1 row_mask:0xf bank_mask:0xf bound_ctrl:1
	v_add_f32_dpp v37, v37, v37 row_shr:1 row_mask:0xf bank_mask:0xf bound_ctrl:1
	v_add_f32_dpp v38, v38, v38 row_shr:1 row_mask:0xf bank_mask:0xf bound_ctrl:1
	v_add_f32_dpp v39, v39, v39 row_shr:1 row_mask:0xf bank_mask:0xf bound_ctrl:1
	v_add_f32_dpp v32, v32, v32 row_shr:2 row_mask:0xf bank_mask:0xf bound_ctrl:1
	v_add_f32_dpp v33, v33, v33 row_shr:2 row_mask:0xf bank_mask:0xf bound_ctrl:1
	v_add_f32_dpp v34, v34, v34 row_shr:2 row_mask:0xf bank_mask:0xf bound_ctrl:1
	v_add_f32_dpp v35, v35, v35 row_shr:2 row_mask:0xf bank_mask:0xf bound_ctrl:1
	v_add_f32_dpp v36, v36, v36 row_shr:2 row_mask:0xf bank_mask:0xf bound_ctrl:1
	v_add_f32_dpp v37, v37, v37 row_shr:2 row_mask:0xf bank_mask:0xf bound_ctrl:1
	v_add_f32_dpp v38, v38, v38 row_shr:2 row_mask:0xf bank_mask:0xf bound_ctrl:1
	v_add_f32_dpp v39, v39, v39 row_shr:2 row_mask:0xf bank_mask:0xf bound_ctrl:1
	v_add_f32_dpp v32, v32, v32 row_shr:4 row_mask:0xf bank_mask:0xf bound_ctrl:1
	v_add_f32_dpp v33, v33, v33 row_shr:4 row_mask:0xf bank_mask:0xf bound_ctrl:1
	v_add_f32_dpp v34, v34, v34 row_shr:4 row_mask:0xf bank_mask:0xf bound_ctrl:1
	v_add_f32_dpp v35, v35, v35 row_shr:4 row_mask:0xf bank_mask:0xf bound_ctrl:1
	v_add_f32_dpp v36, v36, v36 row_shr:4 row_mask:0xf bank_mask:0xf bound_ctrl:1
	v_add_f32_dpp v37, v37, v37 row_shr:4 row_mask:0xf bank_mask:0xf bound_ctrl:1
	v_add_f32_dpp v38, v38, v38 row_shr:4 row_mask:0xf bank_mask:0xf bound_ctrl:1
	v_add_f32_dpp v39, v39, v39 row_shr:4 row_mask:0xf bank_mask:0xf bound_ctrl:1
	v_add_f32_dpp v32, v32, v32 row_shr:8 row_mask:0xf bank_mask:0xf bound_ctrl:1
	v_add_f32_dpp v33, v33, v33 row_shr:8 row_mask:0xf bank_mask:0xf bound_ctrl:1
	v_add_f32_dpp v34, v34, v34 row_shr:8 row_mask:0xf bank_mask:0xf bound_ctrl:1
	v_add_f32_dpp v35, v35, v35 row_shr:8 row_mask:0xf bank_mask:0xf bound_ctrl:1
	v_add_f32_dpp v36, v36, v36 row_shr:8 row_mask:0xf bank_mask:0xf bound_ctrl:1
	v_add_f32_dpp v37, v37, v37 row_shr:8 row_mask:0xf bank_mask:0xf bound_ctrl:1
	v_add_f32_dpp v38, v38, v38 row_shr:8 row_mask:0xf bank_mask:0xf bound_ctrl:1
	v_add_f32_dpp v39, v39, v39 row_shr:8 row_mask:0xf bank_mask:0xf bound_ctrl:1
	v_mov_b32_dpp v88, v32 row_newbcast:15 row_mask:0xf bank_mask:0xf
	v_mov_b32_dpp v89, v33 row_newbcast:15 row_mask:0xf bank_mask:0xf
	v_mov_b32_dpp v90, v34 row_newbcast:15 row_mask:0xf bank_mask:0xf
	v_mov_b32_dpp v91, v35 row_newbcast:15 row_mask:0xf bank_mask:0xf
	v_mov_b32_dpp v92, v36 row_newbcast:15 row_mask:0xf bank_mask:0xf
	v_mov_b32_dpp v93, v37 row_newbcast:15 row_mask:0xf bank_mask:0xf
	v_mov_b32_dpp v94, v38 row_newbcast:15 row_mask:0xf bank_mask:0xf
	v_mov_b32_dpp v95, v39 row_newbcast:15 row_mask:0xf bank_mask:0xf
	v_add_f32_e32 v32, v32, v170
	v_add_f32_e32 v36, v36, v171
	v_add_f32_e32 v33, v33, v172
	v_add_f32_e32 v37, v37, v173
	v_add_f32_e32 v34, v34, v174
	v_add_f32_e32 v38, v38, v175
	v_add_f32_e32 v35, v35, v176
	v_add_f32_e32 v39, v39, v177
	v_mul_f32_e32 v132, v32, v141
	v_mul_f32_e32 v32, v32, v140
	v_fma_f32 v32, -v36, v141, v32
	v_fma_f32 v36, v36, v140, v132
	v_mul_f32_e32 v133, v33, v145
	v_mul_f32_e32 v33, v33, v144
	v_fma_f32 v33, -v37, v145, v33
	v_fma_f32 v37, v37, v144, v133
	v_mul_f32_e32 v132, v34, v149
	v_mul_f32_e32 v34, v34, v148
	v_fma_f32 v34, -v38, v149, v34
	v_fma_f32 v38, v38, v148, v132
	v_mul_f32_e32 v133, v35, v153
	v_mul_f32_e32 v35, v35, v152
	v_fma_f32 v35, -v39, v153, v35
	v_fma_f32 v39, v39, v152, v133
	v_add_f32_e32 v88, v88, v170
	v_add_f32_e32 v92, v92, v171
	v_mul_f32_e32 v132, v92, v155
	v_mul_f32_e32 v171, v88, v155
	v_fma_f32 v170, v88, v154, -v132
	v_fma_f32 v171, v92, v154, v171
	v_add_f32_e32 v89, v89, v172
	v_add_f32_e32 v93, v93, v173
	v_mul_f32_e32 v133, v93, v159
	v_mul_f32_e32 v173, v89, v159
	v_fma_f32 v172, v89, v158, -v133
	v_fma_f32 v173, v93, v158, v173
	v_add_f32_e32 v90, v90, v174
	v_add_f32_e32 v94, v94, v175
	v_mul_f32_e32 v132, v94, v163
	v_mul_f32_e32 v175, v90, v163
	v_fma_f32 v174, v90, v162, -v132
	v_fma_f32 v175, v94, v162, v175
	v_add_f32_e32 v91, v91, v176
	v_add_f32_e32 v95, v95, v177
	v_mul_f32_e32 v133, v95, v167
	v_mul_f32_e32 v177, v91, v167
	v_fma_f32 v176, v91, v166, -v133
	v_fma_f32 v177, v95, v166, v177
	v_mul_f32_e32 v132, v40, v139
	v_mul_f32_e32 v40, v40, v138
	v_fma_f32 v40, -v44, v139, v40
	v_fma_f32 v44, v44, v138, v132
	v_mul_f32_e32 v133, v41, v143
	v_mul_f32_e32 v41, v41, v142
	v_fma_f32 v41, -v45, v143, v41
	v_fma_f32 v45, v45, v142, v133
	v_mul_f32_e32 v132, v42, v147
	v_mul_f32_e32 v42, v42, v146
	v_fma_f32 v42, -v46, v147, v42
	v_fma_f32 v46, v46, v146, v132
	v_mul_f32_e32 v133, v43, v151
	v_mul_f32_e32 v43, v43, v150
	v_fma_f32 v43, -v47, v151, v43
	v_fma_f32 v47, v47, v150, v133
	v_add_f32_dpp v40, v40, v40 row_shr:1 row_mask:0xf bank_mask:0xf bound_ctrl:1
	v_add_f32_dpp v41, v41, v41 row_shr:1 row_mask:0xf bank_mask:0xf bound_ctrl:1
	v_add_f32_dpp v42, v42, v42 row_shr:1 row_mask:0xf bank_mask:0xf bound_ctrl:1
	v_add_f32_dpp v43, v43, v43 row_shr:1 row_mask:0xf bank_mask:0xf bound_ctrl:1
	v_add_f32_dpp v44, v44, v44 row_shr:1 row_mask:0xf bank_mask:0xf bound_ctrl:1
	v_add_f32_dpp v45, v45, v45 row_shr:1 row_mask:0xf bank_mask:0xf bound_ctrl:1
	v_add_f32_dpp v46, v46, v46 row_shr:1 row_mask:0xf bank_mask:0xf bound_ctrl:1
	v_add_f32_dpp v47, v47, v47 row_shr:1 row_mask:0xf bank_mask:0xf bound_ctrl:1
	v_add_f32_dpp v40, v40, v40 row_shr:2 row_mask:0xf bank_mask:0xf bound_ctrl:1
	v_add_f32_dpp v41, v41, v41 row_shr:2 row_mask:0xf bank_mask:0xf bound_ctrl:1
	v_add_f32_dpp v42, v42, v42 row_shr:2 row_mask:0xf bank_mask:0xf bound_ctrl:1
	v_add_f32_dpp v43, v43, v43 row_shr:2 row_mask:0xf bank_mask:0xf bound_ctrl:1
	v_add_f32_dpp v44, v44, v44 row_shr:2 row_mask:0xf bank_mask:0xf bound_ctrl:1
	v_add_f32_dpp v45, v45, v45 row_shr:2 row_mask:0xf bank_mask:0xf bound_ctrl:1
	v_add_f32_dpp v46, v46, v46 row_shr:2 row_mask:0xf bank_mask:0xf bound_ctrl:1
	v_add_f32_dpp v47, v47, v47 row_shr:2 row_mask:0xf bank_mask:0xf bound_ctrl:1
	v_add_f32_dpp v40, v40, v40 row_shr:4 row_mask:0xf bank_mask:0xf bound_ctrl:1
	v_add_f32_dpp v41, v41, v41 row_shr:4 row_mask:0xf bank_mask:0xf bound_ctrl:1
	v_add_f32_dpp v42, v42, v42 row_shr:4 row_mask:0xf bank_mask:0xf bound_ctrl:1
	v_add_f32_dpp v43, v43, v43 row_shr:4 row_mask:0xf bank_mask:0xf bound_ctrl:1
	v_add_f32_dpp v44, v44, v44 row_shr:4 row_mask:0xf bank_mask:0xf bound_ctrl:1
	v_add_f32_dpp v45, v45, v45 row_shr:4 row_mask:0xf bank_mask:0xf bound_ctrl:1
	v_add_f32_dpp v46, v46, v46 row_shr:4 row_mask:0xf bank_mask:0xf bound_ctrl:1
	v_add_f32_dpp v47, v47, v47 row_shr:4 row_mask:0xf bank_mask:0xf bound_ctrl:1
	v_add_f32_dpp v40, v40, v40 row_shr:8 row_mask:0xf bank_mask:0xf bound_ctrl:1
	v_add_f32_dpp v41, v41, v41 row_shr:8 row_mask:0xf bank_mask:0xf bound_ctrl:1
	v_add_f32_dpp v42, v42, v42 row_shr:8 row_mask:0xf bank_mask:0xf bound_ctrl:1
	v_add_f32_dpp v43, v43, v43 row_shr:8 row_mask:0xf bank_mask:0xf bound_ctrl:1
	v_add_f32_dpp v44, v44, v44 row_shr:8 row_mask:0xf bank_mask:0xf bound_ctrl:1
	v_add_f32_dpp v45, v45, v45 row_shr:8 row_mask:0xf bank_mask:0xf bound_ctrl:1
	v_add_f32_dpp v46, v46, v46 row_shr:8 row_mask:0xf bank_mask:0xf bound_ctrl:1
	v_add_f32_dpp v47, v47, v47 row_shr:8 row_mask:0xf bank_mask:0xf bound_ctrl:1
	v_mov_b32_dpp v88, v40 row_newbcast:15 row_mask:0xf bank_mask:0xf
	v_mov_b32_dpp v89, v41 row_newbcast:15 row_mask:0xf bank_mask:0xf
	v_mov_b32_dpp v90, v42 row_newbcast:15 row_mask:0xf bank_mask:0xf
	v_mov_b32_dpp v91, v43 row_newbcast:15 row_mask:0xf bank_mask:0xf
	v_mov_b32_dpp v92, v44 row_newbcast:15 row_mask:0xf bank_mask:0xf
	v_mov_b32_dpp v93, v45 row_newbcast:15 row_mask:0xf bank_mask:0xf
	v_mov_b32_dpp v94, v46 row_newbcast:15 row_mask:0xf bank_mask:0xf
	v_mov_b32_dpp v95, v47 row_newbcast:15 row_mask:0xf bank_mask:0xf
	v_add_f32_e32 v40, v40, v170
	v_add_f32_e32 v44, v44, v171
	v_add_f32_e32 v41, v41, v172
	v_add_f32_e32 v45, v45, v173
	v_add_f32_e32 v42, v42, v174
	v_add_f32_e32 v46, v46, v175
	v_add_f32_e32 v43, v43, v176
	v_add_f32_e32 v47, v47, v177
	v_mul_f32_e32 v132, v40, v141
	v_mul_f32_e32 v40, v40, v140
	v_fma_f32 v40, -v44, v141, v40
	v_fma_f32 v44, v44, v140, v132
	v_mul_f32_e32 v133, v41, v145
	v_mul_f32_e32 v41, v41, v144
	v_fma_f32 v41, -v45, v145, v41
	v_fma_f32 v45, v45, v144, v133
	v_mul_f32_e32 v132, v42, v149
	v_mul_f32_e32 v42, v42, v148
	v_fma_f32 v42, -v46, v149, v42
	v_fma_f32 v46, v46, v148, v132
	v_mul_f32_e32 v133, v43, v153
	v_mul_f32_e32 v43, v43, v152
	v_fma_f32 v43, -v47, v153, v43
	v_fma_f32 v47, v47, v152, v133
	v_add_f32_e32 v88, v88, v170
	v_add_f32_e32 v92, v92, v171
	v_mul_f32_e32 v132, v92, v155
	v_mul_f32_e32 v171, v88, v155
	v_fma_f32 v170, v88, v154, -v132
	v_fma_f32 v171, v92, v154, v171
	v_add_f32_e32 v89, v89, v172
	v_add_f32_e32 v93, v93, v173
	v_mul_f32_e32 v133, v93, v159
	v_mul_f32_e32 v173, v89, v159
	v_fma_f32 v172, v89, v158, -v133
	v_fma_f32 v173, v93, v158, v173
	v_add_f32_e32 v90, v90, v174
	v_add_f32_e32 v94, v94, v175
	v_mul_f32_e32 v132, v94, v163
	v_mul_f32_e32 v175, v90, v163
	v_fma_f32 v174, v90, v162, -v132
	v_fma_f32 v175, v94, v162, v175
	v_add_f32_e32 v91, v91, v176
	v_add_f32_e32 v95, v95, v177
	v_mul_f32_e32 v133, v95, v167
	v_mul_f32_e32 v177, v91, v167
	v_fma_f32 v176, v91, v166, -v133
	v_fma_f32 v177, v95, v166, v177
	v_mul_f32_e32 v132, v48, v139
	v_mul_f32_e32 v48, v48, v138
	v_fma_f32 v48, -v52, v139, v48
	v_fma_f32 v52, v52, v138, v132
	v_mul_f32_e32 v133, v49, v143
	v_mul_f32_e32 v49, v49, v142
	v_fma_f32 v49, -v53, v143, v49
	v_fma_f32 v53, v53, v142, v133
	v_mul_f32_e32 v132, v50, v147
	v_mul_f32_e32 v50, v50, v146
	v_fma_f32 v50, -v54, v147, v50
	v_fma_f32 v54, v54, v146, v132
	v_mul_f32_e32 v133, v51, v151
	v_mul_f32_e32 v51, v51, v150
	v_fma_f32 v51, -v55, v151, v51
	v_fma_f32 v55, v55, v150, v133
	v_add_f32_dpp v48, v48, v48 row_shr:1 row_mask:0xf bank_mask:0xf bound_ctrl:1
	v_add_f32_dpp v49, v49, v49 row_shr:1 row_mask:0xf bank_mask:0xf bound_ctrl:1
	v_add_f32_dpp v50, v50, v50 row_shr:1 row_mask:0xf bank_mask:0xf bound_ctrl:1
	v_add_f32_dpp v51, v51, v51 row_shr:1 row_mask:0xf bank_mask:0xf bound_ctrl:1
	v_add_f32_dpp v52, v52, v52 row_shr:1 row_mask:0xf bank_mask:0xf bound_ctrl:1
	v_add_f32_dpp v53, v53, v53 row_shr:1 row_mask:0xf bank_mask:0xf bound_ctrl:1
	v_add_f32_dpp v54, v54, v54 row_shr:1 row_mask:0xf bank_mask:0xf bound_ctrl:1
	v_add_f32_dpp v55, v55, v55 row_shr:1 row_mask:0xf bank_mask:0xf bound_ctrl:1
	v_add_f32_dpp v48, v48, v48 row_shr:2 row_mask:0xf bank_mask:0xf bound_ctrl:1
	v_add_f32_dpp v49, v49, v49 row_shr:2 row_mask:0xf bank_mask:0xf bound_ctrl:1
	v_add_f32_dpp v50, v50, v50 row_shr:2 row_mask:0xf bank_mask:0xf bound_ctrl:1
	v_add_f32_dpp v51, v51, v51 row_shr:2 row_mask:0xf bank_mask:0xf bound_ctrl:1
	v_add_f32_dpp v52, v52, v52 row_shr:2 row_mask:0xf bank_mask:0xf bound_ctrl:1
	v_add_f32_dpp v53, v53, v53 row_shr:2 row_mask:0xf bank_mask:0xf bound_ctrl:1
	v_add_f32_dpp v54, v54, v54 row_shr:2 row_mask:0xf bank_mask:0xf bound_ctrl:1
	v_add_f32_dpp v55, v55, v55 row_shr:2 row_mask:0xf bank_mask:0xf bound_ctrl:1
	v_add_f32_dpp v48, v48, v48 row_shr:4 row_mask:0xf bank_mask:0xf bound_ctrl:1
	v_add_f32_dpp v49, v49, v49 row_shr:4 row_mask:0xf bank_mask:0xf bound_ctrl:1
	v_add_f32_dpp v50, v50, v50 row_shr:4 row_mask:0xf bank_mask:0xf bound_ctrl:1
	v_add_f32_dpp v51, v51, v51 row_shr:4 row_mask:0xf bank_mask:0xf bound_ctrl:1
	v_add_f32_dpp v52, v52, v52 row_shr:4 row_mask:0xf bank_mask:0xf bound_ctrl:1
	v_add_f32_dpp v53, v53, v53 row_shr:4 row_mask:0xf bank_mask:0xf bound_ctrl:1
	v_add_f32_dpp v54, v54, v54 row_shr:4 row_mask:0xf bank_mask:0xf bound_ctrl:1
	v_add_f32_dpp v55, v55, v55 row_shr:4 row_mask:0xf bank_mask:0xf bound_ctrl:1
	v_add_f32_dpp v48, v48, v48 row_shr:8 row_mask:0xf bank_mask:0xf bound_ctrl:1
	v_add_f32_dpp v49, v49, v49 row_shr:8 row_mask:0xf bank_mask:0xf bound_ctrl:1
	v_add_f32_dpp v50, v50, v50 row_shr:8 row_mask:0xf bank_mask:0xf bound_ctrl:1
	v_add_f32_dpp v51, v51, v51 row_shr:8 row_mask:0xf bank_mask:0xf bound_ctrl:1
	v_add_f32_dpp v52, v52, v52 row_shr:8 row_mask:0xf bank_mask:0xf bound_ctrl:1
	v_add_f32_dpp v53, v53, v53 row_shr:8 row_mask:0xf bank_mask:0xf bound_ctrl:1
	v_add_f32_dpp v54, v54, v54 row_shr:8 row_mask:0xf bank_mask:0xf bound_ctrl:1
	v_add_f32_dpp v55, v55, v55 row_shr:8 row_mask:0xf bank_mask:0xf bound_ctrl:1
	v_mov_b32_dpp v88, v48 row_newbcast:15 row_mask:0xf bank_mask:0xf
	v_mov_b32_dpp v89, v49 row_newbcast:15 row_mask:0xf bank_mask:0xf
	v_mov_b32_dpp v90, v50 row_newbcast:15 row_mask:0xf bank_mask:0xf
	v_mov_b32_dpp v91, v51 row_newbcast:15 row_mask:0xf bank_mask:0xf
	v_mov_b32_dpp v92, v52 row_newbcast:15 row_mask:0xf bank_mask:0xf
	v_mov_b32_dpp v93, v53 row_newbcast:15 row_mask:0xf bank_mask:0xf
	v_mov_b32_dpp v94, v54 row_newbcast:15 row_mask:0xf bank_mask:0xf
	v_mov_b32_dpp v95, v55 row_newbcast:15 row_mask:0xf bank_mask:0xf
	v_add_f32_e32 v48, v48, v170
	v_add_f32_e32 v52, v52, v171
	v_add_f32_e32 v49, v49, v172
	v_add_f32_e32 v53, v53, v173
	v_add_f32_e32 v50, v50, v174
	v_add_f32_e32 v54, v54, v175
	v_add_f32_e32 v51, v51, v176
	v_add_f32_e32 v55, v55, v177
	v_mul_f32_e32 v132, v48, v141
	v_mul_f32_e32 v48, v48, v140
	v_fma_f32 v48, -v52, v141, v48
	v_fma_f32 v52, v52, v140, v132
	v_mul_f32_e32 v133, v49, v145
	v_mul_f32_e32 v49, v49, v144
	v_fma_f32 v49, -v53, v145, v49
	v_fma_f32 v53, v53, v144, v133
	v_mul_f32_e32 v132, v50, v149
	v_mul_f32_e32 v50, v50, v148
	v_fma_f32 v50, -v54, v149, v50
	v_fma_f32 v54, v54, v148, v132
	v_mul_f32_e32 v133, v51, v153
	v_mul_f32_e32 v51, v51, v152
	v_fma_f32 v51, -v55, v153, v51
	v_fma_f32 v55, v55, v152, v133
	v_add_f32_e32 v88, v88, v170
	v_add_f32_e32 v92, v92, v171
	v_mul_f32_e32 v132, v92, v155
	v_mul_f32_e32 v171, v88, v155
	v_fma_f32 v170, v88, v154, -v132
	v_fma_f32 v171, v92, v154, v171
	v_add_f32_e32 v89, v89, v172
	v_add_f32_e32 v93, v93, v173
	v_mul_f32_e32 v133, v93, v159
	v_mul_f32_e32 v173, v89, v159
	v_fma_f32 v172, v89, v158, -v133
	v_fma_f32 v173, v93, v158, v173
	v_add_f32_e32 v90, v90, v174
	v_add_f32_e32 v94, v94, v175
	v_mul_f32_e32 v132, v94, v163
	v_mul_f32_e32 v175, v90, v163
	v_fma_f32 v174, v90, v162, -v132
	v_fma_f32 v175, v94, v162, v175
	v_add_f32_e32 v91, v91, v176
	v_add_f32_e32 v95, v95, v177
	v_mul_f32_e32 v133, v95, v167
	v_mul_f32_e32 v177, v91, v167
	v_fma_f32 v176, v91, v166, -v133
	v_fma_f32 v177, v95, v166, v177
	v_mul_f32_e32 v132, v56, v139
	v_mul_f32_e32 v56, v56, v138
	v_fma_f32 v56, -v60, v139, v56
	v_fma_f32 v60, v60, v138, v132
	v_mul_f32_e32 v133, v57, v143
	v_mul_f32_e32 v57, v57, v142
	v_fma_f32 v57, -v61, v143, v57
	v_fma_f32 v61, v61, v142, v133
	v_mul_f32_e32 v132, v58, v147
	v_mul_f32_e32 v58, v58, v146
	v_fma_f32 v58, -v62, v147, v58
	v_fma_f32 v62, v62, v146, v132
	v_mul_f32_e32 v133, v59, v151
	v_mul_f32_e32 v59, v59, v150
	v_fma_f32 v59, -v63, v151, v59
	v_fma_f32 v63, v63, v150, v133
	v_add_f32_dpp v56, v56, v56 row_shr:1 row_mask:0xf bank_mask:0xf bound_ctrl:1
	v_add_f32_dpp v57, v57, v57 row_shr:1 row_mask:0xf bank_mask:0xf bound_ctrl:1
	v_add_f32_dpp v58, v58, v58 row_shr:1 row_mask:0xf bank_mask:0xf bound_ctrl:1
	v_add_f32_dpp v59, v59, v59 row_shr:1 row_mask:0xf bank_mask:0xf bound_ctrl:1
	v_add_f32_dpp v60, v60, v60 row_shr:1 row_mask:0xf bank_mask:0xf bound_ctrl:1
	v_add_f32_dpp v61, v61, v61 row_shr:1 row_mask:0xf bank_mask:0xf bound_ctrl:1
	v_add_f32_dpp v62, v62, v62 row_shr:1 row_mask:0xf bank_mask:0xf bound_ctrl:1
	v_add_f32_dpp v63, v63, v63 row_shr:1 row_mask:0xf bank_mask:0xf bound_ctrl:1
	v_add_f32_dpp v56, v56, v56 row_shr:2 row_mask:0xf bank_mask:0xf bound_ctrl:1
	v_add_f32_dpp v57, v57, v57 row_shr:2 row_mask:0xf bank_mask:0xf bound_ctrl:1
	v_add_f32_dpp v58, v58, v58 row_shr:2 row_mask:0xf bank_mask:0xf bound_ctrl:1
	v_add_f32_dpp v59, v59, v59 row_shr:2 row_mask:0xf bank_mask:0xf bound_ctrl:1
	v_add_f32_dpp v60, v60, v60 row_shr:2 row_mask:0xf bank_mask:0xf bound_ctrl:1
	v_add_f32_dpp v61, v61, v61 row_shr:2 row_mask:0xf bank_mask:0xf bound_ctrl:1
	v_add_f32_dpp v62, v62, v62 row_shr:2 row_mask:0xf bank_mask:0xf bound_ctrl:1
	v_add_f32_dpp v63, v63, v63 row_shr:2 row_mask:0xf bank_mask:0xf bound_ctrl:1
	v_add_f32_dpp v56, v56, v56 row_shr:4 row_mask:0xf bank_mask:0xf bound_ctrl:1
	v_add_f32_dpp v57, v57, v57 row_shr:4 row_mask:0xf bank_mask:0xf bound_ctrl:1
	v_add_f32_dpp v58, v58, v58 row_shr:4 row_mask:0xf bank_mask:0xf bound_ctrl:1
	v_add_f32_dpp v59, v59, v59 row_shr:4 row_mask:0xf bank_mask:0xf bound_ctrl:1
	v_add_f32_dpp v60, v60, v60 row_shr:4 row_mask:0xf bank_mask:0xf bound_ctrl:1
	v_add_f32_dpp v61, v61, v61 row_shr:4 row_mask:0xf bank_mask:0xf bound_ctrl:1
	v_add_f32_dpp v62, v62, v62 row_shr:4 row_mask:0xf bank_mask:0xf bound_ctrl:1
	v_add_f32_dpp v63, v63, v63 row_shr:4 row_mask:0xf bank_mask:0xf bound_ctrl:1
	v_add_f32_dpp v56, v56, v56 row_shr:8 row_mask:0xf bank_mask:0xf bound_ctrl:1
	v_add_f32_dpp v57, v57, v57 row_shr:8 row_mask:0xf bank_mask:0xf bound_ctrl:1
	v_add_f32_dpp v58, v58, v58 row_shr:8 row_mask:0xf bank_mask:0xf bound_ctrl:1
	v_add_f32_dpp v59, v59, v59 row_shr:8 row_mask:0xf bank_mask:0xf bound_ctrl:1
	v_add_f32_dpp v60, v60, v60 row_shr:8 row_mask:0xf bank_mask:0xf bound_ctrl:1
	v_add_f32_dpp v61, v61, v61 row_shr:8 row_mask:0xf bank_mask:0xf bound_ctrl:1
	v_add_f32_dpp v62, v62, v62 row_shr:8 row_mask:0xf bank_mask:0xf bound_ctrl:1
	v_add_f32_dpp v63, v63, v63 row_shr:8 row_mask:0xf bank_mask:0xf bound_ctrl:1
	v_mov_b32_dpp v88, v56 row_newbcast:15 row_mask:0xf bank_mask:0xf
	v_mov_b32_dpp v89, v57 row_newbcast:15 row_mask:0xf bank_mask:0xf
	v_mov_b32_dpp v90, v58 row_newbcast:15 row_mask:0xf bank_mask:0xf
	v_mov_b32_dpp v91, v59 row_newbcast:15 row_mask:0xf bank_mask:0xf
	v_mov_b32_dpp v92, v60 row_newbcast:15 row_mask:0xf bank_mask:0xf
	v_mov_b32_dpp v93, v61 row_newbcast:15 row_mask:0xf bank_mask:0xf
	v_mov_b32_dpp v94, v62 row_newbcast:15 row_mask:0xf bank_mask:0xf
	v_mov_b32_dpp v95, v63 row_newbcast:15 row_mask:0xf bank_mask:0xf
	v_add_f32_e32 v56, v56, v170
	v_add_f32_e32 v60, v60, v171
	v_add_f32_e32 v57, v57, v172
	v_add_f32_e32 v61, v61, v173
	v_add_f32_e32 v58, v58, v174
	v_add_f32_e32 v62, v62, v175
	v_add_f32_e32 v59, v59, v176
	v_add_f32_e32 v63, v63, v177
	v_mul_f32_e32 v132, v56, v141
	v_mul_f32_e32 v56, v56, v140
	v_fma_f32 v56, -v60, v141, v56
	v_fma_f32 v60, v60, v140, v132
	v_mul_f32_e32 v133, v57, v145
	v_mul_f32_e32 v57, v57, v144
	v_fma_f32 v57, -v61, v145, v57
	v_fma_f32 v61, v61, v144, v133
	v_mul_f32_e32 v132, v58, v149
	v_mul_f32_e32 v58, v58, v148
	v_fma_f32 v58, -v62, v149, v58
	v_fma_f32 v62, v62, v148, v132
	v_mul_f32_e32 v133, v59, v153
	v_mul_f32_e32 v59, v59, v152
	v_fma_f32 v59, -v63, v153, v59
	v_fma_f32 v63, v63, v152, v133
	v_add_f32_e32 v88, v88, v170
	v_add_f32_e32 v92, v92, v171
	v_mul_f32_e32 v132, v92, v155
	v_mul_f32_e32 v171, v88, v155
	v_fma_f32 v170, v88, v154, -v132
	v_fma_f32 v171, v92, v154, v171
	v_add_f32_e32 v89, v89, v172
	v_add_f32_e32 v93, v93, v173
	v_mul_f32_e32 v133, v93, v159
	v_mul_f32_e32 v173, v89, v159
	v_fma_f32 v172, v89, v158, -v133
	v_fma_f32 v173, v93, v158, v173
	v_add_f32_e32 v90, v90, v174
	v_add_f32_e32 v94, v94, v175
	v_mul_f32_e32 v132, v94, v163
	v_mul_f32_e32 v175, v90, v163
	v_fma_f32 v174, v90, v162, -v132
	v_fma_f32 v175, v94, v162, v175
	v_add_f32_e32 v91, v91, v176
	v_add_f32_e32 v95, v95, v177
	v_mul_f32_e32 v133, v95, v167
	v_mul_f32_e32 v177, v91, v167
	v_fma_f32 v176, v91, v166, -v133
	v_fma_f32 v177, v95, v166, v177
	s_waitcnt vmcnt(14)
	v_cvt_pk_bf16_f32 v80, v80, v81
	v_cvt_pk_bf16_f32 v81, v82, v83
	v_cvt_pk_bf16_f32 v82, -v84, -v85
	v_cvt_pk_bf16_f32 v83, -v86, -v87
	v_cvt_pk_bf16_f32 v96, v32, v33
	v_cvt_pk_bf16_f32 v97, v34, v35
	v_cvt_pk_bf16_f32 v98, v36, v37
	v_cvt_pk_bf16_f32 v99, v38, v39
	s_nop 1
	v_mfma_f32_16x16x32_bf16 v[16:19], v[80:83], v[96:99], 0
	v_cvt_pk_bf16_f32 v96, v40, v41
	v_cvt_pk_bf16_f32 v97, v42, v43
	v_cvt_pk_bf16_f32 v98, v44, v45
	v_cvt_pk_bf16_f32 v99, v46, v47
	s_nop 1
	v_mfma_f32_16x16x32_bf16 v[20:23], v[80:83], v[96:99], 0
	v_cvt_pk_bf16_f32 v96, v48, v49
	v_cvt_pk_bf16_f32 v97, v50, v51
	v_cvt_pk_bf16_f32 v98, v52, v53
	v_cvt_pk_bf16_f32 v99, v54, v55
	s_nop 1
	v_mfma_f32_16x16x32_bf16 v[24:27], v[80:83], v[96:99], 0
	v_cvt_pk_bf16_f32 v96, v56, v57
	v_cvt_pk_bf16_f32 v97, v58, v59
	v_cvt_pk_bf16_f32 v98, v60, v61
	v_cvt_pk_bf16_f32 v99, v62, v63
	s_nop 1
	v_mfma_f32_16x16x32_bf16 v[28:31], v[80:83], v[96:99], 0
	s_waitcnt vmcnt(10)
	v_cvt_pk_bf16_f32 v64, v64, v65
	v_cvt_pk_bf16_f32 v65, v66, v67
	v_cvt_pk_bf16_f32 v66, v68, v69
	v_cvt_pk_bf16_f32 v67, v70, v71
	v_cvt_pk_bf16_f32 v72, v72, v73
	v_cvt_pk_bf16_f32 v73, v74, v75
	v_cvt_pk_bf16_f32 v74, v76, v77
	v_cvt_pk_bf16_f32 v75, v78, v79
	global_load_dwordx4 v[80:83], v136, s[38:39]
	global_load_dwordx4 v[84:87], v136, s[40:41]
	s_add_u32 s38, s38, 0x40
	s_addc_u32 s39, s39, 0
	s_add_u32 s40, s40, 0x40
	s_addc_u32 s41, s41, 0
	s_nop 0
	v_mfma_f32_16x16x32_bf16 v[32:35], v[64:67], v[0:3], 0
	v_mfma_f32_16x16x32_bf16 v[36:39], v[72:75], v[0:3], 0
	v_mfma_f32_16x16x32_bf16 v[40:43], v[64:67], v[4:7], 0
	v_mfma_f32_16x16x32_bf16 v[44:47], v[72:75], v[4:7], 0
	v_mfma_f32_16x16x32_bf16 v[48:51], v[64:67], v[8:11], 0
	v_mfma_f32_16x16x32_bf16 v[52:55], v[72:75], v[8:11], 0
	v_mfma_f32_16x16x32_bf16 v[56:59], v[64:67], v[12:15], 0
	v_mfma_f32_16x16x32_bf16 v[60:63], v[72:75], v[12:15], 0
	s_mov_b32 exec_hi, 0
	global_load_dwordx4 v[64:67], v135, s[20:21]
	global_load_dwordx4 v[68:71], v135, s[20:21] offset:16
	global_load_dwordx4 v[72:75], v135, s[22:23]
	global_load_dwordx4 v[76:79], v135, s[22:23] offset:16
	s_mov_b64 exec, -1
	s_add_u32 s20, s20, 0x400
	s_addc_u32 s21, s21, 0
	s_add_u32 s22, s22, 0x400
	s_addc_u32 s23, s23, 0
	global_load_dwordx4 v[138:141], v134, s[42:43] offset:0
	global_load_dwordx4 v[142:145], v134, s[42:43] offset:16
	global_load_dwordx4 v[146:149], v134, s[42:43] offset:32
	global_load_dwordx4 v[150:153], v134, s[42:43] offset:48
	global_load_dwordx4 v[154:157], v134, s[42:43] offset:64
	global_load_dwordx4 v[158:161], v134, s[42:43] offset:80
	global_load_dwordx4 v[162:165], v134, s[42:43] offset:96
	global_load_dwordx4 v[166:169], v134, s[42:43] offset:112
	global_load_dwordx4 v[170:173], v206, s[44:45]
	global_load_dwordx4 v[174:177], v206, s[44:45] offset:16
	s_add_u32 s42, s42, 0x2000
	s_addc_u32 s43, s43, 0
	s_add_u32 s44, s44, 0x80
	s_addc_u32 s45, s45, 0
	s_waitcnt vmcnt(16)
	v_mul_f32_e32 v132, v179, v119
	v_mul_f32_e32 v133, v178, v119
	v_fma_f32 v178, v178, v118, -v132
	v_fma_f32 v179, v179, v118, v133
	v_mul_f32_e32 v132, v181, v123
	v_mul_f32_e32 v133, v180, v123
	v_fma_f32 v180, v180, v122, -v132
	v_fma_f32 v181, v181, v122, v133
	v_mul_f32_e32 v132, v183, v127
	v_mul_f32_e32 v133, v182, v127
	v_fma_f32 v182, v182, v126, -v132
	v_fma_f32 v183, v183, v126, v133
	v_mul_f32_e32 v132, v185, v131
	v_mul_f32_e32 v133, v184, v131
	v_fma_f32 v184, v184, v130, -v132
	v_fma_f32 v185, v185, v130, v133
	v_mul_f32_e32 v132, v32, v101
	v_mul_f32_e32 v32, v32, v100
	v_fma_f32 v32, -v36, v101, v32
	v_fma_f32 v36, v36, v100, v132
	v_mul_f32_e32 v133, v33, v105
	v_mul_f32_e32 v33, v33, v104
	v_fma_f32 v33, -v37, v105, v33
	v_fma_f32 v37, v37, v104, v133
	v_mul_f32_e32 v132, v34, v109
	v_mul_f32_e32 v34, v34, v108
	v_fma_f32 v34, -v38, v109, v34
	v_fma_f32 v38, v38, v108, v132
	v_mul_f32_e32 v133, v35, v113
	v_mul_f32_e32 v35, v35, v112
	v_fma_f32 v35, -v39, v113, v35
	v_fma_f32 v39, v39, v112, v133
	v_add_f32_dpp v32, v32, v32 row_shr:1 row_mask:0xf bank_mask:0xf bound_ctrl:1
	v_add_f32_dpp v33, v33, v33 row_shr:1 row_mask:0xf bank_mask:0xf bound_ctrl:1
	v_add_f32_dpp v34, v34, v34 row_shr:1 row_mask:0xf bank_mask:0xf bound_ctrl:1
	v_add_f32_dpp v35, v35, v35 row_shr:1 row_mask:0xf bank_mask:0xf bound_ctrl:1
	v_add_f32_dpp v36, v36, v36 row_shr:1 row_mask:0xf bank_mask:0xf bound_ctrl:1
	v_add_f32_dpp v37, v37, v37 row_shr:1 row_mask:0xf bank_mask:0xf bound_ctrl:1
	v_add_f32_dpp v38, v38, v38 row_shr:1 row_mask:0xf bank_mask:0xf bound_ctrl:1
	v_add_f32_dpp v39, v39, v39 row_shr:1 row_mask:0xf bank_mask:0xf bound_ctrl:1
	v_add_f32_dpp v32, v32, v32 row_shr:2 row_mask:0xf bank_mask:0xf bound_ctrl:1
	v_add_f32_dpp v33, v33, v33 row_shr:2 row_mask:0xf bank_mask:0xf bound_ctrl:1
	v_add_f32_dpp v34, v34, v34 row_shr:2 row_mask:0xf bank_mask:0xf bound_ctrl:1
	v_add_f32_dpp v35, v35, v35 row_shr:2 row_mask:0xf bank_mask:0xf bound_ctrl:1
	v_add_f32_dpp v36, v36, v36 row_shr:2 row_mask:0xf bank_mask:0xf bound_ctrl:1
	v_add_f32_dpp v37, v37, v37 row_shr:2 row_mask:0xf bank_mask:0xf bound_ctrl:1
	v_add_f32_dpp v38, v38, v38 row_shr:2 row_mask:0xf bank_mask:0xf bound_ctrl:1
	v_add_f32_dpp v39, v39, v39 row_shr:2 row_mask:0xf bank_mask:0xf bound_ctrl:1
	v_add_f32_dpp v32, v32, v32 row_shr:4 row_mask:0xf bank_mask:0xf bound_ctrl:1
	v_add_f32_dpp v33, v33, v33 row_shr:4 row_mask:0xf bank_mask:0xf bound_ctrl:1
	v_add_f32_dpp v34, v34, v34 row_shr:4 row_mask:0xf bank_mask:0xf bound_ctrl:1
	v_add_f32_dpp v35, v35, v35 row_shr:4 row_mask:0xf bank_mask:0xf bound_ctrl:1
	v_add_f32_dpp v36, v36, v36 row_shr:4 row_mask:0xf bank_mask:0xf bound_ctrl:1
	v_add_f32_dpp v37, v37, v37 row_shr:4 row_mask:0xf bank_mask:0xf bound_ctrl:1
	v_add_f32_dpp v38, v38, v38 row_shr:4 row_mask:0xf bank_mask:0xf bound_ctrl:1
	v_add_f32_dpp v39, v39, v39 row_shr:4 row_mask:0xf bank_mask:0xf bound_ctrl:1
	v_add_f32_dpp v32, v32, v32 row_shr:8 row_mask:0xf bank_mask:0xf bound_ctrl:1
	v_add_f32_dpp v33, v33, v33 row_shr:8 row_mask:0xf bank_mask:0xf bound_ctrl:1
	v_add_f32_dpp v34, v34, v34 row_shr:8 row_mask:0xf bank_mask:0xf bound_ctrl:1
	v_add_f32_dpp v35, v35, v35 row_shr:8 row_mask:0xf bank_mask:0xf bound_ctrl:1
	v_add_f32_dpp v36, v36, v36 row_shr:8 row_mask:0xf bank_mask:0xf bound_ctrl:1
	v_add_f32_dpp v37, v37, v37 row_shr:8 row_mask:0xf bank_mask:0xf bound_ctrl:1
	v_add_f32_dpp v38, v38, v38 row_shr:8 row_mask:0xf bank_mask:0xf bound_ctrl:1
	v_add_f32_dpp v39, v39, v39 row_shr:8 row_mask:0xf bank_mask:0xf bound_ctrl:1
	v_mov_b32_dpp v88, v32 row_newbcast:15 row_mask:0xf bank_mask:0xf
	v_mov_b32_dpp v89, v33 row_newbcast:15 row_mask:0xf bank_mask:0xf
	v_mov_b32_dpp v90, v34 row_newbcast:15 row_mask:0xf bank_mask:0xf
	v_mov_b32_dpp v91, v35 row_newbcast:15 row_mask:0xf bank_mask:0xf
	v_mov_b32_dpp v92, v36 row_newbcast:15 row_mask:0xf bank_mask:0xf
	v_mov_b32_dpp v93, v37 row_newbcast:15 row_mask:0xf bank_mask:0xf
	v_mov_b32_dpp v94, v38 row_newbcast:15 row_mask:0xf bank_mask:0xf
	v_mov_b32_dpp v95, v39 row_newbcast:15 row_mask:0xf bank_mask:0xf
	v_add_f32_e32 v32, v32, v178
	v_add_f32_e32 v36, v36, v179
	v_add_f32_e32 v33, v33, v180
	v_add_f32_e32 v37, v37, v181
	v_add_f32_e32 v34, v34, v182
	v_add_f32_e32 v38, v38, v183
	v_add_f32_e32 v35, v35, v184
	v_add_f32_e32 v39, v39, v185
	v_mul_f32_e32 v132, v32, v103
	v_mul_f32_e32 v32, v32, v102
	v_fma_f32 v32, -v36, v103, v32
	v_fma_f32 v36, v36, v102, v132
	v_mul_f32_e32 v133, v33, v107
	v_mul_f32_e32 v33, v33, v106
	v_fma_f32 v33, -v37, v107, v33
	v_fma_f32 v37, v37, v106, v133
	v_mul_f32_e32 v132, v34, v111
	v_mul_f32_e32 v34, v34, v110
	v_fma_f32 v34, -v38, v111, v34
	v_fma_f32 v38, v38, v110, v132
	v_mul_f32_e32 v133, v35, v115
	v_mul_f32_e32 v35, v35, v114
	v_fma_f32 v35, -v39, v115, v35
	v_fma_f32 v39, v39, v114, v133
	v_add_f32_e32 v88, v88, v178
	v_add_f32_e32 v92, v92, v179
	v_mul_f32_e32 v132, v92, v117
	v_mul_f32_e32 v179, v88, v117
	v_fma_f32 v178, v88, v116, -v132
	v_fma_f32 v179, v92, v116, v179
	v_add_f32_e32 v89, v89, v180
	v_add_f32_e32 v93, v93, v181
	v_mul_f32_e32 v133, v93, v121
	v_mul_f32_e32 v181, v89, v121
	v_fma_f32 v180, v89, v120, -v133
	v_fma_f32 v181, v93, v120, v181
	v_add_f32_e32 v90, v90, v182
	v_add_f32_e32 v94, v94, v183
	v_mul_f32_e32 v132, v94, v125
	v_mul_f32_e32 v183, v90, v125
	v_fma_f32 v182, v90, v124, -v132
	v_fma_f32 v183, v94, v124, v183
	v_add_f32_e32 v91, v91, v184
	v_add_f32_e32 v95, v95, v185
	v_mul_f32_e32 v133, v95, v129
	v_mul_f32_e32 v185, v91, v129
	v_fma_f32 v184, v91, v128, -v133
	v_fma_f32 v185, v95, v128, v185
	v_mul_f32_e32 v132, v40, v101
	v_mul_f32_e32 v40, v40, v100
	v_fma_f32 v40, -v44, v101, v40
	v_fma_f32 v44, v44, v100, v132
	v_mul_f32_e32 v133, v41, v105
	v_mul_f32_e32 v41, v41, v104
	v_fma_f32 v41, -v45, v105, v41
	v_fma_f32 v45, v45, v104, v133
	v_mul_f32_e32 v132, v42, v109
	v_mul_f32_e32 v42, v42, v108
	v_fma_f32 v42, -v46, v109, v42
	v_fma_f32 v46, v46, v108, v132
	v_mul_f32_e32 v133, v43, v113
	v_mul_f32_e32 v43, v43, v112
	v_fma_f32 v43, -v47, v113, v43
	v_fma_f32 v47, v47, v112, v133
	v_add_f32_dpp v40, v40, v40 row_shr:1 row_mask:0xf bank_mask:0xf bound_ctrl:1
	v_add_f32_dpp v41, v41, v41 row_shr:1 row_mask:0xf bank_mask:0xf bound_ctrl:1
	v_add_f32_dpp v42, v42, v42 row_shr:1 row_mask:0xf bank_mask:0xf bound_ctrl:1
	v_add_f32_dpp v43, v43, v43 row_shr:1 row_mask:0xf bank_mask:0xf bound_ctrl:1
	v_add_f32_dpp v44, v44, v44 row_shr:1 row_mask:0xf bank_mask:0xf bound_ctrl:1
	v_add_f32_dpp v45, v45, v45 row_shr:1 row_mask:0xf bank_mask:0xf bound_ctrl:1
	v_add_f32_dpp v46, v46, v46 row_shr:1 row_mask:0xf bank_mask:0xf bound_ctrl:1
	v_add_f32_dpp v47, v47, v47 row_shr:1 row_mask:0xf bank_mask:0xf bound_ctrl:1
	v_add_f32_dpp v40, v40, v40 row_shr:2 row_mask:0xf bank_mask:0xf bound_ctrl:1
	v_add_f32_dpp v41, v41, v41 row_shr:2 row_mask:0xf bank_mask:0xf bound_ctrl:1
	v_add_f32_dpp v42, v42, v42 row_shr:2 row_mask:0xf bank_mask:0xf bound_ctrl:1
	v_add_f32_dpp v43, v43, v43 row_shr:2 row_mask:0xf bank_mask:0xf bound_ctrl:1
	v_add_f32_dpp v44, v44, v44 row_shr:2 row_mask:0xf bank_mask:0xf bound_ctrl:1
	v_add_f32_dpp v45, v45, v45 row_shr:2 row_mask:0xf bank_mask:0xf bound_ctrl:1
	v_add_f32_dpp v46, v46, v46 row_shr:2 row_mask:0xf bank_mask:0xf bound_ctrl:1
	v_add_f32_dpp v47, v47, v47 row_shr:2 row_mask:0xf bank_mask:0xf bound_ctrl:1
	v_add_f32_dpp v40, v40, v40 row_shr:4 row_mask:0xf bank_mask:0xf bound_ctrl:1
	v_add_f32_dpp v41, v41, v41 row_shr:4 row_mask:0xf bank_mask:0xf bound_ctrl:1
	v_add_f32_dpp v42, v42, v42 row_shr:4 row_mask:0xf bank_mask:0xf bound_ctrl:1
	v_add_f32_dpp v43, v43, v43 row_shr:4 row_mask:0xf bank_mask:0xf bound_ctrl:1
	v_add_f32_dpp v44, v44, v44 row_shr:4 row_mask:0xf bank_mask:0xf bound_ctrl:1
	v_add_f32_dpp v45, v45, v45 row_shr:4 row_mask:0xf bank_mask:0xf bound_ctrl:1
	v_add_f32_dpp v46, v46, v46 row_shr:4 row_mask:0xf bank_mask:0xf bound_ctrl:1
	v_add_f32_dpp v47, v47, v47 row_shr:4 row_mask:0xf bank_mask:0xf bound_ctrl:1
	v_add_f32_dpp v40, v40, v40 row_shr:8 row_mask:0xf bank_mask:0xf bound_ctrl:1
	v_add_f32_dpp v41, v41, v41 row_shr:8 row_mask:0xf bank_mask:0xf bound_ctrl:1
	v_add_f32_dpp v42, v42, v42 row_shr:8 row_mask:0xf bank_mask:0xf bound_ctrl:1
	v_add_f32_dpp v43, v43, v43 row_shr:8 row_mask:0xf bank_mask:0xf bound_ctrl:1
	v_add_f32_dpp v44, v44, v44 row_shr:8 row_mask:0xf bank_mask:0xf bound_ctrl:1
	v_add_f32_dpp v45, v45, v45 row_shr:8 row_mask:0xf bank_mask:0xf bound_ctrl:1
	v_add_f32_dpp v46, v46, v46 row_shr:8 row_mask:0xf bank_mask:0xf bound_ctrl:1
	v_add_f32_dpp v47, v47, v47 row_shr:8 row_mask:0xf bank_mask:0xf bound_ctrl:1
	v_mov_b32_dpp v88, v40 row_newbcast:15 row_mask:0xf bank_mask:0xf
	v_mov_b32_dpp v89, v41 row_newbcast:15 row_mask:0xf bank_mask:0xf
	v_mov_b32_dpp v90, v42 row_newbcast:15 row_mask:0xf bank_mask:0xf
	v_mov_b32_dpp v91, v43 row_newbcast:15 row_mask:0xf bank_mask:0xf
	v_mov_b32_dpp v92, v44 row_newbcast:15 row_mask:0xf bank_mask:0xf
	v_mov_b32_dpp v93, v45 row_newbcast:15 row_mask:0xf bank_mask:0xf
	v_mov_b32_dpp v94, v46 row_newbcast:15 row_mask:0xf bank_mask:0xf
	v_mov_b32_dpp v95, v47 row_newbcast:15 row_mask:0xf bank_mask:0xf
	v_add_f32_e32 v40, v40, v178
	v_add_f32_e32 v44, v44, v179
	v_add_f32_e32 v41, v41, v180
	v_add_f32_e32 v45, v45, v181
	v_add_f32_e32 v42, v42, v182
	v_add_f32_e32 v46, v46, v183
	v_add_f32_e32 v43, v43, v184
	v_add_f32_e32 v47, v47, v185
	v_mul_f32_e32 v132, v40, v103
	v_mul_f32_e32 v40, v40, v102
	v_fma_f32 v40, -v44, v103, v40
	v_fma_f32 v44, v44, v102, v132
	v_mul_f32_e32 v133, v41, v107
	v_mul_f32_e32 v41, v41, v106
	v_fma_f32 v41, -v45, v107, v41
	v_fma_f32 v45, v45, v106, v133
	v_mul_f32_e32 v132, v42, v111
	v_mul_f32_e32 v42, v42, v110
	v_fma_f32 v42, -v46, v111, v42
	v_fma_f32 v46, v46, v110, v132
	v_mul_f32_e32 v133, v43, v115
	v_mul_f32_e32 v43, v43, v114
	v_fma_f32 v43, -v47, v115, v43
	v_fma_f32 v47, v47, v114, v133
	v_add_f32_e32 v88, v88, v178
	v_add_f32_e32 v92, v92, v179
	v_mul_f32_e32 v132, v92, v117
	v_mul_f32_e32 v179, v88, v117
	v_fma_f32 v178, v88, v116, -v132
	v_fma_f32 v179, v92, v116, v179
	v_add_f32_e32 v89, v89, v180
	v_add_f32_e32 v93, v93, v181
	v_mul_f32_e32 v133, v93, v121
	v_mul_f32_e32 v181, v89, v121
	v_fma_f32 v180, v89, v120, -v133
	v_fma_f32 v181, v93, v120, v181
	v_add_f32_e32 v90, v90, v182
	v_add_f32_e32 v94, v94, v183
	v_mul_f32_e32 v132, v94, v125
	v_mul_f32_e32 v183, v90, v125
	v_fma_f32 v182, v90, v124, -v132
	v_fma_f32 v183, v94, v124, v183
	v_add_f32_e32 v91, v91, v184
	v_add_f32_e32 v95, v95, v185
	v_mul_f32_e32 v133, v95, v129
	v_mul_f32_e32 v185, v91, v129
	v_fma_f32 v184, v91, v128, -v133
	v_fma_f32 v185, v95, v128, v185
	v_mul_f32_e32 v132, v48, v101
	v_mul_f32_e32 v48, v48, v100
	v_fma_f32 v48, -v52, v101, v48
	v_fma_f32 v52, v52, v100, v132
	v_mul_f32_e32 v133, v49, v105
	v_mul_f32_e32 v49, v49, v104
	v_fma_f32 v49, -v53, v105, v49
	v_fma_f32 v53, v53, v104, v133
	v_mul_f32_e32 v132, v50, v109
	v_mul_f32_e32 v50, v50, v108
	v_fma_f32 v50, -v54, v109, v50
	v_fma_f32 v54, v54, v108, v132
	v_mul_f32_e32 v133, v51, v113
	v_mul_f32_e32 v51, v51, v112
	v_fma_f32 v51, -v55, v113, v51
	v_fma_f32 v55, v55, v112, v133
	v_add_f32_dpp v48, v48, v48 row_shr:1 row_mask:0xf bank_mask:0xf bound_ctrl:1
	v_add_f32_dpp v49, v49, v49 row_shr:1 row_mask:0xf bank_mask:0xf bound_ctrl:1
	v_add_f32_dpp v50, v50, v50 row_shr:1 row_mask:0xf bank_mask:0xf bound_ctrl:1
	v_add_f32_dpp v51, v51, v51 row_shr:1 row_mask:0xf bank_mask:0xf bound_ctrl:1
	v_add_f32_dpp v52, v52, v52 row_shr:1 row_mask:0xf bank_mask:0xf bound_ctrl:1
	v_add_f32_dpp v53, v53, v53 row_shr:1 row_mask:0xf bank_mask:0xf bound_ctrl:1
	v_add_f32_dpp v54, v54, v54 row_shr:1 row_mask:0xf bank_mask:0xf bound_ctrl:1
	v_add_f32_dpp v55, v55, v55 row_shr:1 row_mask:0xf bank_mask:0xf bound_ctrl:1
	v_add_f32_dpp v48, v48, v48 row_shr:2 row_mask:0xf bank_mask:0xf bound_ctrl:1
	v_add_f32_dpp v49, v49, v49 row_shr:2 row_mask:0xf bank_mask:0xf bound_ctrl:1
	v_add_f32_dpp v50, v50, v50 row_shr:2 row_mask:0xf bank_mask:0xf bound_ctrl:1
	v_add_f32_dpp v51, v51, v51 row_shr:2 row_mask:0xf bank_mask:0xf bound_ctrl:1
	v_add_f32_dpp v52, v52, v52 row_shr:2 row_mask:0xf bank_mask:0xf bound_ctrl:1
	v_add_f32_dpp v53, v53, v53 row_shr:2 row_mask:0xf bank_mask:0xf bound_ctrl:1
	v_add_f32_dpp v54, v54, v54 row_shr:2 row_mask:0xf bank_mask:0xf bound_ctrl:1
	v_add_f32_dpp v55, v55, v55 row_shr:2 row_mask:0xf bank_mask:0xf bound_ctrl:1
	v_add_f32_dpp v48, v48, v48 row_shr:4 row_mask:0xf bank_mask:0xf bound_ctrl:1
	v_add_f32_dpp v49, v49, v49 row_shr:4 row_mask:0xf bank_mask:0xf bound_ctrl:1
	v_add_f32_dpp v50, v50, v50 row_shr:4 row_mask:0xf bank_mask:0xf bound_ctrl:1
	v_add_f32_dpp v51, v51, v51 row_shr:4 row_mask:0xf bank_mask:0xf bound_ctrl:1
	v_add_f32_dpp v52, v52, v52 row_shr:4 row_mask:0xf bank_mask:0xf bound_ctrl:1
	v_add_f32_dpp v53, v53, v53 row_shr:4 row_mask:0xf bank_mask:0xf bound_ctrl:1
	v_add_f32_dpp v54, v54, v54 row_shr:4 row_mask:0xf bank_mask:0xf bound_ctrl:1
	v_add_f32_dpp v55, v55, v55 row_shr:4 row_mask:0xf bank_mask:0xf bound_ctrl:1
	v_add_f32_dpp v48, v48, v48 row_shr:8 row_mask:0xf bank_mask:0xf bound_ctrl:1
	v_add_f32_dpp v49, v49, v49 row_shr:8 row_mask:0xf bank_mask:0xf bound_ctrl:1
	v_add_f32_dpp v50, v50, v50 row_shr:8 row_mask:0xf bank_mask:0xf bound_ctrl:1
	v_add_f32_dpp v51, v51, v51 row_shr:8 row_mask:0xf bank_mask:0xf bound_ctrl:1
	v_add_f32_dpp v52, v52, v52 row_shr:8 row_mask:0xf bank_mask:0xf bound_ctrl:1
	v_add_f32_dpp v53, v53, v53 row_shr:8 row_mask:0xf bank_mask:0xf bound_ctrl:1
	v_add_f32_dpp v54, v54, v54 row_shr:8 row_mask:0xf bank_mask:0xf bound_ctrl:1
	v_add_f32_dpp v55, v55, v55 row_shr:8 row_mask:0xf bank_mask:0xf bound_ctrl:1
	v_mov_b32_dpp v88, v48 row_newbcast:15 row_mask:0xf bank_mask:0xf
	v_mov_b32_dpp v89, v49 row_newbcast:15 row_mask:0xf bank_mask:0xf
	v_mov_b32_dpp v90, v50 row_newbcast:15 row_mask:0xf bank_mask:0xf
	v_mov_b32_dpp v91, v51 row_newbcast:15 row_mask:0xf bank_mask:0xf
	v_mov_b32_dpp v92, v52 row_newbcast:15 row_mask:0xf bank_mask:0xf
	v_mov_b32_dpp v93, v53 row_newbcast:15 row_mask:0xf bank_mask:0xf
	v_mov_b32_dpp v94, v54 row_newbcast:15 row_mask:0xf bank_mask:0xf
	v_mov_b32_dpp v95, v55 row_newbcast:15 row_mask:0xf bank_mask:0xf
	v_add_f32_e32 v48, v48, v178
	v_add_f32_e32 v52, v52, v179
	v_add_f32_e32 v49, v49, v180
	v_add_f32_e32 v53, v53, v181
	v_add_f32_e32 v50, v50, v182
	v_add_f32_e32 v54, v54, v183
	v_add_f32_e32 v51, v51, v184
	v_add_f32_e32 v55, v55, v185
	v_mul_f32_e32 v132, v48, v103
	v_mul_f32_e32 v48, v48, v102
	v_fma_f32 v48, -v52, v103, v48
	v_fma_f32 v52, v52, v102, v132
	v_mul_f32_e32 v133, v49, v107
	v_mul_f32_e32 v49, v49, v106
	v_fma_f32 v49, -v53, v107, v49
	v_fma_f32 v53, v53, v106, v133
	v_mul_f32_e32 v132, v50, v111
	v_mul_f32_e32 v50, v50, v110
	v_fma_f32 v50, -v54, v111, v50
	v_fma_f32 v54, v54, v110, v132
	v_mul_f32_e32 v133, v51, v115
	v_mul_f32_e32 v51, v51, v114
	v_fma_f32 v51, -v55, v115, v51
	v_fma_f32 v55, v55, v114, v133
	v_add_f32_e32 v88, v88, v178
	v_add_f32_e32 v92, v92, v179
	v_mul_f32_e32 v132, v92, v117
	v_mul_f32_e32 v179, v88, v117
	v_fma_f32 v178, v88, v116, -v132
	v_fma_f32 v179, v92, v116, v179
	v_add_f32_e32 v89, v89, v180
	v_add_f32_e32 v93, v93, v181
	v_mul_f32_e32 v133, v93, v121
	v_mul_f32_e32 v181, v89, v121
	v_fma_f32 v180, v89, v120, -v133
	v_fma_f32 v181, v93, v120, v181
	v_add_f32_e32 v90, v90, v182
	v_add_f32_e32 v94, v94, v183
	v_mul_f32_e32 v132, v94, v125
	v_mul_f32_e32 v183, v90, v125
	v_fma_f32 v182, v90, v124, -v132
	v_fma_f32 v183, v94, v124, v183
	v_add_f32_e32 v91, v91, v184
	v_add_f32_e32 v95, v95, v185
	v_mul_f32_e32 v133, v95, v129
	v_mul_f32_e32 v185, v91, v129
	v_fma_f32 v184, v91, v128, -v133
	v_fma_f32 v185, v95, v128, v185
	v_mul_f32_e32 v132, v56, v101
	v_mul_f32_e32 v56, v56, v100
	v_fma_f32 v56, -v60, v101, v56
	v_fma_f32 v60, v60, v100, v132
	v_mul_f32_e32 v133, v57, v105
	v_mul_f32_e32 v57, v57, v104
	v_fma_f32 v57, -v61, v105, v57
	v_fma_f32 v61, v61, v104, v133
	v_mul_f32_e32 v132, v58, v109
	v_mul_f32_e32 v58, v58, v108
	v_fma_f32 v58, -v62, v109, v58
	v_fma_f32 v62, v62, v108, v132
	v_mul_f32_e32 v133, v59, v113
	v_mul_f32_e32 v59, v59, v112
	v_fma_f32 v59, -v63, v113, v59
	v_fma_f32 v63, v63, v112, v133
	v_add_f32_dpp v56, v56, v56 row_shr:1 row_mask:0xf bank_mask:0xf bound_ctrl:1
	v_add_f32_dpp v57, v57, v57 row_shr:1 row_mask:0xf bank_mask:0xf bound_ctrl:1
	v_add_f32_dpp v58, v58, v58 row_shr:1 row_mask:0xf bank_mask:0xf bound_ctrl:1
	v_add_f32_dpp v59, v59, v59 row_shr:1 row_mask:0xf bank_mask:0xf bound_ctrl:1
	v_add_f32_dpp v60, v60, v60 row_shr:1 row_mask:0xf bank_mask:0xf bound_ctrl:1
	v_add_f32_dpp v61, v61, v61 row_shr:1 row_mask:0xf bank_mask:0xf bound_ctrl:1
	v_add_f32_dpp v62, v62, v62 row_shr:1 row_mask:0xf bank_mask:0xf bound_ctrl:1
	v_add_f32_dpp v63, v63, v63 row_shr:1 row_mask:0xf bank_mask:0xf bound_ctrl:1
	v_add_f32_dpp v56, v56, v56 row_shr:2 row_mask:0xf bank_mask:0xf bound_ctrl:1
	v_add_f32_dpp v57, v57, v57 row_shr:2 row_mask:0xf bank_mask:0xf bound_ctrl:1
	v_add_f32_dpp v58, v58, v58 row_shr:2 row_mask:0xf bank_mask:0xf bound_ctrl:1
	v_add_f32_dpp v59, v59, v59 row_shr:2 row_mask:0xf bank_mask:0xf bound_ctrl:1
	v_add_f32_dpp v60, v60, v60 row_shr:2 row_mask:0xf bank_mask:0xf bound_ctrl:1
	v_add_f32_dpp v61, v61, v61 row_shr:2 row_mask:0xf bank_mask:0xf bound_ctrl:1
	v_add_f32_dpp v62, v62, v62 row_shr:2 row_mask:0xf bank_mask:0xf bound_ctrl:1
	v_add_f32_dpp v63, v63, v63 row_shr:2 row_mask:0xf bank_mask:0xf bound_ctrl:1
	v_add_f32_dpp v56, v56, v56 row_shr:4 row_mask:0xf bank_mask:0xf bound_ctrl:1
	v_add_f32_dpp v57, v57, v57 row_shr:4 row_mask:0xf bank_mask:0xf bound_ctrl:1
	v_add_f32_dpp v58, v58, v58 row_shr:4 row_mask:0xf bank_mask:0xf bound_ctrl:1
	v_add_f32_dpp v59, v59, v59 row_shr:4 row_mask:0xf bank_mask:0xf bound_ctrl:1
	v_add_f32_dpp v60, v60, v60 row_shr:4 row_mask:0xf bank_mask:0xf bound_ctrl:1
	v_add_f32_dpp v61, v61, v61 row_shr:4 row_mask:0xf bank_mask:0xf bound_ctrl:1
	v_add_f32_dpp v62, v62, v62 row_shr:4 row_mask:0xf bank_mask:0xf bound_ctrl:1
	v_add_f32_dpp v63, v63, v63 row_shr:4 row_mask:0xf bank_mask:0xf bound_ctrl:1
	v_add_f32_dpp v56, v56, v56 row_shr:8 row_mask:0xf bank_mask:0xf bound_ctrl:1
	v_add_f32_dpp v57, v57, v57 row_shr:8 row_mask:0xf bank_mask:0xf bound_ctrl:1
	v_add_f32_dpp v58, v58, v58 row_shr:8 row_mask:0xf bank_mask:0xf bound_ctrl:1
	v_add_f32_dpp v59, v59, v59 row_shr:8 row_mask:0xf bank_mask:0xf bound_ctrl:1
	v_add_f32_dpp v60, v60, v60 row_shr:8 row_mask:0xf bank_mask:0xf bound_ctrl:1
	v_add_f32_dpp v61, v61, v61 row_shr:8 row_mask:0xf bank_mask:0xf bound_ctrl:1
	v_add_f32_dpp v62, v62, v62 row_shr:8 row_mask:0xf bank_mask:0xf bound_ctrl:1
	v_add_f32_dpp v63, v63, v63 row_shr:8 row_mask:0xf bank_mask:0xf bound_ctrl:1
	v_mov_b32_dpp v88, v56 row_newbcast:15 row_mask:0xf bank_mask:0xf
	v_mov_b32_dpp v89, v57 row_newbcast:15 row_mask:0xf bank_mask:0xf
	v_mov_b32_dpp v90, v58 row_newbcast:15 row_mask:0xf bank_mask:0xf
	v_mov_b32_dpp v91, v59 row_newbcast:15 row_mask:0xf bank_mask:0xf
	v_mov_b32_dpp v92, v60 row_newbcast:15 row_mask:0xf bank_mask:0xf
	v_mov_b32_dpp v93, v61 row_newbcast:15 row_mask:0xf bank_mask:0xf
	v_mov_b32_dpp v94, v62 row_newbcast:15 row_mask:0xf bank_mask:0xf
	v_mov_b32_dpp v95, v63 row_newbcast:15 row_mask:0xf bank_mask:0xf
	v_add_f32_e32 v56, v56, v178
	v_add_f32_e32 v60, v60, v179
	v_add_f32_e32 v57, v57, v180
	v_add_f32_e32 v61, v61, v181
	v_add_f32_e32 v58, v58, v182
	v_add_f32_e32 v62, v62, v183
	v_add_f32_e32 v59, v59, v184
	v_add_f32_e32 v63, v63, v185
	v_mul_f32_e32 v132, v56, v103
	v_mul_f32_e32 v56, v56, v102
	v_fma_f32 v56, -v60, v103, v56
	v_fma_f32 v60, v60, v102, v132
	v_mul_f32_e32 v133, v57, v107
	v_mul_f32_e32 v57, v57, v106
	v_fma_f32 v57, -v61, v107, v57
	v_fma_f32 v61, v61, v106, v133
	v_mul_f32_e32 v132, v58, v111
	v_mul_f32_e32 v58, v58, v110
	v_fma_f32 v58, -v62, v111, v58
	v_fma_f32 v62, v62, v110, v132
	v_mul_f32_e32 v133, v59, v115
	v_mul_f32_e32 v59, v59, v114
	v_fma_f32 v59, -v63, v115, v59
	v_fma_f32 v63, v63, v114, v133
	v_add_f32_e32 v88, v88, v178
	v_add_f32_e32 v92, v92, v179
	v_mul_f32_e32 v132, v92, v117
	v_mul_f32_e32 v179, v88, v117
	v_fma_f32 v178, v88, v116, -v132
	v_fma_f32 v179, v92, v116, v179
	v_add_f32_e32 v89, v89, v180
	v_add_f32_e32 v93, v93, v181
	v_mul_f32_e32 v133, v93, v121
	v_mul_f32_e32 v181, v89, v121
	v_fma_f32 v180, v89, v120, -v133
	v_fma_f32 v181, v93, v120, v181
	v_add_f32_e32 v90, v90, v182
	v_add_f32_e32 v94, v94, v183
	v_mul_f32_e32 v132, v94, v125
	v_mul_f32_e32 v183, v90, v125
	v_fma_f32 v182, v90, v124, -v132
	v_fma_f32 v183, v94, v124, v183
	v_add_f32_e32 v91, v91, v184
	v_add_f32_e32 v95, v95, v185
	v_mul_f32_e32 v133, v95, v129
	v_mul_f32_e32 v185, v91, v129
	v_fma_f32 v184, v91, v128, -v133
	v_fma_f32 v185, v95, v128, v185
	s_waitcnt vmcnt(14)
	v_cvt_pk_bf16_f32 v80, v80, v81
	v_cvt_pk_bf16_f32 v81, v82, v83
	v_cvt_pk_bf16_f32 v82, -v84, -v85
	v_cvt_pk_bf16_f32 v83, -v86, -v87
	v_cvt_pk_bf16_f32 v96, v32, v33
	v_cvt_pk_bf16_f32 v97, v34, v35
	v_cvt_pk_bf16_f32 v98, v36, v37
	v_cvt_pk_bf16_f32 v99, v38, v39
	s_nop 1
	v_mfma_f32_16x16x32_bf16 v[16:19], v[80:83], v[96:99], v[16:19]
	v_cvt_pk_bf16_f32 v96, v40, v41
	v_cvt_pk_bf16_f32 v97, v42, v43
	v_cvt_pk_bf16_f32 v98, v44, v45
	v_cvt_pk_bf16_f32 v99, v46, v47
	s_nop 1
	v_mfma_f32_16x16x32_bf16 v[20:23], v[80:83], v[96:99], v[20:23]
	v_cvt_pk_bf16_f32 v96, v48, v49
	v_cvt_pk_bf16_f32 v97, v50, v51
	v_cvt_pk_bf16_f32 v98, v52, v53
	v_cvt_pk_bf16_f32 v99, v54, v55
	s_nop 1
	v_mfma_f32_16x16x32_bf16 v[24:27], v[80:83], v[96:99], v[24:27]
	v_cvt_pk_bf16_f32 v96, v56, v57
	v_cvt_pk_bf16_f32 v97, v58, v59
	v_cvt_pk_bf16_f32 v98, v60, v61
	v_cvt_pk_bf16_f32 v99, v62, v63
	s_nop 1
	v_mfma_f32_16x16x32_bf16 v[28:31], v[80:83], v[96:99], v[28:31]
	s_waitcnt vmcnt(10)
	v_cvt_pk_bf16_f32 v64, v64, v65
	v_cvt_pk_bf16_f32 v65, v66, v67
	v_cvt_pk_bf16_f32 v66, v68, v69
	v_cvt_pk_bf16_f32 v67, v70, v71
	v_cvt_pk_bf16_f32 v72, v72, v73
	v_cvt_pk_bf16_f32 v73, v74, v75
	v_cvt_pk_bf16_f32 v74, v76, v77
	v_cvt_pk_bf16_f32 v75, v78, v79
	global_load_dwordx4 v[80:83], v136, s[38:39]
	global_load_dwordx4 v[84:87], v136, s[40:41]
	s_add_u32 s38, s38, 0x40
	s_addc_u32 s39, s39, 0
	s_add_u32 s40, s40, 0x40
	s_addc_u32 s41, s41, 0
	s_nop 0
	v_mfma_f32_16x16x32_bf16 v[32:35], v[64:67], v[0:3], 0
	v_mfma_f32_16x16x32_bf16 v[36:39], v[72:75], v[0:3], 0
	v_mfma_f32_16x16x32_bf16 v[40:43], v[64:67], v[4:7], 0
	v_mfma_f32_16x16x32_bf16 v[44:47], v[72:75], v[4:7], 0
	v_mfma_f32_16x16x32_bf16 v[48:51], v[64:67], v[8:11], 0
	v_mfma_f32_16x16x32_bf16 v[52:55], v[72:75], v[8:11], 0
	v_mfma_f32_16x16x32_bf16 v[56:59], v[64:67], v[12:15], 0
	v_mfma_f32_16x16x32_bf16 v[60:63], v[72:75], v[12:15], 0
	s_mov_b32 exec_hi, 0
	global_load_dwordx4 v[64:67], v135, s[20:21]
	global_load_dwordx4 v[68:71], v135, s[20:21] offset:16
	global_load_dwordx4 v[72:75], v135, s[22:23]
	global_load_dwordx4 v[76:79], v135, s[22:23] offset:16
	s_mov_b64 exec, -1
	global_load_dwordx4 v[100:103], v134, s[42:43] offset:0
	global_load_dwordx4 v[104:107], v134, s[42:43] offset:16
	global_load_dwordx4 v[108:111], v134, s[42:43] offset:32
	global_load_dwordx4 v[112:115], v134, s[42:43] offset:48
	global_load_dwordx4 v[116:119], v134, s[42:43] offset:64
	global_load_dwordx4 v[120:123], v134, s[42:43] offset:80
	global_load_dwordx4 v[124:127], v134, s[42:43] offset:96
	global_load_dwordx4 v[128:131], v134, s[42:43] offset:112
	global_load_dwordx4 v[178:181], v206, s[44:45]
	global_load_dwordx4 v[182:185], v206, s[44:45] offset:16
	s_waitcnt vmcnt(16)
	v_mul_f32_e32 v132, v171, v157
	v_mul_f32_e32 v133, v170, v157
	v_fma_f32 v170, v170, v156, -v132
	v_fma_f32 v171, v171, v156, v133
	v_mul_f32_e32 v132, v173, v161
	v_mul_f32_e32 v133, v172, v161
	v_fma_f32 v172, v172, v160, -v132
	v_fma_f32 v173, v173, v160, v133
	v_mul_f32_e32 v132, v175, v165
	v_mul_f32_e32 v133, v174, v165
	v_fma_f32 v174, v174, v164, -v132
	v_fma_f32 v175, v175, v164, v133
	v_mul_f32_e32 v132, v177, v169
	v_mul_f32_e32 v133, v176, v169
	v_fma_f32 v176, v176, v168, -v132
	v_fma_f32 v177, v177, v168, v133
	v_mul_f32_e32 v132, v32, v139
	v_mul_f32_e32 v32, v32, v138
	v_fma_f32 v32, -v36, v139, v32
	v_fma_f32 v36, v36, v138, v132
	v_mul_f32_e32 v133, v33, v143
	v_mul_f32_e32 v33, v33, v142
	v_fma_f32 v33, -v37, v143, v33
	v_fma_f32 v37, v37, v142, v133
	v_mul_f32_e32 v132, v34, v147
	v_mul_f32_e32 v34, v34, v146
	v_fma_f32 v34, -v38, v147, v34
	v_fma_f32 v38, v38, v146, v132
	v_mul_f32_e32 v133, v35, v151
	v_mul_f32_e32 v35, v35, v150
	v_fma_f32 v35, -v39, v151, v35
	v_fma_f32 v39, v39, v150, v133
	v_add_f32_dpp v32, v32, v32 row_shr:1 row_mask:0xf bank_mask:0xf bound_ctrl:1
	v_add_f32_dpp v33, v33, v33 row_shr:1 row_mask:0xf bank_mask:0xf bound_ctrl:1
	v_add_f32_dpp v34, v34, v34 row_shr:1 row_mask:0xf bank_mask:0xf bound_ctrl:1
	v_add_f32_dpp v35, v35, v35 row_shr:1 row_mask:0xf bank_mask:0xf bound_ctrl:1
	v_add_f32_dpp v36, v36, v36 row_shr:1 row_mask:0xf bank_mask:0xf bound_ctrl:1
	v_add_f32_dpp v37, v37, v37 row_shr:1 row_mask:0xf bank_mask:0xf bound_ctrl:1
	v_add_f32_dpp v38, v38, v38 row_shr:1 row_mask:0xf bank_mask:0xf bound_ctrl:1
	v_add_f32_dpp v39, v39, v39 row_shr:1 row_mask:0xf bank_mask:0xf bound_ctrl:1
	v_add_f32_dpp v32, v32, v32 row_shr:2 row_mask:0xf bank_mask:0xf bound_ctrl:1
	v_add_f32_dpp v33, v33, v33 row_shr:2 row_mask:0xf bank_mask:0xf bound_ctrl:1
	v_add_f32_dpp v34, v34, v34 row_shr:2 row_mask:0xf bank_mask:0xf bound_ctrl:1
	v_add_f32_dpp v35, v35, v35 row_shr:2 row_mask:0xf bank_mask:0xf bound_ctrl:1
	v_add_f32_dpp v36, v36, v36 row_shr:2 row_mask:0xf bank_mask:0xf bound_ctrl:1
	v_add_f32_dpp v37, v37, v37 row_shr:2 row_mask:0xf bank_mask:0xf bound_ctrl:1
	v_add_f32_dpp v38, v38, v38 row_shr:2 row_mask:0xf bank_mask:0xf bound_ctrl:1
	v_add_f32_dpp v39, v39, v39 row_shr:2 row_mask:0xf bank_mask:0xf bound_ctrl:1
	v_add_f32_dpp v32, v32, v32 row_shr:4 row_mask:0xf bank_mask:0xf bound_ctrl:1
	v_add_f32_dpp v33, v33, v33 row_shr:4 row_mask:0xf bank_mask:0xf bound_ctrl:1
	v_add_f32_dpp v34, v34, v34 row_shr:4 row_mask:0xf bank_mask:0xf bound_ctrl:1
	v_add_f32_dpp v35, v35, v35 row_shr:4 row_mask:0xf bank_mask:0xf bound_ctrl:1
	v_add_f32_dpp v36, v36, v36 row_shr:4 row_mask:0xf bank_mask:0xf bound_ctrl:1
	v_add_f32_dpp v37, v37, v37 row_shr:4 row_mask:0xf bank_mask:0xf bound_ctrl:1
	v_add_f32_dpp v38, v38, v38 row_shr:4 row_mask:0xf bank_mask:0xf bound_ctrl:1
	v_add_f32_dpp v39, v39, v39 row_shr:4 row_mask:0xf bank_mask:0xf bound_ctrl:1
	v_add_f32_dpp v32, v32, v32 row_shr:8 row_mask:0xf bank_mask:0xf bound_ctrl:1
	v_add_f32_dpp v33, v33, v33 row_shr:8 row_mask:0xf bank_mask:0xf bound_ctrl:1
	v_add_f32_dpp v34, v34, v34 row_shr:8 row_mask:0xf bank_mask:0xf bound_ctrl:1
	v_add_f32_dpp v35, v35, v35 row_shr:8 row_mask:0xf bank_mask:0xf bound_ctrl:1
	v_add_f32_dpp v36, v36, v36 row_shr:8 row_mask:0xf bank_mask:0xf bound_ctrl:1
	v_add_f32_dpp v37, v37, v37 row_shr:8 row_mask:0xf bank_mask:0xf bound_ctrl:1
	v_add_f32_dpp v38, v38, v38 row_shr:8 row_mask:0xf bank_mask:0xf bound_ctrl:1
	v_add_f32_dpp v39, v39, v39 row_shr:8 row_mask:0xf bank_mask:0xf bound_ctrl:1
	v_mov_b32_dpp v88, v32 row_newbcast:15 row_mask:0xf bank_mask:0xf
	v_mov_b32_dpp v89, v33 row_newbcast:15 row_mask:0xf bank_mask:0xf
	v_mov_b32_dpp v90, v34 row_newbcast:15 row_mask:0xf bank_mask:0xf
	v_mov_b32_dpp v91, v35 row_newbcast:15 row_mask:0xf bank_mask:0xf
	v_mov_b32_dpp v92, v36 row_newbcast:15 row_mask:0xf bank_mask:0xf
	v_mov_b32_dpp v93, v37 row_newbcast:15 row_mask:0xf bank_mask:0xf
	v_mov_b32_dpp v94, v38 row_newbcast:15 row_mask:0xf bank_mask:0xf
	v_mov_b32_dpp v95, v39 row_newbcast:15 row_mask:0xf bank_mask:0xf
	v_add_f32_e32 v32, v32, v170
	v_add_f32_e32 v36, v36, v171
	v_add_f32_e32 v33, v33, v172
	v_add_f32_e32 v37, v37, v173
	v_add_f32_e32 v34, v34, v174
	v_add_f32_e32 v38, v38, v175
	v_add_f32_e32 v35, v35, v176
	v_add_f32_e32 v39, v39, v177
	v_mul_f32_e32 v132, v32, v141
	v_mul_f32_e32 v32, v32, v140
	v_fma_f32 v32, -v36, v141, v32
	v_fma_f32 v36, v36, v140, v132
	v_mul_f32_e32 v133, v33, v145
	v_mul_f32_e32 v33, v33, v144
	v_fma_f32 v33, -v37, v145, v33
	v_fma_f32 v37, v37, v144, v133
	v_mul_f32_e32 v132, v34, v149
	v_mul_f32_e32 v34, v34, v148
	v_fma_f32 v34, -v38, v149, v34
	v_fma_f32 v38, v38, v148, v132
	v_mul_f32_e32 v133, v35, v153
	v_mul_f32_e32 v35, v35, v152
	v_fma_f32 v35, -v39, v153, v35
	v_fma_f32 v39, v39, v152, v133
	v_add_f32_e32 v88, v88, v170
	v_add_f32_e32 v92, v92, v171
	v_mul_f32_e32 v132, v92, v155
	v_mul_f32_e32 v171, v88, v155
	v_fma_f32 v170, v88, v154, -v132
	v_fma_f32 v171, v92, v154, v171
	v_add_f32_e32 v89, v89, v172
	v_add_f32_e32 v93, v93, v173
	v_mul_f32_e32 v133, v93, v159
	v_mul_f32_e32 v173, v89, v159
	v_fma_f32 v172, v89, v158, -v133
	v_fma_f32 v173, v93, v158, v173
	v_add_f32_e32 v90, v90, v174
	v_add_f32_e32 v94, v94, v175
	v_mul_f32_e32 v132, v94, v163
	v_mul_f32_e32 v175, v90, v163
	v_fma_f32 v174, v90, v162, -v132
	v_fma_f32 v175, v94, v162, v175
	v_add_f32_e32 v91, v91, v176
	v_add_f32_e32 v95, v95, v177
	v_mul_f32_e32 v133, v95, v167
	v_mul_f32_e32 v177, v91, v167
	v_fma_f32 v176, v91, v166, -v133
	v_fma_f32 v177, v95, v166, v177
	v_mul_f32_e32 v132, v40, v139
	v_mul_f32_e32 v40, v40, v138
	v_fma_f32 v40, -v44, v139, v40
	v_fma_f32 v44, v44, v138, v132
	v_mul_f32_e32 v133, v41, v143
	v_mul_f32_e32 v41, v41, v142
	v_fma_f32 v41, -v45, v143, v41
	v_fma_f32 v45, v45, v142, v133
	v_mul_f32_e32 v132, v42, v147
	v_mul_f32_e32 v42, v42, v146
	v_fma_f32 v42, -v46, v147, v42
	v_fma_f32 v46, v46, v146, v132
	v_mul_f32_e32 v133, v43, v151
	v_mul_f32_e32 v43, v43, v150
	v_fma_f32 v43, -v47, v151, v43
	v_fma_f32 v47, v47, v150, v133
	v_add_f32_dpp v40, v40, v40 row_shr:1 row_mask:0xf bank_mask:0xf bound_ctrl:1
	v_add_f32_dpp v41, v41, v41 row_shr:1 row_mask:0xf bank_mask:0xf bound_ctrl:1
	v_add_f32_dpp v42, v42, v42 row_shr:1 row_mask:0xf bank_mask:0xf bound_ctrl:1
	v_add_f32_dpp v43, v43, v43 row_shr:1 row_mask:0xf bank_mask:0xf bound_ctrl:1
	v_add_f32_dpp v44, v44, v44 row_shr:1 row_mask:0xf bank_mask:0xf bound_ctrl:1
	v_add_f32_dpp v45, v45, v45 row_shr:1 row_mask:0xf bank_mask:0xf bound_ctrl:1
	v_add_f32_dpp v46, v46, v46 row_shr:1 row_mask:0xf bank_mask:0xf bound_ctrl:1
	v_add_f32_dpp v47, v47, v47 row_shr:1 row_mask:0xf bank_mask:0xf bound_ctrl:1
	v_add_f32_dpp v40, v40, v40 row_shr:2 row_mask:0xf bank_mask:0xf bound_ctrl:1
	v_add_f32_dpp v41, v41, v41 row_shr:2 row_mask:0xf bank_mask:0xf bound_ctrl:1
	v_add_f32_dpp v42, v42, v42 row_shr:2 row_mask:0xf bank_mask:0xf bound_ctrl:1
	v_add_f32_dpp v43, v43, v43 row_shr:2 row_mask:0xf bank_mask:0xf bound_ctrl:1
	v_add_f32_dpp v44, v44, v44 row_shr:2 row_mask:0xf bank_mask:0xf bound_ctrl:1
	v_add_f32_dpp v45, v45, v45 row_shr:2 row_mask:0xf bank_mask:0xf bound_ctrl:1
	v_add_f32_dpp v46, v46, v46 row_shr:2 row_mask:0xf bank_mask:0xf bound_ctrl:1
	v_add_f32_dpp v47, v47, v47 row_shr:2 row_mask:0xf bank_mask:0xf bound_ctrl:1
	v_add_f32_dpp v40, v40, v40 row_shr:4 row_mask:0xf bank_mask:0xf bound_ctrl:1
	v_add_f32_dpp v41, v41, v41 row_shr:4 row_mask:0xf bank_mask:0xf bound_ctrl:1
	v_add_f32_dpp v42, v42, v42 row_shr:4 row_mask:0xf bank_mask:0xf bound_ctrl:1
	v_add_f32_dpp v43, v43, v43 row_shr:4 row_mask:0xf bank_mask:0xf bound_ctrl:1
	v_add_f32_dpp v44, v44, v44 row_shr:4 row_mask:0xf bank_mask:0xf bound_ctrl:1
	v_add_f32_dpp v45, v45, v45 row_shr:4 row_mask:0xf bank_mask:0xf bound_ctrl:1
	v_add_f32_dpp v46, v46, v46 row_shr:4 row_mask:0xf bank_mask:0xf bound_ctrl:1
	v_add_f32_dpp v47, v47, v47 row_shr:4 row_mask:0xf bank_mask:0xf bound_ctrl:1
	v_add_f32_dpp v40, v40, v40 row_shr:8 row_mask:0xf bank_mask:0xf bound_ctrl:1
	v_add_f32_dpp v41, v41, v41 row_shr:8 row_mask:0xf bank_mask:0xf bound_ctrl:1
	v_add_f32_dpp v42, v42, v42 row_shr:8 row_mask:0xf bank_mask:0xf bound_ctrl:1
	v_add_f32_dpp v43, v43, v43 row_shr:8 row_mask:0xf bank_mask:0xf bound_ctrl:1
	v_add_f32_dpp v44, v44, v44 row_shr:8 row_mask:0xf bank_mask:0xf bound_ctrl:1
	v_add_f32_dpp v45, v45, v45 row_shr:8 row_mask:0xf bank_mask:0xf bound_ctrl:1
	v_add_f32_dpp v46, v46, v46 row_shr:8 row_mask:0xf bank_mask:0xf bound_ctrl:1
	v_add_f32_dpp v47, v47, v47 row_shr:8 row_mask:0xf bank_mask:0xf bound_ctrl:1
	v_mov_b32_dpp v88, v40 row_newbcast:15 row_mask:0xf bank_mask:0xf
	v_mov_b32_dpp v89, v41 row_newbcast:15 row_mask:0xf bank_mask:0xf
	v_mov_b32_dpp v90, v42 row_newbcast:15 row_mask:0xf bank_mask:0xf
	v_mov_b32_dpp v91, v43 row_newbcast:15 row_mask:0xf bank_mask:0xf
	v_mov_b32_dpp v92, v44 row_newbcast:15 row_mask:0xf bank_mask:0xf
	v_mov_b32_dpp v93, v45 row_newbcast:15 row_mask:0xf bank_mask:0xf
	v_mov_b32_dpp v94, v46 row_newbcast:15 row_mask:0xf bank_mask:0xf
	v_mov_b32_dpp v95, v47 row_newbcast:15 row_mask:0xf bank_mask:0xf
	v_add_f32_e32 v40, v40, v170
	v_add_f32_e32 v44, v44, v171
	v_add_f32_e32 v41, v41, v172
	v_add_f32_e32 v45, v45, v173
	v_add_f32_e32 v42, v42, v174
	v_add_f32_e32 v46, v46, v175
	v_add_f32_e32 v43, v43, v176
	v_add_f32_e32 v47, v47, v177
	v_mul_f32_e32 v132, v40, v141
	v_mul_f32_e32 v40, v40, v140
	v_fma_f32 v40, -v44, v141, v40
	v_fma_f32 v44, v44, v140, v132
	v_mul_f32_e32 v133, v41, v145
	v_mul_f32_e32 v41, v41, v144
	v_fma_f32 v41, -v45, v145, v41
	v_fma_f32 v45, v45, v144, v133
	v_mul_f32_e32 v132, v42, v149
	v_mul_f32_e32 v42, v42, v148
	v_fma_f32 v42, -v46, v149, v42
	v_fma_f32 v46, v46, v148, v132
	v_mul_f32_e32 v133, v43, v153
	v_mul_f32_e32 v43, v43, v152
	v_fma_f32 v43, -v47, v153, v43
	v_fma_f32 v47, v47, v152, v133
	v_add_f32_e32 v88, v88, v170
	v_add_f32_e32 v92, v92, v171
	v_mul_f32_e32 v132, v92, v155
	v_mul_f32_e32 v171, v88, v155
	v_fma_f32 v170, v88, v154, -v132
	v_fma_f32 v171, v92, v154, v171
	v_add_f32_e32 v89, v89, v172
	v_add_f32_e32 v93, v93, v173
	v_mul_f32_e32 v133, v93, v159
	v_mul_f32_e32 v173, v89, v159
	v_fma_f32 v172, v89, v158, -v133
	v_fma_f32 v173, v93, v158, v173
	v_add_f32_e32 v90, v90, v174
	v_add_f32_e32 v94, v94, v175
	v_mul_f32_e32 v132, v94, v163
	v_mul_f32_e32 v175, v90, v163
	v_fma_f32 v174, v90, v162, -v132
	v_fma_f32 v175, v94, v162, v175
	v_add_f32_e32 v91, v91, v176
	v_add_f32_e32 v95, v95, v177
	v_mul_f32_e32 v133, v95, v167
	v_mul_f32_e32 v177, v91, v167
	v_fma_f32 v176, v91, v166, -v133
	v_fma_f32 v177, v95, v166, v177
	v_mul_f32_e32 v132, v48, v139
	v_mul_f32_e32 v48, v48, v138
	v_fma_f32 v48, -v52, v139, v48
	v_fma_f32 v52, v52, v138, v132
	v_mul_f32_e32 v133, v49, v143
	v_mul_f32_e32 v49, v49, v142
	v_fma_f32 v49, -v53, v143, v49
	v_fma_f32 v53, v53, v142, v133
	v_mul_f32_e32 v132, v50, v147
	v_mul_f32_e32 v50, v50, v146
	v_fma_f32 v50, -v54, v147, v50
	v_fma_f32 v54, v54, v146, v132
	v_mul_f32_e32 v133, v51, v151
	v_mul_f32_e32 v51, v51, v150
	v_fma_f32 v51, -v55, v151, v51
	v_fma_f32 v55, v55, v150, v133
	v_add_f32_dpp v48, v48, v48 row_shr:1 row_mask:0xf bank_mask:0xf bound_ctrl:1
	v_add_f32_dpp v49, v49, v49 row_shr:1 row_mask:0xf bank_mask:0xf bound_ctrl:1
	v_add_f32_dpp v50, v50, v50 row_shr:1 row_mask:0xf bank_mask:0xf bound_ctrl:1
	v_add_f32_dpp v51, v51, v51 row_shr:1 row_mask:0xf bank_mask:0xf bound_ctrl:1
	v_add_f32_dpp v52, v52, v52 row_shr:1 row_mask:0xf bank_mask:0xf bound_ctrl:1
	v_add_f32_dpp v53, v53, v53 row_shr:1 row_mask:0xf bank_mask:0xf bound_ctrl:1
	v_add_f32_dpp v54, v54, v54 row_shr:1 row_mask:0xf bank_mask:0xf bound_ctrl:1
	v_add_f32_dpp v55, v55, v55 row_shr:1 row_mask:0xf bank_mask:0xf bound_ctrl:1
	v_add_f32_dpp v48, v48, v48 row_shr:2 row_mask:0xf bank_mask:0xf bound_ctrl:1
	v_add_f32_dpp v49, v49, v49 row_shr:2 row_mask:0xf bank_mask:0xf bound_ctrl:1
	v_add_f32_dpp v50, v50, v50 row_shr:2 row_mask:0xf bank_mask:0xf bound_ctrl:1
	v_add_f32_dpp v51, v51, v51 row_shr:2 row_mask:0xf bank_mask:0xf bound_ctrl:1
	v_add_f32_dpp v52, v52, v52 row_shr:2 row_mask:0xf bank_mask:0xf bound_ctrl:1
	v_add_f32_dpp v53, v53, v53 row_shr:2 row_mask:0xf bank_mask:0xf bound_ctrl:1
	v_add_f32_dpp v54, v54, v54 row_shr:2 row_mask:0xf bank_mask:0xf bound_ctrl:1
	v_add_f32_dpp v55, v55, v55 row_shr:2 row_mask:0xf bank_mask:0xf bound_ctrl:1
	v_add_f32_dpp v48, v48, v48 row_shr:4 row_mask:0xf bank_mask:0xf bound_ctrl:1
	v_add_f32_dpp v49, v49, v49 row_shr:4 row_mask:0xf bank_mask:0xf bound_ctrl:1
	v_add_f32_dpp v50, v50, v50 row_shr:4 row_mask:0xf bank_mask:0xf bound_ctrl:1
	v_add_f32_dpp v51, v51, v51 row_shr:4 row_mask:0xf bank_mask:0xf bound_ctrl:1
	v_add_f32_dpp v52, v52, v52 row_shr:4 row_mask:0xf bank_mask:0xf bound_ctrl:1
	v_add_f32_dpp v53, v53, v53 row_shr:4 row_mask:0xf bank_mask:0xf bound_ctrl:1
	v_add_f32_dpp v54, v54, v54 row_shr:4 row_mask:0xf bank_mask:0xf bound_ctrl:1
	v_add_f32_dpp v55, v55, v55 row_shr:4 row_mask:0xf bank_mask:0xf bound_ctrl:1
	v_add_f32_dpp v48, v48, v48 row_shr:8 row_mask:0xf bank_mask:0xf bound_ctrl:1
	v_add_f32_dpp v49, v49, v49 row_shr:8 row_mask:0xf bank_mask:0xf bound_ctrl:1
	v_add_f32_dpp v50, v50, v50 row_shr:8 row_mask:0xf bank_mask:0xf bound_ctrl:1
	v_add_f32_dpp v51, v51, v51 row_shr:8 row_mask:0xf bank_mask:0xf bound_ctrl:1
	v_add_f32_dpp v52, v52, v52 row_shr:8 row_mask:0xf bank_mask:0xf bound_ctrl:1
	v_add_f32_dpp v53, v53, v53 row_shr:8 row_mask:0xf bank_mask:0xf bound_ctrl:1
	v_add_f32_dpp v54, v54, v54 row_shr:8 row_mask:0xf bank_mask:0xf bound_ctrl:1
	v_add_f32_dpp v55, v55, v55 row_shr:8 row_mask:0xf bank_mask:0xf bound_ctrl:1
	v_mov_b32_dpp v88, v48 row_newbcast:15 row_mask:0xf bank_mask:0xf
	v_mov_b32_dpp v89, v49 row_newbcast:15 row_mask:0xf bank_mask:0xf
	v_mov_b32_dpp v90, v50 row_newbcast:15 row_mask:0xf bank_mask:0xf
	v_mov_b32_dpp v91, v51 row_newbcast:15 row_mask:0xf bank_mask:0xf
	v_mov_b32_dpp v92, v52 row_newbcast:15 row_mask:0xf bank_mask:0xf
	v_mov_b32_dpp v93, v53 row_newbcast:15 row_mask:0xf bank_mask:0xf
	v_mov_b32_dpp v94, v54 row_newbcast:15 row_mask:0xf bank_mask:0xf
	v_mov_b32_dpp v95, v55 row_newbcast:15 row_mask:0xf bank_mask:0xf
	v_add_f32_e32 v48, v48, v170
	v_add_f32_e32 v52, v52, v171
	v_add_f32_e32 v49, v49, v172
	v_add_f32_e32 v53, v53, v173
	v_add_f32_e32 v50, v50, v174
	v_add_f32_e32 v54, v54, v175
	v_add_f32_e32 v51, v51, v176
	v_add_f32_e32 v55, v55, v177
	v_mul_f32_e32 v132, v48, v141
	v_mul_f32_e32 v48, v48, v140
	v_fma_f32 v48, -v52, v141, v48
	v_fma_f32 v52, v52, v140, v132
	v_mul_f32_e32 v133, v49, v145
	v_mul_f32_e32 v49, v49, v144
	v_fma_f32 v49, -v53, v145, v49
	v_fma_f32 v53, v53, v144, v133
	v_mul_f32_e32 v132, v50, v149
	v_mul_f32_e32 v50, v50, v148
	v_fma_f32 v50, -v54, v149, v50
	v_fma_f32 v54, v54, v148, v132
	v_mul_f32_e32 v133, v51, v153
	v_mul_f32_e32 v51, v51, v152
	v_fma_f32 v51, -v55, v153, v51
	v_fma_f32 v55, v55, v152, v133
	v_add_f32_e32 v88, v88, v170
	v_add_f32_e32 v92, v92, v171
	v_mul_f32_e32 v132, v92, v155
	v_mul_f32_e32 v171, v88, v155
	v_fma_f32 v170, v88, v154, -v132
	v_fma_f32 v171, v92, v154, v171
	v_add_f32_e32 v89, v89, v172
	v_add_f32_e32 v93, v93, v173
	v_mul_f32_e32 v133, v93, v159
	v_mul_f32_e32 v173, v89, v159
	v_fma_f32 v172, v89, v158, -v133
	v_fma_f32 v173, v93, v158, v173
	v_add_f32_e32 v90, v90, v174
	v_add_f32_e32 v94, v94, v175
	v_mul_f32_e32 v132, v94, v163
	v_mul_f32_e32 v175, v90, v163
	v_fma_f32 v174, v90, v162, -v132
	v_fma_f32 v175, v94, v162, v175
	v_add_f32_e32 v91, v91, v176
	v_add_f32_e32 v95, v95, v177
	v_mul_f32_e32 v133, v95, v167
	v_mul_f32_e32 v177, v91, v167
	v_fma_f32 v176, v91, v166, -v133
	v_fma_f32 v177, v95, v166, v177
	v_mul_f32_e32 v132, v56, v139
	v_mul_f32_e32 v56, v56, v138
	v_fma_f32 v56, -v60, v139, v56
	v_fma_f32 v60, v60, v138, v132
	v_mul_f32_e32 v133, v57, v143
	v_mul_f32_e32 v57, v57, v142
	v_fma_f32 v57, -v61, v143, v57
	v_fma_f32 v61, v61, v142, v133
	v_mul_f32_e32 v132, v58, v147
	v_mul_f32_e32 v58, v58, v146
	v_fma_f32 v58, -v62, v147, v58
	v_fma_f32 v62, v62, v146, v132
	v_mul_f32_e32 v133, v59, v151
	v_mul_f32_e32 v59, v59, v150
	v_fma_f32 v59, -v63, v151, v59
	v_fma_f32 v63, v63, v150, v133
	v_add_f32_dpp v56, v56, v56 row_shr:1 row_mask:0xf bank_mask:0xf bound_ctrl:1
	v_add_f32_dpp v57, v57, v57 row_shr:1 row_mask:0xf bank_mask:0xf bound_ctrl:1
	v_add_f32_dpp v58, v58, v58 row_shr:1 row_mask:0xf bank_mask:0xf bound_ctrl:1
	v_add_f32_dpp v59, v59, v59 row_shr:1 row_mask:0xf bank_mask:0xf bound_ctrl:1
	v_add_f32_dpp v60, v60, v60 row_shr:1 row_mask:0xf bank_mask:0xf bound_ctrl:1
	v_add_f32_dpp v61, v61, v61 row_shr:1 row_mask:0xf bank_mask:0xf bound_ctrl:1
	v_add_f32_dpp v62, v62, v62 row_shr:1 row_mask:0xf bank_mask:0xf bound_ctrl:1
	v_add_f32_dpp v63, v63, v63 row_shr:1 row_mask:0xf bank_mask:0xf bound_ctrl:1
	v_add_f32_dpp v56, v56, v56 row_shr:2 row_mask:0xf bank_mask:0xf bound_ctrl:1
	v_add_f32_dpp v57, v57, v57 row_shr:2 row_mask:0xf bank_mask:0xf bound_ctrl:1
	v_add_f32_dpp v58, v58, v58 row_shr:2 row_mask:0xf bank_mask:0xf bound_ctrl:1
	v_add_f32_dpp v59, v59, v59 row_shr:2 row_mask:0xf bank_mask:0xf bound_ctrl:1
	v_add_f32_dpp v60, v60, v60 row_shr:2 row_mask:0xf bank_mask:0xf bound_ctrl:1
	v_add_f32_dpp v61, v61, v61 row_shr:2 row_mask:0xf bank_mask:0xf bound_ctrl:1
	v_add_f32_dpp v62, v62, v62 row_shr:2 row_mask:0xf bank_mask:0xf bound_ctrl:1
	v_add_f32_dpp v63, v63, v63 row_shr:2 row_mask:0xf bank_mask:0xf bound_ctrl:1
	v_add_f32_dpp v56, v56, v56 row_shr:4 row_mask:0xf bank_mask:0xf bound_ctrl:1
	v_add_f32_dpp v57, v57, v57 row_shr:4 row_mask:0xf bank_mask:0xf bound_ctrl:1
	v_add_f32_dpp v58, v58, v58 row_shr:4 row_mask:0xf bank_mask:0xf bound_ctrl:1
	v_add_f32_dpp v59, v59, v59 row_shr:4 row_mask:0xf bank_mask:0xf bound_ctrl:1
	v_add_f32_dpp v60, v60, v60 row_shr:4 row_mask:0xf bank_mask:0xf bound_ctrl:1
	v_add_f32_dpp v61, v61, v61 row_shr:4 row_mask:0xf bank_mask:0xf bound_ctrl:1
	v_add_f32_dpp v62, v62, v62 row_shr:4 row_mask:0xf bank_mask:0xf bound_ctrl:1
	v_add_f32_dpp v63, v63, v63 row_shr:4 row_mask:0xf bank_mask:0xf bound_ctrl:1
	v_add_f32_dpp v56, v56, v56 row_shr:8 row_mask:0xf bank_mask:0xf bound_ctrl:1
	v_add_f32_dpp v57, v57, v57 row_shr:8 row_mask:0xf bank_mask:0xf bound_ctrl:1
	v_add_f32_dpp v58, v58, v58 row_shr:8 row_mask:0xf bank_mask:0xf bound_ctrl:1
	v_add_f32_dpp v59, v59, v59 row_shr:8 row_mask:0xf bank_mask:0xf bound_ctrl:1
	v_add_f32_dpp v60, v60, v60 row_shr:8 row_mask:0xf bank_mask:0xf bound_ctrl:1
	v_add_f32_dpp v61, v61, v61 row_shr:8 row_mask:0xf bank_mask:0xf bound_ctrl:1
	v_add_f32_dpp v62, v62, v62 row_shr:8 row_mask:0xf bank_mask:0xf bound_ctrl:1
	v_add_f32_dpp v63, v63, v63 row_shr:8 row_mask:0xf bank_mask:0xf bound_ctrl:1
	v_mov_b32_dpp v88, v56 row_newbcast:15 row_mask:0xf bank_mask:0xf
	v_mov_b32_dpp v89, v57 row_newbcast:15 row_mask:0xf bank_mask:0xf
	v_mov_b32_dpp v90, v58 row_newbcast:15 row_mask:0xf bank_mask:0xf
	v_mov_b32_dpp v91, v59 row_newbcast:15 row_mask:0xf bank_mask:0xf
	v_mov_b32_dpp v92, v60 row_newbcast:15 row_mask:0xf bank_mask:0xf
	v_mov_b32_dpp v93, v61 row_newbcast:15 row_mask:0xf bank_mask:0xf
	v_mov_b32_dpp v94, v62 row_newbcast:15 row_mask:0xf bank_mask:0xf
	v_mov_b32_dpp v95, v63 row_newbcast:15 row_mask:0xf bank_mask:0xf
	v_add_f32_e32 v56, v56, v170
	v_add_f32_e32 v60, v60, v171
	v_add_f32_e32 v57, v57, v172
	v_add_f32_e32 v61, v61, v173
	v_add_f32_e32 v58, v58, v174
	v_add_f32_e32 v62, v62, v175
	v_add_f32_e32 v59, v59, v176
	v_add_f32_e32 v63, v63, v177
	v_mul_f32_e32 v132, v56, v141
	v_mul_f32_e32 v56, v56, v140
	v_fma_f32 v56, -v60, v141, v56
	v_fma_f32 v60, v60, v140, v132
	v_mul_f32_e32 v133, v57, v145
	v_mul_f32_e32 v57, v57, v144
	v_fma_f32 v57, -v61, v145, v57
	v_fma_f32 v61, v61, v144, v133
	v_mul_f32_e32 v132, v58, v149
	v_mul_f32_e32 v58, v58, v148
	v_fma_f32 v58, -v62, v149, v58
	v_fma_f32 v62, v62, v148, v132
	v_mul_f32_e32 v133, v59, v153
	v_mul_f32_e32 v59, v59, v152
	v_fma_f32 v59, -v63, v153, v59
	v_fma_f32 v63, v63, v152, v133
	v_add_f32_e32 v88, v88, v170
	v_add_f32_e32 v92, v92, v171
	v_mul_f32_e32 v132, v92, v155
	v_mul_f32_e32 v171, v88, v155
	v_fma_f32 v170, v88, v154, -v132
	v_fma_f32 v171, v92, v154, v171
	v_add_f32_e32 v89, v89, v172
	v_add_f32_e32 v93, v93, v173
	v_mul_f32_e32 v133, v93, v159
	v_mul_f32_e32 v173, v89, v159
	v_fma_f32 v172, v89, v158, -v133
	v_fma_f32 v173, v93, v158, v173
	v_add_f32_e32 v90, v90, v174
	v_add_f32_e32 v94, v94, v175
	v_mul_f32_e32 v132, v94, v163
	v_mul_f32_e32 v175, v90, v163
	v_fma_f32 v174, v90, v162, -v132
	v_fma_f32 v175, v94, v162, v175
	v_add_f32_e32 v91, v91, v176
	v_add_f32_e32 v95, v95, v177
	v_mul_f32_e32 v133, v95, v167
	v_mul_f32_e32 v177, v91, v167
	v_fma_f32 v176, v91, v166, -v133
	v_fma_f32 v177, v95, v166, v177
	s_waitcnt vmcnt(14)
	v_cvt_pk_bf16_f32 v80, v80, v81
	v_cvt_pk_bf16_f32 v81, v82, v83
	v_cvt_pk_bf16_f32 v82, -v84, -v85
	v_cvt_pk_bf16_f32 v83, -v86, -v87
	v_cvt_pk_bf16_f32 v96, v32, v33
	v_cvt_pk_bf16_f32 v97, v34, v35
	v_cvt_pk_bf16_f32 v98, v36, v37
	v_cvt_pk_bf16_f32 v99, v38, v39
	s_nop 1
	v_mfma_f32_16x16x32_bf16 v[16:19], v[80:83], v[96:99], v[16:19]
	v_cvt_pk_bf16_f32 v96, v40, v41
	v_cvt_pk_bf16_f32 v97, v42, v43
	v_cvt_pk_bf16_f32 v98, v44, v45
	v_cvt_pk_bf16_f32 v99, v46, v47
	s_nop 1
	v_mfma_f32_16x16x32_bf16 v[20:23], v[80:83], v[96:99], v[20:23]
	v_cvt_pk_bf16_f32 v96, v48, v49
	v_cvt_pk_bf16_f32 v97, v50, v51
	v_cvt_pk_bf16_f32 v98, v52, v53
	v_cvt_pk_bf16_f32 v99, v54, v55
	s_nop 1
	v_mfma_f32_16x16x32_bf16 v[24:27], v[80:83], v[96:99], v[24:27]
	v_cvt_pk_bf16_f32 v96, v56, v57
	v_cvt_pk_bf16_f32 v97, v58, v59
	v_cvt_pk_bf16_f32 v98, v60, v61
	v_cvt_pk_bf16_f32 v99, v62, v63
	s_nop 1
	v_mfma_f32_16x16x32_bf16 v[28:31], v[80:83], v[96:99], v[28:31]
	s_waitcnt vmcnt(10)
	v_cvt_pk_bf16_f32 v64, v64, v65
	v_cvt_pk_bf16_f32 v65, v66, v67
	v_cvt_pk_bf16_f32 v66, v68, v69
	v_cvt_pk_bf16_f32 v67, v70, v71
	v_cvt_pk_bf16_f32 v72, v72, v73
	v_cvt_pk_bf16_f32 v73, v74, v75
	v_cvt_pk_bf16_f32 v74, v76, v77
	v_cvt_pk_bf16_f32 v75, v78, v79
	global_load_dwordx4 v[80:83], v136, s[38:39]
	global_load_dwordx4 v[84:87], v136, s[40:41]
	s_nop 0
	v_mfma_f32_16x16x32_bf16 v[32:35], v[64:67], v[0:3], 0
	v_mfma_f32_16x16x32_bf16 v[36:39], v[72:75], v[0:3], 0
	v_mfma_f32_16x16x32_bf16 v[40:43], v[64:67], v[4:7], 0
	v_mfma_f32_16x16x32_bf16 v[44:47], v[72:75], v[4:7], 0
	v_mfma_f32_16x16x32_bf16 v[48:51], v[64:67], v[8:11], 0
	v_mfma_f32_16x16x32_bf16 v[52:55], v[72:75], v[8:11], 0
	v_mfma_f32_16x16x32_bf16 v[56:59], v[64:67], v[12:15], 0
	v_mfma_f32_16x16x32_bf16 v[60:63], v[72:75], v[12:15], 0
	v_readlane_b32 s10, v247, 28
	s_sub_i32 s11, 3, s8
	s_sub_i32 s17, 71, s8
	s_cmp_lt_u32 s8, 4
	s_cselect_b32 s11, s11, s17
	s_lshl_b32 s16, s10, 1
	s_add_i32 s16, s16, 1
	s_lshl_b32 s16, s16, 4
	s_add_i32 s16, s16, s7
	s_lshl_b32 s17, s6, 1
	s_add_i32 s17, s17, 1
	s_lshl_b32 s17, s17, 4
	s_add_i32 s17, s17, s7
	s_mul_i32 s17, s17, 68
	s_add_i32 s17, s17, s11
	s_lshl_b32 s17, s17, 6
	s_lshl_b32 s20, s16, 12
	s_add_u32 s20, s20, 0x11fb20
	s_add_u32 s20, s4, s20
	s_addc_u32 s21, s5, 0
	s_add_u32 s22, s20, 0x40000
	s_addc_u32 s23, s21, 0
	s_lshl_b32 s38, s16, 12
	s_add_u32 s38, s38, 0x19fb20
	s_add_u32 s38, s4, s38
	s_addc_u32 s39, s5, 0
	s_add_u32 s40, s38, 0x40000
	s_addc_u32 s41, s39, 0
	s_lshl_b32 s42, s16, 15
	s_add_u32 s42, s42, 0xf900000
	s_add_u32 s42, s4, s42
	s_addc_u32 s43, s5, 0
	s_lshl_b32 s44, s17, 3
	s_add_u32 s44, s44, 0x740000
	s_add_u32 s44, s4, s44
	s_addc_u32 s45, s5, 0
	s_mov_b32 exec_hi, 0
	global_load_dwordx4 v[64:67], v135, s[20:21]
	global_load_dwordx4 v[68:71], v135, s[20:21] offset:16
	global_load_dwordx4 v[72:75], v135, s[22:23]
	global_load_dwordx4 v[76:79], v135, s[22:23] offset:16
	s_mov_b64 exec, -1
	s_add_u32 s20, s20, 0x400
	s_addc_u32 s21, s21, 0
	s_add_u32 s22, s22, 0x400
	s_addc_u32 s23, s23, 0
	global_load_dwordx4 v[138:141], v134, s[42:43] offset:0
	global_load_dwordx4 v[142:145], v134, s[42:43] offset:16
	global_load_dwordx4 v[146:149], v134, s[42:43] offset:32
	global_load_dwordx4 v[150:153], v134, s[42:43] offset:48
	global_load_dwordx4 v[154:157], v134, s[42:43] offset:64
	global_load_dwordx4 v[158:161], v134, s[42:43] offset:80
	global_load_dwordx4 v[162:165], v134, s[42:43] offset:96
	global_load_dwordx4 v[166:169], v134, s[42:43] offset:112
	global_load_dwordx4 v[170:173], v206, s[44:45]
	global_load_dwordx4 v[174:177], v206, s[44:45] offset:16
	s_add_u32 s42, s42, 0x2000
	s_addc_u32 s43, s43, 0
	s_add_u32 s44, s44, 0x80
	s_addc_u32 s45, s45, 0
	s_waitcnt vmcnt(16)
	v_mul_f32_e32 v132, v179, v119
	v_mul_f32_e32 v133, v178, v119
	v_fma_f32 v178, v178, v118, -v132
	v_fma_f32 v179, v179, v118, v133
	v_mul_f32_e32 v132, v181, v123
	v_mul_f32_e32 v133, v180, v123
	v_fma_f32 v180, v180, v122, -v132
	v_fma_f32 v181, v181, v122, v133
	v_mul_f32_e32 v132, v183, v127
	v_mul_f32_e32 v133, v182, v127
	v_fma_f32 v182, v182, v126, -v132
	v_fma_f32 v183, v183, v126, v133
	v_mul_f32_e32 v132, v185, v131
	v_mul_f32_e32 v133, v184, v131
	v_fma_f32 v184, v184, v130, -v132
	v_fma_f32 v185, v185, v130, v133
	v_mul_f32_e32 v132, v32, v101
	v_mul_f32_e32 v32, v32, v100
	v_fma_f32 v32, -v36, v101, v32
	v_fma_f32 v36, v36, v100, v132
	v_mul_f32_e32 v133, v33, v105
	v_mul_f32_e32 v33, v33, v104
	v_fma_f32 v33, -v37, v105, v33
	v_fma_f32 v37, v37, v104, v133
	v_mul_f32_e32 v132, v34, v109
	v_mul_f32_e32 v34, v34, v108
	v_fma_f32 v34, -v38, v109, v34
	v_fma_f32 v38, v38, v108, v132
	v_mul_f32_e32 v133, v35, v113
	v_mul_f32_e32 v35, v35, v112
	v_fma_f32 v35, -v39, v113, v35
	v_fma_f32 v39, v39, v112, v133
	v_add_f32_dpp v32, v32, v32 row_shr:1 row_mask:0xf bank_mask:0xf bound_ctrl:1
	v_add_f32_dpp v33, v33, v33 row_shr:1 row_mask:0xf bank_mask:0xf bound_ctrl:1
	v_add_f32_dpp v34, v34, v34 row_shr:1 row_mask:0xf bank_mask:0xf bound_ctrl:1
	v_add_f32_dpp v35, v35, v35 row_shr:1 row_mask:0xf bank_mask:0xf bound_ctrl:1
	v_add_f32_dpp v36, v36, v36 row_shr:1 row_mask:0xf bank_mask:0xf bound_ctrl:1
	v_add_f32_dpp v37, v37, v37 row_shr:1 row_mask:0xf bank_mask:0xf bound_ctrl:1
	v_add_f32_dpp v38, v38, v38 row_shr:1 row_mask:0xf bank_mask:0xf bound_ctrl:1
	v_add_f32_dpp v39, v39, v39 row_shr:1 row_mask:0xf bank_mask:0xf bound_ctrl:1
	v_add_f32_dpp v32, v32, v32 row_shr:2 row_mask:0xf bank_mask:0xf bound_ctrl:1
	v_add_f32_dpp v33, v33, v33 row_shr:2 row_mask:0xf bank_mask:0xf bound_ctrl:1
	v_add_f32_dpp v34, v34, v34 row_shr:2 row_mask:0xf bank_mask:0xf bound_ctrl:1
	v_add_f32_dpp v35, v35, v35 row_shr:2 row_mask:0xf bank_mask:0xf bound_ctrl:1
	v_add_f32_dpp v36, v36, v36 row_shr:2 row_mask:0xf bank_mask:0xf bound_ctrl:1
	v_add_f32_dpp v37, v37, v37 row_shr:2 row_mask:0xf bank_mask:0xf bound_ctrl:1
	v_add_f32_dpp v38, v38, v38 row_shr:2 row_mask:0xf bank_mask:0xf bound_ctrl:1
	v_add_f32_dpp v39, v39, v39 row_shr:2 row_mask:0xf bank_mask:0xf bound_ctrl:1
	v_add_f32_dpp v32, v32, v32 row_shr:4 row_mask:0xf bank_mask:0xf bound_ctrl:1
	v_add_f32_dpp v33, v33, v33 row_shr:4 row_mask:0xf bank_mask:0xf bound_ctrl:1
	v_add_f32_dpp v34, v34, v34 row_shr:4 row_mask:0xf bank_mask:0xf bound_ctrl:1
	v_add_f32_dpp v35, v35, v35 row_shr:4 row_mask:0xf bank_mask:0xf bound_ctrl:1
	v_add_f32_dpp v36, v36, v36 row_shr:4 row_mask:0xf bank_mask:0xf bound_ctrl:1
	v_add_f32_dpp v37, v37, v37 row_shr:4 row_mask:0xf bank_mask:0xf bound_ctrl:1
	v_add_f32_dpp v38, v38, v38 row_shr:4 row_mask:0xf bank_mask:0xf bound_ctrl:1
	v_add_f32_dpp v39, v39, v39 row_shr:4 row_mask:0xf bank_mask:0xf bound_ctrl:1
	v_add_f32_dpp v32, v32, v32 row_shr:8 row_mask:0xf bank_mask:0xf bound_ctrl:1
	v_add_f32_dpp v33, v33, v33 row_shr:8 row_mask:0xf bank_mask:0xf bound_ctrl:1
	v_add_f32_dpp v34, v34, v34 row_shr:8 row_mask:0xf bank_mask:0xf bound_ctrl:1
	v_add_f32_dpp v35, v35, v35 row_shr:8 row_mask:0xf bank_mask:0xf bound_ctrl:1
	v_add_f32_dpp v36, v36, v36 row_shr:8 row_mask:0xf bank_mask:0xf bound_ctrl:1
	v_add_f32_dpp v37, v37, v37 row_shr:8 row_mask:0xf bank_mask:0xf bound_ctrl:1
	v_add_f32_dpp v38, v38, v38 row_shr:8 row_mask:0xf bank_mask:0xf bound_ctrl:1
	v_add_f32_dpp v39, v39, v39 row_shr:8 row_mask:0xf bank_mask:0xf bound_ctrl:1
	v_mov_b32_dpp v88, v32 row_newbcast:15 row_mask:0xf bank_mask:0xf
	v_mov_b32_dpp v89, v33 row_newbcast:15 row_mask:0xf bank_mask:0xf
	v_mov_b32_dpp v90, v34 row_newbcast:15 row_mask:0xf bank_mask:0xf
	v_mov_b32_dpp v91, v35 row_newbcast:15 row_mask:0xf bank_mask:0xf
	v_mov_b32_dpp v92, v36 row_newbcast:15 row_mask:0xf bank_mask:0xf
	v_mov_b32_dpp v93, v37 row_newbcast:15 row_mask:0xf bank_mask:0xf
	v_mov_b32_dpp v94, v38 row_newbcast:15 row_mask:0xf bank_mask:0xf
	v_mov_b32_dpp v95, v39 row_newbcast:15 row_mask:0xf bank_mask:0xf
	v_add_f32_e32 v32, v32, v178
	v_add_f32_e32 v36, v36, v179
	v_add_f32_e32 v33, v33, v180
	v_add_f32_e32 v37, v37, v181
	v_add_f32_e32 v34, v34, v182
	v_add_f32_e32 v38, v38, v183
	v_add_f32_e32 v35, v35, v184
	v_add_f32_e32 v39, v39, v185
	v_mul_f32_e32 v132, v32, v103
	v_mul_f32_e32 v32, v32, v102
	v_fma_f32 v32, -v36, v103, v32
	v_fma_f32 v36, v36, v102, v132
	v_mul_f32_e32 v133, v33, v107
	v_mul_f32_e32 v33, v33, v106
	v_fma_f32 v33, -v37, v107, v33
	v_fma_f32 v37, v37, v106, v133
	v_mul_f32_e32 v132, v34, v111
	v_mul_f32_e32 v34, v34, v110
	v_fma_f32 v34, -v38, v111, v34
	v_fma_f32 v38, v38, v110, v132
	v_mul_f32_e32 v133, v35, v115
	v_mul_f32_e32 v35, v35, v114
	v_fma_f32 v35, -v39, v115, v35
	v_fma_f32 v39, v39, v114, v133
	v_add_f32_e32 v88, v88, v178
	v_add_f32_e32 v92, v92, v179
	v_mul_f32_e32 v132, v92, v117
	v_mul_f32_e32 v179, v88, v117
	v_fma_f32 v178, v88, v116, -v132
	v_fma_f32 v179, v92, v116, v179
	v_add_f32_e32 v89, v89, v180
	v_add_f32_e32 v93, v93, v181
	v_mul_f32_e32 v133, v93, v121
	v_mul_f32_e32 v181, v89, v121
	v_fma_f32 v180, v89, v120, -v133
	v_fma_f32 v181, v93, v120, v181
	v_add_f32_e32 v90, v90, v182
	v_add_f32_e32 v94, v94, v183
	v_mul_f32_e32 v132, v94, v125
	v_mul_f32_e32 v183, v90, v125
	v_fma_f32 v182, v90, v124, -v132
	v_fma_f32 v183, v94, v124, v183
	v_add_f32_e32 v91, v91, v184
	v_add_f32_e32 v95, v95, v185
	v_mul_f32_e32 v133, v95, v129
	v_mul_f32_e32 v185, v91, v129
	v_fma_f32 v184, v91, v128, -v133
	v_fma_f32 v185, v95, v128, v185
	v_mul_f32_e32 v132, v40, v101
	v_mul_f32_e32 v40, v40, v100
	v_fma_f32 v40, -v44, v101, v40
	v_fma_f32 v44, v44, v100, v132
	v_mul_f32_e32 v133, v41, v105
	v_mul_f32_e32 v41, v41, v104
	v_fma_f32 v41, -v45, v105, v41
	v_fma_f32 v45, v45, v104, v133
	v_mul_f32_e32 v132, v42, v109
	v_mul_f32_e32 v42, v42, v108
	v_fma_f32 v42, -v46, v109, v42
	v_fma_f32 v46, v46, v108, v132
	v_mul_f32_e32 v133, v43, v113
	v_mul_f32_e32 v43, v43, v112
	v_fma_f32 v43, -v47, v113, v43
	v_fma_f32 v47, v47, v112, v133
	v_add_f32_dpp v40, v40, v40 row_shr:1 row_mask:0xf bank_mask:0xf bound_ctrl:1
	v_add_f32_dpp v41, v41, v41 row_shr:1 row_mask:0xf bank_mask:0xf bound_ctrl:1
	v_add_f32_dpp v42, v42, v42 row_shr:1 row_mask:0xf bank_mask:0xf bound_ctrl:1
	v_add_f32_dpp v43, v43, v43 row_shr:1 row_mask:0xf bank_mask:0xf bound_ctrl:1
	v_add_f32_dpp v44, v44, v44 row_shr:1 row_mask:0xf bank_mask:0xf bound_ctrl:1
	v_add_f32_dpp v45, v45, v45 row_shr:1 row_mask:0xf bank_mask:0xf bound_ctrl:1
	v_add_f32_dpp v46, v46, v46 row_shr:1 row_mask:0xf bank_mask:0xf bound_ctrl:1
	v_add_f32_dpp v47, v47, v47 row_shr:1 row_mask:0xf bank_mask:0xf bound_ctrl:1
	v_add_f32_dpp v40, v40, v40 row_shr:2 row_mask:0xf bank_mask:0xf bound_ctrl:1
	v_add_f32_dpp v41, v41, v41 row_shr:2 row_mask:0xf bank_mask:0xf bound_ctrl:1
	v_add_f32_dpp v42, v42, v42 row_shr:2 row_mask:0xf bank_mask:0xf bound_ctrl:1
	v_add_f32_dpp v43, v43, v43 row_shr:2 row_mask:0xf bank_mask:0xf bound_ctrl:1
	v_add_f32_dpp v44, v44, v44 row_shr:2 row_mask:0xf bank_mask:0xf bound_ctrl:1
	v_add_f32_dpp v45, v45, v45 row_shr:2 row_mask:0xf bank_mask:0xf bound_ctrl:1
	v_add_f32_dpp v46, v46, v46 row_shr:2 row_mask:0xf bank_mask:0xf bound_ctrl:1
	v_add_f32_dpp v47, v47, v47 row_shr:2 row_mask:0xf bank_mask:0xf bound_ctrl:1
	v_add_f32_dpp v40, v40, v40 row_shr:4 row_mask:0xf bank_mask:0xf bound_ctrl:1
	v_add_f32_dpp v41, v41, v41 row_shr:4 row_mask:0xf bank_mask:0xf bound_ctrl:1
	v_add_f32_dpp v42, v42, v42 row_shr:4 row_mask:0xf bank_mask:0xf bound_ctrl:1
	v_add_f32_dpp v43, v43, v43 row_shr:4 row_mask:0xf bank_mask:0xf bound_ctrl:1
	v_add_f32_dpp v44, v44, v44 row_shr:4 row_mask:0xf bank_mask:0xf bound_ctrl:1
	v_add_f32_dpp v45, v45, v45 row_shr:4 row_mask:0xf bank_mask:0xf bound_ctrl:1
	v_add_f32_dpp v46, v46, v46 row_shr:4 row_mask:0xf bank_mask:0xf bound_ctrl:1
	v_add_f32_dpp v47, v47, v47 row_shr:4 row_mask:0xf bank_mask:0xf bound_ctrl:1
	v_add_f32_dpp v40, v40, v40 row_shr:8 row_mask:0xf bank_mask:0xf bound_ctrl:1
	v_add_f32_dpp v41, v41, v41 row_shr:8 row_mask:0xf bank_mask:0xf bound_ctrl:1
	v_add_f32_dpp v42, v42, v42 row_shr:8 row_mask:0xf bank_mask:0xf bound_ctrl:1
	v_add_f32_dpp v43, v43, v43 row_shr:8 row_mask:0xf bank_mask:0xf bound_ctrl:1
	v_add_f32_dpp v44, v44, v44 row_shr:8 row_mask:0xf bank_mask:0xf bound_ctrl:1
	v_add_f32_dpp v45, v45, v45 row_shr:8 row_mask:0xf bank_mask:0xf bound_ctrl:1
	v_add_f32_dpp v46, v46, v46 row_shr:8 row_mask:0xf bank_mask:0xf bound_ctrl:1
	v_add_f32_dpp v47, v47, v47 row_shr:8 row_mask:0xf bank_mask:0xf bound_ctrl:1
	v_mov_b32_dpp v88, v40 row_newbcast:15 row_mask:0xf bank_mask:0xf
	v_mov_b32_dpp v89, v41 row_newbcast:15 row_mask:0xf bank_mask:0xf
	v_mov_b32_dpp v90, v42 row_newbcast:15 row_mask:0xf bank_mask:0xf
	v_mov_b32_dpp v91, v43 row_newbcast:15 row_mask:0xf bank_mask:0xf
	v_mov_b32_dpp v92, v44 row_newbcast:15 row_mask:0xf bank_mask:0xf
	v_mov_b32_dpp v93, v45 row_newbcast:15 row_mask:0xf bank_mask:0xf
	v_mov_b32_dpp v94, v46 row_newbcast:15 row_mask:0xf bank_mask:0xf
	v_mov_b32_dpp v95, v47 row_newbcast:15 row_mask:0xf bank_mask:0xf
	v_add_f32_e32 v40, v40, v178
	v_add_f32_e32 v44, v44, v179
	v_add_f32_e32 v41, v41, v180
	v_add_f32_e32 v45, v45, v181
	v_add_f32_e32 v42, v42, v182
	v_add_f32_e32 v46, v46, v183
	v_add_f32_e32 v43, v43, v184
	v_add_f32_e32 v47, v47, v185
	v_mul_f32_e32 v132, v40, v103
	v_mul_f32_e32 v40, v40, v102
	v_fma_f32 v40, -v44, v103, v40
	v_fma_f32 v44, v44, v102, v132
	v_mul_f32_e32 v133, v41, v107
	v_mul_f32_e32 v41, v41, v106
	v_fma_f32 v41, -v45, v107, v41
	v_fma_f32 v45, v45, v106, v133
	v_mul_f32_e32 v132, v42, v111
	v_mul_f32_e32 v42, v42, v110
	v_fma_f32 v42, -v46, v111, v42
	v_fma_f32 v46, v46, v110, v132
	v_mul_f32_e32 v133, v43, v115
	v_mul_f32_e32 v43, v43, v114
	v_fma_f32 v43, -v47, v115, v43
	v_fma_f32 v47, v47, v114, v133
	v_add_f32_e32 v88, v88, v178
	v_add_f32_e32 v92, v92, v179
	v_mul_f32_e32 v132, v92, v117
	v_mul_f32_e32 v179, v88, v117
	v_fma_f32 v178, v88, v116, -v132
	v_fma_f32 v179, v92, v116, v179
	v_add_f32_e32 v89, v89, v180
	v_add_f32_e32 v93, v93, v181
	v_mul_f32_e32 v133, v93, v121
	v_mul_f32_e32 v181, v89, v121
	v_fma_f32 v180, v89, v120, -v133
	v_fma_f32 v181, v93, v120, v181
	v_add_f32_e32 v90, v90, v182
	v_add_f32_e32 v94, v94, v183
	v_mul_f32_e32 v132, v94, v125
	v_mul_f32_e32 v183, v90, v125
	v_fma_f32 v182, v90, v124, -v132
	v_fma_f32 v183, v94, v124, v183
	v_add_f32_e32 v91, v91, v184
	v_add_f32_e32 v95, v95, v185
	v_mul_f32_e32 v133, v95, v129
	v_mul_f32_e32 v185, v91, v129
	v_fma_f32 v184, v91, v128, -v133
	v_fma_f32 v185, v95, v128, v185
	v_mul_f32_e32 v132, v48, v101
	v_mul_f32_e32 v48, v48, v100
	v_fma_f32 v48, -v52, v101, v48
	v_fma_f32 v52, v52, v100, v132
	v_mul_f32_e32 v133, v49, v105
	v_mul_f32_e32 v49, v49, v104
	v_fma_f32 v49, -v53, v105, v49
	v_fma_f32 v53, v53, v104, v133
	v_mul_f32_e32 v132, v50, v109
	v_mul_f32_e32 v50, v50, v108
	v_fma_f32 v50, -v54, v109, v50
	v_fma_f32 v54, v54, v108, v132
	v_mul_f32_e32 v133, v51, v113
	v_mul_f32_e32 v51, v51, v112
	v_fma_f32 v51, -v55, v113, v51
	v_fma_f32 v55, v55, v112, v133
	v_add_f32_dpp v48, v48, v48 row_shr:1 row_mask:0xf bank_mask:0xf bound_ctrl:1
	v_add_f32_dpp v49, v49, v49 row_shr:1 row_mask:0xf bank_mask:0xf bound_ctrl:1
	v_add_f32_dpp v50, v50, v50 row_shr:1 row_mask:0xf bank_mask:0xf bound_ctrl:1
	v_add_f32_dpp v51, v51, v51 row_shr:1 row_mask:0xf bank_mask:0xf bound_ctrl:1
	v_add_f32_dpp v52, v52, v52 row_shr:1 row_mask:0xf bank_mask:0xf bound_ctrl:1
	v_add_f32_dpp v53, v53, v53 row_shr:1 row_mask:0xf bank_mask:0xf bound_ctrl:1
	v_add_f32_dpp v54, v54, v54 row_shr:1 row_mask:0xf bank_mask:0xf bound_ctrl:1
	v_add_f32_dpp v55, v55, v55 row_shr:1 row_mask:0xf bank_mask:0xf bound_ctrl:1
	v_add_f32_dpp v48, v48, v48 row_shr:2 row_mask:0xf bank_mask:0xf bound_ctrl:1
	v_add_f32_dpp v49, v49, v49 row_shr:2 row_mask:0xf bank_mask:0xf bound_ctrl:1
	v_add_f32_dpp v50, v50, v50 row_shr:2 row_mask:0xf bank_mask:0xf bound_ctrl:1
	v_add_f32_dpp v51, v51, v51 row_shr:2 row_mask:0xf bank_mask:0xf bound_ctrl:1
	v_add_f32_dpp v52, v52, v52 row_shr:2 row_mask:0xf bank_mask:0xf bound_ctrl:1
	v_add_f32_dpp v53, v53, v53 row_shr:2 row_mask:0xf bank_mask:0xf bound_ctrl:1
	v_add_f32_dpp v54, v54, v54 row_shr:2 row_mask:0xf bank_mask:0xf bound_ctrl:1
	v_add_f32_dpp v55, v55, v55 row_shr:2 row_mask:0xf bank_mask:0xf bound_ctrl:1
	v_add_f32_dpp v48, v48, v48 row_shr:4 row_mask:0xf bank_mask:0xf bound_ctrl:1
	v_add_f32_dpp v49, v49, v49 row_shr:4 row_mask:0xf bank_mask:0xf bound_ctrl:1
	v_add_f32_dpp v50, v50, v50 row_shr:4 row_mask:0xf bank_mask:0xf bound_ctrl:1
	v_add_f32_dpp v51, v51, v51 row_shr:4 row_mask:0xf bank_mask:0xf bound_ctrl:1
	v_add_f32_dpp v52, v52, v52 row_shr:4 row_mask:0xf bank_mask:0xf bound_ctrl:1
	v_add_f32_dpp v53, v53, v53 row_shr:4 row_mask:0xf bank_mask:0xf bound_ctrl:1
	v_add_f32_dpp v54, v54, v54 row_shr:4 row_mask:0xf bank_mask:0xf bound_ctrl:1
	v_add_f32_dpp v55, v55, v55 row_shr:4 row_mask:0xf bank_mask:0xf bound_ctrl:1
	v_add_f32_dpp v48, v48, v48 row_shr:8 row_mask:0xf bank_mask:0xf bound_ctrl:1
	v_add_f32_dpp v49, v49, v49 row_shr:8 row_mask:0xf bank_mask:0xf bound_ctrl:1
	v_add_f32_dpp v50, v50, v50 row_shr:8 row_mask:0xf bank_mask:0xf bound_ctrl:1
	v_add_f32_dpp v51, v51, v51 row_shr:8 row_mask:0xf bank_mask:0xf bound_ctrl:1
	v_add_f32_dpp v52, v52, v52 row_shr:8 row_mask:0xf bank_mask:0xf bound_ctrl:1
	v_add_f32_dpp v53, v53, v53 row_shr:8 row_mask:0xf bank_mask:0xf bound_ctrl:1
	v_add_f32_dpp v54, v54, v54 row_shr:8 row_mask:0xf bank_mask:0xf bound_ctrl:1
	v_add_f32_dpp v55, v55, v55 row_shr:8 row_mask:0xf bank_mask:0xf bound_ctrl:1
	v_mov_b32_dpp v88, v48 row_newbcast:15 row_mask:0xf bank_mask:0xf
	v_mov_b32_dpp v89, v49 row_newbcast:15 row_mask:0xf bank_mask:0xf
	v_mov_b32_dpp v90, v50 row_newbcast:15 row_mask:0xf bank_mask:0xf
	v_mov_b32_dpp v91, v51 row_newbcast:15 row_mask:0xf bank_mask:0xf
	v_mov_b32_dpp v92, v52 row_newbcast:15 row_mask:0xf bank_mask:0xf
	v_mov_b32_dpp v93, v53 row_newbcast:15 row_mask:0xf bank_mask:0xf
	v_mov_b32_dpp v94, v54 row_newbcast:15 row_mask:0xf bank_mask:0xf
	v_mov_b32_dpp v95, v55 row_newbcast:15 row_mask:0xf bank_mask:0xf
	v_add_f32_e32 v48, v48, v178
	v_add_f32_e32 v52, v52, v179
	v_add_f32_e32 v49, v49, v180
	v_add_f32_e32 v53, v53, v181
	v_add_f32_e32 v50, v50, v182
	v_add_f32_e32 v54, v54, v183
	v_add_f32_e32 v51, v51, v184
	v_add_f32_e32 v55, v55, v185
	v_mul_f32_e32 v132, v48, v103
	v_mul_f32_e32 v48, v48, v102
	v_fma_f32 v48, -v52, v103, v48
	v_fma_f32 v52, v52, v102, v132
	v_mul_f32_e32 v133, v49, v107
	v_mul_f32_e32 v49, v49, v106
	v_fma_f32 v49, -v53, v107, v49
	v_fma_f32 v53, v53, v106, v133
	v_mul_f32_e32 v132, v50, v111
	v_mul_f32_e32 v50, v50, v110
	v_fma_f32 v50, -v54, v111, v50
	v_fma_f32 v54, v54, v110, v132
	v_mul_f32_e32 v133, v51, v115
	v_mul_f32_e32 v51, v51, v114
	v_fma_f32 v51, -v55, v115, v51
	v_fma_f32 v55, v55, v114, v133
	v_add_f32_e32 v88, v88, v178
	v_add_f32_e32 v92, v92, v179
	v_mul_f32_e32 v132, v92, v117
	v_mul_f32_e32 v179, v88, v117
	v_fma_f32 v178, v88, v116, -v132
	v_fma_f32 v179, v92, v116, v179
	v_add_f32_e32 v89, v89, v180
	v_add_f32_e32 v93, v93, v181
	v_mul_f32_e32 v133, v93, v121
	v_mul_f32_e32 v181, v89, v121
	v_fma_f32 v180, v89, v120, -v133
	v_fma_f32 v181, v93, v120, v181
	v_add_f32_e32 v90, v90, v182
	v_add_f32_e32 v94, v94, v183
	v_mul_f32_e32 v132, v94, v125
	v_mul_f32_e32 v183, v90, v125
	v_fma_f32 v182, v90, v124, -v132
	v_fma_f32 v183, v94, v124, v183
	v_add_f32_e32 v91, v91, v184
	v_add_f32_e32 v95, v95, v185
	v_mul_f32_e32 v133, v95, v129
	v_mul_f32_e32 v185, v91, v129
	v_fma_f32 v184, v91, v128, -v133
	v_fma_f32 v185, v95, v128, v185
	v_mul_f32_e32 v132, v56, v101
	v_mul_f32_e32 v56, v56, v100
	v_fma_f32 v56, -v60, v101, v56
	v_fma_f32 v60, v60, v100, v132
	v_mul_f32_e32 v133, v57, v105
	v_mul_f32_e32 v57, v57, v104
	v_fma_f32 v57, -v61, v105, v57
	v_fma_f32 v61, v61, v104, v133
	v_mul_f32_e32 v132, v58, v109
	v_mul_f32_e32 v58, v58, v108
	v_fma_f32 v58, -v62, v109, v58
	v_fma_f32 v62, v62, v108, v132
	v_mul_f32_e32 v133, v59, v113
	v_mul_f32_e32 v59, v59, v112
	v_fma_f32 v59, -v63, v113, v59
	v_fma_f32 v63, v63, v112, v133
	v_add_f32_dpp v56, v56, v56 row_shr:1 row_mask:0xf bank_mask:0xf bound_ctrl:1
	v_add_f32_dpp v57, v57, v57 row_shr:1 row_mask:0xf bank_mask:0xf bound_ctrl:1
	v_add_f32_dpp v58, v58, v58 row_shr:1 row_mask:0xf bank_mask:0xf bound_ctrl:1
	v_add_f32_dpp v59, v59, v59 row_shr:1 row_mask:0xf bank_mask:0xf bound_ctrl:1
	v_add_f32_dpp v60, v60, v60 row_shr:1 row_mask:0xf bank_mask:0xf bound_ctrl:1
	v_add_f32_dpp v61, v61, v61 row_shr:1 row_mask:0xf bank_mask:0xf bound_ctrl:1
	v_add_f32_dpp v62, v62, v62 row_shr:1 row_mask:0xf bank_mask:0xf bound_ctrl:1
	v_add_f32_dpp v63, v63, v63 row_shr:1 row_mask:0xf bank_mask:0xf bound_ctrl:1
	v_add_f32_dpp v56, v56, v56 row_shr:2 row_mask:0xf bank_mask:0xf bound_ctrl:1
	v_add_f32_dpp v57, v57, v57 row_shr:2 row_mask:0xf bank_mask:0xf bound_ctrl:1
	v_add_f32_dpp v58, v58, v58 row_shr:2 row_mask:0xf bank_mask:0xf bound_ctrl:1
	v_add_f32_dpp v59, v59, v59 row_shr:2 row_mask:0xf bank_mask:0xf bound_ctrl:1
	v_add_f32_dpp v60, v60, v60 row_shr:2 row_mask:0xf bank_mask:0xf bound_ctrl:1
	v_add_f32_dpp v61, v61, v61 row_shr:2 row_mask:0xf bank_mask:0xf bound_ctrl:1
	v_add_f32_dpp v62, v62, v62 row_shr:2 row_mask:0xf bank_mask:0xf bound_ctrl:1
	v_add_f32_dpp v63, v63, v63 row_shr:2 row_mask:0xf bank_mask:0xf bound_ctrl:1
	v_add_f32_dpp v56, v56, v56 row_shr:4 row_mask:0xf bank_mask:0xf bound_ctrl:1
	v_add_f32_dpp v57, v57, v57 row_shr:4 row_mask:0xf bank_mask:0xf bound_ctrl:1
	v_add_f32_dpp v58, v58, v58 row_shr:4 row_mask:0xf bank_mask:0xf bound_ctrl:1
	v_add_f32_dpp v59, v59, v59 row_shr:4 row_mask:0xf bank_mask:0xf bound_ctrl:1
	v_add_f32_dpp v60, v60, v60 row_shr:4 row_mask:0xf bank_mask:0xf bound_ctrl:1
	v_add_f32_dpp v61, v61, v61 row_shr:4 row_mask:0xf bank_mask:0xf bound_ctrl:1
	v_add_f32_dpp v62, v62, v62 row_shr:4 row_mask:0xf bank_mask:0xf bound_ctrl:1
	v_add_f32_dpp v63, v63, v63 row_shr:4 row_mask:0xf bank_mask:0xf bound_ctrl:1
	v_add_f32_dpp v56, v56, v56 row_shr:8 row_mask:0xf bank_mask:0xf bound_ctrl:1
	v_add_f32_dpp v57, v57, v57 row_shr:8 row_mask:0xf bank_mask:0xf bound_ctrl:1
	v_add_f32_dpp v58, v58, v58 row_shr:8 row_mask:0xf bank_mask:0xf bound_ctrl:1
	v_add_f32_dpp v59, v59, v59 row_shr:8 row_mask:0xf bank_mask:0xf bound_ctrl:1
	v_add_f32_dpp v60, v60, v60 row_shr:8 row_mask:0xf bank_mask:0xf bound_ctrl:1
	v_add_f32_dpp v61, v61, v61 row_shr:8 row_mask:0xf bank_mask:0xf bound_ctrl:1
	v_add_f32_dpp v62, v62, v62 row_shr:8 row_mask:0xf bank_mask:0xf bound_ctrl:1
	v_add_f32_dpp v63, v63, v63 row_shr:8 row_mask:0xf bank_mask:0xf bound_ctrl:1
	v_mov_b32_dpp v88, v56 row_newbcast:15 row_mask:0xf bank_mask:0xf
	v_mov_b32_dpp v89, v57 row_newbcast:15 row_mask:0xf bank_mask:0xf
	v_mov_b32_dpp v90, v58 row_newbcast:15 row_mask:0xf bank_mask:0xf
	v_mov_b32_dpp v91, v59 row_newbcast:15 row_mask:0xf bank_mask:0xf
	v_mov_b32_dpp v92, v60 row_newbcast:15 row_mask:0xf bank_mask:0xf
	v_mov_b32_dpp v93, v61 row_newbcast:15 row_mask:0xf bank_mask:0xf
	v_mov_b32_dpp v94, v62 row_newbcast:15 row_mask:0xf bank_mask:0xf
	v_mov_b32_dpp v95, v63 row_newbcast:15 row_mask:0xf bank_mask:0xf
	v_add_f32_e32 v56, v56, v178
	v_add_f32_e32 v60, v60, v179
	v_add_f32_e32 v57, v57, v180
	v_add_f32_e32 v61, v61, v181
	v_add_f32_e32 v58, v58, v182
	v_add_f32_e32 v62, v62, v183
	v_add_f32_e32 v59, v59, v184
	v_add_f32_e32 v63, v63, v185
	v_mul_f32_e32 v132, v56, v103
	v_mul_f32_e32 v56, v56, v102
	v_fma_f32 v56, -v60, v103, v56
	v_fma_f32 v60, v60, v102, v132
	v_mul_f32_e32 v133, v57, v107
	v_mul_f32_e32 v57, v57, v106
	v_fma_f32 v57, -v61, v107, v57
	v_fma_f32 v61, v61, v106, v133
	v_mul_f32_e32 v132, v58, v111
	v_mul_f32_e32 v58, v58, v110
	v_fma_f32 v58, -v62, v111, v58
	v_fma_f32 v62, v62, v110, v132
	v_mul_f32_e32 v133, v59, v115
	v_mul_f32_e32 v59, v59, v114
	v_fma_f32 v59, -v63, v115, v59
	v_fma_f32 v63, v63, v114, v133
	v_add_f32_e32 v88, v88, v178
	v_add_f32_e32 v92, v92, v179
	v_mul_f32_e32 v132, v92, v117
	v_mul_f32_e32 v179, v88, v117
	v_fma_f32 v178, v88, v116, -v132
	v_fma_f32 v179, v92, v116, v179
	v_add_f32_e32 v89, v89, v180
	v_add_f32_e32 v93, v93, v181
	v_mul_f32_e32 v133, v93, v121
	v_mul_f32_e32 v181, v89, v121
	v_fma_f32 v180, v89, v120, -v133
	v_fma_f32 v181, v93, v120, v181
	v_add_f32_e32 v90, v90, v182
	v_add_f32_e32 v94, v94, v183
	v_mul_f32_e32 v132, v94, v125
	v_mul_f32_e32 v183, v90, v125
	v_fma_f32 v182, v90, v124, -v132
	v_fma_f32 v183, v94, v124, v183
	v_add_f32_e32 v91, v91, v184
	v_add_f32_e32 v95, v95, v185
	v_mul_f32_e32 v133, v95, v129
	v_mul_f32_e32 v185, v91, v129
	v_fma_f32 v184, v91, v128, -v133
	v_fma_f32 v185, v95, v128, v185
	s_waitcnt vmcnt(14)
	v_cvt_pk_bf16_f32 v80, v80, v81
	v_cvt_pk_bf16_f32 v81, v82, v83
	v_cvt_pk_bf16_f32 v82, -v84, -v85
	v_cvt_pk_bf16_f32 v83, -v86, -v87
	v_cvt_pk_bf16_f32 v96, v32, v33
	v_cvt_pk_bf16_f32 v97, v34, v35
	v_cvt_pk_bf16_f32 v98, v36, v37
	v_cvt_pk_bf16_f32 v99, v38, v39
	s_nop 1
	v_mfma_f32_16x16x32_bf16 v[16:19], v[80:83], v[96:99], v[16:19]
	v_cvt_pk_bf16_f32 v96, v40, v41
	v_cvt_pk_bf16_f32 v97, v42, v43
	v_cvt_pk_bf16_f32 v98, v44, v45
	v_cvt_pk_bf16_f32 v99, v46, v47
	s_nop 1
	v_mfma_f32_16x16x32_bf16 v[20:23], v[80:83], v[96:99], v[20:23]
	v_cvt_pk_bf16_f32 v96, v48, v49
	v_cvt_pk_bf16_f32 v97, v50, v51
	v_cvt_pk_bf16_f32 v98, v52, v53
	v_cvt_pk_bf16_f32 v99, v54, v55
	s_nop 1
	v_mfma_f32_16x16x32_bf16 v[24:27], v[80:83], v[96:99], v[24:27]
	v_cvt_pk_bf16_f32 v96, v56, v57
	v_cvt_pk_bf16_f32 v97, v58, v59
	v_cvt_pk_bf16_f32 v98, v60, v61
	v_cvt_pk_bf16_f32 v99, v62, v63
	s_nop 1
	v_mfma_f32_16x16x32_bf16 v[28:31], v[80:83], v[96:99], v[28:31]
	s_waitcnt vmcnt(10)
	v_cvt_pk_bf16_f32 v64, v64, v65
	v_cvt_pk_bf16_f32 v65, v66, v67
	v_cvt_pk_bf16_f32 v66, v68, v69
	v_cvt_pk_bf16_f32 v67, v70, v71
	v_cvt_pk_bf16_f32 v72, v72, v73
	v_cvt_pk_bf16_f32 v73, v74, v75
	v_cvt_pk_bf16_f32 v74, v76, v77
	v_cvt_pk_bf16_f32 v75, v78, v79
	global_load_dwordx4 v[80:83], v136, s[38:39]
	global_load_dwordx4 v[84:87], v136, s[40:41]
	s_add_u32 s38, s38, 0x40
	s_addc_u32 s39, s39, 0
	s_add_u32 s40, s40, 0x40
	s_addc_u32 s41, s41, 0
	s_nop 0
	v_mfma_f32_16x16x32_bf16 v[32:35], v[64:67], v[0:3], 0
	v_mfma_f32_16x16x32_bf16 v[36:39], v[72:75], v[0:3], 0
	v_mfma_f32_16x16x32_bf16 v[40:43], v[64:67], v[4:7], 0
	v_mfma_f32_16x16x32_bf16 v[44:47], v[72:75], v[4:7], 0
	v_mfma_f32_16x16x32_bf16 v[48:51], v[64:67], v[8:11], 0
	v_mfma_f32_16x16x32_bf16 v[52:55], v[72:75], v[8:11], 0
	v_mfma_f32_16x16x32_bf16 v[56:59], v[64:67], v[12:15], 0
	v_mfma_f32_16x16x32_bf16 v[60:63], v[72:75], v[12:15], 0
	s_mov_b32 exec_hi, 0
	global_load_dwordx4 v[64:67], v135, s[20:21]
	global_load_dwordx4 v[68:71], v135, s[20:21] offset:16
	global_load_dwordx4 v[72:75], v135, s[22:23]
	global_load_dwordx4 v[76:79], v135, s[22:23] offset:16
	s_mov_b64 exec, -1
	s_add_u32 s20, s20, 0x400
	s_addc_u32 s21, s21, 0
	s_add_u32 s22, s22, 0x400
	s_addc_u32 s23, s23, 0
	global_load_dwordx4 v[100:103], v134, s[42:43] offset:0
	global_load_dwordx4 v[104:107], v134, s[42:43] offset:16
	global_load_dwordx4 v[108:111], v134, s[42:43] offset:32
	global_load_dwordx4 v[112:115], v134, s[42:43] offset:48
	global_load_dwordx4 v[116:119], v134, s[42:43] offset:64
	global_load_dwordx4 v[120:123], v134, s[42:43] offset:80
	global_load_dwordx4 v[124:127], v134, s[42:43] offset:96
	global_load_dwordx4 v[128:131], v134, s[42:43] offset:112
	global_load_dwordx4 v[178:181], v206, s[44:45]
	global_load_dwordx4 v[182:185], v206, s[44:45] offset:16
	s_add_u32 s42, s42, 0x2000
	s_addc_u32 s43, s43, 0
	s_add_u32 s44, s44, 0x80
	s_addc_u32 s45, s45, 0
	s_waitcnt vmcnt(16)
	v_mul_f32_e32 v132, v171, v157
	v_mul_f32_e32 v133, v170, v157
	v_fma_f32 v170, v170, v156, -v132
	v_fma_f32 v171, v171, v156, v133
	v_mul_f32_e32 v132, v173, v161
	v_mul_f32_e32 v133, v172, v161
	v_fma_f32 v172, v172, v160, -v132
	v_fma_f32 v173, v173, v160, v133
	v_mul_f32_e32 v132, v175, v165
	v_mul_f32_e32 v133, v174, v165
	v_fma_f32 v174, v174, v164, -v132
	v_fma_f32 v175, v175, v164, v133
	v_mul_f32_e32 v132, v177, v169
	v_mul_f32_e32 v133, v176, v169
	v_fma_f32 v176, v176, v168, -v132
	v_fma_f32 v177, v177, v168, v133
	v_mul_f32_e32 v132, v56, v139
	v_mul_f32_e32 v56, v56, v138
	v_fma_f32 v56, -v60, v139, v56
	v_fma_f32 v60, v60, v138, v132
	v_mul_f32_e32 v133, v57, v143
	v_mul_f32_e32 v57, v57, v142
	v_fma_f32 v57, -v61, v143, v57
	v_fma_f32 v61, v61, v142, v133
	v_mul_f32_e32 v132, v58, v147
	v_mul_f32_e32 v58, v58, v146
	v_fma_f32 v58, -v62, v147, v58
	v_fma_f32 v62, v62, v146, v132
	v_mul_f32_e32 v133, v59, v151
	v_mul_f32_e32 v59, v59, v150
	v_fma_f32 v59, -v63, v151, v59
	v_fma_f32 v63, v63, v150, v133
	v_add_f32_dpp v56, v56, v56 row_shl:1 row_mask:0xf bank_mask:0xf bound_ctrl:1
	v_add_f32_dpp v57, v57, v57 row_shl:1 row_mask:0xf bank_mask:0xf bound_ctrl:1
	v_add_f32_dpp v58, v58, v58 row_shl:1 row_mask:0xf bank_mask:0xf bound_ctrl:1
	v_add_f32_dpp v59, v59, v59 row_shl:1 row_mask:0xf bank_mask:0xf bound_ctrl:1
	v_add_f32_dpp v60, v60, v60 row_shl:1 row_mask:0xf bank_mask:0xf bound_ctrl:1
	v_add_f32_dpp v61, v61, v61 row_shl:1 row_mask:0xf bank_mask:0xf bound_ctrl:1
	v_add_f32_dpp v62, v62, v62 row_shl:1 row_mask:0xf bank_mask:0xf bound_ctrl:1
	v_add_f32_dpp v63, v63, v63 row_shl:1 row_mask:0xf bank_mask:0xf bound_ctrl:1
	v_add_f32_dpp v56, v56, v56 row_shl:2 row_mask:0xf bank_mask:0xf bound_ctrl:1
	v_add_f32_dpp v57, v57, v57 row_shl:2 row_mask:0xf bank_mask:0xf bound_ctrl:1
	v_add_f32_dpp v58, v58, v58 row_shl:2 row_mask:0xf bank_mask:0xf bound_ctrl:1
	v_add_f32_dpp v59, v59, v59 row_shl:2 row_mask:0xf bank_mask:0xf bound_ctrl:1
	v_add_f32_dpp v60, v60, v60 row_shl:2 row_mask:0xf bank_mask:0xf bound_ctrl:1
	v_add_f32_dpp v61, v61, v61 row_shl:2 row_mask:0xf bank_mask:0xf bound_ctrl:1
	v_add_f32_dpp v62, v62, v62 row_shl:2 row_mask:0xf bank_mask:0xf bound_ctrl:1
	v_add_f32_dpp v63, v63, v63 row_shl:2 row_mask:0xf bank_mask:0xf bound_ctrl:1
	v_add_f32_dpp v56, v56, v56 row_shl:4 row_mask:0xf bank_mask:0xf bound_ctrl:1
	v_add_f32_dpp v57, v57, v57 row_shl:4 row_mask:0xf bank_mask:0xf bound_ctrl:1
	v_add_f32_dpp v58, v58, v58 row_shl:4 row_mask:0xf bank_mask:0xf bound_ctrl:1
	v_add_f32_dpp v59, v59, v59 row_shl:4 row_mask:0xf bank_mask:0xf bound_ctrl:1
	v_add_f32_dpp v60, v60, v60 row_shl:4 row_mask:0xf bank_mask:0xf bound_ctrl:1
	v_add_f32_dpp v61, v61, v61 row_shl:4 row_mask:0xf bank_mask:0xf bound_ctrl:1
	v_add_f32_dpp v62, v62, v62 row_shl:4 row_mask:0xf bank_mask:0xf bound_ctrl:1
	v_add_f32_dpp v63, v63, v63 row_shl:4 row_mask:0xf bank_mask:0xf bound_ctrl:1
	v_add_f32_dpp v56, v56, v56 row_shl:8 row_mask:0xf bank_mask:0xf bound_ctrl:1
	v_add_f32_dpp v57, v57, v57 row_shl:8 row_mask:0xf bank_mask:0xf bound_ctrl:1
	v_add_f32_dpp v58, v58, v58 row_shl:8 row_mask:0xf bank_mask:0xf bound_ctrl:1
	v_add_f32_dpp v59, v59, v59 row_shl:8 row_mask:0xf bank_mask:0xf bound_ctrl:1
	v_add_f32_dpp v60, v60, v60 row_shl:8 row_mask:0xf bank_mask:0xf bound_ctrl:1
	v_add_f32_dpp v61, v61, v61 row_shl:8 row_mask:0xf bank_mask:0xf bound_ctrl:1
	v_add_f32_dpp v62, v62, v62 row_shl:8 row_mask:0xf bank_mask:0xf bound_ctrl:1
	v_add_f32_dpp v63, v63, v63 row_shl:8 row_mask:0xf bank_mask:0xf bound_ctrl:1
	v_mov_b32_dpp v88, v56 row_newbcast:0 row_mask:0xf bank_mask:0xf
	v_mov_b32_dpp v89, v57 row_newbcast:0 row_mask:0xf bank_mask:0xf
	v_mov_b32_dpp v90, v58 row_newbcast:0 row_mask:0xf bank_mask:0xf
	v_mov_b32_dpp v91, v59 row_newbcast:0 row_mask:0xf bank_mask:0xf
	v_mov_b32_dpp v92, v60 row_newbcast:0 row_mask:0xf bank_mask:0xf
	v_mov_b32_dpp v93, v61 row_newbcast:0 row_mask:0xf bank_mask:0xf
	v_mov_b32_dpp v94, v62 row_newbcast:0 row_mask:0xf bank_mask:0xf
	v_mov_b32_dpp v95, v63 row_newbcast:0 row_mask:0xf bank_mask:0xf
	v_add_f32_e32 v56, v56, v170
	v_add_f32_e32 v60, v60, v171
	v_add_f32_e32 v57, v57, v172
	v_add_f32_e32 v61, v61, v173
	v_add_f32_e32 v58, v58, v174
	v_add_f32_e32 v62, v62, v175
	v_add_f32_e32 v59, v59, v176
	v_add_f32_e32 v63, v63, v177
	v_mul_f32_e32 v132, v56, v141
	v_mul_f32_e32 v56, v56, v140
	v_fma_f32 v56, -v60, v141, v56
	v_fma_f32 v60, v60, v140, v132
	v_mul_f32_e32 v133, v57, v145
	v_mul_f32_e32 v57, v57, v144
	v_fma_f32 v57, -v61, v145, v57
	v_fma_f32 v61, v61, v144, v133
	v_mul_f32_e32 v132, v58, v149
	v_mul_f32_e32 v58, v58, v148
	v_fma_f32 v58, -v62, v149, v58
	v_fma_f32 v62, v62, v148, v132
	v_mul_f32_e32 v133, v59, v153
	v_mul_f32_e32 v59, v59, v152
	v_fma_f32 v59, -v63, v153, v59
	v_fma_f32 v63, v63, v152, v133
	v_add_f32_e32 v88, v88, v170
	v_add_f32_e32 v92, v92, v171
	v_mul_f32_e32 v132, v92, v155
	v_mul_f32_e32 v171, v88, v155
	v_fma_f32 v170, v88, v154, -v132
	v_fma_f32 v171, v92, v154, v171
	v_add_f32_e32 v89, v89, v172
	v_add_f32_e32 v93, v93, v173
	v_mul_f32_e32 v133, v93, v159
	v_mul_f32_e32 v173, v89, v159
	v_fma_f32 v172, v89, v158, -v133
	v_fma_f32 v173, v93, v158, v173
	v_add_f32_e32 v90, v90, v174
	v_add_f32_e32 v94, v94, v175
	v_mul_f32_e32 v132, v94, v163
	v_mul_f32_e32 v175, v90, v163
	v_fma_f32 v174, v90, v162, -v132
	v_fma_f32 v175, v94, v162, v175
	v_add_f32_e32 v91, v91, v176
	v_add_f32_e32 v95, v95, v177
	v_mul_f32_e32 v133, v95, v167
	v_mul_f32_e32 v177, v91, v167
	v_fma_f32 v176, v91, v166, -v133
	v_fma_f32 v177, v95, v166, v177
	v_mul_f32_e32 v132, v48, v139
	v_mul_f32_e32 v48, v48, v138
	v_fma_f32 v48, -v52, v139, v48
	v_fma_f32 v52, v52, v138, v132
	v_mul_f32_e32 v133, v49, v143
	v_mul_f32_e32 v49, v49, v142
	v_fma_f32 v49, -v53, v143, v49
	v_fma_f32 v53, v53, v142, v133
	v_mul_f32_e32 v132, v50, v147
	v_mul_f32_e32 v50, v50, v146
	v_fma_f32 v50, -v54, v147, v50
	v_fma_f32 v54, v54, v146, v132
	v_mul_f32_e32 v133, v51, v151
	v_mul_f32_e32 v51, v51, v150
	v_fma_f32 v51, -v55, v151, v51
	v_fma_f32 v55, v55, v150, v133
	v_add_f32_dpp v48, v48, v48 row_shl:1 row_mask:0xf bank_mask:0xf bound_ctrl:1
	v_add_f32_dpp v49, v49, v49 row_shl:1 row_mask:0xf bank_mask:0xf bound_ctrl:1
	v_add_f32_dpp v50, v50, v50 row_shl:1 row_mask:0xf bank_mask:0xf bound_ctrl:1
	v_add_f32_dpp v51, v51, v51 row_shl:1 row_mask:0xf bank_mask:0xf bound_ctrl:1
	v_add_f32_dpp v52, v52, v52 row_shl:1 row_mask:0xf bank_mask:0xf bound_ctrl:1
	v_add_f32_dpp v53, v53, v53 row_shl:1 row_mask:0xf bank_mask:0xf bound_ctrl:1
	v_add_f32_dpp v54, v54, v54 row_shl:1 row_mask:0xf bank_mask:0xf bound_ctrl:1
	v_add_f32_dpp v55, v55, v55 row_shl:1 row_mask:0xf bank_mask:0xf bound_ctrl:1
	v_add_f32_dpp v48, v48, v48 row_shl:2 row_mask:0xf bank_mask:0xf bound_ctrl:1
	v_add_f32_dpp v49, v49, v49 row_shl:2 row_mask:0xf bank_mask:0xf bound_ctrl:1
	v_add_f32_dpp v50, v50, v50 row_shl:2 row_mask:0xf bank_mask:0xf bound_ctrl:1
	v_add_f32_dpp v51, v51, v51 row_shl:2 row_mask:0xf bank_mask:0xf bound_ctrl:1
	v_add_f32_dpp v52, v52, v52 row_shl:2 row_mask:0xf bank_mask:0xf bound_ctrl:1
	v_add_f32_dpp v53, v53, v53 row_shl:2 row_mask:0xf bank_mask:0xf bound_ctrl:1
	v_add_f32_dpp v54, v54, v54 row_shl:2 row_mask:0xf bank_mask:0xf bound_ctrl:1
	v_add_f32_dpp v55, v55, v55 row_shl:2 row_mask:0xf bank_mask:0xf bound_ctrl:1
	v_add_f32_dpp v48, v48, v48 row_shl:4 row_mask:0xf bank_mask:0xf bound_ctrl:1
	v_add_f32_dpp v49, v49, v49 row_shl:4 row_mask:0xf bank_mask:0xf bound_ctrl:1
	v_add_f32_dpp v50, v50, v50 row_shl:4 row_mask:0xf bank_mask:0xf bound_ctrl:1
	v_add_f32_dpp v51, v51, v51 row_shl:4 row_mask:0xf bank_mask:0xf bound_ctrl:1
	v_add_f32_dpp v52, v52, v52 row_shl:4 row_mask:0xf bank_mask:0xf bound_ctrl:1
	v_add_f32_dpp v53, v53, v53 row_shl:4 row_mask:0xf bank_mask:0xf bound_ctrl:1
	v_add_f32_dpp v54, v54, v54 row_shl:4 row_mask:0xf bank_mask:0xf bound_ctrl:1
	v_add_f32_dpp v55, v55, v55 row_shl:4 row_mask:0xf bank_mask:0xf bound_ctrl:1
	v_add_f32_dpp v48, v48, v48 row_shl:8 row_mask:0xf bank_mask:0xf bound_ctrl:1
	v_add_f32_dpp v49, v49, v49 row_shl:8 row_mask:0xf bank_mask:0xf bound_ctrl:1
	v_add_f32_dpp v50, v50, v50 row_shl:8 row_mask:0xf bank_mask:0xf bound_ctrl:1
	v_add_f32_dpp v51, v51, v51 row_shl:8 row_mask:0xf bank_mask:0xf bound_ctrl:1
	v_add_f32_dpp v52, v52, v52 row_shl:8 row_mask:0xf bank_mask:0xf bound_ctrl:1
	v_add_f32_dpp v53, v53, v53 row_shl:8 row_mask:0xf bank_mask:0xf bound_ctrl:1
	v_add_f32_dpp v54, v54, v54 row_shl:8 row_mask:0xf bank_mask:0xf bound_ctrl:1
	v_add_f32_dpp v55, v55, v55 row_shl:8 row_mask:0xf bank_mask:0xf bound_ctrl:1
	v_mov_b32_dpp v88, v48 row_newbcast:0 row_mask:0xf bank_mask:0xf
	v_mov_b32_dpp v89, v49 row_newbcast:0 row_mask:0xf bank_mask:0xf
	v_mov_b32_dpp v90, v50 row_newbcast:0 row_mask:0xf bank_mask:0xf
	v_mov_b32_dpp v91, v51 row_newbcast:0 row_mask:0xf bank_mask:0xf
	v_mov_b32_dpp v92, v52 row_newbcast:0 row_mask:0xf bank_mask:0xf
	v_mov_b32_dpp v93, v53 row_newbcast:0 row_mask:0xf bank_mask:0xf
	v_mov_b32_dpp v94, v54 row_newbcast:0 row_mask:0xf bank_mask:0xf
	v_mov_b32_dpp v95, v55 row_newbcast:0 row_mask:0xf bank_mask:0xf
	v_add_f32_e32 v48, v48, v170
	v_add_f32_e32 v52, v52, v171
	v_add_f32_e32 v49, v49, v172
	v_add_f32_e32 v53, v53, v173
	v_add_f32_e32 v50, v50, v174
	v_add_f32_e32 v54, v54, v175
	v_add_f32_e32 v51, v51, v176
	v_add_f32_e32 v55, v55, v177
	v_mul_f32_e32 v132, v48, v141
	v_mul_f32_e32 v48, v48, v140
	v_fma_f32 v48, -v52, v141, v48
	v_fma_f32 v52, v52, v140, v132
	v_mul_f32_e32 v133, v49, v145
	v_mul_f32_e32 v49, v49, v144
	v_fma_f32 v49, -v53, v145, v49
	v_fma_f32 v53, v53, v144, v133
	v_mul_f32_e32 v132, v50, v149
	v_mul_f32_e32 v50, v50, v148
	v_fma_f32 v50, -v54, v149, v50
	v_fma_f32 v54, v54, v148, v132
	v_mul_f32_e32 v133, v51, v153
	v_mul_f32_e32 v51, v51, v152
	v_fma_f32 v51, -v55, v153, v51
	v_fma_f32 v55, v55, v152, v133
	v_add_f32_e32 v88, v88, v170
	v_add_f32_e32 v92, v92, v171
	v_mul_f32_e32 v132, v92, v155
	v_mul_f32_e32 v171, v88, v155
	v_fma_f32 v170, v88, v154, -v132
	v_fma_f32 v171, v92, v154, v171
	v_add_f32_e32 v89, v89, v172
	v_add_f32_e32 v93, v93, v173
	v_mul_f32_e32 v133, v93, v159
	v_mul_f32_e32 v173, v89, v159
	v_fma_f32 v172, v89, v158, -v133
	v_fma_f32 v173, v93, v158, v173
	v_add_f32_e32 v90, v90, v174
	v_add_f32_e32 v94, v94, v175
	v_mul_f32_e32 v132, v94, v163
	v_mul_f32_e32 v175, v90, v163
	v_fma_f32 v174, v90, v162, -v132
	v_fma_f32 v175, v94, v162, v175
	v_add_f32_e32 v91, v91, v176
	v_add_f32_e32 v95, v95, v177
	v_mul_f32_e32 v133, v95, v167
	v_mul_f32_e32 v177, v91, v167
	v_fma_f32 v176, v91, v166, -v133
	v_fma_f32 v177, v95, v166, v177
	v_mul_f32_e32 v132, v40, v139
	v_mul_f32_e32 v40, v40, v138
	v_fma_f32 v40, -v44, v139, v40
	v_fma_f32 v44, v44, v138, v132
	v_mul_f32_e32 v133, v41, v143
	v_mul_f32_e32 v41, v41, v142
	v_fma_f32 v41, -v45, v143, v41
	v_fma_f32 v45, v45, v142, v133
	v_mul_f32_e32 v132, v42, v147
	v_mul_f32_e32 v42, v42, v146
	v_fma_f32 v42, -v46, v147, v42
	v_fma_f32 v46, v46, v146, v132
	v_mul_f32_e32 v133, v43, v151
	v_mul_f32_e32 v43, v43, v150
	v_fma_f32 v43, -v47, v151, v43
	v_fma_f32 v47, v47, v150, v133
	v_add_f32_dpp v40, v40, v40 row_shl:1 row_mask:0xf bank_mask:0xf bound_ctrl:1
	v_add_f32_dpp v41, v41, v41 row_shl:1 row_mask:0xf bank_mask:0xf bound_ctrl:1
	v_add_f32_dpp v42, v42, v42 row_shl:1 row_mask:0xf bank_mask:0xf bound_ctrl:1
	v_add_f32_dpp v43, v43, v43 row_shl:1 row_mask:0xf bank_mask:0xf bound_ctrl:1
	v_add_f32_dpp v44, v44, v44 row_shl:1 row_mask:0xf bank_mask:0xf bound_ctrl:1
	v_add_f32_dpp v45, v45, v45 row_shl:1 row_mask:0xf bank_mask:0xf bound_ctrl:1
	v_add_f32_dpp v46, v46, v46 row_shl:1 row_mask:0xf bank_mask:0xf bound_ctrl:1
	v_add_f32_dpp v47, v47, v47 row_shl:1 row_mask:0xf bank_mask:0xf bound_ctrl:1
	v_add_f32_dpp v40, v40, v40 row_shl:2 row_mask:0xf bank_mask:0xf bound_ctrl:1
	v_add_f32_dpp v41, v41, v41 row_shl:2 row_mask:0xf bank_mask:0xf bound_ctrl:1
	v_add_f32_dpp v42, v42, v42 row_shl:2 row_mask:0xf bank_mask:0xf bound_ctrl:1
	v_add_f32_dpp v43, v43, v43 row_shl:2 row_mask:0xf bank_mask:0xf bound_ctrl:1
	v_add_f32_dpp v44, v44, v44 row_shl:2 row_mask:0xf bank_mask:0xf bound_ctrl:1
	v_add_f32_dpp v45, v45, v45 row_shl:2 row_mask:0xf bank_mask:0xf bound_ctrl:1
	v_add_f32_dpp v46, v46, v46 row_shl:2 row_mask:0xf bank_mask:0xf bound_ctrl:1
	v_add_f32_dpp v47, v47, v47 row_shl:2 row_mask:0xf bank_mask:0xf bound_ctrl:1
	v_add_f32_dpp v40, v40, v40 row_shl:4 row_mask:0xf bank_mask:0xf bound_ctrl:1
	v_add_f32_dpp v41, v41, v41 row_shl:4 row_mask:0xf bank_mask:0xf bound_ctrl:1
	v_add_f32_dpp v42, v42, v42 row_shl:4 row_mask:0xf bank_mask:0xf bound_ctrl:1
	v_add_f32_dpp v43, v43, v43 row_shl:4 row_mask:0xf bank_mask:0xf bound_ctrl:1
	v_add_f32_dpp v44, v44, v44 row_shl:4 row_mask:0xf bank_mask:0xf bound_ctrl:1
	v_add_f32_dpp v45, v45, v45 row_shl:4 row_mask:0xf bank_mask:0xf bound_ctrl:1
	v_add_f32_dpp v46, v46, v46 row_shl:4 row_mask:0xf bank_mask:0xf bound_ctrl:1
	v_add_f32_dpp v47, v47, v47 row_shl:4 row_mask:0xf bank_mask:0xf bound_ctrl:1
	v_add_f32_dpp v40, v40, v40 row_shl:8 row_mask:0xf bank_mask:0xf bound_ctrl:1
	v_add_f32_dpp v41, v41, v41 row_shl:8 row_mask:0xf bank_mask:0xf bound_ctrl:1
	v_add_f32_dpp v42, v42, v42 row_shl:8 row_mask:0xf bank_mask:0xf bound_ctrl:1
	v_add_f32_dpp v43, v43, v43 row_shl:8 row_mask:0xf bank_mask:0xf bound_ctrl:1
	v_add_f32_dpp v44, v44, v44 row_shl:8 row_mask:0xf bank_mask:0xf bound_ctrl:1
	v_add_f32_dpp v45, v45, v45 row_shl:8 row_mask:0xf bank_mask:0xf bound_ctrl:1
	v_add_f32_dpp v46, v46, v46 row_shl:8 row_mask:0xf bank_mask:0xf bound_ctrl:1
	v_add_f32_dpp v47, v47, v47 row_shl:8 row_mask:0xf bank_mask:0xf bound_ctrl:1
	v_mov_b32_dpp v88, v40 row_newbcast:0 row_mask:0xf bank_mask:0xf
	v_mov_b32_dpp v89, v41 row_newbcast:0 row_mask:0xf bank_mask:0xf
	v_mov_b32_dpp v90, v42 row_newbcast:0 row_mask:0xf bank_mask:0xf
	v_mov_b32_dpp v91, v43 row_newbcast:0 row_mask:0xf bank_mask:0xf
	v_mov_b32_dpp v92, v44 row_newbcast:0 row_mask:0xf bank_mask:0xf
	v_mov_b32_dpp v93, v45 row_newbcast:0 row_mask:0xf bank_mask:0xf
	v_mov_b32_dpp v94, v46 row_newbcast:0 row_mask:0xf bank_mask:0xf
	v_mov_b32_dpp v95, v47 row_newbcast:0 row_mask:0xf bank_mask:0xf
	v_add_f32_e32 v40, v40, v170
	v_add_f32_e32 v44, v44, v171
	v_add_f32_e32 v41, v41, v172
	v_add_f32_e32 v45, v45, v173
	v_add_f32_e32 v42, v42, v174
	v_add_f32_e32 v46, v46, v175
	v_add_f32_e32 v43, v43, v176
	v_add_f32_e32 v47, v47, v177
	v_mul_f32_e32 v132, v40, v141
	v_mul_f32_e32 v40, v40, v140
	v_fma_f32 v40, -v44, v141, v40
	v_fma_f32 v44, v44, v140, v132
	v_mul_f32_e32 v133, v41, v145
	v_mul_f32_e32 v41, v41, v144
	v_fma_f32 v41, -v45, v145, v41
	v_fma_f32 v45, v45, v144, v133
	v_mul_f32_e32 v132, v42, v149
	v_mul_f32_e32 v42, v42, v148
	v_fma_f32 v42, -v46, v149, v42
	v_fma_f32 v46, v46, v148, v132
	v_mul_f32_e32 v133, v43, v153
	v_mul_f32_e32 v43, v43, v152
	v_fma_f32 v43, -v47, v153, v43
	v_fma_f32 v47, v47, v152, v133
	v_add_f32_e32 v88, v88, v170
	v_add_f32_e32 v92, v92, v171
	v_mul_f32_e32 v132, v92, v155
	v_mul_f32_e32 v171, v88, v155
	v_fma_f32 v170, v88, v154, -v132
	v_fma_f32 v171, v92, v154, v171
	v_add_f32_e32 v89, v89, v172
	v_add_f32_e32 v93, v93, v173
	v_mul_f32_e32 v133, v93, v159
	v_mul_f32_e32 v173, v89, v159
	v_fma_f32 v172, v89, v158, -v133
	v_fma_f32 v173, v93, v158, v173
	v_add_f32_e32 v90, v90, v174
	v_add_f32_e32 v94, v94, v175
	v_mul_f32_e32 v132, v94, v163
	v_mul_f32_e32 v175, v90, v163
	v_fma_f32 v174, v90, v162, -v132
	v_fma_f32 v175, v94, v162, v175
	v_add_f32_e32 v91, v91, v176
	v_add_f32_e32 v95, v95, v177
	v_mul_f32_e32 v133, v95, v167
	v_mul_f32_e32 v177, v91, v167
	v_fma_f32 v176, v91, v166, -v133
	v_fma_f32 v177, v95, v166, v177
	v_mul_f32_e32 v132, v32, v139
	v_mul_f32_e32 v32, v32, v138
	v_fma_f32 v32, -v36, v139, v32
	v_fma_f32 v36, v36, v138, v132
	v_mul_f32_e32 v133, v33, v143
	v_mul_f32_e32 v33, v33, v142
	v_fma_f32 v33, -v37, v143, v33
	v_fma_f32 v37, v37, v142, v133
	v_mul_f32_e32 v132, v34, v147
	v_mul_f32_e32 v34, v34, v146
	v_fma_f32 v34, -v38, v147, v34
	v_fma_f32 v38, v38, v146, v132
	v_mul_f32_e32 v133, v35, v151
	v_mul_f32_e32 v35, v35, v150
	v_fma_f32 v35, -v39, v151, v35
	v_fma_f32 v39, v39, v150, v133
	v_add_f32_dpp v32, v32, v32 row_shl:1 row_mask:0xf bank_mask:0xf bound_ctrl:1
	v_add_f32_dpp v33, v33, v33 row_shl:1 row_mask:0xf bank_mask:0xf bound_ctrl:1
	v_add_f32_dpp v34, v34, v34 row_shl:1 row_mask:0xf bank_mask:0xf bound_ctrl:1
	v_add_f32_dpp v35, v35, v35 row_shl:1 row_mask:0xf bank_mask:0xf bound_ctrl:1
	v_add_f32_dpp v36, v36, v36 row_shl:1 row_mask:0xf bank_mask:0xf bound_ctrl:1
	v_add_f32_dpp v37, v37, v37 row_shl:1 row_mask:0xf bank_mask:0xf bound_ctrl:1
	v_add_f32_dpp v38, v38, v38 row_shl:1 row_mask:0xf bank_mask:0xf bound_ctrl:1
	v_add_f32_dpp v39, v39, v39 row_shl:1 row_mask:0xf bank_mask:0xf bound_ctrl:1
	v_add_f32_dpp v32, v32, v32 row_shl:2 row_mask:0xf bank_mask:0xf bound_ctrl:1
	v_add_f32_dpp v33, v33, v33 row_shl:2 row_mask:0xf bank_mask:0xf bound_ctrl:1
	v_add_f32_dpp v34, v34, v34 row_shl:2 row_mask:0xf bank_mask:0xf bound_ctrl:1
	v_add_f32_dpp v35, v35, v35 row_shl:2 row_mask:0xf bank_mask:0xf bound_ctrl:1
	v_add_f32_dpp v36, v36, v36 row_shl:2 row_mask:0xf bank_mask:0xf bound_ctrl:1
	v_add_f32_dpp v37, v37, v37 row_shl:2 row_mask:0xf bank_mask:0xf bound_ctrl:1
	v_add_f32_dpp v38, v38, v38 row_shl:2 row_mask:0xf bank_mask:0xf bound_ctrl:1
	v_add_f32_dpp v39, v39, v39 row_shl:2 row_mask:0xf bank_mask:0xf bound_ctrl:1
	v_add_f32_dpp v32, v32, v32 row_shl:4 row_mask:0xf bank_mask:0xf bound_ctrl:1
	v_add_f32_dpp v33, v33, v33 row_shl:4 row_mask:0xf bank_mask:0xf bound_ctrl:1
	v_add_f32_dpp v34, v34, v34 row_shl:4 row_mask:0xf bank_mask:0xf bound_ctrl:1
	v_add_f32_dpp v35, v35, v35 row_shl:4 row_mask:0xf bank_mask:0xf bound_ctrl:1
	v_add_f32_dpp v36, v36, v36 row_shl:4 row_mask:0xf bank_mask:0xf bound_ctrl:1
	v_add_f32_dpp v37, v37, v37 row_shl:4 row_mask:0xf bank_mask:0xf bound_ctrl:1
	v_add_f32_dpp v38, v38, v38 row_shl:4 row_mask:0xf bank_mask:0xf bound_ctrl:1
	v_add_f32_dpp v39, v39, v39 row_shl:4 row_mask:0xf bank_mask:0xf bound_ctrl:1
	v_add_f32_dpp v32, v32, v32 row_shl:8 row_mask:0xf bank_mask:0xf bound_ctrl:1
	v_add_f32_dpp v33, v33, v33 row_shl:8 row_mask:0xf bank_mask:0xf bound_ctrl:1
	v_add_f32_dpp v34, v34, v34 row_shl:8 row_mask:0xf bank_mask:0xf bound_ctrl:1
	v_add_f32_dpp v35, v35, v35 row_shl:8 row_mask:0xf bank_mask:0xf bound_ctrl:1
	v_add_f32_dpp v36, v36, v36 row_shl:8 row_mask:0xf bank_mask:0xf bound_ctrl:1
	v_add_f32_dpp v37, v37, v37 row_shl:8 row_mask:0xf bank_mask:0xf bound_ctrl:1
	v_add_f32_dpp v38, v38, v38 row_shl:8 row_mask:0xf bank_mask:0xf bound_ctrl:1
	v_add_f32_dpp v39, v39, v39 row_shl:8 row_mask:0xf bank_mask:0xf bound_ctrl:1
	v_mov_b32_dpp v88, v32 row_newbcast:0 row_mask:0xf bank_mask:0xf
	v_mov_b32_dpp v89, v33 row_newbcast:0 row_mask:0xf bank_mask:0xf
	v_mov_b32_dpp v90, v34 row_newbcast:0 row_mask:0xf bank_mask:0xf
	v_mov_b32_dpp v91, v35 row_newbcast:0 row_mask:0xf bank_mask:0xf
	v_mov_b32_dpp v92, v36 row_newbcast:0 row_mask:0xf bank_mask:0xf
	v_mov_b32_dpp v93, v37 row_newbcast:0 row_mask:0xf bank_mask:0xf
	v_mov_b32_dpp v94, v38 row_newbcast:0 row_mask:0xf bank_mask:0xf
	v_mov_b32_dpp v95, v39 row_newbcast:0 row_mask:0xf bank_mask:0xf
	v_add_f32_e32 v32, v32, v170
	v_add_f32_e32 v36, v36, v171
	v_add_f32_e32 v33, v33, v172
	v_add_f32_e32 v37, v37, v173
	v_add_f32_e32 v34, v34, v174
	v_add_f32_e32 v38, v38, v175
	v_add_f32_e32 v35, v35, v176
	v_add_f32_e32 v39, v39, v177
	v_mul_f32_e32 v132, v32, v141
	v_mul_f32_e32 v32, v32, v140
	v_fma_f32 v32, -v36, v141, v32
	v_fma_f32 v36, v36, v140, v132
	v_mul_f32_e32 v133, v33, v145
	v_mul_f32_e32 v33, v33, v144
	v_fma_f32 v33, -v37, v145, v33
	v_fma_f32 v37, v37, v144, v133
	v_mul_f32_e32 v132, v34, v149
	v_mul_f32_e32 v34, v34, v148
	v_fma_f32 v34, -v38, v149, v34
	v_fma_f32 v38, v38, v148, v132
	v_mul_f32_e32 v133, v35, v153
	v_mul_f32_e32 v35, v35, v152
	v_fma_f32 v35, -v39, v153, v35
	v_fma_f32 v39, v39, v152, v133
	v_add_f32_e32 v88, v88, v170
	v_add_f32_e32 v92, v92, v171
	v_mul_f32_e32 v132, v92, v155
	v_mul_f32_e32 v171, v88, v155
	v_fma_f32 v170, v88, v154, -v132
	v_fma_f32 v171, v92, v154, v171
	v_add_f32_e32 v89, v89, v172
	v_add_f32_e32 v93, v93, v173
	v_mul_f32_e32 v133, v93, v159
	v_mul_f32_e32 v173, v89, v159
	v_fma_f32 v172, v89, v158, -v133
	v_fma_f32 v173, v93, v158, v173
	v_add_f32_e32 v90, v90, v174
	v_add_f32_e32 v94, v94, v175
	v_mul_f32_e32 v132, v94, v163
	v_mul_f32_e32 v175, v90, v163
	v_fma_f32 v174, v90, v162, -v132
	v_fma_f32 v175, v94, v162, v175
	v_add_f32_e32 v91, v91, v176
	v_add_f32_e32 v95, v95, v177
	v_mul_f32_e32 v133, v95, v167
	v_mul_f32_e32 v177, v91, v167
	v_fma_f32 v176, v91, v166, -v133
	v_fma_f32 v177, v95, v166, v177
	s_waitcnt vmcnt(14)
	v_cvt_pk_bf16_f32 v80, v80, v81
	v_cvt_pk_bf16_f32 v81, v82, v83
	v_cvt_pk_bf16_f32 v82, -v84, -v85
	v_cvt_pk_bf16_f32 v83, -v86, -v87
	v_cvt_pk_bf16_f32 v96, v32, v33
	v_cvt_pk_bf16_f32 v97, v34, v35
	v_cvt_pk_bf16_f32 v98, v36, v37
	v_cvt_pk_bf16_f32 v99, v38, v39
	s_nop 1
	v_mfma_f32_16x16x32_bf16 v[16:19], v[80:83], v[96:99], v[16:19]
	v_cvt_pk_bf16_f32 v96, v40, v41
	v_cvt_pk_bf16_f32 v97, v42, v43
	v_cvt_pk_bf16_f32 v98, v44, v45
	v_cvt_pk_bf16_f32 v99, v46, v47
	s_nop 1
	v_mfma_f32_16x16x32_bf16 v[20:23], v[80:83], v[96:99], v[20:23]
	v_cvt_pk_bf16_f32 v96, v48, v49
	v_cvt_pk_bf16_f32 v97, v50, v51
	v_cvt_pk_bf16_f32 v98, v52, v53
	v_cvt_pk_bf16_f32 v99, v54, v55
	s_nop 1
	v_mfma_f32_16x16x32_bf16 v[24:27], v[80:83], v[96:99], v[24:27]
	v_cvt_pk_bf16_f32 v96, v56, v57
	v_cvt_pk_bf16_f32 v97, v58, v59
	v_cvt_pk_bf16_f32 v98, v60, v61
	v_cvt_pk_bf16_f32 v99, v62, v63
	s_nop 1
	v_mfma_f32_16x16x32_bf16 v[28:31], v[80:83], v[96:99], v[28:31]
	s_waitcnt vmcnt(10)
	v_cvt_pk_bf16_f32 v64, v64, v65
	v_cvt_pk_bf16_f32 v65, v66, v67
	v_cvt_pk_bf16_f32 v66, v68, v69
	v_cvt_pk_bf16_f32 v67, v70, v71
	v_cvt_pk_bf16_f32 v72, v72, v73
	v_cvt_pk_bf16_f32 v73, v74, v75
	v_cvt_pk_bf16_f32 v74, v76, v77
	v_cvt_pk_bf16_f32 v75, v78, v79
	global_load_dwordx4 v[80:83], v136, s[38:39]
	global_load_dwordx4 v[84:87], v136, s[40:41]
	s_add_u32 s38, s38, 0x40
	s_addc_u32 s39, s39, 0
	s_add_u32 s40, s40, 0x40
	s_addc_u32 s41, s41, 0
	s_nop 0
	v_mfma_f32_16x16x32_bf16 v[32:35], v[64:67], v[0:3], 0
	v_mfma_f32_16x16x32_bf16 v[36:39], v[72:75], v[0:3], 0
	v_mfma_f32_16x16x32_bf16 v[40:43], v[64:67], v[4:7], 0
	v_mfma_f32_16x16x32_bf16 v[44:47], v[72:75], v[4:7], 0
	v_mfma_f32_16x16x32_bf16 v[48:51], v[64:67], v[8:11], 0
	v_mfma_f32_16x16x32_bf16 v[52:55], v[72:75], v[8:11], 0
	v_mfma_f32_16x16x32_bf16 v[56:59], v[64:67], v[12:15], 0
	v_mfma_f32_16x16x32_bf16 v[60:63], v[72:75], v[12:15], 0
	s_mov_b32 exec_hi, 0
	global_load_dwordx4 v[64:67], v135, s[20:21]
	global_load_dwordx4 v[68:71], v135, s[20:21] offset:16
	global_load_dwordx4 v[72:75], v135, s[22:23]
	global_load_dwordx4 v[76:79], v135, s[22:23] offset:16
	s_mov_b64 exec, -1
	s_add_u32 s20, s20, 0x400
	s_addc_u32 s21, s21, 0
	s_add_u32 s22, s22, 0x400
	s_addc_u32 s23, s23, 0
	global_load_dwordx4 v[138:141], v134, s[42:43] offset:0
	global_load_dwordx4 v[142:145], v134, s[42:43] offset:16
	global_load_dwordx4 v[146:149], v134, s[42:43] offset:32
	global_load_dwordx4 v[150:153], v134, s[42:43] offset:48
	global_load_dwordx4 v[154:157], v134, s[42:43] offset:64
	global_load_dwordx4 v[158:161], v134, s[42:43] offset:80
	global_load_dwordx4 v[162:165], v134, s[42:43] offset:96
	global_load_dwordx4 v[166:169], v134, s[42:43] offset:112
	global_load_dwordx4 v[170:173], v206, s[44:45]
	global_load_dwordx4 v[174:177], v206, s[44:45] offset:16
	s_add_u32 s42, s42, 0x2000
	s_addc_u32 s43, s43, 0
	s_add_u32 s44, s44, 0x80
	s_addc_u32 s45, s45, 0
	s_waitcnt vmcnt(16)
	v_mul_f32_e32 v132, v179, v119
	v_mul_f32_e32 v133, v178, v119
	v_fma_f32 v178, v178, v118, -v132
	v_fma_f32 v179, v179, v118, v133
	v_mul_f32_e32 v132, v181, v123
	v_mul_f32_e32 v133, v180, v123
	v_fma_f32 v180, v180, v122, -v132
	v_fma_f32 v181, v181, v122, v133
	v_mul_f32_e32 v132, v183, v127
	v_mul_f32_e32 v133, v182, v127
	v_fma_f32 v182, v182, v126, -v132
	v_fma_f32 v183, v183, v126, v133
	v_mul_f32_e32 v132, v185, v131
	v_mul_f32_e32 v133, v184, v131
	v_fma_f32 v184, v184, v130, -v132
	v_fma_f32 v185, v185, v130, v133
	v_mul_f32_e32 v132, v56, v101
	v_mul_f32_e32 v56, v56, v100
	v_fma_f32 v56, -v60, v101, v56
	v_fma_f32 v60, v60, v100, v132
	v_mul_f32_e32 v133, v57, v105
	v_mul_f32_e32 v57, v57, v104
	v_fma_f32 v57, -v61, v105, v57
	v_fma_f32 v61, v61, v104, v133
	v_mul_f32_e32 v132, v58, v109
	v_mul_f32_e32 v58, v58, v108
	v_fma_f32 v58, -v62, v109, v58
	v_fma_f32 v62, v62, v108, v132
	v_mul_f32_e32 v133, v59, v113
	v_mul_f32_e32 v59, v59, v112
	v_fma_f32 v59, -v63, v113, v59
	v_fma_f32 v63, v63, v112, v133
	v_add_f32_dpp v56, v56, v56 row_shl:1 row_mask:0xf bank_mask:0xf bound_ctrl:1
	v_add_f32_dpp v57, v57, v57 row_shl:1 row_mask:0xf bank_mask:0xf bound_ctrl:1
	v_add_f32_dpp v58, v58, v58 row_shl:1 row_mask:0xf bank_mask:0xf bound_ctrl:1
	v_add_f32_dpp v59, v59, v59 row_shl:1 row_mask:0xf bank_mask:0xf bound_ctrl:1
	v_add_f32_dpp v60, v60, v60 row_shl:1 row_mask:0xf bank_mask:0xf bound_ctrl:1
	v_add_f32_dpp v61, v61, v61 row_shl:1 row_mask:0xf bank_mask:0xf bound_ctrl:1
	v_add_f32_dpp v62, v62, v62 row_shl:1 row_mask:0xf bank_mask:0xf bound_ctrl:1
	v_add_f32_dpp v63, v63, v63 row_shl:1 row_mask:0xf bank_mask:0xf bound_ctrl:1
	v_add_f32_dpp v56, v56, v56 row_shl:2 row_mask:0xf bank_mask:0xf bound_ctrl:1
	v_add_f32_dpp v57, v57, v57 row_shl:2 row_mask:0xf bank_mask:0xf bound_ctrl:1
	v_add_f32_dpp v58, v58, v58 row_shl:2 row_mask:0xf bank_mask:0xf bound_ctrl:1
	v_add_f32_dpp v59, v59, v59 row_shl:2 row_mask:0xf bank_mask:0xf bound_ctrl:1
	v_add_f32_dpp v60, v60, v60 row_shl:2 row_mask:0xf bank_mask:0xf bound_ctrl:1
	v_add_f32_dpp v61, v61, v61 row_shl:2 row_mask:0xf bank_mask:0xf bound_ctrl:1
	v_add_f32_dpp v62, v62, v62 row_shl:2 row_mask:0xf bank_mask:0xf bound_ctrl:1
	v_add_f32_dpp v63, v63, v63 row_shl:2 row_mask:0xf bank_mask:0xf bound_ctrl:1
	v_add_f32_dpp v56, v56, v56 row_shl:4 row_mask:0xf bank_mask:0xf bound_ctrl:1
	v_add_f32_dpp v57, v57, v57 row_shl:4 row_mask:0xf bank_mask:0xf bound_ctrl:1
	v_add_f32_dpp v58, v58, v58 row_shl:4 row_mask:0xf bank_mask:0xf bound_ctrl:1
	v_add_f32_dpp v59, v59, v59 row_shl:4 row_mask:0xf bank_mask:0xf bound_ctrl:1
	v_add_f32_dpp v60, v60, v60 row_shl:4 row_mask:0xf bank_mask:0xf bound_ctrl:1
	v_add_f32_dpp v61, v61, v61 row_shl:4 row_mask:0xf bank_mask:0xf bound_ctrl:1
	v_add_f32_dpp v62, v62, v62 row_shl:4 row_mask:0xf bank_mask:0xf bound_ctrl:1
	v_add_f32_dpp v63, v63, v63 row_shl:4 row_mask:0xf bank_mask:0xf bound_ctrl:1
	v_add_f32_dpp v56, v56, v56 row_shl:8 row_mask:0xf bank_mask:0xf bound_ctrl:1
	v_add_f32_dpp v57, v57, v57 row_shl:8 row_mask:0xf bank_mask:0xf bound_ctrl:1
	v_add_f32_dpp v58, v58, v58 row_shl:8 row_mask:0xf bank_mask:0xf bound_ctrl:1
	v_add_f32_dpp v59, v59, v59 row_shl:8 row_mask:0xf bank_mask:0xf bound_ctrl:1
	v_add_f32_dpp v60, v60, v60 row_shl:8 row_mask:0xf bank_mask:0xf bound_ctrl:1
	v_add_f32_dpp v61, v61, v61 row_shl:8 row_mask:0xf bank_mask:0xf bound_ctrl:1
	v_add_f32_dpp v62, v62, v62 row_shl:8 row_mask:0xf bank_mask:0xf bound_ctrl:1
	v_add_f32_dpp v63, v63, v63 row_shl:8 row_mask:0xf bank_mask:0xf bound_ctrl:1
	v_mov_b32_dpp v88, v56 row_newbcast:0 row_mask:0xf bank_mask:0xf
	v_mov_b32_dpp v89, v57 row_newbcast:0 row_mask:0xf bank_mask:0xf
	v_mov_b32_dpp v90, v58 row_newbcast:0 row_mask:0xf bank_mask:0xf
	v_mov_b32_dpp v91, v59 row_newbcast:0 row_mask:0xf bank_mask:0xf
	v_mov_b32_dpp v92, v60 row_newbcast:0 row_mask:0xf bank_mask:0xf
	v_mov_b32_dpp v93, v61 row_newbcast:0 row_mask:0xf bank_mask:0xf
	v_mov_b32_dpp v94, v62 row_newbcast:0 row_mask:0xf bank_mask:0xf
	v_mov_b32_dpp v95, v63 row_newbcast:0 row_mask:0xf bank_mask:0xf
	v_add_f32_e32 v56, v56, v178
	v_add_f32_e32 v60, v60, v179
	v_add_f32_e32 v57, v57, v180
	v_add_f32_e32 v61, v61, v181
	v_add_f32_e32 v58, v58, v182
	v_add_f32_e32 v62, v62, v183
	v_add_f32_e32 v59, v59, v184
	v_add_f32_e32 v63, v63, v185
	v_mul_f32_e32 v132, v56, v103
	v_mul_f32_e32 v56, v56, v102
	v_fma_f32 v56, -v60, v103, v56
	v_fma_f32 v60, v60, v102, v132
	v_mul_f32_e32 v133, v57, v107
	v_mul_f32_e32 v57, v57, v106
	v_fma_f32 v57, -v61, v107, v57
	v_fma_f32 v61, v61, v106, v133
	v_mul_f32_e32 v132, v58, v111
	v_mul_f32_e32 v58, v58, v110
	v_fma_f32 v58, -v62, v111, v58
	v_fma_f32 v62, v62, v110, v132
	v_mul_f32_e32 v133, v59, v115
	v_mul_f32_e32 v59, v59, v114
	v_fma_f32 v59, -v63, v115, v59
	v_fma_f32 v63, v63, v114, v133
	v_add_f32_e32 v88, v88, v178
	v_add_f32_e32 v92, v92, v179
	v_mul_f32_e32 v132, v92, v117
	v_mul_f32_e32 v179, v88, v117
	v_fma_f32 v178, v88, v116, -v132
	v_fma_f32 v179, v92, v116, v179
	v_add_f32_e32 v89, v89, v180
	v_add_f32_e32 v93, v93, v181
	v_mul_f32_e32 v133, v93, v121
	v_mul_f32_e32 v181, v89, v121
	v_fma_f32 v180, v89, v120, -v133
	v_fma_f32 v181, v93, v120, v181
	v_add_f32_e32 v90, v90, v182
	v_add_f32_e32 v94, v94, v183
	v_mul_f32_e32 v132, v94, v125
	v_mul_f32_e32 v183, v90, v125
	v_fma_f32 v182, v90, v124, -v132
	v_fma_f32 v183, v94, v124, v183
	v_add_f32_e32 v91, v91, v184
	v_add_f32_e32 v95, v95, v185
	v_mul_f32_e32 v133, v95, v129
	v_mul_f32_e32 v185, v91, v129
	v_fma_f32 v184, v91, v128, -v133
	v_fma_f32 v185, v95, v128, v185
	v_mul_f32_e32 v132, v48, v101
	v_mul_f32_e32 v48, v48, v100
	v_fma_f32 v48, -v52, v101, v48
	v_fma_f32 v52, v52, v100, v132
	v_mul_f32_e32 v133, v49, v105
	v_mul_f32_e32 v49, v49, v104
	v_fma_f32 v49, -v53, v105, v49
	v_fma_f32 v53, v53, v104, v133
	v_mul_f32_e32 v132, v50, v109
	v_mul_f32_e32 v50, v50, v108
	v_fma_f32 v50, -v54, v109, v50
	v_fma_f32 v54, v54, v108, v132
	v_mul_f32_e32 v133, v51, v113
	v_mul_f32_e32 v51, v51, v112
	v_fma_f32 v51, -v55, v113, v51
	v_fma_f32 v55, v55, v112, v133
	v_add_f32_dpp v48, v48, v48 row_shl:1 row_mask:0xf bank_mask:0xf bound_ctrl:1
	v_add_f32_dpp v49, v49, v49 row_shl:1 row_mask:0xf bank_mask:0xf bound_ctrl:1
	v_add_f32_dpp v50, v50, v50 row_shl:1 row_mask:0xf bank_mask:0xf bound_ctrl:1
	v_add_f32_dpp v51, v51, v51 row_shl:1 row_mask:0xf bank_mask:0xf bound_ctrl:1
	v_add_f32_dpp v52, v52, v52 row_shl:1 row_mask:0xf bank_mask:0xf bound_ctrl:1
	v_add_f32_dpp v53, v53, v53 row_shl:1 row_mask:0xf bank_mask:0xf bound_ctrl:1
	v_add_f32_dpp v54, v54, v54 row_shl:1 row_mask:0xf bank_mask:0xf bound_ctrl:1
	v_add_f32_dpp v55, v55, v55 row_shl:1 row_mask:0xf bank_mask:0xf bound_ctrl:1
	v_add_f32_dpp v48, v48, v48 row_shl:2 row_mask:0xf bank_mask:0xf bound_ctrl:1
	v_add_f32_dpp v49, v49, v49 row_shl:2 row_mask:0xf bank_mask:0xf bound_ctrl:1
	v_add_f32_dpp v50, v50, v50 row_shl:2 row_mask:0xf bank_mask:0xf bound_ctrl:1
	v_add_f32_dpp v51, v51, v51 row_shl:2 row_mask:0xf bank_mask:0xf bound_ctrl:1
	v_add_f32_dpp v52, v52, v52 row_shl:2 row_mask:0xf bank_mask:0xf bound_ctrl:1
	v_add_f32_dpp v53, v53, v53 row_shl:2 row_mask:0xf bank_mask:0xf bound_ctrl:1
	v_add_f32_dpp v54, v54, v54 row_shl:2 row_mask:0xf bank_mask:0xf bound_ctrl:1
	v_add_f32_dpp v55, v55, v55 row_shl:2 row_mask:0xf bank_mask:0xf bound_ctrl:1
	v_add_f32_dpp v48, v48, v48 row_shl:4 row_mask:0xf bank_mask:0xf bound_ctrl:1
	v_add_f32_dpp v49, v49, v49 row_shl:4 row_mask:0xf bank_mask:0xf bound_ctrl:1
	v_add_f32_dpp v50, v50, v50 row_shl:4 row_mask:0xf bank_mask:0xf bound_ctrl:1
	v_add_f32_dpp v51, v51, v51 row_shl:4 row_mask:0xf bank_mask:0xf bound_ctrl:1
	v_add_f32_dpp v52, v52, v52 row_shl:4 row_mask:0xf bank_mask:0xf bound_ctrl:1
	v_add_f32_dpp v53, v53, v53 row_shl:4 row_mask:0xf bank_mask:0xf bound_ctrl:1
	v_add_f32_dpp v54, v54, v54 row_shl:4 row_mask:0xf bank_mask:0xf bound_ctrl:1
	v_add_f32_dpp v55, v55, v55 row_shl:4 row_mask:0xf bank_mask:0xf bound_ctrl:1
	v_add_f32_dpp v48, v48, v48 row_shl:8 row_mask:0xf bank_mask:0xf bound_ctrl:1
	v_add_f32_dpp v49, v49, v49 row_shl:8 row_mask:0xf bank_mask:0xf bound_ctrl:1
	v_add_f32_dpp v50, v50, v50 row_shl:8 row_mask:0xf bank_mask:0xf bound_ctrl:1
	v_add_f32_dpp v51, v51, v51 row_shl:8 row_mask:0xf bank_mask:0xf bound_ctrl:1
	v_add_f32_dpp v52, v52, v52 row_shl:8 row_mask:0xf bank_mask:0xf bound_ctrl:1
	v_add_f32_dpp v53, v53, v53 row_shl:8 row_mask:0xf bank_mask:0xf bound_ctrl:1
	v_add_f32_dpp v54, v54, v54 row_shl:8 row_mask:0xf bank_mask:0xf bound_ctrl:1
	v_add_f32_dpp v55, v55, v55 row_shl:8 row_mask:0xf bank_mask:0xf bound_ctrl:1
	v_mov_b32_dpp v88, v48 row_newbcast:0 row_mask:0xf bank_mask:0xf
	v_mov_b32_dpp v89, v49 row_newbcast:0 row_mask:0xf bank_mask:0xf
	v_mov_b32_dpp v90, v50 row_newbcast:0 row_mask:0xf bank_mask:0xf
	v_mov_b32_dpp v91, v51 row_newbcast:0 row_mask:0xf bank_mask:0xf
	v_mov_b32_dpp v92, v52 row_newbcast:0 row_mask:0xf bank_mask:0xf
	v_mov_b32_dpp v93, v53 row_newbcast:0 row_mask:0xf bank_mask:0xf
	v_mov_b32_dpp v94, v54 row_newbcast:0 row_mask:0xf bank_mask:0xf
	v_mov_b32_dpp v95, v55 row_newbcast:0 row_mask:0xf bank_mask:0xf
	v_add_f32_e32 v48, v48, v178
	v_add_f32_e32 v52, v52, v179
	v_add_f32_e32 v49, v49, v180
	v_add_f32_e32 v53, v53, v181
	v_add_f32_e32 v50, v50, v182
	v_add_f32_e32 v54, v54, v183
	v_add_f32_e32 v51, v51, v184
	v_add_f32_e32 v55, v55, v185
	v_mul_f32_e32 v132, v48, v103
	v_mul_f32_e32 v48, v48, v102
	v_fma_f32 v48, -v52, v103, v48
	v_fma_f32 v52, v52, v102, v132
	v_mul_f32_e32 v133, v49, v107
	v_mul_f32_e32 v49, v49, v106
	v_fma_f32 v49, -v53, v107, v49
	v_fma_f32 v53, v53, v106, v133
	v_mul_f32_e32 v132, v50, v111
	v_mul_f32_e32 v50, v50, v110
	v_fma_f32 v50, -v54, v111, v50
	v_fma_f32 v54, v54, v110, v132
	v_mul_f32_e32 v133, v51, v115
	v_mul_f32_e32 v51, v51, v114
	v_fma_f32 v51, -v55, v115, v51
	v_fma_f32 v55, v55, v114, v133
	v_add_f32_e32 v88, v88, v178
	v_add_f32_e32 v92, v92, v179
	v_mul_f32_e32 v132, v92, v117
	v_mul_f32_e32 v179, v88, v117
	v_fma_f32 v178, v88, v116, -v132
	v_fma_f32 v179, v92, v116, v179
	v_add_f32_e32 v89, v89, v180
	v_add_f32_e32 v93, v93, v181
	v_mul_f32_e32 v133, v93, v121
	v_mul_f32_e32 v181, v89, v121
	v_fma_f32 v180, v89, v120, -v133
	v_fma_f32 v181, v93, v120, v181
	v_add_f32_e32 v90, v90, v182
	v_add_f32_e32 v94, v94, v183
	v_mul_f32_e32 v132, v94, v125
	v_mul_f32_e32 v183, v90, v125
	v_fma_f32 v182, v90, v124, -v132
	v_fma_f32 v183, v94, v124, v183
	v_add_f32_e32 v91, v91, v184
	v_add_f32_e32 v95, v95, v185
	v_mul_f32_e32 v133, v95, v129
	v_mul_f32_e32 v185, v91, v129
	v_fma_f32 v184, v91, v128, -v133
	v_fma_f32 v185, v95, v128, v185
	v_mul_f32_e32 v132, v40, v101
	v_mul_f32_e32 v40, v40, v100
	v_fma_f32 v40, -v44, v101, v40
	v_fma_f32 v44, v44, v100, v132
	v_mul_f32_e32 v133, v41, v105
	v_mul_f32_e32 v41, v41, v104
	v_fma_f32 v41, -v45, v105, v41
	v_fma_f32 v45, v45, v104, v133
	v_mul_f32_e32 v132, v42, v109
	v_mul_f32_e32 v42, v42, v108
	v_fma_f32 v42, -v46, v109, v42
	v_fma_f32 v46, v46, v108, v132
	v_mul_f32_e32 v133, v43, v113
	v_mul_f32_e32 v43, v43, v112
	v_fma_f32 v43, -v47, v113, v43
	v_fma_f32 v47, v47, v112, v133
	v_add_f32_dpp v40, v40, v40 row_shl:1 row_mask:0xf bank_mask:0xf bound_ctrl:1
	v_add_f32_dpp v41, v41, v41 row_shl:1 row_mask:0xf bank_mask:0xf bound_ctrl:1
	v_add_f32_dpp v42, v42, v42 row_shl:1 row_mask:0xf bank_mask:0xf bound_ctrl:1
	v_add_f32_dpp v43, v43, v43 row_shl:1 row_mask:0xf bank_mask:0xf bound_ctrl:1
	v_add_f32_dpp v44, v44, v44 row_shl:1 row_mask:0xf bank_mask:0xf bound_ctrl:1
	v_add_f32_dpp v45, v45, v45 row_shl:1 row_mask:0xf bank_mask:0xf bound_ctrl:1
	v_add_f32_dpp v46, v46, v46 row_shl:1 row_mask:0xf bank_mask:0xf bound_ctrl:1
	v_add_f32_dpp v47, v47, v47 row_shl:1 row_mask:0xf bank_mask:0xf bound_ctrl:1
	v_add_f32_dpp v40, v40, v40 row_shl:2 row_mask:0xf bank_mask:0xf bound_ctrl:1
	v_add_f32_dpp v41, v41, v41 row_shl:2 row_mask:0xf bank_mask:0xf bound_ctrl:1
	v_add_f32_dpp v42, v42, v42 row_shl:2 row_mask:0xf bank_mask:0xf bound_ctrl:1
	v_add_f32_dpp v43, v43, v43 row_shl:2 row_mask:0xf bank_mask:0xf bound_ctrl:1
	v_add_f32_dpp v44, v44, v44 row_shl:2 row_mask:0xf bank_mask:0xf bound_ctrl:1
	v_add_f32_dpp v45, v45, v45 row_shl:2 row_mask:0xf bank_mask:0xf bound_ctrl:1
	v_add_f32_dpp v46, v46, v46 row_shl:2 row_mask:0xf bank_mask:0xf bound_ctrl:1
	v_add_f32_dpp v47, v47, v47 row_shl:2 row_mask:0xf bank_mask:0xf bound_ctrl:1
	v_add_f32_dpp v40, v40, v40 row_shl:4 row_mask:0xf bank_mask:0xf bound_ctrl:1
	v_add_f32_dpp v41, v41, v41 row_shl:4 row_mask:0xf bank_mask:0xf bound_ctrl:1
	v_add_f32_dpp v42, v42, v42 row_shl:4 row_mask:0xf bank_mask:0xf bound_ctrl:1
	v_add_f32_dpp v43, v43, v43 row_shl:4 row_mask:0xf bank_mask:0xf bound_ctrl:1
	v_add_f32_dpp v44, v44, v44 row_shl:4 row_mask:0xf bank_mask:0xf bound_ctrl:1
	v_add_f32_dpp v45, v45, v45 row_shl:4 row_mask:0xf bank_mask:0xf bound_ctrl:1
	v_add_f32_dpp v46, v46, v46 row_shl:4 row_mask:0xf bank_mask:0xf bound_ctrl:1
	v_add_f32_dpp v47, v47, v47 row_shl:4 row_mask:0xf bank_mask:0xf bound_ctrl:1
	v_add_f32_dpp v40, v40, v40 row_shl:8 row_mask:0xf bank_mask:0xf bound_ctrl:1
	v_add_f32_dpp v41, v41, v41 row_shl:8 row_mask:0xf bank_mask:0xf bound_ctrl:1
	v_add_f32_dpp v42, v42, v42 row_shl:8 row_mask:0xf bank_mask:0xf bound_ctrl:1
	v_add_f32_dpp v43, v43, v43 row_shl:8 row_mask:0xf bank_mask:0xf bound_ctrl:1
	v_add_f32_dpp v44, v44, v44 row_shl:8 row_mask:0xf bank_mask:0xf bound_ctrl:1
	v_add_f32_dpp v45, v45, v45 row_shl:8 row_mask:0xf bank_mask:0xf bound_ctrl:1
	v_add_f32_dpp v46, v46, v46 row_shl:8 row_mask:0xf bank_mask:0xf bound_ctrl:1
	v_add_f32_dpp v47, v47, v47 row_shl:8 row_mask:0xf bank_mask:0xf bound_ctrl:1
	v_mov_b32_dpp v88, v40 row_newbcast:0 row_mask:0xf bank_mask:0xf
	v_mov_b32_dpp v89, v41 row_newbcast:0 row_mask:0xf bank_mask:0xf
	v_mov_b32_dpp v90, v42 row_newbcast:0 row_mask:0xf bank_mask:0xf
	v_mov_b32_dpp v91, v43 row_newbcast:0 row_mask:0xf bank_mask:0xf
	v_mov_b32_dpp v92, v44 row_newbcast:0 row_mask:0xf bank_mask:0xf
	v_mov_b32_dpp v93, v45 row_newbcast:0 row_mask:0xf bank_mask:0xf
	v_mov_b32_dpp v94, v46 row_newbcast:0 row_mask:0xf bank_mask:0xf
	v_mov_b32_dpp v95, v47 row_newbcast:0 row_mask:0xf bank_mask:0xf
	v_add_f32_e32 v40, v40, v178
	v_add_f32_e32 v44, v44, v179
	v_add_f32_e32 v41, v41, v180
	v_add_f32_e32 v45, v45, v181
	v_add_f32_e32 v42, v42, v182
	v_add_f32_e32 v46, v46, v183
	v_add_f32_e32 v43, v43, v184
	v_add_f32_e32 v47, v47, v185
	v_mul_f32_e32 v132, v40, v103
	v_mul_f32_e32 v40, v40, v102
	v_fma_f32 v40, -v44, v103, v40
	v_fma_f32 v44, v44, v102, v132
	v_mul_f32_e32 v133, v41, v107
	v_mul_f32_e32 v41, v41, v106
	v_fma_f32 v41, -v45, v107, v41
	v_fma_f32 v45, v45, v106, v133
	v_mul_f32_e32 v132, v42, v111
	v_mul_f32_e32 v42, v42, v110
	v_fma_f32 v42, -v46, v111, v42
	v_fma_f32 v46, v46, v110, v132
	v_mul_f32_e32 v133, v43, v115
	v_mul_f32_e32 v43, v43, v114
	v_fma_f32 v43, -v47, v115, v43
	v_fma_f32 v47, v47, v114, v133
	v_add_f32_e32 v88, v88, v178
	v_add_f32_e32 v92, v92, v179
	v_mul_f32_e32 v132, v92, v117
	v_mul_f32_e32 v179, v88, v117
	v_fma_f32 v178, v88, v116, -v132
	v_fma_f32 v179, v92, v116, v179
	v_add_f32_e32 v89, v89, v180
	v_add_f32_e32 v93, v93, v181
	v_mul_f32_e32 v133, v93, v121
	v_mul_f32_e32 v181, v89, v121
	v_fma_f32 v180, v89, v120, -v133
	v_fma_f32 v181, v93, v120, v181
	v_add_f32_e32 v90, v90, v182
	v_add_f32_e32 v94, v94, v183
	v_mul_f32_e32 v132, v94, v125
	v_mul_f32_e32 v183, v90, v125
	v_fma_f32 v182, v90, v124, -v132
	v_fma_f32 v183, v94, v124, v183
	v_add_f32_e32 v91, v91, v184
	v_add_f32_e32 v95, v95, v185
	v_mul_f32_e32 v133, v95, v129
	v_mul_f32_e32 v185, v91, v129
	v_fma_f32 v184, v91, v128, -v133
	v_fma_f32 v185, v95, v128, v185
	v_mul_f32_e32 v132, v32, v101
	v_mul_f32_e32 v32, v32, v100
	v_fma_f32 v32, -v36, v101, v32
	v_fma_f32 v36, v36, v100, v132
	v_mul_f32_e32 v133, v33, v105
	v_mul_f32_e32 v33, v33, v104
	v_fma_f32 v33, -v37, v105, v33
	v_fma_f32 v37, v37, v104, v133
	v_mul_f32_e32 v132, v34, v109
	v_mul_f32_e32 v34, v34, v108
	v_fma_f32 v34, -v38, v109, v34
	v_fma_f32 v38, v38, v108, v132
	v_mul_f32_e32 v133, v35, v113
	v_mul_f32_e32 v35, v35, v112
	v_fma_f32 v35, -v39, v113, v35
	v_fma_f32 v39, v39, v112, v133
	v_add_f32_dpp v32, v32, v32 row_shl:1 row_mask:0xf bank_mask:0xf bound_ctrl:1
	v_add_f32_dpp v33, v33, v33 row_shl:1 row_mask:0xf bank_mask:0xf bound_ctrl:1
	v_add_f32_dpp v34, v34, v34 row_shl:1 row_mask:0xf bank_mask:0xf bound_ctrl:1
	v_add_f32_dpp v35, v35, v35 row_shl:1 row_mask:0xf bank_mask:0xf bound_ctrl:1
	v_add_f32_dpp v36, v36, v36 row_shl:1 row_mask:0xf bank_mask:0xf bound_ctrl:1
	v_add_f32_dpp v37, v37, v37 row_shl:1 row_mask:0xf bank_mask:0xf bound_ctrl:1
	v_add_f32_dpp v38, v38, v38 row_shl:1 row_mask:0xf bank_mask:0xf bound_ctrl:1
	v_add_f32_dpp v39, v39, v39 row_shl:1 row_mask:0xf bank_mask:0xf bound_ctrl:1
	v_add_f32_dpp v32, v32, v32 row_shl:2 row_mask:0xf bank_mask:0xf bound_ctrl:1
	v_add_f32_dpp v33, v33, v33 row_shl:2 row_mask:0xf bank_mask:0xf bound_ctrl:1
	v_add_f32_dpp v34, v34, v34 row_shl:2 row_mask:0xf bank_mask:0xf bound_ctrl:1
	v_add_f32_dpp v35, v35, v35 row_shl:2 row_mask:0xf bank_mask:0xf bound_ctrl:1
	v_add_f32_dpp v36, v36, v36 row_shl:2 row_mask:0xf bank_mask:0xf bound_ctrl:1
	v_add_f32_dpp v37, v37, v37 row_shl:2 row_mask:0xf bank_mask:0xf bound_ctrl:1
	v_add_f32_dpp v38, v38, v38 row_shl:2 row_mask:0xf bank_mask:0xf bound_ctrl:1
	v_add_f32_dpp v39, v39, v39 row_shl:2 row_mask:0xf bank_mask:0xf bound_ctrl:1
	v_add_f32_dpp v32, v32, v32 row_shl:4 row_mask:0xf bank_mask:0xf bound_ctrl:1
	v_add_f32_dpp v33, v33, v33 row_shl:4 row_mask:0xf bank_mask:0xf bound_ctrl:1
	v_add_f32_dpp v34, v34, v34 row_shl:4 row_mask:0xf bank_mask:0xf bound_ctrl:1
	v_add_f32_dpp v35, v35, v35 row_shl:4 row_mask:0xf bank_mask:0xf bound_ctrl:1
	v_add_f32_dpp v36, v36, v36 row_shl:4 row_mask:0xf bank_mask:0xf bound_ctrl:1
	v_add_f32_dpp v37, v37, v37 row_shl:4 row_mask:0xf bank_mask:0xf bound_ctrl:1
	v_add_f32_dpp v38, v38, v38 row_shl:4 row_mask:0xf bank_mask:0xf bound_ctrl:1
	v_add_f32_dpp v39, v39, v39 row_shl:4 row_mask:0xf bank_mask:0xf bound_ctrl:1
	v_add_f32_dpp v32, v32, v32 row_shl:8 row_mask:0xf bank_mask:0xf bound_ctrl:1
	v_add_f32_dpp v33, v33, v33 row_shl:8 row_mask:0xf bank_mask:0xf bound_ctrl:1
	v_add_f32_dpp v34, v34, v34 row_shl:8 row_mask:0xf bank_mask:0xf bound_ctrl:1
	v_add_f32_dpp v35, v35, v35 row_shl:8 row_mask:0xf bank_mask:0xf bound_ctrl:1
	v_add_f32_dpp v36, v36, v36 row_shl:8 row_mask:0xf bank_mask:0xf bound_ctrl:1
	v_add_f32_dpp v37, v37, v37 row_shl:8 row_mask:0xf bank_mask:0xf bound_ctrl:1
	v_add_f32_dpp v38, v38, v38 row_shl:8 row_mask:0xf bank_mask:0xf bound_ctrl:1
	v_add_f32_dpp v39, v39, v39 row_shl:8 row_mask:0xf bank_mask:0xf bound_ctrl:1
	v_mov_b32_dpp v88, v32 row_newbcast:0 row_mask:0xf bank_mask:0xf
	v_mov_b32_dpp v89, v33 row_newbcast:0 row_mask:0xf bank_mask:0xf
	v_mov_b32_dpp v90, v34 row_newbcast:0 row_mask:0xf bank_mask:0xf
	v_mov_b32_dpp v91, v35 row_newbcast:0 row_mask:0xf bank_mask:0xf
	v_mov_b32_dpp v92, v36 row_newbcast:0 row_mask:0xf bank_mask:0xf
	v_mov_b32_dpp v93, v37 row_newbcast:0 row_mask:0xf bank_mask:0xf
	v_mov_b32_dpp v94, v38 row_newbcast:0 row_mask:0xf bank_mask:0xf
	v_mov_b32_dpp v95, v39 row_newbcast:0 row_mask:0xf bank_mask:0xf
	v_add_f32_e32 v32, v32, v178
	v_add_f32_e32 v36, v36, v179
	v_add_f32_e32 v33, v33, v180
	v_add_f32_e32 v37, v37, v181
	v_add_f32_e32 v34, v34, v182
	v_add_f32_e32 v38, v38, v183
	v_add_f32_e32 v35, v35, v184
	v_add_f32_e32 v39, v39, v185
	v_mul_f32_e32 v132, v32, v103
	v_mul_f32_e32 v32, v32, v102
	v_fma_f32 v32, -v36, v103, v32
	v_fma_f32 v36, v36, v102, v132
	v_mul_f32_e32 v133, v33, v107
	v_mul_f32_e32 v33, v33, v106
	v_fma_f32 v33, -v37, v107, v33
	v_fma_f32 v37, v37, v106, v133
	v_mul_f32_e32 v132, v34, v111
	v_mul_f32_e32 v34, v34, v110
	v_fma_f32 v34, -v38, v111, v34
	v_fma_f32 v38, v38, v110, v132
	v_mul_f32_e32 v133, v35, v115
	v_mul_f32_e32 v35, v35, v114
	v_fma_f32 v35, -v39, v115, v35
	v_fma_f32 v39, v39, v114, v133
	v_add_f32_e32 v88, v88, v178
	v_add_f32_e32 v92, v92, v179
	v_mul_f32_e32 v132, v92, v117
	v_mul_f32_e32 v179, v88, v117
	v_fma_f32 v178, v88, v116, -v132
	v_fma_f32 v179, v92, v116, v179
	v_add_f32_e32 v89, v89, v180
	v_add_f32_e32 v93, v93, v181
	v_mul_f32_e32 v133, v93, v121
	v_mul_f32_e32 v181, v89, v121
	v_fma_f32 v180, v89, v120, -v133
	v_fma_f32 v181, v93, v120, v181
	v_add_f32_e32 v90, v90, v182
	v_add_f32_e32 v94, v94, v183
	v_mul_f32_e32 v132, v94, v125
	v_mul_f32_e32 v183, v90, v125
	v_fma_f32 v182, v90, v124, -v132
	v_fma_f32 v183, v94, v124, v183
	v_add_f32_e32 v91, v91, v184
	v_add_f32_e32 v95, v95, v185
	v_mul_f32_e32 v133, v95, v129
	v_mul_f32_e32 v185, v91, v129
	v_fma_f32 v184, v91, v128, -v133
	v_fma_f32 v185, v95, v128, v185
	s_waitcnt vmcnt(14)
	v_cvt_pk_bf16_f32 v80, v80, v81
	v_cvt_pk_bf16_f32 v81, v82, v83
	v_cvt_pk_bf16_f32 v82, -v84, -v85
	v_cvt_pk_bf16_f32 v83, -v86, -v87
	v_cvt_pk_bf16_f32 v96, v32, v33
	v_cvt_pk_bf16_f32 v97, v34, v35
	v_cvt_pk_bf16_f32 v98, v36, v37
	v_cvt_pk_bf16_f32 v99, v38, v39
	s_nop 1
	v_mfma_f32_16x16x32_bf16 v[16:19], v[80:83], v[96:99], v[16:19]
	v_cvt_pk_bf16_f32 v96, v40, v41
	v_cvt_pk_bf16_f32 v97, v42, v43
	v_cvt_pk_bf16_f32 v98, v44, v45
	v_cvt_pk_bf16_f32 v99, v46, v47
	s_nop 1
	v_mfma_f32_16x16x32_bf16 v[20:23], v[80:83], v[96:99], v[20:23]
	v_cvt_pk_bf16_f32 v96, v48, v49
	v_cvt_pk_bf16_f32 v97, v50, v51
	v_cvt_pk_bf16_f32 v98, v52, v53
	v_cvt_pk_bf16_f32 v99, v54, v55
	s_nop 1
	v_mfma_f32_16x16x32_bf16 v[24:27], v[80:83], v[96:99], v[24:27]
	v_cvt_pk_bf16_f32 v96, v56, v57
	v_cvt_pk_bf16_f32 v97, v58, v59
	v_cvt_pk_bf16_f32 v98, v60, v61
	v_cvt_pk_bf16_f32 v99, v62, v63
	s_nop 1
	v_mfma_f32_16x16x32_bf16 v[28:31], v[80:83], v[96:99], v[28:31]
	s_waitcnt vmcnt(10)
	v_cvt_pk_bf16_f32 v64, v64, v65
	v_cvt_pk_bf16_f32 v65, v66, v67
	v_cvt_pk_bf16_f32 v66, v68, v69
	v_cvt_pk_bf16_f32 v67, v70, v71
	v_cvt_pk_bf16_f32 v72, v72, v73
	v_cvt_pk_bf16_f32 v73, v74, v75
	v_cvt_pk_bf16_f32 v74, v76, v77
	v_cvt_pk_bf16_f32 v75, v78, v79
	global_load_dwordx4 v[80:83], v136, s[38:39]
	global_load_dwordx4 v[84:87], v136, s[40:41]
	s_add_u32 s38, s38, 0x40
	s_addc_u32 s39, s39, 0
	s_add_u32 s40, s40, 0x40
	s_addc_u32 s41, s41, 0
	s_nop 0
	v_mfma_f32_16x16x32_bf16 v[32:35], v[64:67], v[0:3], 0
	v_mfma_f32_16x16x32_bf16 v[36:39], v[72:75], v[0:3], 0
	v_mfma_f32_16x16x32_bf16 v[40:43], v[64:67], v[4:7], 0
	v_mfma_f32_16x16x32_bf16 v[44:47], v[72:75], v[4:7], 0
	v_mfma_f32_16x16x32_bf16 v[48:51], v[64:67], v[8:11], 0
	v_mfma_f32_16x16x32_bf16 v[52:55], v[72:75], v[8:11], 0
	v_mfma_f32_16x16x32_bf16 v[56:59], v[64:67], v[12:15], 0
	v_mfma_f32_16x16x32_bf16 v[60:63], v[72:75], v[12:15], 0
	s_mov_b32 exec_hi, 0
	global_load_dwordx4 v[64:67], v135, s[20:21]
	global_load_dwordx4 v[68:71], v135, s[20:21] offset:16
	global_load_dwordx4 v[72:75], v135, s[22:23]
	global_load_dwordx4 v[76:79], v135, s[22:23] offset:16
	s_mov_b64 exec, -1
	global_load_dwordx4 v[100:103], v134, s[42:43] offset:0
	global_load_dwordx4 v[104:107], v134, s[42:43] offset:16
	global_load_dwordx4 v[108:111], v134, s[42:43] offset:32
	global_load_dwordx4 v[112:115], v134, s[42:43] offset:48
	global_load_dwordx4 v[116:119], v134, s[42:43] offset:64
	global_load_dwordx4 v[120:123], v134, s[42:43] offset:80
	global_load_dwordx4 v[124:127], v134, s[42:43] offset:96
	global_load_dwordx4 v[128:131], v134, s[42:43] offset:112
	global_load_dwordx4 v[178:181], v206, s[44:45]
	global_load_dwordx4 v[182:185], v206, s[44:45] offset:16
	s_waitcnt vmcnt(16)
	v_mul_f32_e32 v132, v171, v157
	v_mul_f32_e32 v133, v170, v157
	v_fma_f32 v170, v170, v156, -v132
	v_fma_f32 v171, v171, v156, v133
	v_mul_f32_e32 v132, v173, v161
	v_mul_f32_e32 v133, v172, v161
	v_fma_f32 v172, v172, v160, -v132
	v_fma_f32 v173, v173, v160, v133
	v_mul_f32_e32 v132, v175, v165
	v_mul_f32_e32 v133, v174, v165
	v_fma_f32 v174, v174, v164, -v132
	v_fma_f32 v175, v175, v164, v133
	v_mul_f32_e32 v132, v177, v169
	v_mul_f32_e32 v133, v176, v169
	v_fma_f32 v176, v176, v168, -v132
	v_fma_f32 v177, v177, v168, v133
	v_mul_f32_e32 v132, v56, v139
	v_mul_f32_e32 v56, v56, v138
	v_fma_f32 v56, -v60, v139, v56
	v_fma_f32 v60, v60, v138, v132
	v_mul_f32_e32 v133, v57, v143
	v_mul_f32_e32 v57, v57, v142
	v_fma_f32 v57, -v61, v143, v57
	v_fma_f32 v61, v61, v142, v133
	v_mul_f32_e32 v132, v58, v147
	v_mul_f32_e32 v58, v58, v146
	v_fma_f32 v58, -v62, v147, v58
	v_fma_f32 v62, v62, v146, v132
	v_mul_f32_e32 v133, v59, v151
	v_mul_f32_e32 v59, v59, v150
	v_fma_f32 v59, -v63, v151, v59
	v_fma_f32 v63, v63, v150, v133
	v_add_f32_dpp v56, v56, v56 row_shl:1 row_mask:0xf bank_mask:0xf bound_ctrl:1
	v_add_f32_dpp v57, v57, v57 row_shl:1 row_mask:0xf bank_mask:0xf bound_ctrl:1
	v_add_f32_dpp v58, v58, v58 row_shl:1 row_mask:0xf bank_mask:0xf bound_ctrl:1
	v_add_f32_dpp v59, v59, v59 row_shl:1 row_mask:0xf bank_mask:0xf bound_ctrl:1
	v_add_f32_dpp v60, v60, v60 row_shl:1 row_mask:0xf bank_mask:0xf bound_ctrl:1
	v_add_f32_dpp v61, v61, v61 row_shl:1 row_mask:0xf bank_mask:0xf bound_ctrl:1
	v_add_f32_dpp v62, v62, v62 row_shl:1 row_mask:0xf bank_mask:0xf bound_ctrl:1
	v_add_f32_dpp v63, v63, v63 row_shl:1 row_mask:0xf bank_mask:0xf bound_ctrl:1
	v_add_f32_dpp v56, v56, v56 row_shl:2 row_mask:0xf bank_mask:0xf bound_ctrl:1
	v_add_f32_dpp v57, v57, v57 row_shl:2 row_mask:0xf bank_mask:0xf bound_ctrl:1
	v_add_f32_dpp v58, v58, v58 row_shl:2 row_mask:0xf bank_mask:0xf bound_ctrl:1
	v_add_f32_dpp v59, v59, v59 row_shl:2 row_mask:0xf bank_mask:0xf bound_ctrl:1
	v_add_f32_dpp v60, v60, v60 row_shl:2 row_mask:0xf bank_mask:0xf bound_ctrl:1
	v_add_f32_dpp v61, v61, v61 row_shl:2 row_mask:0xf bank_mask:0xf bound_ctrl:1
	v_add_f32_dpp v62, v62, v62 row_shl:2 row_mask:0xf bank_mask:0xf bound_ctrl:1
	v_add_f32_dpp v63, v63, v63 row_shl:2 row_mask:0xf bank_mask:0xf bound_ctrl:1
	v_add_f32_dpp v56, v56, v56 row_shl:4 row_mask:0xf bank_mask:0xf bound_ctrl:1
	v_add_f32_dpp v57, v57, v57 row_shl:4 row_mask:0xf bank_mask:0xf bound_ctrl:1
	v_add_f32_dpp v58, v58, v58 row_shl:4 row_mask:0xf bank_mask:0xf bound_ctrl:1
	v_add_f32_dpp v59, v59, v59 row_shl:4 row_mask:0xf bank_mask:0xf bound_ctrl:1
	v_add_f32_dpp v60, v60, v60 row_shl:4 row_mask:0xf bank_mask:0xf bound_ctrl:1
	v_add_f32_dpp v61, v61, v61 row_shl:4 row_mask:0xf bank_mask:0xf bound_ctrl:1
	v_add_f32_dpp v62, v62, v62 row_shl:4 row_mask:0xf bank_mask:0xf bound_ctrl:1
	v_add_f32_dpp v63, v63, v63 row_shl:4 row_mask:0xf bank_mask:0xf bound_ctrl:1
	v_add_f32_dpp v56, v56, v56 row_shl:8 row_mask:0xf bank_mask:0xf bound_ctrl:1
	v_add_f32_dpp v57, v57, v57 row_shl:8 row_mask:0xf bank_mask:0xf bound_ctrl:1
	v_add_f32_dpp v58, v58, v58 row_shl:8 row_mask:0xf bank_mask:0xf bound_ctrl:1
	v_add_f32_dpp v59, v59, v59 row_shl:8 row_mask:0xf bank_mask:0xf bound_ctrl:1
	v_add_f32_dpp v60, v60, v60 row_shl:8 row_mask:0xf bank_mask:0xf bound_ctrl:1
	v_add_f32_dpp v61, v61, v61 row_shl:8 row_mask:0xf bank_mask:0xf bound_ctrl:1
	v_add_f32_dpp v62, v62, v62 row_shl:8 row_mask:0xf bank_mask:0xf bound_ctrl:1
	v_add_f32_dpp v63, v63, v63 row_shl:8 row_mask:0xf bank_mask:0xf bound_ctrl:1
	v_mov_b32_dpp v88, v56 row_newbcast:0 row_mask:0xf bank_mask:0xf
	v_mov_b32_dpp v89, v57 row_newbcast:0 row_mask:0xf bank_mask:0xf
	v_mov_b32_dpp v90, v58 row_newbcast:0 row_mask:0xf bank_mask:0xf
	v_mov_b32_dpp v91, v59 row_newbcast:0 row_mask:0xf bank_mask:0xf
	v_mov_b32_dpp v92, v60 row_newbcast:0 row_mask:0xf bank_mask:0xf
	v_mov_b32_dpp v93, v61 row_newbcast:0 row_mask:0xf bank_mask:0xf
	v_mov_b32_dpp v94, v62 row_newbcast:0 row_mask:0xf bank_mask:0xf
	v_mov_b32_dpp v95, v63 row_newbcast:0 row_mask:0xf bank_mask:0xf
	v_add_f32_e32 v56, v56, v170
	v_add_f32_e32 v60, v60, v171
	v_add_f32_e32 v57, v57, v172
	v_add_f32_e32 v61, v61, v173
	v_add_f32_e32 v58, v58, v174
	v_add_f32_e32 v62, v62, v175
	v_add_f32_e32 v59, v59, v176
	v_add_f32_e32 v63, v63, v177
	v_mul_f32_e32 v132, v56, v141
	v_mul_f32_e32 v56, v56, v140
	v_fma_f32 v56, -v60, v141, v56
	v_fma_f32 v60, v60, v140, v132
	v_mul_f32_e32 v133, v57, v145
	v_mul_f32_e32 v57, v57, v144
	v_fma_f32 v57, -v61, v145, v57
	v_fma_f32 v61, v61, v144, v133
	v_mul_f32_e32 v132, v58, v149
	v_mul_f32_e32 v58, v58, v148
	v_fma_f32 v58, -v62, v149, v58
	v_fma_f32 v62, v62, v148, v132
	v_mul_f32_e32 v133, v59, v153
	v_mul_f32_e32 v59, v59, v152
	v_fma_f32 v59, -v63, v153, v59
	v_fma_f32 v63, v63, v152, v133
	v_add_f32_e32 v88, v88, v170
	v_add_f32_e32 v92, v92, v171
	v_mul_f32_e32 v132, v92, v155
	v_mul_f32_e32 v171, v88, v155
	v_fma_f32 v170, v88, v154, -v132
	v_fma_f32 v171, v92, v154, v171
	v_add_f32_e32 v89, v89, v172
	v_add_f32_e32 v93, v93, v173
	v_mul_f32_e32 v133, v93, v159
	v_mul_f32_e32 v173, v89, v159
	v_fma_f32 v172, v89, v158, -v133
	v_fma_f32 v173, v93, v158, v173
	v_add_f32_e32 v90, v90, v174
	v_add_f32_e32 v94, v94, v175
	v_mul_f32_e32 v132, v94, v163
	v_mul_f32_e32 v175, v90, v163
	v_fma_f32 v174, v90, v162, -v132
	v_fma_f32 v175, v94, v162, v175
	v_add_f32_e32 v91, v91, v176
	v_add_f32_e32 v95, v95, v177
	v_mul_f32_e32 v133, v95, v167
	v_mul_f32_e32 v177, v91, v167
	v_fma_f32 v176, v91, v166, -v133
	v_fma_f32 v177, v95, v166, v177
	v_mul_f32_e32 v132, v48, v139
	v_mul_f32_e32 v48, v48, v138
	v_fma_f32 v48, -v52, v139, v48
	v_fma_f32 v52, v52, v138, v132
	v_mul_f32_e32 v133, v49, v143
	v_mul_f32_e32 v49, v49, v142
	v_fma_f32 v49, -v53, v143, v49
	v_fma_f32 v53, v53, v142, v133
	v_mul_f32_e32 v132, v50, v147
	v_mul_f32_e32 v50, v50, v146
	v_fma_f32 v50, -v54, v147, v50
	v_fma_f32 v54, v54, v146, v132
	v_mul_f32_e32 v133, v51, v151
	v_mul_f32_e32 v51, v51, v150
	v_fma_f32 v51, -v55, v151, v51
	v_fma_f32 v55, v55, v150, v133
	v_add_f32_dpp v48, v48, v48 row_shl:1 row_mask:0xf bank_mask:0xf bound_ctrl:1
	v_add_f32_dpp v49, v49, v49 row_shl:1 row_mask:0xf bank_mask:0xf bound_ctrl:1
	v_add_f32_dpp v50, v50, v50 row_shl:1 row_mask:0xf bank_mask:0xf bound_ctrl:1
	v_add_f32_dpp v51, v51, v51 row_shl:1 row_mask:0xf bank_mask:0xf bound_ctrl:1
	v_add_f32_dpp v52, v52, v52 row_shl:1 row_mask:0xf bank_mask:0xf bound_ctrl:1
	v_add_f32_dpp v53, v53, v53 row_shl:1 row_mask:0xf bank_mask:0xf bound_ctrl:1
	v_add_f32_dpp v54, v54, v54 row_shl:1 row_mask:0xf bank_mask:0xf bound_ctrl:1
	v_add_f32_dpp v55, v55, v55 row_shl:1 row_mask:0xf bank_mask:0xf bound_ctrl:1
	v_add_f32_dpp v48, v48, v48 row_shl:2 row_mask:0xf bank_mask:0xf bound_ctrl:1
	v_add_f32_dpp v49, v49, v49 row_shl:2 row_mask:0xf bank_mask:0xf bound_ctrl:1
	v_add_f32_dpp v50, v50, v50 row_shl:2 row_mask:0xf bank_mask:0xf bound_ctrl:1
	v_add_f32_dpp v51, v51, v51 row_shl:2 row_mask:0xf bank_mask:0xf bound_ctrl:1
	v_add_f32_dpp v52, v52, v52 row_shl:2 row_mask:0xf bank_mask:0xf bound_ctrl:1
	v_add_f32_dpp v53, v53, v53 row_shl:2 row_mask:0xf bank_mask:0xf bound_ctrl:1
	v_add_f32_dpp v54, v54, v54 row_shl:2 row_mask:0xf bank_mask:0xf bound_ctrl:1
	v_add_f32_dpp v55, v55, v55 row_shl:2 row_mask:0xf bank_mask:0xf bound_ctrl:1
	v_add_f32_dpp v48, v48, v48 row_shl:4 row_mask:0xf bank_mask:0xf bound_ctrl:1
	v_add_f32_dpp v49, v49, v49 row_shl:4 row_mask:0xf bank_mask:0xf bound_ctrl:1
	v_add_f32_dpp v50, v50, v50 row_shl:4 row_mask:0xf bank_mask:0xf bound_ctrl:1
	v_add_f32_dpp v51, v51, v51 row_shl:4 row_mask:0xf bank_mask:0xf bound_ctrl:1
	v_add_f32_dpp v52, v52, v52 row_shl:4 row_mask:0xf bank_mask:0xf bound_ctrl:1
	v_add_f32_dpp v53, v53, v53 row_shl:4 row_mask:0xf bank_mask:0xf bound_ctrl:1
	v_add_f32_dpp v54, v54, v54 row_shl:4 row_mask:0xf bank_mask:0xf bound_ctrl:1
	v_add_f32_dpp v55, v55, v55 row_shl:4 row_mask:0xf bank_mask:0xf bound_ctrl:1
	v_add_f32_dpp v48, v48, v48 row_shl:8 row_mask:0xf bank_mask:0xf bound_ctrl:1
	v_add_f32_dpp v49, v49, v49 row_shl:8 row_mask:0xf bank_mask:0xf bound_ctrl:1
	v_add_f32_dpp v50, v50, v50 row_shl:8 row_mask:0xf bank_mask:0xf bound_ctrl:1
	v_add_f32_dpp v51, v51, v51 row_shl:8 row_mask:0xf bank_mask:0xf bound_ctrl:1
	v_add_f32_dpp v52, v52, v52 row_shl:8 row_mask:0xf bank_mask:0xf bound_ctrl:1
	v_add_f32_dpp v53, v53, v53 row_shl:8 row_mask:0xf bank_mask:0xf bound_ctrl:1
	v_add_f32_dpp v54, v54, v54 row_shl:8 row_mask:0xf bank_mask:0xf bound_ctrl:1
	v_add_f32_dpp v55, v55, v55 row_shl:8 row_mask:0xf bank_mask:0xf bound_ctrl:1
	v_mov_b32_dpp v88, v48 row_newbcast:0 row_mask:0xf bank_mask:0xf
	v_mov_b32_dpp v89, v49 row_newbcast:0 row_mask:0xf bank_mask:0xf
	v_mov_b32_dpp v90, v50 row_newbcast:0 row_mask:0xf bank_mask:0xf
	v_mov_b32_dpp v91, v51 row_newbcast:0 row_mask:0xf bank_mask:0xf
	v_mov_b32_dpp v92, v52 row_newbcast:0 row_mask:0xf bank_mask:0xf
	v_mov_b32_dpp v93, v53 row_newbcast:0 row_mask:0xf bank_mask:0xf
	v_mov_b32_dpp v94, v54 row_newbcast:0 row_mask:0xf bank_mask:0xf
	v_mov_b32_dpp v95, v55 row_newbcast:0 row_mask:0xf bank_mask:0xf
	v_add_f32_e32 v48, v48, v170
	v_add_f32_e32 v52, v52, v171
	v_add_f32_e32 v49, v49, v172
	v_add_f32_e32 v53, v53, v173
	v_add_f32_e32 v50, v50, v174
	v_add_f32_e32 v54, v54, v175
	v_add_f32_e32 v51, v51, v176
	v_add_f32_e32 v55, v55, v177
	v_mul_f32_e32 v132, v48, v141
	v_mul_f32_e32 v48, v48, v140
	v_fma_f32 v48, -v52, v141, v48
	v_fma_f32 v52, v52, v140, v132
	v_mul_f32_e32 v133, v49, v145
	v_mul_f32_e32 v49, v49, v144
	v_fma_f32 v49, -v53, v145, v49
	v_fma_f32 v53, v53, v144, v133
	v_mul_f32_e32 v132, v50, v149
	v_mul_f32_e32 v50, v50, v148
	v_fma_f32 v50, -v54, v149, v50
	v_fma_f32 v54, v54, v148, v132
	v_mul_f32_e32 v133, v51, v153
	v_mul_f32_e32 v51, v51, v152
	v_fma_f32 v51, -v55, v153, v51
	v_fma_f32 v55, v55, v152, v133
	v_add_f32_e32 v88, v88, v170
	v_add_f32_e32 v92, v92, v171
	v_mul_f32_e32 v132, v92, v155
	v_mul_f32_e32 v171, v88, v155
	v_fma_f32 v170, v88, v154, -v132
	v_fma_f32 v171, v92, v154, v171
	v_add_f32_e32 v89, v89, v172
	v_add_f32_e32 v93, v93, v173
	v_mul_f32_e32 v133, v93, v159
	v_mul_f32_e32 v173, v89, v159
	v_fma_f32 v172, v89, v158, -v133
	v_fma_f32 v173, v93, v158, v173
	v_add_f32_e32 v90, v90, v174
	v_add_f32_e32 v94, v94, v175
	v_mul_f32_e32 v132, v94, v163
	v_mul_f32_e32 v175, v90, v163
	v_fma_f32 v174, v90, v162, -v132
	v_fma_f32 v175, v94, v162, v175
	v_add_f32_e32 v91, v91, v176
	v_add_f32_e32 v95, v95, v177
	v_mul_f32_e32 v133, v95, v167
	v_mul_f32_e32 v177, v91, v167
	v_fma_f32 v176, v91, v166, -v133
	v_fma_f32 v177, v95, v166, v177
	v_mul_f32_e32 v132, v40, v139
	v_mul_f32_e32 v40, v40, v138
	v_fma_f32 v40, -v44, v139, v40
	v_fma_f32 v44, v44, v138, v132
	v_mul_f32_e32 v133, v41, v143
	v_mul_f32_e32 v41, v41, v142
	v_fma_f32 v41, -v45, v143, v41
	v_fma_f32 v45, v45, v142, v133
	v_mul_f32_e32 v132, v42, v147
	v_mul_f32_e32 v42, v42, v146
	v_fma_f32 v42, -v46, v147, v42
	v_fma_f32 v46, v46, v146, v132
	v_mul_f32_e32 v133, v43, v151
	v_mul_f32_e32 v43, v43, v150
	v_fma_f32 v43, -v47, v151, v43
	v_fma_f32 v47, v47, v150, v133
	v_add_f32_dpp v40, v40, v40 row_shl:1 row_mask:0xf bank_mask:0xf bound_ctrl:1
	v_add_f32_dpp v41, v41, v41 row_shl:1 row_mask:0xf bank_mask:0xf bound_ctrl:1
	v_add_f32_dpp v42, v42, v42 row_shl:1 row_mask:0xf bank_mask:0xf bound_ctrl:1
	v_add_f32_dpp v43, v43, v43 row_shl:1 row_mask:0xf bank_mask:0xf bound_ctrl:1
	v_add_f32_dpp v44, v44, v44 row_shl:1 row_mask:0xf bank_mask:0xf bound_ctrl:1
	v_add_f32_dpp v45, v45, v45 row_shl:1 row_mask:0xf bank_mask:0xf bound_ctrl:1
	v_add_f32_dpp v46, v46, v46 row_shl:1 row_mask:0xf bank_mask:0xf bound_ctrl:1
	v_add_f32_dpp v47, v47, v47 row_shl:1 row_mask:0xf bank_mask:0xf bound_ctrl:1
	v_add_f32_dpp v40, v40, v40 row_shl:2 row_mask:0xf bank_mask:0xf bound_ctrl:1
	v_add_f32_dpp v41, v41, v41 row_shl:2 row_mask:0xf bank_mask:0xf bound_ctrl:1
	v_add_f32_dpp v42, v42, v42 row_shl:2 row_mask:0xf bank_mask:0xf bound_ctrl:1
	v_add_f32_dpp v43, v43, v43 row_shl:2 row_mask:0xf bank_mask:0xf bound_ctrl:1
	v_add_f32_dpp v44, v44, v44 row_shl:2 row_mask:0xf bank_mask:0xf bound_ctrl:1
	v_add_f32_dpp v45, v45, v45 row_shl:2 row_mask:0xf bank_mask:0xf bound_ctrl:1
	v_add_f32_dpp v46, v46, v46 row_shl:2 row_mask:0xf bank_mask:0xf bound_ctrl:1
	v_add_f32_dpp v47, v47, v47 row_shl:2 row_mask:0xf bank_mask:0xf bound_ctrl:1
	v_add_f32_dpp v40, v40, v40 row_shl:4 row_mask:0xf bank_mask:0xf bound_ctrl:1
	v_add_f32_dpp v41, v41, v41 row_shl:4 row_mask:0xf bank_mask:0xf bound_ctrl:1
	v_add_f32_dpp v42, v42, v42 row_shl:4 row_mask:0xf bank_mask:0xf bound_ctrl:1
	v_add_f32_dpp v43, v43, v43 row_shl:4 row_mask:0xf bank_mask:0xf bound_ctrl:1
	v_add_f32_dpp v44, v44, v44 row_shl:4 row_mask:0xf bank_mask:0xf bound_ctrl:1
	v_add_f32_dpp v45, v45, v45 row_shl:4 row_mask:0xf bank_mask:0xf bound_ctrl:1
	v_add_f32_dpp v46, v46, v46 row_shl:4 row_mask:0xf bank_mask:0xf bound_ctrl:1
	v_add_f32_dpp v47, v47, v47 row_shl:4 row_mask:0xf bank_mask:0xf bound_ctrl:1
	v_add_f32_dpp v40, v40, v40 row_shl:8 row_mask:0xf bank_mask:0xf bound_ctrl:1
	v_add_f32_dpp v41, v41, v41 row_shl:8 row_mask:0xf bank_mask:0xf bound_ctrl:1
	v_add_f32_dpp v42, v42, v42 row_shl:8 row_mask:0xf bank_mask:0xf bound_ctrl:1
	v_add_f32_dpp v43, v43, v43 row_shl:8 row_mask:0xf bank_mask:0xf bound_ctrl:1
	v_add_f32_dpp v44, v44, v44 row_shl:8 row_mask:0xf bank_mask:0xf bound_ctrl:1
	v_add_f32_dpp v45, v45, v45 row_shl:8 row_mask:0xf bank_mask:0xf bound_ctrl:1
	v_add_f32_dpp v46, v46, v46 row_shl:8 row_mask:0xf bank_mask:0xf bound_ctrl:1
	v_add_f32_dpp v47, v47, v47 row_shl:8 row_mask:0xf bank_mask:0xf bound_ctrl:1
	v_mov_b32_dpp v88, v40 row_newbcast:0 row_mask:0xf bank_mask:0xf
	v_mov_b32_dpp v89, v41 row_newbcast:0 row_mask:0xf bank_mask:0xf
	v_mov_b32_dpp v90, v42 row_newbcast:0 row_mask:0xf bank_mask:0xf
	v_mov_b32_dpp v91, v43 row_newbcast:0 row_mask:0xf bank_mask:0xf
	v_mov_b32_dpp v92, v44 row_newbcast:0 row_mask:0xf bank_mask:0xf
	v_mov_b32_dpp v93, v45 row_newbcast:0 row_mask:0xf bank_mask:0xf
	v_mov_b32_dpp v94, v46 row_newbcast:0 row_mask:0xf bank_mask:0xf
	v_mov_b32_dpp v95, v47 row_newbcast:0 row_mask:0xf bank_mask:0xf
	v_add_f32_e32 v40, v40, v170
	v_add_f32_e32 v44, v44, v171
	v_add_f32_e32 v41, v41, v172
	v_add_f32_e32 v45, v45, v173
	v_add_f32_e32 v42, v42, v174
	v_add_f32_e32 v46, v46, v175
	v_add_f32_e32 v43, v43, v176
	v_add_f32_e32 v47, v47, v177
	v_mul_f32_e32 v132, v40, v141
	v_mul_f32_e32 v40, v40, v140
	v_fma_f32 v40, -v44, v141, v40
	v_fma_f32 v44, v44, v140, v132
	v_mul_f32_e32 v133, v41, v145
	v_mul_f32_e32 v41, v41, v144
	v_fma_f32 v41, -v45, v145, v41
	v_fma_f32 v45, v45, v144, v133
	v_mul_f32_e32 v132, v42, v149
	v_mul_f32_e32 v42, v42, v148
	v_fma_f32 v42, -v46, v149, v42
	v_fma_f32 v46, v46, v148, v132
	v_mul_f32_e32 v133, v43, v153
	v_mul_f32_e32 v43, v43, v152
	v_fma_f32 v43, -v47, v153, v43
	v_fma_f32 v47, v47, v152, v133
	v_add_f32_e32 v88, v88, v170
	v_add_f32_e32 v92, v92, v171
	v_mul_f32_e32 v132, v92, v155
	v_mul_f32_e32 v171, v88, v155
	v_fma_f32 v170, v88, v154, -v132
	v_fma_f32 v171, v92, v154, v171
	v_add_f32_e32 v89, v89, v172
	v_add_f32_e32 v93, v93, v173
	v_mul_f32_e32 v133, v93, v159
	v_mul_f32_e32 v173, v89, v159
	v_fma_f32 v172, v89, v158, -v133
	v_fma_f32 v173, v93, v158, v173
	v_add_f32_e32 v90, v90, v174
	v_add_f32_e32 v94, v94, v175
	v_mul_f32_e32 v132, v94, v163
	v_mul_f32_e32 v175, v90, v163
	v_fma_f32 v174, v90, v162, -v132
	v_fma_f32 v175, v94, v162, v175
	v_add_f32_e32 v91, v91, v176
	v_add_f32_e32 v95, v95, v177
	v_mul_f32_e32 v133, v95, v167
	v_mul_f32_e32 v177, v91, v167
	v_fma_f32 v176, v91, v166, -v133
	v_fma_f32 v177, v95, v166, v177
	v_mul_f32_e32 v132, v32, v139
	v_mul_f32_e32 v32, v32, v138
	v_fma_f32 v32, -v36, v139, v32
	v_fma_f32 v36, v36, v138, v132
	v_mul_f32_e32 v133, v33, v143
	v_mul_f32_e32 v33, v33, v142
	v_fma_f32 v33, -v37, v143, v33
	v_fma_f32 v37, v37, v142, v133
	v_mul_f32_e32 v132, v34, v147
	v_mul_f32_e32 v34, v34, v146
	v_fma_f32 v34, -v38, v147, v34
	v_fma_f32 v38, v38, v146, v132
	v_mul_f32_e32 v133, v35, v151
	v_mul_f32_e32 v35, v35, v150
	v_fma_f32 v35, -v39, v151, v35
	v_fma_f32 v39, v39, v150, v133
	v_add_f32_dpp v32, v32, v32 row_shl:1 row_mask:0xf bank_mask:0xf bound_ctrl:1
	v_add_f32_dpp v33, v33, v33 row_shl:1 row_mask:0xf bank_mask:0xf bound_ctrl:1
	v_add_f32_dpp v34, v34, v34 row_shl:1 row_mask:0xf bank_mask:0xf bound_ctrl:1
	v_add_f32_dpp v35, v35, v35 row_shl:1 row_mask:0xf bank_mask:0xf bound_ctrl:1
	v_add_f32_dpp v36, v36, v36 row_shl:1 row_mask:0xf bank_mask:0xf bound_ctrl:1
	v_add_f32_dpp v37, v37, v37 row_shl:1 row_mask:0xf bank_mask:0xf bound_ctrl:1
	v_add_f32_dpp v38, v38, v38 row_shl:1 row_mask:0xf bank_mask:0xf bound_ctrl:1
	v_add_f32_dpp v39, v39, v39 row_shl:1 row_mask:0xf bank_mask:0xf bound_ctrl:1
	v_add_f32_dpp v32, v32, v32 row_shl:2 row_mask:0xf bank_mask:0xf bound_ctrl:1
	v_add_f32_dpp v33, v33, v33 row_shl:2 row_mask:0xf bank_mask:0xf bound_ctrl:1
	v_add_f32_dpp v34, v34, v34 row_shl:2 row_mask:0xf bank_mask:0xf bound_ctrl:1
	v_add_f32_dpp v35, v35, v35 row_shl:2 row_mask:0xf bank_mask:0xf bound_ctrl:1
	v_add_f32_dpp v36, v36, v36 row_shl:2 row_mask:0xf bank_mask:0xf bound_ctrl:1
	v_add_f32_dpp v37, v37, v37 row_shl:2 row_mask:0xf bank_mask:0xf bound_ctrl:1
	v_add_f32_dpp v38, v38, v38 row_shl:2 row_mask:0xf bank_mask:0xf bound_ctrl:1
	v_add_f32_dpp v39, v39, v39 row_shl:2 row_mask:0xf bank_mask:0xf bound_ctrl:1
	v_add_f32_dpp v32, v32, v32 row_shl:4 row_mask:0xf bank_mask:0xf bound_ctrl:1
	v_add_f32_dpp v33, v33, v33 row_shl:4 row_mask:0xf bank_mask:0xf bound_ctrl:1
	v_add_f32_dpp v34, v34, v34 row_shl:4 row_mask:0xf bank_mask:0xf bound_ctrl:1
	v_add_f32_dpp v35, v35, v35 row_shl:4 row_mask:0xf bank_mask:0xf bound_ctrl:1
	v_add_f32_dpp v36, v36, v36 row_shl:4 row_mask:0xf bank_mask:0xf bound_ctrl:1
	v_add_f32_dpp v37, v37, v37 row_shl:4 row_mask:0xf bank_mask:0xf bound_ctrl:1
	v_add_f32_dpp v38, v38, v38 row_shl:4 row_mask:0xf bank_mask:0xf bound_ctrl:1
	v_add_f32_dpp v39, v39, v39 row_shl:4 row_mask:0xf bank_mask:0xf bound_ctrl:1
	v_add_f32_dpp v32, v32, v32 row_shl:8 row_mask:0xf bank_mask:0xf bound_ctrl:1
	v_add_f32_dpp v33, v33, v33 row_shl:8 row_mask:0xf bank_mask:0xf bound_ctrl:1
	v_add_f32_dpp v34, v34, v34 row_shl:8 row_mask:0xf bank_mask:0xf bound_ctrl:1
	v_add_f32_dpp v35, v35, v35 row_shl:8 row_mask:0xf bank_mask:0xf bound_ctrl:1
	v_add_f32_dpp v36, v36, v36 row_shl:8 row_mask:0xf bank_mask:0xf bound_ctrl:1
	v_add_f32_dpp v37, v37, v37 row_shl:8 row_mask:0xf bank_mask:0xf bound_ctrl:1
	v_add_f32_dpp v38, v38, v38 row_shl:8 row_mask:0xf bank_mask:0xf bound_ctrl:1
	v_add_f32_dpp v39, v39, v39 row_shl:8 row_mask:0xf bank_mask:0xf bound_ctrl:1
	v_mov_b32_dpp v88, v32 row_newbcast:0 row_mask:0xf bank_mask:0xf
	v_mov_b32_dpp v89, v33 row_newbcast:0 row_mask:0xf bank_mask:0xf
	v_mov_b32_dpp v90, v34 row_newbcast:0 row_mask:0xf bank_mask:0xf
	v_mov_b32_dpp v91, v35 row_newbcast:0 row_mask:0xf bank_mask:0xf
	v_mov_b32_dpp v92, v36 row_newbcast:0 row_mask:0xf bank_mask:0xf
	v_mov_b32_dpp v93, v37 row_newbcast:0 row_mask:0xf bank_mask:0xf
	v_mov_b32_dpp v94, v38 row_newbcast:0 row_mask:0xf bank_mask:0xf
	v_mov_b32_dpp v95, v39 row_newbcast:0 row_mask:0xf bank_mask:0xf
	v_add_f32_e32 v32, v32, v170
	v_add_f32_e32 v36, v36, v171
	v_add_f32_e32 v33, v33, v172
	v_add_f32_e32 v37, v37, v173
	v_add_f32_e32 v34, v34, v174
	v_add_f32_e32 v38, v38, v175
	v_add_f32_e32 v35, v35, v176
	v_add_f32_e32 v39, v39, v177
	v_mul_f32_e32 v132, v32, v141
	v_mul_f32_e32 v32, v32, v140
	v_fma_f32 v32, -v36, v141, v32
	v_fma_f32 v36, v36, v140, v132
	v_mul_f32_e32 v133, v33, v145
	v_mul_f32_e32 v33, v33, v144
	v_fma_f32 v33, -v37, v145, v33
	v_fma_f32 v37, v37, v144, v133
	v_mul_f32_e32 v132, v34, v149
	v_mul_f32_e32 v34, v34, v148
	v_fma_f32 v34, -v38, v149, v34
	v_fma_f32 v38, v38, v148, v132
	v_mul_f32_e32 v133, v35, v153
	v_mul_f32_e32 v35, v35, v152
	v_fma_f32 v35, -v39, v153, v35
	v_fma_f32 v39, v39, v152, v133
	v_add_f32_e32 v88, v88, v170
	v_add_f32_e32 v92, v92, v171
	v_mul_f32_e32 v132, v92, v155
	v_mul_f32_e32 v171, v88, v155
	v_fma_f32 v170, v88, v154, -v132
	v_fma_f32 v171, v92, v154, v171
	v_add_f32_e32 v89, v89, v172
	v_add_f32_e32 v93, v93, v173
	v_mul_f32_e32 v133, v93, v159
	v_mul_f32_e32 v173, v89, v159
	v_fma_f32 v172, v89, v158, -v133
	v_fma_f32 v173, v93, v158, v173
	v_add_f32_e32 v90, v90, v174
	v_add_f32_e32 v94, v94, v175
	v_mul_f32_e32 v132, v94, v163
	v_mul_f32_e32 v175, v90, v163
	v_fma_f32 v174, v90, v162, -v132
	v_fma_f32 v175, v94, v162, v175
	v_add_f32_e32 v91, v91, v176
	v_add_f32_e32 v95, v95, v177
	v_mul_f32_e32 v133, v95, v167
	v_mul_f32_e32 v177, v91, v167
	v_fma_f32 v176, v91, v166, -v133
	v_fma_f32 v177, v95, v166, v177
	s_waitcnt vmcnt(14)
	v_cvt_pk_bf16_f32 v80, v80, v81
	v_cvt_pk_bf16_f32 v81, v82, v83
	v_cvt_pk_bf16_f32 v82, -v84, -v85
	v_cvt_pk_bf16_f32 v83, -v86, -v87
	v_cvt_pk_bf16_f32 v96, v32, v33
	v_cvt_pk_bf16_f32 v97, v34, v35
	v_cvt_pk_bf16_f32 v98, v36, v37
	v_cvt_pk_bf16_f32 v99, v38, v39
	s_nop 1
	v_mfma_f32_16x16x32_bf16 v[16:19], v[80:83], v[96:99], v[16:19]
	v_cvt_pk_bf16_f32 v96, v40, v41
	v_cvt_pk_bf16_f32 v97, v42, v43
	v_cvt_pk_bf16_f32 v98, v44, v45
	v_cvt_pk_bf16_f32 v99, v46, v47
	s_nop 1
	v_mfma_f32_16x16x32_bf16 v[20:23], v[80:83], v[96:99], v[20:23]
	v_cvt_pk_bf16_f32 v96, v48, v49
	v_cvt_pk_bf16_f32 v97, v50, v51
	v_cvt_pk_bf16_f32 v98, v52, v53
	v_cvt_pk_bf16_f32 v99, v54, v55
	s_nop 1
	v_mfma_f32_16x16x32_bf16 v[24:27], v[80:83], v[96:99], v[24:27]
	v_cvt_pk_bf16_f32 v96, v56, v57
	v_cvt_pk_bf16_f32 v97, v58, v59
	v_cvt_pk_bf16_f32 v98, v60, v61
	v_cvt_pk_bf16_f32 v99, v62, v63
	s_nop 1
	v_mfma_f32_16x16x32_bf16 v[28:31], v[80:83], v[96:99], v[28:31]
	s_waitcnt vmcnt(10)
	v_cvt_pk_bf16_f32 v64, v64, v65
	v_cvt_pk_bf16_f32 v65, v66, v67
	v_cvt_pk_bf16_f32 v66, v68, v69
	v_cvt_pk_bf16_f32 v67, v70, v71
	v_cvt_pk_bf16_f32 v72, v72, v73
	v_cvt_pk_bf16_f32 v73, v74, v75
	v_cvt_pk_bf16_f32 v74, v76, v77
	v_cvt_pk_bf16_f32 v75, v78, v79
	global_load_dwordx4 v[80:83], v136, s[38:39]
	global_load_dwordx4 v[84:87], v136, s[40:41]
	s_nop 0
	v_mfma_f32_16x16x32_bf16 v[32:35], v[64:67], v[0:3], 0
	v_mfma_f32_16x16x32_bf16 v[36:39], v[72:75], v[0:3], 0
	v_mfma_f32_16x16x32_bf16 v[40:43], v[64:67], v[4:7], 0
	v_mfma_f32_16x16x32_bf16 v[44:47], v[72:75], v[4:7], 0
	v_mfma_f32_16x16x32_bf16 v[48:51], v[64:67], v[8:11], 0
	v_mfma_f32_16x16x32_bf16 v[52:55], v[72:75], v[8:11], 0
	v_mfma_f32_16x16x32_bf16 v[56:59], v[64:67], v[12:15], 0
	v_mfma_f32_16x16x32_bf16 v[60:63], v[72:75], v[12:15], 0
	s_waitcnt vmcnt(2)
	v_mul_f32_e32 v132, v179, v119
	v_mul_f32_e32 v133, v178, v119
	v_fma_f32 v178, v178, v118, -v132
	v_fma_f32 v179, v179, v118, v133
	v_mul_f32_e32 v132, v181, v123
	v_mul_f32_e32 v133, v180, v123
	v_fma_f32 v180, v180, v122, -v132
	v_fma_f32 v181, v181, v122, v133
	v_mul_f32_e32 v132, v183, v127
	v_mul_f32_e32 v133, v182, v127
	v_fma_f32 v182, v182, v126, -v132
	v_fma_f32 v183, v183, v126, v133
	v_mul_f32_e32 v132, v185, v131
	v_mul_f32_e32 v133, v184, v131
	v_fma_f32 v184, v184, v130, -v132
	v_fma_f32 v185, v185, v130, v133
	v_mul_f32_e32 v132, v56, v101
	v_mul_f32_e32 v56, v56, v100
	v_fma_f32 v56, -v60, v101, v56
	v_fma_f32 v60, v60, v100, v132
	v_mul_f32_e32 v133, v57, v105
	v_mul_f32_e32 v57, v57, v104
	v_fma_f32 v57, -v61, v105, v57
	v_fma_f32 v61, v61, v104, v133
	v_mul_f32_e32 v132, v58, v109
	v_mul_f32_e32 v58, v58, v108
	v_fma_f32 v58, -v62, v109, v58
	v_fma_f32 v62, v62, v108, v132
	v_mul_f32_e32 v133, v59, v113
	v_mul_f32_e32 v59, v59, v112
	v_fma_f32 v59, -v63, v113, v59
	v_fma_f32 v63, v63, v112, v133
	v_add_f32_dpp v56, v56, v56 row_shl:1 row_mask:0xf bank_mask:0xf bound_ctrl:1
	v_add_f32_dpp v57, v57, v57 row_shl:1 row_mask:0xf bank_mask:0xf bound_ctrl:1
	v_add_f32_dpp v58, v58, v58 row_shl:1 row_mask:0xf bank_mask:0xf bound_ctrl:1
	v_add_f32_dpp v59, v59, v59 row_shl:1 row_mask:0xf bank_mask:0xf bound_ctrl:1
	v_add_f32_dpp v60, v60, v60 row_shl:1 row_mask:0xf bank_mask:0xf bound_ctrl:1
	v_add_f32_dpp v61, v61, v61 row_shl:1 row_mask:0xf bank_mask:0xf bound_ctrl:1
	v_add_f32_dpp v62, v62, v62 row_shl:1 row_mask:0xf bank_mask:0xf bound_ctrl:1
	v_add_f32_dpp v63, v63, v63 row_shl:1 row_mask:0xf bank_mask:0xf bound_ctrl:1
	v_add_f32_dpp v56, v56, v56 row_shl:2 row_mask:0xf bank_mask:0xf bound_ctrl:1
	v_add_f32_dpp v57, v57, v57 row_shl:2 row_mask:0xf bank_mask:0xf bound_ctrl:1
	v_add_f32_dpp v58, v58, v58 row_shl:2 row_mask:0xf bank_mask:0xf bound_ctrl:1
	v_add_f32_dpp v59, v59, v59 row_shl:2 row_mask:0xf bank_mask:0xf bound_ctrl:1
	v_add_f32_dpp v60, v60, v60 row_shl:2 row_mask:0xf bank_mask:0xf bound_ctrl:1
	v_add_f32_dpp v61, v61, v61 row_shl:2 row_mask:0xf bank_mask:0xf bound_ctrl:1
	v_add_f32_dpp v62, v62, v62 row_shl:2 row_mask:0xf bank_mask:0xf bound_ctrl:1
	v_add_f32_dpp v63, v63, v63 row_shl:2 row_mask:0xf bank_mask:0xf bound_ctrl:1
	v_add_f32_dpp v56, v56, v56 row_shl:4 row_mask:0xf bank_mask:0xf bound_ctrl:1
	v_add_f32_dpp v57, v57, v57 row_shl:4 row_mask:0xf bank_mask:0xf bound_ctrl:1
	v_add_f32_dpp v58, v58, v58 row_shl:4 row_mask:0xf bank_mask:0xf bound_ctrl:1
	v_add_f32_dpp v59, v59, v59 row_shl:4 row_mask:0xf bank_mask:0xf bound_ctrl:1
	v_add_f32_dpp v60, v60, v60 row_shl:4 row_mask:0xf bank_mask:0xf bound_ctrl:1
	v_add_f32_dpp v61, v61, v61 row_shl:4 row_mask:0xf bank_mask:0xf bound_ctrl:1
	v_add_f32_dpp v62, v62, v62 row_shl:4 row_mask:0xf bank_mask:0xf bound_ctrl:1
	v_add_f32_dpp v63, v63, v63 row_shl:4 row_mask:0xf bank_mask:0xf bound_ctrl:1
	v_add_f32_dpp v56, v56, v56 row_shl:8 row_mask:0xf bank_mask:0xf bound_ctrl:1
	v_add_f32_dpp v57, v57, v57 row_shl:8 row_mask:0xf bank_mask:0xf bound_ctrl:1
	v_add_f32_dpp v58, v58, v58 row_shl:8 row_mask:0xf bank_mask:0xf bound_ctrl:1
	v_add_f32_dpp v59, v59, v59 row_shl:8 row_mask:0xf bank_mask:0xf bound_ctrl:1
	v_add_f32_dpp v60, v60, v60 row_shl:8 row_mask:0xf bank_mask:0xf bound_ctrl:1
	v_add_f32_dpp v61, v61, v61 row_shl:8 row_mask:0xf bank_mask:0xf bound_ctrl:1
	v_add_f32_dpp v62, v62, v62 row_shl:8 row_mask:0xf bank_mask:0xf bound_ctrl:1
	v_add_f32_dpp v63, v63, v63 row_shl:8 row_mask:0xf bank_mask:0xf bound_ctrl:1
	v_mov_b32_dpp v88, v56 row_newbcast:0 row_mask:0xf bank_mask:0xf
	v_mov_b32_dpp v89, v57 row_newbcast:0 row_mask:0xf bank_mask:0xf
	v_mov_b32_dpp v90, v58 row_newbcast:0 row_mask:0xf bank_mask:0xf
	v_mov_b32_dpp v91, v59 row_newbcast:0 row_mask:0xf bank_mask:0xf
	v_mov_b32_dpp v92, v60 row_newbcast:0 row_mask:0xf bank_mask:0xf
	v_mov_b32_dpp v93, v61 row_newbcast:0 row_mask:0xf bank_mask:0xf
	v_mov_b32_dpp v94, v62 row_newbcast:0 row_mask:0xf bank_mask:0xf
	v_mov_b32_dpp v95, v63 row_newbcast:0 row_mask:0xf bank_mask:0xf
	v_add_f32_e32 v56, v56, v178
	v_add_f32_e32 v60, v60, v179
	v_add_f32_e32 v57, v57, v180
	v_add_f32_e32 v61, v61, v181
	v_add_f32_e32 v58, v58, v182
	v_add_f32_e32 v62, v62, v183
	v_add_f32_e32 v59, v59, v184
	v_add_f32_e32 v63, v63, v185
	v_mul_f32_e32 v132, v56, v103
	v_mul_f32_e32 v56, v56, v102
	v_fma_f32 v56, -v60, v103, v56
	v_fma_f32 v60, v60, v102, v132
	v_mul_f32_e32 v133, v57, v107
	v_mul_f32_e32 v57, v57, v106
	v_fma_f32 v57, -v61, v107, v57
	v_fma_f32 v61, v61, v106, v133
	v_mul_f32_e32 v132, v58, v111
	v_mul_f32_e32 v58, v58, v110
	v_fma_f32 v58, -v62, v111, v58
	v_fma_f32 v62, v62, v110, v132
	v_mul_f32_e32 v133, v59, v115
	v_mul_f32_e32 v59, v59, v114
	v_fma_f32 v59, -v63, v115, v59
	v_fma_f32 v63, v63, v114, v133
	v_add_f32_e32 v88, v88, v178
	v_add_f32_e32 v92, v92, v179
	v_mul_f32_e32 v132, v92, v117
	v_mul_f32_e32 v179, v88, v117
	v_fma_f32 v178, v88, v116, -v132
	v_fma_f32 v179, v92, v116, v179
	v_add_f32_e32 v89, v89, v180
	v_add_f32_e32 v93, v93, v181
	v_mul_f32_e32 v133, v93, v121
	v_mul_f32_e32 v181, v89, v121
	v_fma_f32 v180, v89, v120, -v133
	v_fma_f32 v181, v93, v120, v181
	v_add_f32_e32 v90, v90, v182
	v_add_f32_e32 v94, v94, v183
	v_mul_f32_e32 v132, v94, v125
	v_mul_f32_e32 v183, v90, v125
	v_fma_f32 v182, v90, v124, -v132
	v_fma_f32 v183, v94, v124, v183
	v_add_f32_e32 v91, v91, v184
	v_add_f32_e32 v95, v95, v185
	v_mul_f32_e32 v133, v95, v129
	v_mul_f32_e32 v185, v91, v129
	v_fma_f32 v184, v91, v128, -v133
	v_fma_f32 v185, v95, v128, v185
	v_mul_f32_e32 v132, v48, v101
	v_mul_f32_e32 v48, v48, v100
	v_fma_f32 v48, -v52, v101, v48
	v_fma_f32 v52, v52, v100, v132
	v_mul_f32_e32 v133, v49, v105
	v_mul_f32_e32 v49, v49, v104
	v_fma_f32 v49, -v53, v105, v49
	v_fma_f32 v53, v53, v104, v133
	v_mul_f32_e32 v132, v50, v109
	v_mul_f32_e32 v50, v50, v108
	v_fma_f32 v50, -v54, v109, v50
	v_fma_f32 v54, v54, v108, v132
	v_mul_f32_e32 v133, v51, v113
	v_mul_f32_e32 v51, v51, v112
	v_fma_f32 v51, -v55, v113, v51
	v_fma_f32 v55, v55, v112, v133
	v_add_f32_dpp v48, v48, v48 row_shl:1 row_mask:0xf bank_mask:0xf bound_ctrl:1
	v_add_f32_dpp v49, v49, v49 row_shl:1 row_mask:0xf bank_mask:0xf bound_ctrl:1
	v_add_f32_dpp v50, v50, v50 row_shl:1 row_mask:0xf bank_mask:0xf bound_ctrl:1
	v_add_f32_dpp v51, v51, v51 row_shl:1 row_mask:0xf bank_mask:0xf bound_ctrl:1
	v_add_f32_dpp v52, v52, v52 row_shl:1 row_mask:0xf bank_mask:0xf bound_ctrl:1
	v_add_f32_dpp v53, v53, v53 row_shl:1 row_mask:0xf bank_mask:0xf bound_ctrl:1
	v_add_f32_dpp v54, v54, v54 row_shl:1 row_mask:0xf bank_mask:0xf bound_ctrl:1
	v_add_f32_dpp v55, v55, v55 row_shl:1 row_mask:0xf bank_mask:0xf bound_ctrl:1
	v_add_f32_dpp v48, v48, v48 row_shl:2 row_mask:0xf bank_mask:0xf bound_ctrl:1
	v_add_f32_dpp v49, v49, v49 row_shl:2 row_mask:0xf bank_mask:0xf bound_ctrl:1
	v_add_f32_dpp v50, v50, v50 row_shl:2 row_mask:0xf bank_mask:0xf bound_ctrl:1
	v_add_f32_dpp v51, v51, v51 row_shl:2 row_mask:0xf bank_mask:0xf bound_ctrl:1
	v_add_f32_dpp v52, v52, v52 row_shl:2 row_mask:0xf bank_mask:0xf bound_ctrl:1
	v_add_f32_dpp v53, v53, v53 row_shl:2 row_mask:0xf bank_mask:0xf bound_ctrl:1
	v_add_f32_dpp v54, v54, v54 row_shl:2 row_mask:0xf bank_mask:0xf bound_ctrl:1
	v_add_f32_dpp v55, v55, v55 row_shl:2 row_mask:0xf bank_mask:0xf bound_ctrl:1
	v_add_f32_dpp v48, v48, v48 row_shl:4 row_mask:0xf bank_mask:0xf bound_ctrl:1
	v_add_f32_dpp v49, v49, v49 row_shl:4 row_mask:0xf bank_mask:0xf bound_ctrl:1
	v_add_f32_dpp v50, v50, v50 row_shl:4 row_mask:0xf bank_mask:0xf bound_ctrl:1
	v_add_f32_dpp v51, v51, v51 row_shl:4 row_mask:0xf bank_mask:0xf bound_ctrl:1
	v_add_f32_dpp v52, v52, v52 row_shl:4 row_mask:0xf bank_mask:0xf bound_ctrl:1
	v_add_f32_dpp v53, v53, v53 row_shl:4 row_mask:0xf bank_mask:0xf bound_ctrl:1
	v_add_f32_dpp v54, v54, v54 row_shl:4 row_mask:0xf bank_mask:0xf bound_ctrl:1
	v_add_f32_dpp v55, v55, v55 row_shl:4 row_mask:0xf bank_mask:0xf bound_ctrl:1
	v_add_f32_dpp v48, v48, v48 row_shl:8 row_mask:0xf bank_mask:0xf bound_ctrl:1
	v_add_f32_dpp v49, v49, v49 row_shl:8 row_mask:0xf bank_mask:0xf bound_ctrl:1
	v_add_f32_dpp v50, v50, v50 row_shl:8 row_mask:0xf bank_mask:0xf bound_ctrl:1
	v_add_f32_dpp v51, v51, v51 row_shl:8 row_mask:0xf bank_mask:0xf bound_ctrl:1
	v_add_f32_dpp v52, v52, v52 row_shl:8 row_mask:0xf bank_mask:0xf bound_ctrl:1
	v_add_f32_dpp v53, v53, v53 row_shl:8 row_mask:0xf bank_mask:0xf bound_ctrl:1
	v_add_f32_dpp v54, v54, v54 row_shl:8 row_mask:0xf bank_mask:0xf bound_ctrl:1
	v_add_f32_dpp v55, v55, v55 row_shl:8 row_mask:0xf bank_mask:0xf bound_ctrl:1
	v_mov_b32_dpp v88, v48 row_newbcast:0 row_mask:0xf bank_mask:0xf
	v_mov_b32_dpp v89, v49 row_newbcast:0 row_mask:0xf bank_mask:0xf
	v_mov_b32_dpp v90, v50 row_newbcast:0 row_mask:0xf bank_mask:0xf
	v_mov_b32_dpp v91, v51 row_newbcast:0 row_mask:0xf bank_mask:0xf
	v_mov_b32_dpp v92, v52 row_newbcast:0 row_mask:0xf bank_mask:0xf
	v_mov_b32_dpp v93, v53 row_newbcast:0 row_mask:0xf bank_mask:0xf
	v_mov_b32_dpp v94, v54 row_newbcast:0 row_mask:0xf bank_mask:0xf
	v_mov_b32_dpp v95, v55 row_newbcast:0 row_mask:0xf bank_mask:0xf
	v_add_f32_e32 v48, v48, v178
	v_add_f32_e32 v52, v52, v179
	v_add_f32_e32 v49, v49, v180
	v_add_f32_e32 v53, v53, v181
	v_add_f32_e32 v50, v50, v182
	v_add_f32_e32 v54, v54, v183
	v_add_f32_e32 v51, v51, v184
	v_add_f32_e32 v55, v55, v185
	v_mul_f32_e32 v132, v48, v103
	v_mul_f32_e32 v48, v48, v102
	v_fma_f32 v48, -v52, v103, v48
	v_fma_f32 v52, v52, v102, v132
	v_mul_f32_e32 v133, v49, v107
	v_mul_f32_e32 v49, v49, v106
	v_fma_f32 v49, -v53, v107, v49
	v_fma_f32 v53, v53, v106, v133
	v_mul_f32_e32 v132, v50, v111
	v_mul_f32_e32 v50, v50, v110
	v_fma_f32 v50, -v54, v111, v50
	v_fma_f32 v54, v54, v110, v132
	v_mul_f32_e32 v133, v51, v115
	v_mul_f32_e32 v51, v51, v114
	v_fma_f32 v51, -v55, v115, v51
	v_fma_f32 v55, v55, v114, v133
	v_add_f32_e32 v88, v88, v178
	v_add_f32_e32 v92, v92, v179
	v_mul_f32_e32 v132, v92, v117
	v_mul_f32_e32 v179, v88, v117
	v_fma_f32 v178, v88, v116, -v132
	v_fma_f32 v179, v92, v116, v179
	v_add_f32_e32 v89, v89, v180
	v_add_f32_e32 v93, v93, v181
	v_mul_f32_e32 v133, v93, v121
	v_mul_f32_e32 v181, v89, v121
	v_fma_f32 v180, v89, v120, -v133
	v_fma_f32 v181, v93, v120, v181
	v_add_f32_e32 v90, v90, v182
	v_add_f32_e32 v94, v94, v183
	v_mul_f32_e32 v132, v94, v125
	v_mul_f32_e32 v183, v90, v125
	v_fma_f32 v182, v90, v124, -v132
	v_fma_f32 v183, v94, v124, v183
	v_add_f32_e32 v91, v91, v184
	v_add_f32_e32 v95, v95, v185
	v_mul_f32_e32 v133, v95, v129
	v_mul_f32_e32 v185, v91, v129
	v_fma_f32 v184, v91, v128, -v133
	v_fma_f32 v185, v95, v128, v185
	v_mul_f32_e32 v132, v40, v101
	v_mul_f32_e32 v40, v40, v100
	v_fma_f32 v40, -v44, v101, v40
	v_fma_f32 v44, v44, v100, v132
	v_mul_f32_e32 v133, v41, v105
	v_mul_f32_e32 v41, v41, v104
	v_fma_f32 v41, -v45, v105, v41
	v_fma_f32 v45, v45, v104, v133
	v_mul_f32_e32 v132, v42, v109
	v_mul_f32_e32 v42, v42, v108
	v_fma_f32 v42, -v46, v109, v42
	v_fma_f32 v46, v46, v108, v132
	v_mul_f32_e32 v133, v43, v113
	v_mul_f32_e32 v43, v43, v112
	v_fma_f32 v43, -v47, v113, v43
	v_fma_f32 v47, v47, v112, v133
	v_add_f32_dpp v40, v40, v40 row_shl:1 row_mask:0xf bank_mask:0xf bound_ctrl:1
	v_add_f32_dpp v41, v41, v41 row_shl:1 row_mask:0xf bank_mask:0xf bound_ctrl:1
	v_add_f32_dpp v42, v42, v42 row_shl:1 row_mask:0xf bank_mask:0xf bound_ctrl:1
	v_add_f32_dpp v43, v43, v43 row_shl:1 row_mask:0xf bank_mask:0xf bound_ctrl:1
	v_add_f32_dpp v44, v44, v44 row_shl:1 row_mask:0xf bank_mask:0xf bound_ctrl:1
	v_add_f32_dpp v45, v45, v45 row_shl:1 row_mask:0xf bank_mask:0xf bound_ctrl:1
	v_add_f32_dpp v46, v46, v46 row_shl:1 row_mask:0xf bank_mask:0xf bound_ctrl:1
	v_add_f32_dpp v47, v47, v47 row_shl:1 row_mask:0xf bank_mask:0xf bound_ctrl:1
	v_add_f32_dpp v40, v40, v40 row_shl:2 row_mask:0xf bank_mask:0xf bound_ctrl:1
	v_add_f32_dpp v41, v41, v41 row_shl:2 row_mask:0xf bank_mask:0xf bound_ctrl:1
	v_add_f32_dpp v42, v42, v42 row_shl:2 row_mask:0xf bank_mask:0xf bound_ctrl:1
	v_add_f32_dpp v43, v43, v43 row_shl:2 row_mask:0xf bank_mask:0xf bound_ctrl:1
	v_add_f32_dpp v44, v44, v44 row_shl:2 row_mask:0xf bank_mask:0xf bound_ctrl:1
	v_add_f32_dpp v45, v45, v45 row_shl:2 row_mask:0xf bank_mask:0xf bound_ctrl:1
	v_add_f32_dpp v46, v46, v46 row_shl:2 row_mask:0xf bank_mask:0xf bound_ctrl:1
	v_add_f32_dpp v47, v47, v47 row_shl:2 row_mask:0xf bank_mask:0xf bound_ctrl:1
	v_add_f32_dpp v40, v40, v40 row_shl:4 row_mask:0xf bank_mask:0xf bound_ctrl:1
	v_add_f32_dpp v41, v41, v41 row_shl:4 row_mask:0xf bank_mask:0xf bound_ctrl:1
	v_add_f32_dpp v42, v42, v42 row_shl:4 row_mask:0xf bank_mask:0xf bound_ctrl:1
	v_add_f32_dpp v43, v43, v43 row_shl:4 row_mask:0xf bank_mask:0xf bound_ctrl:1
	v_add_f32_dpp v44, v44, v44 row_shl:4 row_mask:0xf bank_mask:0xf bound_ctrl:1
	v_add_f32_dpp v45, v45, v45 row_shl:4 row_mask:0xf bank_mask:0xf bound_ctrl:1
	v_add_f32_dpp v46, v46, v46 row_shl:4 row_mask:0xf bank_mask:0xf bound_ctrl:1
	v_add_f32_dpp v47, v47, v47 row_shl:4 row_mask:0xf bank_mask:0xf bound_ctrl:1
	v_add_f32_dpp v40, v40, v40 row_shl:8 row_mask:0xf bank_mask:0xf bound_ctrl:1
	v_add_f32_dpp v41, v41, v41 row_shl:8 row_mask:0xf bank_mask:0xf bound_ctrl:1
	v_add_f32_dpp v42, v42, v42 row_shl:8 row_mask:0xf bank_mask:0xf bound_ctrl:1
	v_add_f32_dpp v43, v43, v43 row_shl:8 row_mask:0xf bank_mask:0xf bound_ctrl:1
	v_add_f32_dpp v44, v44, v44 row_shl:8 row_mask:0xf bank_mask:0xf bound_ctrl:1
	v_add_f32_dpp v45, v45, v45 row_shl:8 row_mask:0xf bank_mask:0xf bound_ctrl:1
	v_add_f32_dpp v46, v46, v46 row_shl:8 row_mask:0xf bank_mask:0xf bound_ctrl:1
	v_add_f32_dpp v47, v47, v47 row_shl:8 row_mask:0xf bank_mask:0xf bound_ctrl:1
	v_mov_b32_dpp v88, v40 row_newbcast:0 row_mask:0xf bank_mask:0xf
	v_mov_b32_dpp v89, v41 row_newbcast:0 row_mask:0xf bank_mask:0xf
	v_mov_b32_dpp v90, v42 row_newbcast:0 row_mask:0xf bank_mask:0xf
	v_mov_b32_dpp v91, v43 row_newbcast:0 row_mask:0xf bank_mask:0xf
	v_mov_b32_dpp v92, v44 row_newbcast:0 row_mask:0xf bank_mask:0xf
	v_mov_b32_dpp v93, v45 row_newbcast:0 row_mask:0xf bank_mask:0xf
	v_mov_b32_dpp v94, v46 row_newbcast:0 row_mask:0xf bank_mask:0xf
	v_mov_b32_dpp v95, v47 row_newbcast:0 row_mask:0xf bank_mask:0xf
	v_add_f32_e32 v40, v40, v178
	v_add_f32_e32 v44, v44, v179
	v_add_f32_e32 v41, v41, v180
	v_add_f32_e32 v45, v45, v181
	v_add_f32_e32 v42, v42, v182
	v_add_f32_e32 v46, v46, v183
	v_add_f32_e32 v43, v43, v184
	v_add_f32_e32 v47, v47, v185
	v_mul_f32_e32 v132, v40, v103
	v_mul_f32_e32 v40, v40, v102
	v_fma_f32 v40, -v44, v103, v40
	v_fma_f32 v44, v44, v102, v132
	v_mul_f32_e32 v133, v41, v107
	v_mul_f32_e32 v41, v41, v106
	v_fma_f32 v41, -v45, v107, v41
	v_fma_f32 v45, v45, v106, v133
	v_mul_f32_e32 v132, v42, v111
	v_mul_f32_e32 v42, v42, v110
	v_fma_f32 v42, -v46, v111, v42
	v_fma_f32 v46, v46, v110, v132
	v_mul_f32_e32 v133, v43, v115
	v_mul_f32_e32 v43, v43, v114
	v_fma_f32 v43, -v47, v115, v43
	v_fma_f32 v47, v47, v114, v133
	v_add_f32_e32 v88, v88, v178
	v_add_f32_e32 v92, v92, v179
	v_mul_f32_e32 v132, v92, v117
	v_mul_f32_e32 v179, v88, v117
	v_fma_f32 v178, v88, v116, -v132
	v_fma_f32 v179, v92, v116, v179
	v_add_f32_e32 v89, v89, v180
	v_add_f32_e32 v93, v93, v181
	v_mul_f32_e32 v133, v93, v121
	v_mul_f32_e32 v181, v89, v121
	v_fma_f32 v180, v89, v120, -v133
	v_fma_f32 v181, v93, v120, v181
	v_add_f32_e32 v90, v90, v182
	v_add_f32_e32 v94, v94, v183
	v_mul_f32_e32 v132, v94, v125
	v_mul_f32_e32 v183, v90, v125
	v_fma_f32 v182, v90, v124, -v132
	v_fma_f32 v183, v94, v124, v183
	v_add_f32_e32 v91, v91, v184
	v_add_f32_e32 v95, v95, v185
	v_mul_f32_e32 v133, v95, v129
	v_mul_f32_e32 v185, v91, v129
	v_fma_f32 v184, v91, v128, -v133
	v_fma_f32 v185, v95, v128, v185
	v_mul_f32_e32 v132, v32, v101
	v_mul_f32_e32 v32, v32, v100
	v_fma_f32 v32, -v36, v101, v32
	v_fma_f32 v36, v36, v100, v132
	v_mul_f32_e32 v133, v33, v105
	v_mul_f32_e32 v33, v33, v104
	v_fma_f32 v33, -v37, v105, v33
	v_fma_f32 v37, v37, v104, v133
	v_mul_f32_e32 v132, v34, v109
	v_mul_f32_e32 v34, v34, v108
	v_fma_f32 v34, -v38, v109, v34
	v_fma_f32 v38, v38, v108, v132
	v_mul_f32_e32 v133, v35, v113
	v_mul_f32_e32 v35, v35, v112
	v_fma_f32 v35, -v39, v113, v35
	v_fma_f32 v39, v39, v112, v133
	v_add_f32_dpp v32, v32, v32 row_shl:1 row_mask:0xf bank_mask:0xf bound_ctrl:1
	v_add_f32_dpp v33, v33, v33 row_shl:1 row_mask:0xf bank_mask:0xf bound_ctrl:1
	v_add_f32_dpp v34, v34, v34 row_shl:1 row_mask:0xf bank_mask:0xf bound_ctrl:1
	v_add_f32_dpp v35, v35, v35 row_shl:1 row_mask:0xf bank_mask:0xf bound_ctrl:1
	v_add_f32_dpp v36, v36, v36 row_shl:1 row_mask:0xf bank_mask:0xf bound_ctrl:1
	v_add_f32_dpp v37, v37, v37 row_shl:1 row_mask:0xf bank_mask:0xf bound_ctrl:1
	v_add_f32_dpp v38, v38, v38 row_shl:1 row_mask:0xf bank_mask:0xf bound_ctrl:1
	v_add_f32_dpp v39, v39, v39 row_shl:1 row_mask:0xf bank_mask:0xf bound_ctrl:1
	v_add_f32_dpp v32, v32, v32 row_shl:2 row_mask:0xf bank_mask:0xf bound_ctrl:1
	v_add_f32_dpp v33, v33, v33 row_shl:2 row_mask:0xf bank_mask:0xf bound_ctrl:1
	v_add_f32_dpp v34, v34, v34 row_shl:2 row_mask:0xf bank_mask:0xf bound_ctrl:1
	v_add_f32_dpp v35, v35, v35 row_shl:2 row_mask:0xf bank_mask:0xf bound_ctrl:1
	v_add_f32_dpp v36, v36, v36 row_shl:2 row_mask:0xf bank_mask:0xf bound_ctrl:1
	v_add_f32_dpp v37, v37, v37 row_shl:2 row_mask:0xf bank_mask:0xf bound_ctrl:1
	v_add_f32_dpp v38, v38, v38 row_shl:2 row_mask:0xf bank_mask:0xf bound_ctrl:1
	v_add_f32_dpp v39, v39, v39 row_shl:2 row_mask:0xf bank_mask:0xf bound_ctrl:1
	v_add_f32_dpp v32, v32, v32 row_shl:4 row_mask:0xf bank_mask:0xf bound_ctrl:1
	v_add_f32_dpp v33, v33, v33 row_shl:4 row_mask:0xf bank_mask:0xf bound_ctrl:1
	v_add_f32_dpp v34, v34, v34 row_shl:4 row_mask:0xf bank_mask:0xf bound_ctrl:1
	v_add_f32_dpp v35, v35, v35 row_shl:4 row_mask:0xf bank_mask:0xf bound_ctrl:1
	v_add_f32_dpp v36, v36, v36 row_shl:4 row_mask:0xf bank_mask:0xf bound_ctrl:1
	v_add_f32_dpp v37, v37, v37 row_shl:4 row_mask:0xf bank_mask:0xf bound_ctrl:1
	v_add_f32_dpp v38, v38, v38 row_shl:4 row_mask:0xf bank_mask:0xf bound_ctrl:1
	v_add_f32_dpp v39, v39, v39 row_shl:4 row_mask:0xf bank_mask:0xf bound_ctrl:1
	v_add_f32_dpp v32, v32, v32 row_shl:8 row_mask:0xf bank_mask:0xf bound_ctrl:1
	v_add_f32_dpp v33, v33, v33 row_shl:8 row_mask:0xf bank_mask:0xf bound_ctrl:1
	v_add_f32_dpp v34, v34, v34 row_shl:8 row_mask:0xf bank_mask:0xf bound_ctrl:1
	v_add_f32_dpp v35, v35, v35 row_shl:8 row_mask:0xf bank_mask:0xf bound_ctrl:1
	v_add_f32_dpp v36, v36, v36 row_shl:8 row_mask:0xf bank_mask:0xf bound_ctrl:1
	v_add_f32_dpp v37, v37, v37 row_shl:8 row_mask:0xf bank_mask:0xf bound_ctrl:1
	v_add_f32_dpp v38, v38, v38 row_shl:8 row_mask:0xf bank_mask:0xf bound_ctrl:1
	v_add_f32_dpp v39, v39, v39 row_shl:8 row_mask:0xf bank_mask:0xf bound_ctrl:1
	v_mov_b32_dpp v88, v32 row_newbcast:0 row_mask:0xf bank_mask:0xf
	v_mov_b32_dpp v89, v33 row_newbcast:0 row_mask:0xf bank_mask:0xf
	v_mov_b32_dpp v90, v34 row_newbcast:0 row_mask:0xf bank_mask:0xf
	v_mov_b32_dpp v91, v35 row_newbcast:0 row_mask:0xf bank_mask:0xf
	v_mov_b32_dpp v92, v36 row_newbcast:0 row_mask:0xf bank_mask:0xf
	v_mov_b32_dpp v93, v37 row_newbcast:0 row_mask:0xf bank_mask:0xf
	v_mov_b32_dpp v94, v38 row_newbcast:0 row_mask:0xf bank_mask:0xf
	v_mov_b32_dpp v95, v39 row_newbcast:0 row_mask:0xf bank_mask:0xf
	v_add_f32_e32 v32, v32, v178
	v_add_f32_e32 v36, v36, v179
	v_add_f32_e32 v33, v33, v180
	v_add_f32_e32 v37, v37, v181
	v_add_f32_e32 v34, v34, v182
	v_add_f32_e32 v38, v38, v183
	v_add_f32_e32 v35, v35, v184
	v_add_f32_e32 v39, v39, v185
	v_mul_f32_e32 v132, v32, v103
	v_mul_f32_e32 v32, v32, v102
	v_fma_f32 v32, -v36, v103, v32
	v_fma_f32 v36, v36, v102, v132
	v_mul_f32_e32 v133, v33, v107
	v_mul_f32_e32 v33, v33, v106
	v_fma_f32 v33, -v37, v107, v33
	v_fma_f32 v37, v37, v106, v133
	v_mul_f32_e32 v132, v34, v111
	v_mul_f32_e32 v34, v34, v110
	v_fma_f32 v34, -v38, v111, v34
	v_fma_f32 v38, v38, v110, v132
	v_mul_f32_e32 v133, v35, v115
	v_mul_f32_e32 v35, v35, v114
	v_fma_f32 v35, -v39, v115, v35
	v_fma_f32 v39, v39, v114, v133
	v_add_f32_e32 v88, v88, v178
	v_add_f32_e32 v92, v92, v179
	v_mul_f32_e32 v132, v92, v117
	v_mul_f32_e32 v179, v88, v117
	v_fma_f32 v178, v88, v116, -v132
	v_fma_f32 v179, v92, v116, v179
	v_add_f32_e32 v89, v89, v180
	v_add_f32_e32 v93, v93, v181
	v_mul_f32_e32 v133, v93, v121
	v_mul_f32_e32 v181, v89, v121
	v_fma_f32 v180, v89, v120, -v133
	v_fma_f32 v181, v93, v120, v181
	v_add_f32_e32 v90, v90, v182
	v_add_f32_e32 v94, v94, v183
	v_mul_f32_e32 v132, v94, v125
	v_mul_f32_e32 v183, v90, v125
	v_fma_f32 v182, v90, v124, -v132
	v_fma_f32 v183, v94, v124, v183
	v_add_f32_e32 v91, v91, v184
	v_add_f32_e32 v95, v95, v185
	v_mul_f32_e32 v133, v95, v129
	v_mul_f32_e32 v185, v91, v129
	v_fma_f32 v184, v91, v128, -v133
	v_fma_f32 v185, v95, v128, v185
	s_waitcnt vmcnt(0)
	v_cvt_pk_bf16_f32 v80, v80, v81
	v_cvt_pk_bf16_f32 v81, v82, v83
	v_cvt_pk_bf16_f32 v82, -v84, -v85
	v_cvt_pk_bf16_f32 v83, -v86, -v87
	v_cvt_pk_bf16_f32 v96, v32, v33
	v_cvt_pk_bf16_f32 v97, v34, v35
	v_cvt_pk_bf16_f32 v98, v36, v37
	v_cvt_pk_bf16_f32 v99, v38, v39
	s_nop 1
	v_mfma_f32_16x16x32_bf16 v[16:19], v[80:83], v[96:99], v[16:19]
	v_cvt_pk_bf16_f32 v96, v40, v41
	v_cvt_pk_bf16_f32 v97, v42, v43
	v_cvt_pk_bf16_f32 v98, v44, v45
	v_cvt_pk_bf16_f32 v99, v46, v47
	s_nop 1
	v_mfma_f32_16x16x32_bf16 v[20:23], v[80:83], v[96:99], v[20:23]
	v_cvt_pk_bf16_f32 v96, v48, v49
	v_cvt_pk_bf16_f32 v97, v50, v51
	v_cvt_pk_bf16_f32 v98, v52, v53
	v_cvt_pk_bf16_f32 v99, v54, v55
	s_nop 1
	v_mfma_f32_16x16x32_bf16 v[24:27], v[80:83], v[96:99], v[24:27]
	v_cvt_pk_bf16_f32 v96, v56, v57
	v_cvt_pk_bf16_f32 v97, v58, v59
	v_cvt_pk_bf16_f32 v98, v60, v61
	v_cvt_pk_bf16_f32 v99, v62, v63
	s_nop 1
	v_mfma_f32_16x16x32_bf16 v[28:31], v[80:83], v[96:99], v[28:31]
	v_and_b32_e32 v100, 15, v205
	v_lshrrev_b32_e32 v101, 4, v205
	v_mul_u32_u24_e32 v102, 0xe00, v100
	v_lshl_add_u32 v102, v101, 3, v102
	v_lshlrev_b32_e32 v103, 9, v100
	v_lshl_add_u32 v103, v101, 3, v103
	v_lshlrev_b32_e32 v104, 4, v101
	s_mul_i32 s18, s9, 0xe00
	s_lshl_b32 s19, s7, 5
	s_add_i32 s18, s18, s19
	s_add_u32 s18, s18, 0x5e00c00
	s_add_u32 s18, s4, s18
	s_addc_u32 s19, s5, 0
	global_load_dwordx2 v[108:109], v102, s[18:19]
	s_add_u32 s18, s18, 0xe000
	s_addc_u32 s19, s19, 0
	global_load_dwordx2 v[110:111], v102, s[18:19]
	s_add_u32 s18, s18, 0xe000
	s_addc_u32 s19, s19, 0
	global_load_dwordx2 v[112:113], v102, s[18:19]
	s_add_u32 s18, s18, 0xe000
	s_addc_u32 s19, s19, 0
	global_load_dwordx2 v[114:115], v102, s[18:19]
	v_readlane_b32 s10, v247, 28
	s_lshl_b32 s10, s10, 10
	s_lshl_b32 s11, s7, 6
	s_add_i32 s10, s10, s11
	s_add_u32 s10, s10, 0x21fb20
	s_add_u32 s20, s4, s10
	s_addc_u32 s21, s5, 0
	global_load_dwordx4 v[116:119], v104, s[20:21]
	s_lshl_b32 s10, s9, 9
	s_add_i32 s10, s10, s11
	s_lshr_b32 s11, s11, 1
	s_sub_i32 s10, s10, s11
	s_add_u32 s10, s10, 0xc500000
	s_add_u32 s22, s4, s10
	s_addc_u32 s23, s5, 0
	s_waitcnt vmcnt(0)
	s_nop 4
	v_lshlrev_b32_e32 v120, 16, v108
	v_and_b32_e32 v121, 0xffff0000, v108
	v_lshlrev_b32_e32 v122, 16, v109
	v_and_b32_e32 v123, 0xffff0000, v109
	v_fmac_f32_e32 v16, v116, v120
	v_fmac_f32_e32 v17, v117, v121
	v_fmac_f32_e32 v18, v118, v122
	v_fmac_f32_e32 v19, v119, v123
	v_cvt_pk_bf16_f32 v124, v16, v17
	v_cvt_pk_bf16_f32 v125, v18, v19
	global_store_dwordx2 v103, v[124:125], s[22:23] offset:0
	s_add_u32 s22, s22, 0x2000
	s_addc_u32 s23, s23, 0
	v_lshlrev_b32_e32 v120, 16, v110
	v_and_b32_e32 v121, 0xffff0000, v110
	v_lshlrev_b32_e32 v122, 16, v111
	v_and_b32_e32 v123, 0xffff0000, v111
	v_fmac_f32_e32 v20, v116, v120
	v_fmac_f32_e32 v21, v117, v121
	v_fmac_f32_e32 v22, v118, v122
	v_fmac_f32_e32 v23, v119, v123
	v_cvt_pk_bf16_f32 v124, v20, v21
	v_cvt_pk_bf16_f32 v125, v22, v23
	global_store_dwordx2 v103, v[124:125], s[22:23] offset:0
	s_add_u32 s22, s22, 0x2000
	s_addc_u32 s23, s23, 0
	v_lshlrev_b32_e32 v120, 16, v112
	v_and_b32_e32 v121, 0xffff0000, v112
	v_lshlrev_b32_e32 v122, 16, v113
	v_and_b32_e32 v123, 0xffff0000, v113
	v_fmac_f32_e32 v24, v116, v120
	v_fmac_f32_e32 v25, v117, v121
	v_fmac_f32_e32 v26, v118, v122
	v_fmac_f32_e32 v27, v119, v123
	v_cvt_pk_bf16_f32 v124, v24, v25
	v_cvt_pk_bf16_f32 v125, v26, v27
	global_store_dwordx2 v103, v[124:125], s[22:23] offset:0
	s_add_u32 s22, s22, 0x2000
	s_addc_u32 s23, s23, 0
	v_lshlrev_b32_e32 v120, 16, v114
	v_and_b32_e32 v121, 0xffff0000, v114
	v_lshlrev_b32_e32 v122, 16, v115
	v_and_b32_e32 v123, 0xffff0000, v115
	v_fmac_f32_e32 v28, v116, v120
	v_fmac_f32_e32 v29, v117, v121
	v_fmac_f32_e32 v30, v118, v122
	v_fmac_f32_e32 v31, v119, v123
	v_cvt_pk_bf16_f32 v124, v28, v29
	v_cvt_pk_bf16_f32 v125, v30, v31
	global_store_dwordx2 v103, v[124:125], s[22:23] offset:0
	s_cmp_eq_u32 s37, 1
	s_cbranch_scc1 .Lss3_done
	s_add_i32 s36, s36, s30
	s_branch .Lss3_top

	.amdhsa_kernel _Z3fwd4Args
		.amdhsa_group_segment_fixed_size 0
		.amdhsa_private_segment_fixed_size 0
		.amdhsa_kernarg_size 576
		.amdhsa_user_sgpr_count 2
		.amdhsa_user_sgpr_dispatch_ptr 0
		.amdhsa_user_sgpr_queue_ptr 0
		.amdhsa_user_sgpr_kernarg_segment_ptr 1
		.amdhsa_user_sgpr_dispatch_id 0
		.amdhsa_user_sgpr_kernarg_preload_length 0
		.amdhsa_user_sgpr_kernarg_preload_offset 0
		.amdhsa_user_sgpr_private_segment_size 0
		.amdhsa_uses_dynamic_stack 0
		.amdhsa_enable_private_segment 0
		.amdhsa_system_sgpr_workgroup_id_x 1
		.amdhsa_system_sgpr_workgroup_id_y 0
		.amdhsa_system_sgpr_workgroup_id_z 0
		.amdhsa_system_sgpr_workgroup_info 0
		.amdhsa_system_vgpr_workitem_id 2
		.amdhsa_next_free_vgpr 248
		.amdhsa_next_free_sgpr 102
		.amdhsa_accum_offset 248
		.amdhsa_reserve_vcc 1
		.amdhsa_float_round_mode_32 0
		.amdhsa_float_round_mode_16_64 0
		.amdhsa_float_denorm_mode_32 3
		.amdhsa_float_denorm_mode_16_64 3
		.amdhsa_dx10_clamp 1
		.amdhsa_ieee_mode 1
		.amdhsa_fp16_overflow 0
		.amdhsa_tg_split 0
		.amdhsa_exception_fp_ieee_invalid_op 0
		.amdhsa_exception_fp_denorm_src 0
		.amdhsa_exception_fp_ieee_div_zero 0
		.amdhsa_exception_fp_ieee_overflow 0
		.amdhsa_exception_fp_ieee_underflow 0
		.amdhsa_exception_fp_ieee_inexact 0
		.amdhsa_exception_int_div_zero 0
	.end_amdhsa_kernel

amdhsa.kernels:
  - .agpr_count:     0
    .args:
      - .offset:         0
        .size:           320
        .value_kind:     by_value
      - .offset:         320
        .size:           4
        .value_kind:     hidden_block_count_x
      - .offset:         324
        .size:           4
        .value_kind:     hidden_block_count_y
      - .offset:         328
        .size:           4
        .value_kind:     hidden_block_count_z
      - .offset:         332
        .size:           2
        .value_kind:     hidden_group_size_x
      - .offset:         334
        .size:           2
        .value_kind:     hidden_group_size_y
      - .offset:         336
        .size:           2
        .value_kind:     hidden_group_size_z
      - .offset:         338
        .size:           2
        .value_kind:     hidden_remainder_x
      - .offset:         340
        .size:           2
        .value_kind:     hidden_remainder_y
      - .offset:         342
        .size:           2
        .value_kind:     hidden_remainder_z
      - .offset:         360
        .size:           8
        .value_kind:     hidden_global_offset_x
      - .offset:         368
        .size:           8
        .value_kind:     hidden_global_offset_y
      - .offset:         376
        .size:           8
        .value_kind:     hidden_global_offset_z
      - .offset:         384
        .size:           2
        .value_kind:     hidden_grid_dims
      - .offset:         408
        .size:           8
        .value_kind:     hidden_multigrid_sync_arg
      - .offset:         440
        .size:           4
        .value_kind:     hidden_dynamic_lds_size
    .group_segment_fixed_size: 0
    .kernarg_segment_align: 8
    .kernarg_segment_size: 576
    .language:       OpenCL C
    .language_version:
      - 2
      - 0
    .max_flat_workgroup_size: 512
    .name:           _Z3fwd4Args
    .private_segment_fixed_size: 0
    .sgpr_count:     108
    .sgpr_spill_count: 229
    .symbol:         _Z3fwd4Args.kd
    .uniform_work_group_size: 1
    .uses_dynamic_stack: false
    .vgpr_count:     248
    .vgpr_spill_count: 0
    .wavefront_size: 64
